# PEER select level-2b rewritten: lane = token, the 50 candidate sums held in registers, static 2-instruction compares per pair (exact ranks)
# speedup vs baseline: 1.0745x; 1.0070x over previous
; __device__ __forceinline__ void ph_peer_select(const Params& P, int layer, const h16* Q, int nrows, char* smem) {
;     ...
;     for (int i = tid; i < 64 * 50; i += NTHR) {
;       const int tok = i / 50, c = i % 50;
;       const float v = cd[tok * 52 + c];
;       int rank = 0;
;       for (int j = 0; j < 50; ++j) { const float o = cd[tok * 52 + j]; rank += (o > v || (o == v && j < c)) ? 1 : 0; }
;       if (rank < TOPK) { tv[tok * 16 + rank] = v; tp[tok * 16 + rank] = c; }
;     }
.LBB0_1893:
	s_or_b64 exec, exec, s[22:23]
	s_waitcnt lgkmcnt(0)
	s_barrier
	s_and_saveexec_b64 s[38:39], s[14:15]
	s_cbranch_execz .LBB0_1898
	s_mov_b64 exec, -1
	v_readfirstlane_b32 s4, v0
	s_lshr_b32 s4, s4, 6
	v_and_b32_e32 v213, 63, v0
	v_mul_u32_u24_e32 v215, 0xd0, v213
	v_add_u32_e32 v215, 0x10800, v215
	v_lshlrev_b32_e32 v213, 6, v213
	v_add_u32_e32 v213, 0x13c00, v213
	ds_read_b128 v[160:163], v215
	ds_read_b128 v[164:167], v215 offset:16
	ds_read_b128 v[168:171], v215 offset:32
	ds_read_b128 v[172:175], v215 offset:48
	ds_read_b128 v[176:179], v215 offset:64
	ds_read_b128 v[180:183], v215 offset:80
	ds_read_b128 v[184:187], v215 offset:96
	ds_read_b128 v[188:191], v215 offset:112
	ds_read_b128 v[192:195], v215 offset:128
	ds_read_b128 v[196:199], v215 offset:144
	ds_read_b128 v[200:203], v215 offset:160
	ds_read_b128 v[204:207], v215 offset:176
	ds_read_b64 v[208:209], v215 offset:192
	s_waitcnt lgkmcnt(0)
	s_cmp_eq_u32 s4, 0
	s_cbranch_scc1 .Lrk0_c0
	s_cmp_eq_u32 s4, 1
	s_cbranch_scc1 .Lrk0_c1
	s_cmp_eq_u32 s4, 2
	s_cbranch_scc1 .Lrk0_c2
	s_cmp_eq_u32 s4, 3
	s_cbranch_scc1 .Lrk0_c3
	s_cmp_eq_u32 s4, 4
	s_cbranch_scc1 .Lrk0_c4
	s_cmp_eq_u32 s4, 5
	s_cbranch_scc1 .Lrk0_c5
	s_cmp_eq_u32 s4, 6
	s_cbranch_scc1 .Lrk0_c6
	s_cmp_eq_u32 s4, 7
	s_cbranch_scc1 .Lrk0_c7
	s_branch .Lrk0_end
.Lrk0_c0:
	v_mov_b32_e32 v212, 0
	v_cmp_gt_f32_e64 s[22:23], v161, v160
	v_cmp_gt_f32_e64 s[24:25], v162, v160
	v_cmp_gt_f32_e64 s[26:27], v163, v160
	v_cmp_gt_f32_e64 s[28:29], v164, v160
	v_addc_co_u32_e64 v212, s[30:31], v212, 0, s[22:23]
	v_addc_co_u32_e64 v212, s[30:31], v212, 0, s[24:25]
	v_addc_co_u32_e64 v212, s[30:31], v212, 0, s[26:27]
	v_addc_co_u32_e64 v212, s[30:31], v212, 0, s[28:29]
	v_cmp_gt_f32_e64 s[22:23], v165, v160
	v_cmp_gt_f32_e64 s[24:25], v166, v160
	v_cmp_gt_f32_e64 s[26:27], v167, v160
	v_cmp_gt_f32_e64 s[28:29], v168, v160
	v_addc_co_u32_e64 v212, s[30:31], v212, 0, s[22:23]
	v_addc_co_u32_e64 v212, s[30:31], v212, 0, s[24:25]
	v_addc_co_u32_e64 v212, s[30:31], v212, 0, s[26:27]
	v_addc_co_u32_e64 v212, s[30:31], v212, 0, s[28:29]
	v_cmp_gt_f32_e64 s[22:23], v169, v160
	v_cmp_gt_f32_e64 s[24:25], v170, v160
	v_cmp_gt_f32_e64 s[26:27], v171, v160
	v_cmp_gt_f32_e64 s[28:29], v172, v160
	v_addc_co_u32_e64 v212, s[30:31], v212, 0, s[22:23]
	v_addc_co_u32_e64 v212, s[30:31], v212, 0, s[24:25]
	v_addc_co_u32_e64 v212, s[30:31], v212, 0, s[26:27]
	v_addc_co_u32_e64 v212, s[30:31], v212, 0, s[28:29]
	v_cmp_gt_f32_e64 s[22:23], v173, v160
	v_cmp_gt_f32_e64 s[24:25], v174, v160
	v_cmp_gt_f32_e64 s[26:27], v175, v160
	v_cmp_gt_f32_e64 s[28:29], v176, v160
	v_addc_co_u32_e64 v212, s[30:31], v212, 0, s[22:23]
	v_addc_co_u32_e64 v212, s[30:31], v212, 0, s[24:25]
	v_addc_co_u32_e64 v212, s[30:31], v212, 0, s[26:27]
	v_addc_co_u32_e64 v212, s[30:31], v212, 0, s[28:29]
	v_cmp_gt_f32_e64 s[22:23], v177, v160
	v_cmp_gt_f32_e64 s[24:25], v178, v160
	v_cmp_gt_f32_e64 s[26:27], v179, v160
	v_cmp_gt_f32_e64 s[28:29], v180, v160
	v_addc_co_u32_e64 v212, s[30:31], v212, 0, s[22:23]
	v_addc_co_u32_e64 v212, s[30:31], v212, 0, s[24:25]
	v_addc_co_u32_e64 v212, s[30:31], v212, 0, s[26:27]
	v_addc_co_u32_e64 v212, s[30:31], v212, 0, s[28:29]
	v_cmp_gt_f32_e64 s[22:23], v181, v160
	v_cmp_gt_f32_e64 s[24:25], v182, v160
	v_cmp_gt_f32_e64 s[26:27], v183, v160
	v_cmp_gt_f32_e64 s[28:29], v184, v160
	v_addc_co_u32_e64 v212, s[30:31], v212, 0, s[22:23]
	v_addc_co_u32_e64 v212, s[30:31], v212, 0, s[24:25]
	v_addc_co_u32_e64 v212, s[30:31], v212, 0, s[26:27]
	v_addc_co_u32_e64 v212, s[30:31], v212, 0, s[28:29]
	v_cmp_gt_f32_e64 s[22:23], v185, v160
	v_cmp_gt_f32_e64 s[24:25], v186, v160
	v_cmp_gt_f32_e64 s[26:27], v187, v160
	v_cmp_gt_f32_e64 s[28:29], v188, v160
	v_addc_co_u32_e64 v212, s[30:31], v212, 0, s[22:23]
	v_addc_co_u32_e64 v212, s[30:31], v212, 0, s[24:25]
	v_addc_co_u32_e64 v212, s[30:31], v212, 0, s[26:27]
	v_addc_co_u32_e64 v212, s[30:31], v212, 0, s[28:29]
	v_cmp_gt_f32_e64 s[22:23], v189, v160
	v_cmp_gt_f32_e64 s[24:25], v190, v160
	v_cmp_gt_f32_e64 s[26:27], v191, v160
	v_cmp_gt_f32_e64 s[28:29], v192, v160
	v_addc_co_u32_e64 v212, s[30:31], v212, 0, s[22:23]
	v_addc_co_u32_e64 v212, s[30:31], v212, 0, s[24:25]
	v_addc_co_u32_e64 v212, s[30:31], v212, 0, s[26:27]
	v_addc_co_u32_e64 v212, s[30:31], v212, 0, s[28:29]
	v_cmp_gt_f32_e64 s[22:23], v193, v160
	v_cmp_gt_f32_e64 s[24:25], v194, v160
	v_cmp_gt_f32_e64 s[26:27], v195, v160
	v_cmp_gt_f32_e64 s[28:29], v196, v160
	v_addc_co_u32_e64 v212, s[30:31], v212, 0, s[22:23]
	v_addc_co_u32_e64 v212, s[30:31], v212, 0, s[24:25]
	v_addc_co_u32_e64 v212, s[30:31], v212, 0, s[26:27]
	v_addc_co_u32_e64 v212, s[30:31], v212, 0, s[28:29]
	v_cmp_gt_f32_e64 s[22:23], v197, v160
	v_cmp_gt_f32_e64 s[24:25], v198, v160
	v_cmp_gt_f32_e64 s[26:27], v199, v160
	v_cmp_gt_f32_e64 s[28:29], v200, v160
	v_addc_co_u32_e64 v212, s[30:31], v212, 0, s[22:23]
	v_addc_co_u32_e64 v212, s[30:31], v212, 0, s[24:25]
	v_addc_co_u32_e64 v212, s[30:31], v212, 0, s[26:27]
	v_addc_co_u32_e64 v212, s[30:31], v212, 0, s[28:29]
	v_cmp_gt_f32_e64 s[22:23], v201, v160
	v_cmp_gt_f32_e64 s[24:25], v202, v160
	v_cmp_gt_f32_e64 s[26:27], v203, v160
	v_cmp_gt_f32_e64 s[28:29], v204, v160
	v_addc_co_u32_e64 v212, s[30:31], v212, 0, s[22:23]
	v_addc_co_u32_e64 v212, s[30:31], v212, 0, s[24:25]
	v_addc_co_u32_e64 v212, s[30:31], v212, 0, s[26:27]
	v_addc_co_u32_e64 v212, s[30:31], v212, 0, s[28:29]
	v_cmp_gt_f32_e64 s[22:23], v205, v160
	v_cmp_gt_f32_e64 s[24:25], v206, v160
	v_cmp_gt_f32_e64 s[26:27], v207, v160
	v_cmp_gt_f32_e64 s[28:29], v208, v160
	v_addc_co_u32_e64 v212, s[30:31], v212, 0, s[22:23]
	v_addc_co_u32_e64 v212, s[30:31], v212, 0, s[24:25]
	v_addc_co_u32_e64 v212, s[30:31], v212, 0, s[26:27]
	v_addc_co_u32_e64 v212, s[30:31], v212, 0, s[28:29]
	v_cmp_gt_f32_e64 s[22:23], v209, v160
	s_nop 0
	s_nop 0
	v_addc_co_u32_e64 v212, s[30:31], v212, 0, s[22:23]
	v_cmp_gt_u32_e32 vcc, 16, v212
	s_and_saveexec_b64 s[40:41], vcc
	v_lshl_add_u32 v214, v212, 2, v213
	v_mov_b32_e32 v212, 0
	ds_write_b32 v214, v160
	ds_write_b32 v214, v212 offset:4096
	s_mov_b64 exec, -1
	s_branch .Lrk0_c8
; __device__ __forceinline__ void ph_peer_select(const Params& P, int layer, const h16* Q, int nrows, char* smem) {
;     ...
;     for (int i = tid; i < 64 * 50; i += NTHR) {
;       const int tok = i / 50, c = i % 50;
;       const float v = cd[tok * 52 + c];
;       int rank = 0;
;       for (int j = 0; j < 50; ++j) { const float o = cd[tok * 52 + j]; rank += (o > v || (o == v && j < c)) ? 1 : 0; }
;       if (rank < TOPK) { tv[tok * 16 + rank] = v; tp[tok * 16 + rank] = c; }
;     }
.Lrk0_c1:
	v_mov_b32_e32 v212, 0
	v_cmp_ge_f32_e64 s[22:23], v160, v161
	v_cmp_gt_f32_e64 s[24:25], v162, v161
	v_cmp_gt_f32_e64 s[26:27], v163, v161
	v_cmp_gt_f32_e64 s[28:29], v164, v161
	v_addc_co_u32_e64 v212, s[30:31], v212, 0, s[22:23]
	v_addc_co_u32_e64 v212, s[30:31], v212, 0, s[24:25]
	v_addc_co_u32_e64 v212, s[30:31], v212, 0, s[26:27]
	v_addc_co_u32_e64 v212, s[30:31], v212, 0, s[28:29]
	v_cmp_gt_f32_e64 s[22:23], v165, v161
	v_cmp_gt_f32_e64 s[24:25], v166, v161
	v_cmp_gt_f32_e64 s[26:27], v167, v161
	v_cmp_gt_f32_e64 s[28:29], v168, v161
	v_addc_co_u32_e64 v212, s[30:31], v212, 0, s[22:23]
	v_addc_co_u32_e64 v212, s[30:31], v212, 0, s[24:25]
	v_addc_co_u32_e64 v212, s[30:31], v212, 0, s[26:27]
	v_addc_co_u32_e64 v212, s[30:31], v212, 0, s[28:29]
	v_cmp_gt_f32_e64 s[22:23], v169, v161
	v_cmp_gt_f32_e64 s[24:25], v170, v161
	v_cmp_gt_f32_e64 s[26:27], v171, v161
	v_cmp_gt_f32_e64 s[28:29], v172, v161
	v_addc_co_u32_e64 v212, s[30:31], v212, 0, s[22:23]
	v_addc_co_u32_e64 v212, s[30:31], v212, 0, s[24:25]
	v_addc_co_u32_e64 v212, s[30:31], v212, 0, s[26:27]
	v_addc_co_u32_e64 v212, s[30:31], v212, 0, s[28:29]
	v_cmp_gt_f32_e64 s[22:23], v173, v161
	v_cmp_gt_f32_e64 s[24:25], v174, v161
	v_cmp_gt_f32_e64 s[26:27], v175, v161
	v_cmp_gt_f32_e64 s[28:29], v176, v161
	v_addc_co_u32_e64 v212, s[30:31], v212, 0, s[22:23]
	v_addc_co_u32_e64 v212, s[30:31], v212, 0, s[24:25]
	v_addc_co_u32_e64 v212, s[30:31], v212, 0, s[26:27]
	v_addc_co_u32_e64 v212, s[30:31], v212, 0, s[28:29]
	v_cmp_gt_f32_e64 s[22:23], v177, v161
	v_cmp_gt_f32_e64 s[24:25], v178, v161
	v_cmp_gt_f32_e64 s[26:27], v179, v161
	v_cmp_gt_f32_e64 s[28:29], v180, v161
	v_addc_co_u32_e64 v212, s[30:31], v212, 0, s[22:23]
	v_addc_co_u32_e64 v212, s[30:31], v212, 0, s[24:25]
	v_addc_co_u32_e64 v212, s[30:31], v212, 0, s[26:27]
	v_addc_co_u32_e64 v212, s[30:31], v212, 0, s[28:29]
	v_cmp_gt_f32_e64 s[22:23], v181, v161
	v_cmp_gt_f32_e64 s[24:25], v182, v161
	v_cmp_gt_f32_e64 s[26:27], v183, v161
	v_cmp_gt_f32_e64 s[28:29], v184, v161
	v_addc_co_u32_e64 v212, s[30:31], v212, 0, s[22:23]
	v_addc_co_u32_e64 v212, s[30:31], v212, 0, s[24:25]
	v_addc_co_u32_e64 v212, s[30:31], v212, 0, s[26:27]
	v_addc_co_u32_e64 v212, s[30:31], v212, 0, s[28:29]
	v_cmp_gt_f32_e64 s[22:23], v185, v161
	v_cmp_gt_f32_e64 s[24:25], v186, v161
	v_cmp_gt_f32_e64 s[26:27], v187, v161
	v_cmp_gt_f32_e64 s[28:29], v188, v161
	v_addc_co_u32_e64 v212, s[30:31], v212, 0, s[22:23]
	v_addc_co_u32_e64 v212, s[30:31], v212, 0, s[24:25]
	v_addc_co_u32_e64 v212, s[30:31], v212, 0, s[26:27]
	v_addc_co_u32_e64 v212, s[30:31], v212, 0, s[28:29]
	v_cmp_gt_f32_e64 s[22:23], v189, v161
	v_cmp_gt_f32_e64 s[24:25], v190, v161
	v_cmp_gt_f32_e64 s[26:27], v191, v161
	v_cmp_gt_f32_e64 s[28:29], v192, v161
	v_addc_co_u32_e64 v212, s[30:31], v212, 0, s[22:23]
	v_addc_co_u32_e64 v212, s[30:31], v212, 0, s[24:25]
	v_addc_co_u32_e64 v212, s[30:31], v212, 0, s[26:27]
	v_addc_co_u32_e64 v212, s[30:31], v212, 0, s[28:29]
	v_cmp_gt_f32_e64 s[22:23], v193, v161
	v_cmp_gt_f32_e64 s[24:25], v194, v161
	v_cmp_gt_f32_e64 s[26:27], v195, v161
	v_cmp_gt_f32_e64 s[28:29], v196, v161
	v_addc_co_u32_e64 v212, s[30:31], v212, 0, s[22:23]
	v_addc_co_u32_e64 v212, s[30:31], v212, 0, s[24:25]
	v_addc_co_u32_e64 v212, s[30:31], v212, 0, s[26:27]
	v_addc_co_u32_e64 v212, s[30:31], v212, 0, s[28:29]
	v_cmp_gt_f32_e64 s[22:23], v197, v161
	v_cmp_gt_f32_e64 s[24:25], v198, v161
	v_cmp_gt_f32_e64 s[26:27], v199, v161
	v_cmp_gt_f32_e64 s[28:29], v200, v161
	v_addc_co_u32_e64 v212, s[30:31], v212, 0, s[22:23]
	v_addc_co_u32_e64 v212, s[30:31], v212, 0, s[24:25]
	v_addc_co_u32_e64 v212, s[30:31], v212, 0, s[26:27]
	v_addc_co_u32_e64 v212, s[30:31], v212, 0, s[28:29]
	v_cmp_gt_f32_e64 s[22:23], v201, v161
	v_cmp_gt_f32_e64 s[24:25], v202, v161
	v_cmp_gt_f32_e64 s[26:27], v203, v161
	v_cmp_gt_f32_e64 s[28:29], v204, v161
	v_addc_co_u32_e64 v212, s[30:31], v212, 0, s[22:23]
	v_addc_co_u32_e64 v212, s[30:31], v212, 0, s[24:25]
	v_addc_co_u32_e64 v212, s[30:31], v212, 0, s[26:27]
	v_addc_co_u32_e64 v212, s[30:31], v212, 0, s[28:29]
	v_cmp_gt_f32_e64 s[22:23], v205, v161
	v_cmp_gt_f32_e64 s[24:25], v206, v161
	v_cmp_gt_f32_e64 s[26:27], v207, v161
	v_cmp_gt_f32_e64 s[28:29], v208, v161
	v_addc_co_u32_e64 v212, s[30:31], v212, 0, s[22:23]
	v_addc_co_u32_e64 v212, s[30:31], v212, 0, s[24:25]
	v_addc_co_u32_e64 v212, s[30:31], v212, 0, s[26:27]
	v_addc_co_u32_e64 v212, s[30:31], v212, 0, s[28:29]
	v_cmp_gt_f32_e64 s[22:23], v209, v161
	s_nop 0
	s_nop 0
	v_addc_co_u32_e64 v212, s[30:31], v212, 0, s[22:23]
	v_cmp_gt_u32_e32 vcc, 16, v212
	s_and_saveexec_b64 s[40:41], vcc
	v_lshl_add_u32 v214, v212, 2, v213
	v_mov_b32_e32 v212, 1
	ds_write_b32 v214, v161
	ds_write_b32 v214, v212 offset:4096
	s_mov_b64 exec, -1
	s_branch .Lrk0_c9
; __device__ __forceinline__ void ph_peer_select(const Params& P, int layer, const h16* Q, int nrows, char* smem) {
;     ...
;     for (int i = tid; i < 64 * 50; i += NTHR) {
;       const int tok = i / 50, c = i % 50;
;       const float v = cd[tok * 52 + c];
;       int rank = 0;
;       for (int j = 0; j < 50; ++j) { const float o = cd[tok * 52 + j]; rank += (o > v || (o == v && j < c)) ? 1 : 0; }
;       if (rank < TOPK) { tv[tok * 16 + rank] = v; tp[tok * 16 + rank] = c; }
;     }
.Lrk0_c2:
	v_mov_b32_e32 v212, 0
	v_cmp_ge_f32_e64 s[22:23], v160, v162
	v_cmp_ge_f32_e64 s[24:25], v161, v162
	v_cmp_gt_f32_e64 s[26:27], v163, v162
	v_cmp_gt_f32_e64 s[28:29], v164, v162
	v_addc_co_u32_e64 v212, s[30:31], v212, 0, s[22:23]
	v_addc_co_u32_e64 v212, s[30:31], v212, 0, s[24:25]
	v_addc_co_u32_e64 v212, s[30:31], v212, 0, s[26:27]
	v_addc_co_u32_e64 v212, s[30:31], v212, 0, s[28:29]
	v_cmp_gt_f32_e64 s[22:23], v165, v162
	v_cmp_gt_f32_e64 s[24:25], v166, v162
	v_cmp_gt_f32_e64 s[26:27], v167, v162
	v_cmp_gt_f32_e64 s[28:29], v168, v162
	v_addc_co_u32_e64 v212, s[30:31], v212, 0, s[22:23]
	v_addc_co_u32_e64 v212, s[30:31], v212, 0, s[24:25]
	v_addc_co_u32_e64 v212, s[30:31], v212, 0, s[26:27]
	v_addc_co_u32_e64 v212, s[30:31], v212, 0, s[28:29]
	v_cmp_gt_f32_e64 s[22:23], v169, v162
	v_cmp_gt_f32_e64 s[24:25], v170, v162
	v_cmp_gt_f32_e64 s[26:27], v171, v162
	v_cmp_gt_f32_e64 s[28:29], v172, v162
	v_addc_co_u32_e64 v212, s[30:31], v212, 0, s[22:23]
	v_addc_co_u32_e64 v212, s[30:31], v212, 0, s[24:25]
	v_addc_co_u32_e64 v212, s[30:31], v212, 0, s[26:27]
	v_addc_co_u32_e64 v212, s[30:31], v212, 0, s[28:29]
	v_cmp_gt_f32_e64 s[22:23], v173, v162
	v_cmp_gt_f32_e64 s[24:25], v174, v162
	v_cmp_gt_f32_e64 s[26:27], v175, v162
	v_cmp_gt_f32_e64 s[28:29], v176, v162
	v_addc_co_u32_e64 v212, s[30:31], v212, 0, s[22:23]
	v_addc_co_u32_e64 v212, s[30:31], v212, 0, s[24:25]
	v_addc_co_u32_e64 v212, s[30:31], v212, 0, s[26:27]
	v_addc_co_u32_e64 v212, s[30:31], v212, 0, s[28:29]
	v_cmp_gt_f32_e64 s[22:23], v177, v162
	v_cmp_gt_f32_e64 s[24:25], v178, v162
	v_cmp_gt_f32_e64 s[26:27], v179, v162
	v_cmp_gt_f32_e64 s[28:29], v180, v162
	v_addc_co_u32_e64 v212, s[30:31], v212, 0, s[22:23]
	v_addc_co_u32_e64 v212, s[30:31], v212, 0, s[24:25]
	v_addc_co_u32_e64 v212, s[30:31], v212, 0, s[26:27]
	v_addc_co_u32_e64 v212, s[30:31], v212, 0, s[28:29]
	v_cmp_gt_f32_e64 s[22:23], v181, v162
	v_cmp_gt_f32_e64 s[24:25], v182, v162
	v_cmp_gt_f32_e64 s[26:27], v183, v162
	v_cmp_gt_f32_e64 s[28:29], v184, v162
	v_addc_co_u32_e64 v212, s[30:31], v212, 0, s[22:23]
	v_addc_co_u32_e64 v212, s[30:31], v212, 0, s[24:25]
	v_addc_co_u32_e64 v212, s[30:31], v212, 0, s[26:27]
	v_addc_co_u32_e64 v212, s[30:31], v212, 0, s[28:29]
	v_cmp_gt_f32_e64 s[22:23], v185, v162
	v_cmp_gt_f32_e64 s[24:25], v186, v162
	v_cmp_gt_f32_e64 s[26:27], v187, v162
	v_cmp_gt_f32_e64 s[28:29], v188, v162
	v_addc_co_u32_e64 v212, s[30:31], v212, 0, s[22:23]
	v_addc_co_u32_e64 v212, s[30:31], v212, 0, s[24:25]
	v_addc_co_u32_e64 v212, s[30:31], v212, 0, s[26:27]
	v_addc_co_u32_e64 v212, s[30:31], v212, 0, s[28:29]
	v_cmp_gt_f32_e64 s[22:23], v189, v162
	v_cmp_gt_f32_e64 s[24:25], v190, v162
	v_cmp_gt_f32_e64 s[26:27], v191, v162
	v_cmp_gt_f32_e64 s[28:29], v192, v162
	v_addc_co_u32_e64 v212, s[30:31], v212, 0, s[22:23]
	v_addc_co_u32_e64 v212, s[30:31], v212, 0, s[24:25]
	v_addc_co_u32_e64 v212, s[30:31], v212, 0, s[26:27]
	v_addc_co_u32_e64 v212, s[30:31], v212, 0, s[28:29]
	v_cmp_gt_f32_e64 s[22:23], v193, v162
	v_cmp_gt_f32_e64 s[24:25], v194, v162
	v_cmp_gt_f32_e64 s[26:27], v195, v162
	v_cmp_gt_f32_e64 s[28:29], v196, v162
	v_addc_co_u32_e64 v212, s[30:31], v212, 0, s[22:23]
	v_addc_co_u32_e64 v212, s[30:31], v212, 0, s[24:25]
	v_addc_co_u32_e64 v212, s[30:31], v212, 0, s[26:27]
	v_addc_co_u32_e64 v212, s[30:31], v212, 0, s[28:29]
	v_cmp_gt_f32_e64 s[22:23], v197, v162
	v_cmp_gt_f32_e64 s[24:25], v198, v162
	v_cmp_gt_f32_e64 s[26:27], v199, v162
	v_cmp_gt_f32_e64 s[28:29], v200, v162
	v_addc_co_u32_e64 v212, s[30:31], v212, 0, s[22:23]
	v_addc_co_u32_e64 v212, s[30:31], v212, 0, s[24:25]
	v_addc_co_u32_e64 v212, s[30:31], v212, 0, s[26:27]
	v_addc_co_u32_e64 v212, s[30:31], v212, 0, s[28:29]
	v_cmp_gt_f32_e64 s[22:23], v201, v162
	v_cmp_gt_f32_e64 s[24:25], v202, v162
	v_cmp_gt_f32_e64 s[26:27], v203, v162
	v_cmp_gt_f32_e64 s[28:29], v204, v162
	v_addc_co_u32_e64 v212, s[30:31], v212, 0, s[22:23]
	v_addc_co_u32_e64 v212, s[30:31], v212, 0, s[24:25]
	v_addc_co_u32_e64 v212, s[30:31], v212, 0, s[26:27]
	v_addc_co_u32_e64 v212, s[30:31], v212, 0, s[28:29]
	v_cmp_gt_f32_e64 s[22:23], v205, v162
	v_cmp_gt_f32_e64 s[24:25], v206, v162
	v_cmp_gt_f32_e64 s[26:27], v207, v162
	v_cmp_gt_f32_e64 s[28:29], v208, v162
	v_addc_co_u32_e64 v212, s[30:31], v212, 0, s[22:23]
	v_addc_co_u32_e64 v212, s[30:31], v212, 0, s[24:25]
	v_addc_co_u32_e64 v212, s[30:31], v212, 0, s[26:27]
	v_addc_co_u32_e64 v212, s[30:31], v212, 0, s[28:29]
	v_cmp_gt_f32_e64 s[22:23], v209, v162
	s_nop 0
	s_nop 0
	v_addc_co_u32_e64 v212, s[30:31], v212, 0, s[22:23]
	v_cmp_gt_u32_e32 vcc, 16, v212
	s_and_saveexec_b64 s[40:41], vcc
	v_lshl_add_u32 v214, v212, 2, v213
	v_mov_b32_e32 v212, 2
	ds_write_b32 v214, v162
	ds_write_b32 v214, v212 offset:4096
	s_mov_b64 exec, -1
	s_branch .Lrk0_c10
; __device__ __forceinline__ void ph_peer_select(const Params& P, int layer, const h16* Q, int nrows, char* smem) {
;     ...
;     for (int i = tid; i < 64 * 50; i += NTHR) {
;       const int tok = i / 50, c = i % 50;
;       const float v = cd[tok * 52 + c];
;       int rank = 0;
;       for (int j = 0; j < 50; ++j) { const float o = cd[tok * 52 + j]; rank += (o > v || (o == v && j < c)) ? 1 : 0; }
;       if (rank < TOPK) { tv[tok * 16 + rank] = v; tp[tok * 16 + rank] = c; }
;     }
.Lrk0_c3:
	v_mov_b32_e32 v212, 0
	v_cmp_ge_f32_e64 s[22:23], v160, v163
	v_cmp_ge_f32_e64 s[24:25], v161, v163
	v_cmp_ge_f32_e64 s[26:27], v162, v163
	v_cmp_gt_f32_e64 s[28:29], v164, v163
	v_addc_co_u32_e64 v212, s[30:31], v212, 0, s[22:23]
	v_addc_co_u32_e64 v212, s[30:31], v212, 0, s[24:25]
	v_addc_co_u32_e64 v212, s[30:31], v212, 0, s[26:27]
	v_addc_co_u32_e64 v212, s[30:31], v212, 0, s[28:29]
	v_cmp_gt_f32_e64 s[22:23], v165, v163
	v_cmp_gt_f32_e64 s[24:25], v166, v163
	v_cmp_gt_f32_e64 s[26:27], v167, v163
	v_cmp_gt_f32_e64 s[28:29], v168, v163
	v_addc_co_u32_e64 v212, s[30:31], v212, 0, s[22:23]
	v_addc_co_u32_e64 v212, s[30:31], v212, 0, s[24:25]
	v_addc_co_u32_e64 v212, s[30:31], v212, 0, s[26:27]
	v_addc_co_u32_e64 v212, s[30:31], v212, 0, s[28:29]
	v_cmp_gt_f32_e64 s[22:23], v169, v163
	v_cmp_gt_f32_e64 s[24:25], v170, v163
	v_cmp_gt_f32_e64 s[26:27], v171, v163
	v_cmp_gt_f32_e64 s[28:29], v172, v163
	v_addc_co_u32_e64 v212, s[30:31], v212, 0, s[22:23]
	v_addc_co_u32_e64 v212, s[30:31], v212, 0, s[24:25]
	v_addc_co_u32_e64 v212, s[30:31], v212, 0, s[26:27]
	v_addc_co_u32_e64 v212, s[30:31], v212, 0, s[28:29]
	v_cmp_gt_f32_e64 s[22:23], v173, v163
	v_cmp_gt_f32_e64 s[24:25], v174, v163
	v_cmp_gt_f32_e64 s[26:27], v175, v163
	v_cmp_gt_f32_e64 s[28:29], v176, v163
	v_addc_co_u32_e64 v212, s[30:31], v212, 0, s[22:23]
	v_addc_co_u32_e64 v212, s[30:31], v212, 0, s[24:25]
	v_addc_co_u32_e64 v212, s[30:31], v212, 0, s[26:27]
	v_addc_co_u32_e64 v212, s[30:31], v212, 0, s[28:29]
	v_cmp_gt_f32_e64 s[22:23], v177, v163
	v_cmp_gt_f32_e64 s[24:25], v178, v163
	v_cmp_gt_f32_e64 s[26:27], v179, v163
	v_cmp_gt_f32_e64 s[28:29], v180, v163
	v_addc_co_u32_e64 v212, s[30:31], v212, 0, s[22:23]
	v_addc_co_u32_e64 v212, s[30:31], v212, 0, s[24:25]
	v_addc_co_u32_e64 v212, s[30:31], v212, 0, s[26:27]
	v_addc_co_u32_e64 v212, s[30:31], v212, 0, s[28:29]
	v_cmp_gt_f32_e64 s[22:23], v181, v163
	v_cmp_gt_f32_e64 s[24:25], v182, v163
	v_cmp_gt_f32_e64 s[26:27], v183, v163
	v_cmp_gt_f32_e64 s[28:29], v184, v163
	v_addc_co_u32_e64 v212, s[30:31], v212, 0, s[22:23]
	v_addc_co_u32_e64 v212, s[30:31], v212, 0, s[24:25]
	v_addc_co_u32_e64 v212, s[30:31], v212, 0, s[26:27]
	v_addc_co_u32_e64 v212, s[30:31], v212, 0, s[28:29]
	v_cmp_gt_f32_e64 s[22:23], v185, v163
	v_cmp_gt_f32_e64 s[24:25], v186, v163
	v_cmp_gt_f32_e64 s[26:27], v187, v163
	v_cmp_gt_f32_e64 s[28:29], v188, v163
	v_addc_co_u32_e64 v212, s[30:31], v212, 0, s[22:23]
	v_addc_co_u32_e64 v212, s[30:31], v212, 0, s[24:25]
	v_addc_co_u32_e64 v212, s[30:31], v212, 0, s[26:27]
	v_addc_co_u32_e64 v212, s[30:31], v212, 0, s[28:29]
	v_cmp_gt_f32_e64 s[22:23], v189, v163
	v_cmp_gt_f32_e64 s[24:25], v190, v163
	v_cmp_gt_f32_e64 s[26:27], v191, v163
	v_cmp_gt_f32_e64 s[28:29], v192, v163
	v_addc_co_u32_e64 v212, s[30:31], v212, 0, s[22:23]
	v_addc_co_u32_e64 v212, s[30:31], v212, 0, s[24:25]
	v_addc_co_u32_e64 v212, s[30:31], v212, 0, s[26:27]
	v_addc_co_u32_e64 v212, s[30:31], v212, 0, s[28:29]
	v_cmp_gt_f32_e64 s[22:23], v193, v163
	v_cmp_gt_f32_e64 s[24:25], v194, v163
	v_cmp_gt_f32_e64 s[26:27], v195, v163
	v_cmp_gt_f32_e64 s[28:29], v196, v163
	v_addc_co_u32_e64 v212, s[30:31], v212, 0, s[22:23]
	v_addc_co_u32_e64 v212, s[30:31], v212, 0, s[24:25]
	v_addc_co_u32_e64 v212, s[30:31], v212, 0, s[26:27]
	v_addc_co_u32_e64 v212, s[30:31], v212, 0, s[28:29]
	v_cmp_gt_f32_e64 s[22:23], v197, v163
	v_cmp_gt_f32_e64 s[24:25], v198, v163
	v_cmp_gt_f32_e64 s[26:27], v199, v163
	v_cmp_gt_f32_e64 s[28:29], v200, v163
	v_addc_co_u32_e64 v212, s[30:31], v212, 0, s[22:23]
	v_addc_co_u32_e64 v212, s[30:31], v212, 0, s[24:25]
	v_addc_co_u32_e64 v212, s[30:31], v212, 0, s[26:27]
	v_addc_co_u32_e64 v212, s[30:31], v212, 0, s[28:29]
	v_cmp_gt_f32_e64 s[22:23], v201, v163
	v_cmp_gt_f32_e64 s[24:25], v202, v163
	v_cmp_gt_f32_e64 s[26:27], v203, v163
	v_cmp_gt_f32_e64 s[28:29], v204, v163
	v_addc_co_u32_e64 v212, s[30:31], v212, 0, s[22:23]
	v_addc_co_u32_e64 v212, s[30:31], v212, 0, s[24:25]
	v_addc_co_u32_e64 v212, s[30:31], v212, 0, s[26:27]
	v_addc_co_u32_e64 v212, s[30:31], v212, 0, s[28:29]
	v_cmp_gt_f32_e64 s[22:23], v205, v163
	v_cmp_gt_f32_e64 s[24:25], v206, v163
	v_cmp_gt_f32_e64 s[26:27], v207, v163
	v_cmp_gt_f32_e64 s[28:29], v208, v163
	v_addc_co_u32_e64 v212, s[30:31], v212, 0, s[22:23]
	v_addc_co_u32_e64 v212, s[30:31], v212, 0, s[24:25]
	v_addc_co_u32_e64 v212, s[30:31], v212, 0, s[26:27]
	v_addc_co_u32_e64 v212, s[30:31], v212, 0, s[28:29]
	v_cmp_gt_f32_e64 s[22:23], v209, v163
	s_nop 0
	s_nop 0
	v_addc_co_u32_e64 v212, s[30:31], v212, 0, s[22:23]
	v_cmp_gt_u32_e32 vcc, 16, v212
	s_and_saveexec_b64 s[40:41], vcc
	v_lshl_add_u32 v214, v212, 2, v213
	v_mov_b32_e32 v212, 3
	ds_write_b32 v214, v163
	ds_write_b32 v214, v212 offset:4096
	s_mov_b64 exec, -1
	s_branch .Lrk0_c11
; __device__ __forceinline__ void ph_peer_select(const Params& P, int layer, const h16* Q, int nrows, char* smem) {
;     ...
;     for (int i = tid; i < 64 * 50; i += NTHR) {
;       const int tok = i / 50, c = i % 50;
;       const float v = cd[tok * 52 + c];
;       int rank = 0;
;       for (int j = 0; j < 50; ++j) { const float o = cd[tok * 52 + j]; rank += (o > v || (o == v && j < c)) ? 1 : 0; }
;       if (rank < TOPK) { tv[tok * 16 + rank] = v; tp[tok * 16 + rank] = c; }
;     }
.Lrk0_c4:
	v_mov_b32_e32 v212, 0
	v_cmp_ge_f32_e64 s[22:23], v160, v164
	v_cmp_ge_f32_e64 s[24:25], v161, v164
	v_cmp_ge_f32_e64 s[26:27], v162, v164
	v_cmp_ge_f32_e64 s[28:29], v163, v164
	v_addc_co_u32_e64 v212, s[30:31], v212, 0, s[22:23]
	v_addc_co_u32_e64 v212, s[30:31], v212, 0, s[24:25]
	v_addc_co_u32_e64 v212, s[30:31], v212, 0, s[26:27]
	v_addc_co_u32_e64 v212, s[30:31], v212, 0, s[28:29]
	v_cmp_gt_f32_e64 s[22:23], v165, v164
	v_cmp_gt_f32_e64 s[24:25], v166, v164
	v_cmp_gt_f32_e64 s[26:27], v167, v164
	v_cmp_gt_f32_e64 s[28:29], v168, v164
	v_addc_co_u32_e64 v212, s[30:31], v212, 0, s[22:23]
	v_addc_co_u32_e64 v212, s[30:31], v212, 0, s[24:25]
	v_addc_co_u32_e64 v212, s[30:31], v212, 0, s[26:27]
	v_addc_co_u32_e64 v212, s[30:31], v212, 0, s[28:29]
	v_cmp_gt_f32_e64 s[22:23], v169, v164
	v_cmp_gt_f32_e64 s[24:25], v170, v164
	v_cmp_gt_f32_e64 s[26:27], v171, v164
	v_cmp_gt_f32_e64 s[28:29], v172, v164
	v_addc_co_u32_e64 v212, s[30:31], v212, 0, s[22:23]
	v_addc_co_u32_e64 v212, s[30:31], v212, 0, s[24:25]
	v_addc_co_u32_e64 v212, s[30:31], v212, 0, s[26:27]
	v_addc_co_u32_e64 v212, s[30:31], v212, 0, s[28:29]
	v_cmp_gt_f32_e64 s[22:23], v173, v164
	v_cmp_gt_f32_e64 s[24:25], v174, v164
	v_cmp_gt_f32_e64 s[26:27], v175, v164
	v_cmp_gt_f32_e64 s[28:29], v176, v164
	v_addc_co_u32_e64 v212, s[30:31], v212, 0, s[22:23]
	v_addc_co_u32_e64 v212, s[30:31], v212, 0, s[24:25]
	v_addc_co_u32_e64 v212, s[30:31], v212, 0, s[26:27]
	v_addc_co_u32_e64 v212, s[30:31], v212, 0, s[28:29]
	v_cmp_gt_f32_e64 s[22:23], v177, v164
	v_cmp_gt_f32_e64 s[24:25], v178, v164
	v_cmp_gt_f32_e64 s[26:27], v179, v164
	v_cmp_gt_f32_e64 s[28:29], v180, v164
	v_addc_co_u32_e64 v212, s[30:31], v212, 0, s[22:23]
	v_addc_co_u32_e64 v212, s[30:31], v212, 0, s[24:25]
	v_addc_co_u32_e64 v212, s[30:31], v212, 0, s[26:27]
	v_addc_co_u32_e64 v212, s[30:31], v212, 0, s[28:29]
	v_cmp_gt_f32_e64 s[22:23], v181, v164
	v_cmp_gt_f32_e64 s[24:25], v182, v164
	v_cmp_gt_f32_e64 s[26:27], v183, v164
	v_cmp_gt_f32_e64 s[28:29], v184, v164
	v_addc_co_u32_e64 v212, s[30:31], v212, 0, s[22:23]
	v_addc_co_u32_e64 v212, s[30:31], v212, 0, s[24:25]
	v_addc_co_u32_e64 v212, s[30:31], v212, 0, s[26:27]
	v_addc_co_u32_e64 v212, s[30:31], v212, 0, s[28:29]
	v_cmp_gt_f32_e64 s[22:23], v185, v164
	v_cmp_gt_f32_e64 s[24:25], v186, v164
	v_cmp_gt_f32_e64 s[26:27], v187, v164
	v_cmp_gt_f32_e64 s[28:29], v188, v164
	v_addc_co_u32_e64 v212, s[30:31], v212, 0, s[22:23]
	v_addc_co_u32_e64 v212, s[30:31], v212, 0, s[24:25]
	v_addc_co_u32_e64 v212, s[30:31], v212, 0, s[26:27]
	v_addc_co_u32_e64 v212, s[30:31], v212, 0, s[28:29]
	v_cmp_gt_f32_e64 s[22:23], v189, v164
	v_cmp_gt_f32_e64 s[24:25], v190, v164
	v_cmp_gt_f32_e64 s[26:27], v191, v164
	v_cmp_gt_f32_e64 s[28:29], v192, v164
	v_addc_co_u32_e64 v212, s[30:31], v212, 0, s[22:23]
	v_addc_co_u32_e64 v212, s[30:31], v212, 0, s[24:25]
	v_addc_co_u32_e64 v212, s[30:31], v212, 0, s[26:27]
	v_addc_co_u32_e64 v212, s[30:31], v212, 0, s[28:29]
	v_cmp_gt_f32_e64 s[22:23], v193, v164
	v_cmp_gt_f32_e64 s[24:25], v194, v164
	v_cmp_gt_f32_e64 s[26:27], v195, v164
	v_cmp_gt_f32_e64 s[28:29], v196, v164
	v_addc_co_u32_e64 v212, s[30:31], v212, 0, s[22:23]
	v_addc_co_u32_e64 v212, s[30:31], v212, 0, s[24:25]
	v_addc_co_u32_e64 v212, s[30:31], v212, 0, s[26:27]
	v_addc_co_u32_e64 v212, s[30:31], v212, 0, s[28:29]
	v_cmp_gt_f32_e64 s[22:23], v197, v164
	v_cmp_gt_f32_e64 s[24:25], v198, v164
	v_cmp_gt_f32_e64 s[26:27], v199, v164
	v_cmp_gt_f32_e64 s[28:29], v200, v164
	v_addc_co_u32_e64 v212, s[30:31], v212, 0, s[22:23]
	v_addc_co_u32_e64 v212, s[30:31], v212, 0, s[24:25]
	v_addc_co_u32_e64 v212, s[30:31], v212, 0, s[26:27]
	v_addc_co_u32_e64 v212, s[30:31], v212, 0, s[28:29]
	v_cmp_gt_f32_e64 s[22:23], v201, v164
	v_cmp_gt_f32_e64 s[24:25], v202, v164
	v_cmp_gt_f32_e64 s[26:27], v203, v164
	v_cmp_gt_f32_e64 s[28:29], v204, v164
	v_addc_co_u32_e64 v212, s[30:31], v212, 0, s[22:23]
	v_addc_co_u32_e64 v212, s[30:31], v212, 0, s[24:25]
	v_addc_co_u32_e64 v212, s[30:31], v212, 0, s[26:27]
	v_addc_co_u32_e64 v212, s[30:31], v212, 0, s[28:29]
	v_cmp_gt_f32_e64 s[22:23], v205, v164
	v_cmp_gt_f32_e64 s[24:25], v206, v164
	v_cmp_gt_f32_e64 s[26:27], v207, v164
	v_cmp_gt_f32_e64 s[28:29], v208, v164
	v_addc_co_u32_e64 v212, s[30:31], v212, 0, s[22:23]
	v_addc_co_u32_e64 v212, s[30:31], v212, 0, s[24:25]
	v_addc_co_u32_e64 v212, s[30:31], v212, 0, s[26:27]
	v_addc_co_u32_e64 v212, s[30:31], v212, 0, s[28:29]
	v_cmp_gt_f32_e64 s[22:23], v209, v164
	s_nop 0
	s_nop 0
	v_addc_co_u32_e64 v212, s[30:31], v212, 0, s[22:23]
	v_cmp_gt_u32_e32 vcc, 16, v212
	s_and_saveexec_b64 s[40:41], vcc
	v_lshl_add_u32 v214, v212, 2, v213
	v_mov_b32_e32 v212, 4
	ds_write_b32 v214, v164
	ds_write_b32 v214, v212 offset:4096
	s_mov_b64 exec, -1
	s_branch .Lrk0_c12
; __device__ __forceinline__ void ph_peer_select(const Params& P, int layer, const h16* Q, int nrows, char* smem) {
;     ...
;     for (int i = tid; i < 64 * 50; i += NTHR) {
;       const int tok = i / 50, c = i % 50;
;       const float v = cd[tok * 52 + c];
;       int rank = 0;
;       for (int j = 0; j < 50; ++j) { const float o = cd[tok * 52 + j]; rank += (o > v || (o == v && j < c)) ? 1 : 0; }
;       if (rank < TOPK) { tv[tok * 16 + rank] = v; tp[tok * 16 + rank] = c; }
;     }
.Lrk0_c5:
	v_mov_b32_e32 v212, 0
	v_cmp_ge_f32_e64 s[22:23], v160, v165
	v_cmp_ge_f32_e64 s[24:25], v161, v165
	v_cmp_ge_f32_e64 s[26:27], v162, v165
	v_cmp_ge_f32_e64 s[28:29], v163, v165
	v_addc_co_u32_e64 v212, s[30:31], v212, 0, s[22:23]
	v_addc_co_u32_e64 v212, s[30:31], v212, 0, s[24:25]
	v_addc_co_u32_e64 v212, s[30:31], v212, 0, s[26:27]
	v_addc_co_u32_e64 v212, s[30:31], v212, 0, s[28:29]
	v_cmp_ge_f32_e64 s[22:23], v164, v165
	v_cmp_gt_f32_e64 s[24:25], v166, v165
	v_cmp_gt_f32_e64 s[26:27], v167, v165
	v_cmp_gt_f32_e64 s[28:29], v168, v165
	v_addc_co_u32_e64 v212, s[30:31], v212, 0, s[22:23]
	v_addc_co_u32_e64 v212, s[30:31], v212, 0, s[24:25]
	v_addc_co_u32_e64 v212, s[30:31], v212, 0, s[26:27]
	v_addc_co_u32_e64 v212, s[30:31], v212, 0, s[28:29]
	v_cmp_gt_f32_e64 s[22:23], v169, v165
	v_cmp_gt_f32_e64 s[24:25], v170, v165
	v_cmp_gt_f32_e64 s[26:27], v171, v165
	v_cmp_gt_f32_e64 s[28:29], v172, v165
	v_addc_co_u32_e64 v212, s[30:31], v212, 0, s[22:23]
	v_addc_co_u32_e64 v212, s[30:31], v212, 0, s[24:25]
	v_addc_co_u32_e64 v212, s[30:31], v212, 0, s[26:27]
	v_addc_co_u32_e64 v212, s[30:31], v212, 0, s[28:29]
	v_cmp_gt_f32_e64 s[22:23], v173, v165
	v_cmp_gt_f32_e64 s[24:25], v174, v165
	v_cmp_gt_f32_e64 s[26:27], v175, v165
	v_cmp_gt_f32_e64 s[28:29], v176, v165
	v_addc_co_u32_e64 v212, s[30:31], v212, 0, s[22:23]
	v_addc_co_u32_e64 v212, s[30:31], v212, 0, s[24:25]
	v_addc_co_u32_e64 v212, s[30:31], v212, 0, s[26:27]
	v_addc_co_u32_e64 v212, s[30:31], v212, 0, s[28:29]
	v_cmp_gt_f32_e64 s[22:23], v177, v165
	v_cmp_gt_f32_e64 s[24:25], v178, v165
	v_cmp_gt_f32_e64 s[26:27], v179, v165
	v_cmp_gt_f32_e64 s[28:29], v180, v165
	v_addc_co_u32_e64 v212, s[30:31], v212, 0, s[22:23]
	v_addc_co_u32_e64 v212, s[30:31], v212, 0, s[24:25]
	v_addc_co_u32_e64 v212, s[30:31], v212, 0, s[26:27]
	v_addc_co_u32_e64 v212, s[30:31], v212, 0, s[28:29]
	v_cmp_gt_f32_e64 s[22:23], v181, v165
	v_cmp_gt_f32_e64 s[24:25], v182, v165
	v_cmp_gt_f32_e64 s[26:27], v183, v165
	v_cmp_gt_f32_e64 s[28:29], v184, v165
	v_addc_co_u32_e64 v212, s[30:31], v212, 0, s[22:23]
	v_addc_co_u32_e64 v212, s[30:31], v212, 0, s[24:25]
	v_addc_co_u32_e64 v212, s[30:31], v212, 0, s[26:27]
	v_addc_co_u32_e64 v212, s[30:31], v212, 0, s[28:29]
	v_cmp_gt_f32_e64 s[22:23], v185, v165
	v_cmp_gt_f32_e64 s[24:25], v186, v165
	v_cmp_gt_f32_e64 s[26:27], v187, v165
	v_cmp_gt_f32_e64 s[28:29], v188, v165
	v_addc_co_u32_e64 v212, s[30:31], v212, 0, s[22:23]
	v_addc_co_u32_e64 v212, s[30:31], v212, 0, s[24:25]
	v_addc_co_u32_e64 v212, s[30:31], v212, 0, s[26:27]
	v_addc_co_u32_e64 v212, s[30:31], v212, 0, s[28:29]
	v_cmp_gt_f32_e64 s[22:23], v189, v165
	v_cmp_gt_f32_e64 s[24:25], v190, v165
	v_cmp_gt_f32_e64 s[26:27], v191, v165
	v_cmp_gt_f32_e64 s[28:29], v192, v165
	v_addc_co_u32_e64 v212, s[30:31], v212, 0, s[22:23]
	v_addc_co_u32_e64 v212, s[30:31], v212, 0, s[24:25]
	v_addc_co_u32_e64 v212, s[30:31], v212, 0, s[26:27]
	v_addc_co_u32_e64 v212, s[30:31], v212, 0, s[28:29]
	v_cmp_gt_f32_e64 s[22:23], v193, v165
	v_cmp_gt_f32_e64 s[24:25], v194, v165
	v_cmp_gt_f32_e64 s[26:27], v195, v165
	v_cmp_gt_f32_e64 s[28:29], v196, v165
	v_addc_co_u32_e64 v212, s[30:31], v212, 0, s[22:23]
	v_addc_co_u32_e64 v212, s[30:31], v212, 0, s[24:25]
	v_addc_co_u32_e64 v212, s[30:31], v212, 0, s[26:27]
	v_addc_co_u32_e64 v212, s[30:31], v212, 0, s[28:29]
	v_cmp_gt_f32_e64 s[22:23], v197, v165
	v_cmp_gt_f32_e64 s[24:25], v198, v165
	v_cmp_gt_f32_e64 s[26:27], v199, v165
	v_cmp_gt_f32_e64 s[28:29], v200, v165
	v_addc_co_u32_e64 v212, s[30:31], v212, 0, s[22:23]
	v_addc_co_u32_e64 v212, s[30:31], v212, 0, s[24:25]
	v_addc_co_u32_e64 v212, s[30:31], v212, 0, s[26:27]
	v_addc_co_u32_e64 v212, s[30:31], v212, 0, s[28:29]
	v_cmp_gt_f32_e64 s[22:23], v201, v165
	v_cmp_gt_f32_e64 s[24:25], v202, v165
	v_cmp_gt_f32_e64 s[26:27], v203, v165
	v_cmp_gt_f32_e64 s[28:29], v204, v165
	v_addc_co_u32_e64 v212, s[30:31], v212, 0, s[22:23]
	v_addc_co_u32_e64 v212, s[30:31], v212, 0, s[24:25]
	v_addc_co_u32_e64 v212, s[30:31], v212, 0, s[26:27]
	v_addc_co_u32_e64 v212, s[30:31], v212, 0, s[28:29]
	v_cmp_gt_f32_e64 s[22:23], v205, v165
	v_cmp_gt_f32_e64 s[24:25], v206, v165
	v_cmp_gt_f32_e64 s[26:27], v207, v165
	v_cmp_gt_f32_e64 s[28:29], v208, v165
	v_addc_co_u32_e64 v212, s[30:31], v212, 0, s[22:23]
	v_addc_co_u32_e64 v212, s[30:31], v212, 0, s[24:25]
	v_addc_co_u32_e64 v212, s[30:31], v212, 0, s[26:27]
	v_addc_co_u32_e64 v212, s[30:31], v212, 0, s[28:29]
	v_cmp_gt_f32_e64 s[22:23], v209, v165
	s_nop 0
	s_nop 0
	v_addc_co_u32_e64 v212, s[30:31], v212, 0, s[22:23]
	v_cmp_gt_u32_e32 vcc, 16, v212
	s_and_saveexec_b64 s[40:41], vcc
	v_lshl_add_u32 v214, v212, 2, v213
	v_mov_b32_e32 v212, 5
	ds_write_b32 v214, v165
	ds_write_b32 v214, v212 offset:4096
	s_mov_b64 exec, -1
	s_branch .Lrk0_c13
; __device__ __forceinline__ void ph_peer_select(const Params& P, int layer, const h16* Q, int nrows, char* smem) {
;     ...
;     for (int i = tid; i < 64 * 50; i += NTHR) {
;       const int tok = i / 50, c = i % 50;
;       const float v = cd[tok * 52 + c];
;       int rank = 0;
;       for (int j = 0; j < 50; ++j) { const float o = cd[tok * 52 + j]; rank += (o > v || (o == v && j < c)) ? 1 : 0; }
;       if (rank < TOPK) { tv[tok * 16 + rank] = v; tp[tok * 16 + rank] = c; }
;     }
.Lrk0_c6:
	v_mov_b32_e32 v212, 0
	v_cmp_ge_f32_e64 s[22:23], v160, v166
	v_cmp_ge_f32_e64 s[24:25], v161, v166
	v_cmp_ge_f32_e64 s[26:27], v162, v166
	v_cmp_ge_f32_e64 s[28:29], v163, v166
	v_addc_co_u32_e64 v212, s[30:31], v212, 0, s[22:23]
	v_addc_co_u32_e64 v212, s[30:31], v212, 0, s[24:25]
	v_addc_co_u32_e64 v212, s[30:31], v212, 0, s[26:27]
	v_addc_co_u32_e64 v212, s[30:31], v212, 0, s[28:29]
	v_cmp_ge_f32_e64 s[22:23], v164, v166
	v_cmp_ge_f32_e64 s[24:25], v165, v166
	v_cmp_gt_f32_e64 s[26:27], v167, v166
	v_cmp_gt_f32_e64 s[28:29], v168, v166
	v_addc_co_u32_e64 v212, s[30:31], v212, 0, s[22:23]
	v_addc_co_u32_e64 v212, s[30:31], v212, 0, s[24:25]
	v_addc_co_u32_e64 v212, s[30:31], v212, 0, s[26:27]
	v_addc_co_u32_e64 v212, s[30:31], v212, 0, s[28:29]
	v_cmp_gt_f32_e64 s[22:23], v169, v166
	v_cmp_gt_f32_e64 s[24:25], v170, v166
	v_cmp_gt_f32_e64 s[26:27], v171, v166
	v_cmp_gt_f32_e64 s[28:29], v172, v166
	v_addc_co_u32_e64 v212, s[30:31], v212, 0, s[22:23]
	v_addc_co_u32_e64 v212, s[30:31], v212, 0, s[24:25]
	v_addc_co_u32_e64 v212, s[30:31], v212, 0, s[26:27]
	v_addc_co_u32_e64 v212, s[30:31], v212, 0, s[28:29]
	v_cmp_gt_f32_e64 s[22:23], v173, v166
	v_cmp_gt_f32_e64 s[24:25], v174, v166
	v_cmp_gt_f32_e64 s[26:27], v175, v166
	v_cmp_gt_f32_e64 s[28:29], v176, v166
	v_addc_co_u32_e64 v212, s[30:31], v212, 0, s[22:23]
	v_addc_co_u32_e64 v212, s[30:31], v212, 0, s[24:25]
	v_addc_co_u32_e64 v212, s[30:31], v212, 0, s[26:27]
	v_addc_co_u32_e64 v212, s[30:31], v212, 0, s[28:29]
	v_cmp_gt_f32_e64 s[22:23], v177, v166
	v_cmp_gt_f32_e64 s[24:25], v178, v166
	v_cmp_gt_f32_e64 s[26:27], v179, v166
	v_cmp_gt_f32_e64 s[28:29], v180, v166
	v_addc_co_u32_e64 v212, s[30:31], v212, 0, s[22:23]
	v_addc_co_u32_e64 v212, s[30:31], v212, 0, s[24:25]
	v_addc_co_u32_e64 v212, s[30:31], v212, 0, s[26:27]
	v_addc_co_u32_e64 v212, s[30:31], v212, 0, s[28:29]
	v_cmp_gt_f32_e64 s[22:23], v181, v166
	v_cmp_gt_f32_e64 s[24:25], v182, v166
	v_cmp_gt_f32_e64 s[26:27], v183, v166
	v_cmp_gt_f32_e64 s[28:29], v184, v166
	v_addc_co_u32_e64 v212, s[30:31], v212, 0, s[22:23]
	v_addc_co_u32_e64 v212, s[30:31], v212, 0, s[24:25]
	v_addc_co_u32_e64 v212, s[30:31], v212, 0, s[26:27]
	v_addc_co_u32_e64 v212, s[30:31], v212, 0, s[28:29]
	v_cmp_gt_f32_e64 s[22:23], v185, v166
	v_cmp_gt_f32_e64 s[24:25], v186, v166
	v_cmp_gt_f32_e64 s[26:27], v187, v166
	v_cmp_gt_f32_e64 s[28:29], v188, v166
	v_addc_co_u32_e64 v212, s[30:31], v212, 0, s[22:23]
	v_addc_co_u32_e64 v212, s[30:31], v212, 0, s[24:25]
	v_addc_co_u32_e64 v212, s[30:31], v212, 0, s[26:27]
	v_addc_co_u32_e64 v212, s[30:31], v212, 0, s[28:29]
	v_cmp_gt_f32_e64 s[22:23], v189, v166
	v_cmp_gt_f32_e64 s[24:25], v190, v166
	v_cmp_gt_f32_e64 s[26:27], v191, v166
	v_cmp_gt_f32_e64 s[28:29], v192, v166
	v_addc_co_u32_e64 v212, s[30:31], v212, 0, s[22:23]
	v_addc_co_u32_e64 v212, s[30:31], v212, 0, s[24:25]
	v_addc_co_u32_e64 v212, s[30:31], v212, 0, s[26:27]
	v_addc_co_u32_e64 v212, s[30:31], v212, 0, s[28:29]
	v_cmp_gt_f32_e64 s[22:23], v193, v166
	v_cmp_gt_f32_e64 s[24:25], v194, v166
	v_cmp_gt_f32_e64 s[26:27], v195, v166
	v_cmp_gt_f32_e64 s[28:29], v196, v166
	v_addc_co_u32_e64 v212, s[30:31], v212, 0, s[22:23]
	v_addc_co_u32_e64 v212, s[30:31], v212, 0, s[24:25]
	v_addc_co_u32_e64 v212, s[30:31], v212, 0, s[26:27]
	v_addc_co_u32_e64 v212, s[30:31], v212, 0, s[28:29]
	v_cmp_gt_f32_e64 s[22:23], v197, v166
	v_cmp_gt_f32_e64 s[24:25], v198, v166
	v_cmp_gt_f32_e64 s[26:27], v199, v166
	v_cmp_gt_f32_e64 s[28:29], v200, v166
	v_addc_co_u32_e64 v212, s[30:31], v212, 0, s[22:23]
	v_addc_co_u32_e64 v212, s[30:31], v212, 0, s[24:25]
	v_addc_co_u32_e64 v212, s[30:31], v212, 0, s[26:27]
	v_addc_co_u32_e64 v212, s[30:31], v212, 0, s[28:29]
	v_cmp_gt_f32_e64 s[22:23], v201, v166
	v_cmp_gt_f32_e64 s[24:25], v202, v166
	v_cmp_gt_f32_e64 s[26:27], v203, v166
	v_cmp_gt_f32_e64 s[28:29], v204, v166
	v_addc_co_u32_e64 v212, s[30:31], v212, 0, s[22:23]
	v_addc_co_u32_e64 v212, s[30:31], v212, 0, s[24:25]
	v_addc_co_u32_e64 v212, s[30:31], v212, 0, s[26:27]
	v_addc_co_u32_e64 v212, s[30:31], v212, 0, s[28:29]
	v_cmp_gt_f32_e64 s[22:23], v205, v166
	v_cmp_gt_f32_e64 s[24:25], v206, v166
	v_cmp_gt_f32_e64 s[26:27], v207, v166
	v_cmp_gt_f32_e64 s[28:29], v208, v166
	v_addc_co_u32_e64 v212, s[30:31], v212, 0, s[22:23]
	v_addc_co_u32_e64 v212, s[30:31], v212, 0, s[24:25]
	v_addc_co_u32_e64 v212, s[30:31], v212, 0, s[26:27]
	v_addc_co_u32_e64 v212, s[30:31], v212, 0, s[28:29]
	v_cmp_gt_f32_e64 s[22:23], v209, v166
	s_nop 0
	s_nop 0
	v_addc_co_u32_e64 v212, s[30:31], v212, 0, s[22:23]
	v_cmp_gt_u32_e32 vcc, 16, v212
	s_and_saveexec_b64 s[40:41], vcc
	v_lshl_add_u32 v214, v212, 2, v213
	v_mov_b32_e32 v212, 6
	ds_write_b32 v214, v166
	ds_write_b32 v214, v212 offset:4096
	s_mov_b64 exec, -1
	s_branch .Lrk0_c14
; __device__ __forceinline__ void ph_peer_select(const Params& P, int layer, const h16* Q, int nrows, char* smem) {
;     ...
;     for (int i = tid; i < 64 * 50; i += NTHR) {
;       const int tok = i / 50, c = i % 50;
;       const float v = cd[tok * 52 + c];
;       int rank = 0;
;       for (int j = 0; j < 50; ++j) { const float o = cd[tok * 52 + j]; rank += (o > v || (o == v && j < c)) ? 1 : 0; }
;       if (rank < TOPK) { tv[tok * 16 + rank] = v; tp[tok * 16 + rank] = c; }
;     }
.Lrk0_c7:
	v_mov_b32_e32 v212, 0
	v_cmp_ge_f32_e64 s[22:23], v160, v167
	v_cmp_ge_f32_e64 s[24:25], v161, v167
	v_cmp_ge_f32_e64 s[26:27], v162, v167
	v_cmp_ge_f32_e64 s[28:29], v163, v167
	v_addc_co_u32_e64 v212, s[30:31], v212, 0, s[22:23]
	v_addc_co_u32_e64 v212, s[30:31], v212, 0, s[24:25]
	v_addc_co_u32_e64 v212, s[30:31], v212, 0, s[26:27]
	v_addc_co_u32_e64 v212, s[30:31], v212, 0, s[28:29]
	v_cmp_ge_f32_e64 s[22:23], v164, v167
	v_cmp_ge_f32_e64 s[24:25], v165, v167
	v_cmp_ge_f32_e64 s[26:27], v166, v167
	v_cmp_gt_f32_e64 s[28:29], v168, v167
	v_addc_co_u32_e64 v212, s[30:31], v212, 0, s[22:23]
	v_addc_co_u32_e64 v212, s[30:31], v212, 0, s[24:25]
	v_addc_co_u32_e64 v212, s[30:31], v212, 0, s[26:27]
	v_addc_co_u32_e64 v212, s[30:31], v212, 0, s[28:29]
	v_cmp_gt_f32_e64 s[22:23], v169, v167
	v_cmp_gt_f32_e64 s[24:25], v170, v167
	v_cmp_gt_f32_e64 s[26:27], v171, v167
	v_cmp_gt_f32_e64 s[28:29], v172, v167
	v_addc_co_u32_e64 v212, s[30:31], v212, 0, s[22:23]
	v_addc_co_u32_e64 v212, s[30:31], v212, 0, s[24:25]
	v_addc_co_u32_e64 v212, s[30:31], v212, 0, s[26:27]
	v_addc_co_u32_e64 v212, s[30:31], v212, 0, s[28:29]
	v_cmp_gt_f32_e64 s[22:23], v173, v167
	v_cmp_gt_f32_e64 s[24:25], v174, v167
	v_cmp_gt_f32_e64 s[26:27], v175, v167
	v_cmp_gt_f32_e64 s[28:29], v176, v167
	v_addc_co_u32_e64 v212, s[30:31], v212, 0, s[22:23]
	v_addc_co_u32_e64 v212, s[30:31], v212, 0, s[24:25]
	v_addc_co_u32_e64 v212, s[30:31], v212, 0, s[26:27]
	v_addc_co_u32_e64 v212, s[30:31], v212, 0, s[28:29]
	v_cmp_gt_f32_e64 s[22:23], v177, v167
	v_cmp_gt_f32_e64 s[24:25], v178, v167
	v_cmp_gt_f32_e64 s[26:27], v179, v167
	v_cmp_gt_f32_e64 s[28:29], v180, v167
	v_addc_co_u32_e64 v212, s[30:31], v212, 0, s[22:23]
	v_addc_co_u32_e64 v212, s[30:31], v212, 0, s[24:25]
	v_addc_co_u32_e64 v212, s[30:31], v212, 0, s[26:27]
	v_addc_co_u32_e64 v212, s[30:31], v212, 0, s[28:29]
	v_cmp_gt_f32_e64 s[22:23], v181, v167
	v_cmp_gt_f32_e64 s[24:25], v182, v167
	v_cmp_gt_f32_e64 s[26:27], v183, v167
	v_cmp_gt_f32_e64 s[28:29], v184, v167
	v_addc_co_u32_e64 v212, s[30:31], v212, 0, s[22:23]
	v_addc_co_u32_e64 v212, s[30:31], v212, 0, s[24:25]
	v_addc_co_u32_e64 v212, s[30:31], v212, 0, s[26:27]
	v_addc_co_u32_e64 v212, s[30:31], v212, 0, s[28:29]
	v_cmp_gt_f32_e64 s[22:23], v185, v167
	v_cmp_gt_f32_e64 s[24:25], v186, v167
	v_cmp_gt_f32_e64 s[26:27], v187, v167
	v_cmp_gt_f32_e64 s[28:29], v188, v167
	v_addc_co_u32_e64 v212, s[30:31], v212, 0, s[22:23]
	v_addc_co_u32_e64 v212, s[30:31], v212, 0, s[24:25]
	v_addc_co_u32_e64 v212, s[30:31], v212, 0, s[26:27]
	v_addc_co_u32_e64 v212, s[30:31], v212, 0, s[28:29]
	v_cmp_gt_f32_e64 s[22:23], v189, v167
	v_cmp_gt_f32_e64 s[24:25], v190, v167
	v_cmp_gt_f32_e64 s[26:27], v191, v167
	v_cmp_gt_f32_e64 s[28:29], v192, v167
	v_addc_co_u32_e64 v212, s[30:31], v212, 0, s[22:23]
	v_addc_co_u32_e64 v212, s[30:31], v212, 0, s[24:25]
	v_addc_co_u32_e64 v212, s[30:31], v212, 0, s[26:27]
	v_addc_co_u32_e64 v212, s[30:31], v212, 0, s[28:29]
	v_cmp_gt_f32_e64 s[22:23], v193, v167
	v_cmp_gt_f32_e64 s[24:25], v194, v167
	v_cmp_gt_f32_e64 s[26:27], v195, v167
	v_cmp_gt_f32_e64 s[28:29], v196, v167
	v_addc_co_u32_e64 v212, s[30:31], v212, 0, s[22:23]
	v_addc_co_u32_e64 v212, s[30:31], v212, 0, s[24:25]
	v_addc_co_u32_e64 v212, s[30:31], v212, 0, s[26:27]
	v_addc_co_u32_e64 v212, s[30:31], v212, 0, s[28:29]
	v_cmp_gt_f32_e64 s[22:23], v197, v167
	v_cmp_gt_f32_e64 s[24:25], v198, v167
	v_cmp_gt_f32_e64 s[26:27], v199, v167
	v_cmp_gt_f32_e64 s[28:29], v200, v167
	v_addc_co_u32_e64 v212, s[30:31], v212, 0, s[22:23]
	v_addc_co_u32_e64 v212, s[30:31], v212, 0, s[24:25]
	v_addc_co_u32_e64 v212, s[30:31], v212, 0, s[26:27]
	v_addc_co_u32_e64 v212, s[30:31], v212, 0, s[28:29]
	v_cmp_gt_f32_e64 s[22:23], v201, v167
	v_cmp_gt_f32_e64 s[24:25], v202, v167
	v_cmp_gt_f32_e64 s[26:27], v203, v167
	v_cmp_gt_f32_e64 s[28:29], v204, v167
	v_addc_co_u32_e64 v212, s[30:31], v212, 0, s[22:23]
	v_addc_co_u32_e64 v212, s[30:31], v212, 0, s[24:25]
	v_addc_co_u32_e64 v212, s[30:31], v212, 0, s[26:27]
	v_addc_co_u32_e64 v212, s[30:31], v212, 0, s[28:29]
	v_cmp_gt_f32_e64 s[22:23], v205, v167
	v_cmp_gt_f32_e64 s[24:25], v206, v167
	v_cmp_gt_f32_e64 s[26:27], v207, v167
	v_cmp_gt_f32_e64 s[28:29], v208, v167
	v_addc_co_u32_e64 v212, s[30:31], v212, 0, s[22:23]
	v_addc_co_u32_e64 v212, s[30:31], v212, 0, s[24:25]
	v_addc_co_u32_e64 v212, s[30:31], v212, 0, s[26:27]
	v_addc_co_u32_e64 v212, s[30:31], v212, 0, s[28:29]
	v_cmp_gt_f32_e64 s[22:23], v209, v167
	s_nop 0
	s_nop 0
	v_addc_co_u32_e64 v212, s[30:31], v212, 0, s[22:23]
	v_cmp_gt_u32_e32 vcc, 16, v212
	s_and_saveexec_b64 s[40:41], vcc
	v_lshl_add_u32 v214, v212, 2, v213
	v_mov_b32_e32 v212, 7
	ds_write_b32 v214, v167
	ds_write_b32 v214, v212 offset:4096
	s_mov_b64 exec, -1
	s_branch .Lrk0_c15
; __device__ __forceinline__ void ph_peer_select(const Params& P, int layer, const h16* Q, int nrows, char* smem) {
;     ...
;     for (int i = tid; i < 64 * 50; i += NTHR) {
;       const int tok = i / 50, c = i % 50;
;       const float v = cd[tok * 52 + c];
;       int rank = 0;
;       for (int j = 0; j < 50; ++j) { const float o = cd[tok * 52 + j]; rank += (o > v || (o == v && j < c)) ? 1 : 0; }
;       if (rank < TOPK) { tv[tok * 16 + rank] = v; tp[tok * 16 + rank] = c; }
;     }
.Lrk0_c8:
	v_mov_b32_e32 v212, 0
	v_cmp_ge_f32_e64 s[22:23], v160, v168
	v_cmp_ge_f32_e64 s[24:25], v161, v168
	v_cmp_ge_f32_e64 s[26:27], v162, v168
	v_cmp_ge_f32_e64 s[28:29], v163, v168
	v_addc_co_u32_e64 v212, s[30:31], v212, 0, s[22:23]
	v_addc_co_u32_e64 v212, s[30:31], v212, 0, s[24:25]
	v_addc_co_u32_e64 v212, s[30:31], v212, 0, s[26:27]
	v_addc_co_u32_e64 v212, s[30:31], v212, 0, s[28:29]
	v_cmp_ge_f32_e64 s[22:23], v164, v168
	v_cmp_ge_f32_e64 s[24:25], v165, v168
	v_cmp_ge_f32_e64 s[26:27], v166, v168
	v_cmp_ge_f32_e64 s[28:29], v167, v168
	v_addc_co_u32_e64 v212, s[30:31], v212, 0, s[22:23]
	v_addc_co_u32_e64 v212, s[30:31], v212, 0, s[24:25]
	v_addc_co_u32_e64 v212, s[30:31], v212, 0, s[26:27]
	v_addc_co_u32_e64 v212, s[30:31], v212, 0, s[28:29]
	v_cmp_gt_f32_e64 s[22:23], v169, v168
	v_cmp_gt_f32_e64 s[24:25], v170, v168
	v_cmp_gt_f32_e64 s[26:27], v171, v168
	v_cmp_gt_f32_e64 s[28:29], v172, v168
	v_addc_co_u32_e64 v212, s[30:31], v212, 0, s[22:23]
	v_addc_co_u32_e64 v212, s[30:31], v212, 0, s[24:25]
	v_addc_co_u32_e64 v212, s[30:31], v212, 0, s[26:27]
	v_addc_co_u32_e64 v212, s[30:31], v212, 0, s[28:29]
	v_cmp_gt_f32_e64 s[22:23], v173, v168
	v_cmp_gt_f32_e64 s[24:25], v174, v168
	v_cmp_gt_f32_e64 s[26:27], v175, v168
	v_cmp_gt_f32_e64 s[28:29], v176, v168
	v_addc_co_u32_e64 v212, s[30:31], v212, 0, s[22:23]
	v_addc_co_u32_e64 v212, s[30:31], v212, 0, s[24:25]
	v_addc_co_u32_e64 v212, s[30:31], v212, 0, s[26:27]
	v_addc_co_u32_e64 v212, s[30:31], v212, 0, s[28:29]
	v_cmp_gt_f32_e64 s[22:23], v177, v168
	v_cmp_gt_f32_e64 s[24:25], v178, v168
	v_cmp_gt_f32_e64 s[26:27], v179, v168
	v_cmp_gt_f32_e64 s[28:29], v180, v168
	v_addc_co_u32_e64 v212, s[30:31], v212, 0, s[22:23]
	v_addc_co_u32_e64 v212, s[30:31], v212, 0, s[24:25]
	v_addc_co_u32_e64 v212, s[30:31], v212, 0, s[26:27]
	v_addc_co_u32_e64 v212, s[30:31], v212, 0, s[28:29]
	v_cmp_gt_f32_e64 s[22:23], v181, v168
	v_cmp_gt_f32_e64 s[24:25], v182, v168
	v_cmp_gt_f32_e64 s[26:27], v183, v168
	v_cmp_gt_f32_e64 s[28:29], v184, v168
	v_addc_co_u32_e64 v212, s[30:31], v212, 0, s[22:23]
	v_addc_co_u32_e64 v212, s[30:31], v212, 0, s[24:25]
	v_addc_co_u32_e64 v212, s[30:31], v212, 0, s[26:27]
	v_addc_co_u32_e64 v212, s[30:31], v212, 0, s[28:29]
	v_cmp_gt_f32_e64 s[22:23], v185, v168
	v_cmp_gt_f32_e64 s[24:25], v186, v168
	v_cmp_gt_f32_e64 s[26:27], v187, v168
	v_cmp_gt_f32_e64 s[28:29], v188, v168
	v_addc_co_u32_e64 v212, s[30:31], v212, 0, s[22:23]
	v_addc_co_u32_e64 v212, s[30:31], v212, 0, s[24:25]
	v_addc_co_u32_e64 v212, s[30:31], v212, 0, s[26:27]
	v_addc_co_u32_e64 v212, s[30:31], v212, 0, s[28:29]
	v_cmp_gt_f32_e64 s[22:23], v189, v168
	v_cmp_gt_f32_e64 s[24:25], v190, v168
	v_cmp_gt_f32_e64 s[26:27], v191, v168
	v_cmp_gt_f32_e64 s[28:29], v192, v168
	v_addc_co_u32_e64 v212, s[30:31], v212, 0, s[22:23]
	v_addc_co_u32_e64 v212, s[30:31], v212, 0, s[24:25]
	v_addc_co_u32_e64 v212, s[30:31], v212, 0, s[26:27]
	v_addc_co_u32_e64 v212, s[30:31], v212, 0, s[28:29]
	v_cmp_gt_f32_e64 s[22:23], v193, v168
	v_cmp_gt_f32_e64 s[24:25], v194, v168
	v_cmp_gt_f32_e64 s[26:27], v195, v168
	v_cmp_gt_f32_e64 s[28:29], v196, v168
	v_addc_co_u32_e64 v212, s[30:31], v212, 0, s[22:23]
	v_addc_co_u32_e64 v212, s[30:31], v212, 0, s[24:25]
	v_addc_co_u32_e64 v212, s[30:31], v212, 0, s[26:27]
	v_addc_co_u32_e64 v212, s[30:31], v212, 0, s[28:29]
	v_cmp_gt_f32_e64 s[22:23], v197, v168
	v_cmp_gt_f32_e64 s[24:25], v198, v168
	v_cmp_gt_f32_e64 s[26:27], v199, v168
	v_cmp_gt_f32_e64 s[28:29], v200, v168
	v_addc_co_u32_e64 v212, s[30:31], v212, 0, s[22:23]
	v_addc_co_u32_e64 v212, s[30:31], v212, 0, s[24:25]
	v_addc_co_u32_e64 v212, s[30:31], v212, 0, s[26:27]
	v_addc_co_u32_e64 v212, s[30:31], v212, 0, s[28:29]
	v_cmp_gt_f32_e64 s[22:23], v201, v168
	v_cmp_gt_f32_e64 s[24:25], v202, v168
	v_cmp_gt_f32_e64 s[26:27], v203, v168
	v_cmp_gt_f32_e64 s[28:29], v204, v168
	v_addc_co_u32_e64 v212, s[30:31], v212, 0, s[22:23]
	v_addc_co_u32_e64 v212, s[30:31], v212, 0, s[24:25]
	v_addc_co_u32_e64 v212, s[30:31], v212, 0, s[26:27]
	v_addc_co_u32_e64 v212, s[30:31], v212, 0, s[28:29]
	v_cmp_gt_f32_e64 s[22:23], v205, v168
	v_cmp_gt_f32_e64 s[24:25], v206, v168
	v_cmp_gt_f32_e64 s[26:27], v207, v168
	v_cmp_gt_f32_e64 s[28:29], v208, v168
	v_addc_co_u32_e64 v212, s[30:31], v212, 0, s[22:23]
	v_addc_co_u32_e64 v212, s[30:31], v212, 0, s[24:25]
	v_addc_co_u32_e64 v212, s[30:31], v212, 0, s[26:27]
	v_addc_co_u32_e64 v212, s[30:31], v212, 0, s[28:29]
	v_cmp_gt_f32_e64 s[22:23], v209, v168
	s_nop 0
	s_nop 0
	v_addc_co_u32_e64 v212, s[30:31], v212, 0, s[22:23]
	v_cmp_gt_u32_e32 vcc, 16, v212
	s_and_saveexec_b64 s[40:41], vcc
	v_lshl_add_u32 v214, v212, 2, v213
	v_mov_b32_e32 v212, 8
	ds_write_b32 v214, v168
	ds_write_b32 v214, v212 offset:4096
	s_mov_b64 exec, -1
	s_branch .Lrk0_c16
; __device__ __forceinline__ void ph_peer_select(const Params& P, int layer, const h16* Q, int nrows, char* smem) {
;     ...
;     for (int i = tid; i < 64 * 50; i += NTHR) {
;       const int tok = i / 50, c = i % 50;
;       const float v = cd[tok * 52 + c];
;       int rank = 0;
;       for (int j = 0; j < 50; ++j) { const float o = cd[tok * 52 + j]; rank += (o > v || (o == v && j < c)) ? 1 : 0; }
;       if (rank < TOPK) { tv[tok * 16 + rank] = v; tp[tok * 16 + rank] = c; }
;     }
.Lrk0_c9:
	v_mov_b32_e32 v212, 0
	v_cmp_ge_f32_e64 s[22:23], v160, v169
	v_cmp_ge_f32_e64 s[24:25], v161, v169
	v_cmp_ge_f32_e64 s[26:27], v162, v169
	v_cmp_ge_f32_e64 s[28:29], v163, v169
	v_addc_co_u32_e64 v212, s[30:31], v212, 0, s[22:23]
	v_addc_co_u32_e64 v212, s[30:31], v212, 0, s[24:25]
	v_addc_co_u32_e64 v212, s[30:31], v212, 0, s[26:27]
	v_addc_co_u32_e64 v212, s[30:31], v212, 0, s[28:29]
	v_cmp_ge_f32_e64 s[22:23], v164, v169
	v_cmp_ge_f32_e64 s[24:25], v165, v169
	v_cmp_ge_f32_e64 s[26:27], v166, v169
	v_cmp_ge_f32_e64 s[28:29], v167, v169
	v_addc_co_u32_e64 v212, s[30:31], v212, 0, s[22:23]
	v_addc_co_u32_e64 v212, s[30:31], v212, 0, s[24:25]
	v_addc_co_u32_e64 v212, s[30:31], v212, 0, s[26:27]
	v_addc_co_u32_e64 v212, s[30:31], v212, 0, s[28:29]
	v_cmp_ge_f32_e64 s[22:23], v168, v169
	v_cmp_gt_f32_e64 s[24:25], v170, v169
	v_cmp_gt_f32_e64 s[26:27], v171, v169
	v_cmp_gt_f32_e64 s[28:29], v172, v169
	v_addc_co_u32_e64 v212, s[30:31], v212, 0, s[22:23]
	v_addc_co_u32_e64 v212, s[30:31], v212, 0, s[24:25]
	v_addc_co_u32_e64 v212, s[30:31], v212, 0, s[26:27]
	v_addc_co_u32_e64 v212, s[30:31], v212, 0, s[28:29]
	v_cmp_gt_f32_e64 s[22:23], v173, v169
	v_cmp_gt_f32_e64 s[24:25], v174, v169
	v_cmp_gt_f32_e64 s[26:27], v175, v169
	v_cmp_gt_f32_e64 s[28:29], v176, v169
	v_addc_co_u32_e64 v212, s[30:31], v212, 0, s[22:23]
	v_addc_co_u32_e64 v212, s[30:31], v212, 0, s[24:25]
	v_addc_co_u32_e64 v212, s[30:31], v212, 0, s[26:27]
	v_addc_co_u32_e64 v212, s[30:31], v212, 0, s[28:29]
	v_cmp_gt_f32_e64 s[22:23], v177, v169
	v_cmp_gt_f32_e64 s[24:25], v178, v169
	v_cmp_gt_f32_e64 s[26:27], v179, v169
	v_cmp_gt_f32_e64 s[28:29], v180, v169
	v_addc_co_u32_e64 v212, s[30:31], v212, 0, s[22:23]
	v_addc_co_u32_e64 v212, s[30:31], v212, 0, s[24:25]
	v_addc_co_u32_e64 v212, s[30:31], v212, 0, s[26:27]
	v_addc_co_u32_e64 v212, s[30:31], v212, 0, s[28:29]
	v_cmp_gt_f32_e64 s[22:23], v181, v169
	v_cmp_gt_f32_e64 s[24:25], v182, v169
	v_cmp_gt_f32_e64 s[26:27], v183, v169
	v_cmp_gt_f32_e64 s[28:29], v184, v169
	v_addc_co_u32_e64 v212, s[30:31], v212, 0, s[22:23]
	v_addc_co_u32_e64 v212, s[30:31], v212, 0, s[24:25]
	v_addc_co_u32_e64 v212, s[30:31], v212, 0, s[26:27]
	v_addc_co_u32_e64 v212, s[30:31], v212, 0, s[28:29]
	v_cmp_gt_f32_e64 s[22:23], v185, v169
	v_cmp_gt_f32_e64 s[24:25], v186, v169
	v_cmp_gt_f32_e64 s[26:27], v187, v169
	v_cmp_gt_f32_e64 s[28:29], v188, v169
	v_addc_co_u32_e64 v212, s[30:31], v212, 0, s[22:23]
	v_addc_co_u32_e64 v212, s[30:31], v212, 0, s[24:25]
	v_addc_co_u32_e64 v212, s[30:31], v212, 0, s[26:27]
	v_addc_co_u32_e64 v212, s[30:31], v212, 0, s[28:29]
	v_cmp_gt_f32_e64 s[22:23], v189, v169
	v_cmp_gt_f32_e64 s[24:25], v190, v169
	v_cmp_gt_f32_e64 s[26:27], v191, v169
	v_cmp_gt_f32_e64 s[28:29], v192, v169
	v_addc_co_u32_e64 v212, s[30:31], v212, 0, s[22:23]
	v_addc_co_u32_e64 v212, s[30:31], v212, 0, s[24:25]
	v_addc_co_u32_e64 v212, s[30:31], v212, 0, s[26:27]
	v_addc_co_u32_e64 v212, s[30:31], v212, 0, s[28:29]
	v_cmp_gt_f32_e64 s[22:23], v193, v169
	v_cmp_gt_f32_e64 s[24:25], v194, v169
	v_cmp_gt_f32_e64 s[26:27], v195, v169
	v_cmp_gt_f32_e64 s[28:29], v196, v169
	v_addc_co_u32_e64 v212, s[30:31], v212, 0, s[22:23]
	v_addc_co_u32_e64 v212, s[30:31], v212, 0, s[24:25]
	v_addc_co_u32_e64 v212, s[30:31], v212, 0, s[26:27]
	v_addc_co_u32_e64 v212, s[30:31], v212, 0, s[28:29]
	v_cmp_gt_f32_e64 s[22:23], v197, v169
	v_cmp_gt_f32_e64 s[24:25], v198, v169
	v_cmp_gt_f32_e64 s[26:27], v199, v169
	v_cmp_gt_f32_e64 s[28:29], v200, v169
	v_addc_co_u32_e64 v212, s[30:31], v212, 0, s[22:23]
	v_addc_co_u32_e64 v212, s[30:31], v212, 0, s[24:25]
	v_addc_co_u32_e64 v212, s[30:31], v212, 0, s[26:27]
	v_addc_co_u32_e64 v212, s[30:31], v212, 0, s[28:29]
	v_cmp_gt_f32_e64 s[22:23], v201, v169
	v_cmp_gt_f32_e64 s[24:25], v202, v169
	v_cmp_gt_f32_e64 s[26:27], v203, v169
	v_cmp_gt_f32_e64 s[28:29], v204, v169
	v_addc_co_u32_e64 v212, s[30:31], v212, 0, s[22:23]
	v_addc_co_u32_e64 v212, s[30:31], v212, 0, s[24:25]
	v_addc_co_u32_e64 v212, s[30:31], v212, 0, s[26:27]
	v_addc_co_u32_e64 v212, s[30:31], v212, 0, s[28:29]
	v_cmp_gt_f32_e64 s[22:23], v205, v169
	v_cmp_gt_f32_e64 s[24:25], v206, v169
	v_cmp_gt_f32_e64 s[26:27], v207, v169
	v_cmp_gt_f32_e64 s[28:29], v208, v169
	v_addc_co_u32_e64 v212, s[30:31], v212, 0, s[22:23]
	v_addc_co_u32_e64 v212, s[30:31], v212, 0, s[24:25]
	v_addc_co_u32_e64 v212, s[30:31], v212, 0, s[26:27]
	v_addc_co_u32_e64 v212, s[30:31], v212, 0, s[28:29]
	v_cmp_gt_f32_e64 s[22:23], v209, v169
	s_nop 0
	s_nop 0
	v_addc_co_u32_e64 v212, s[30:31], v212, 0, s[22:23]
	v_cmp_gt_u32_e32 vcc, 16, v212
	s_and_saveexec_b64 s[40:41], vcc
	v_lshl_add_u32 v214, v212, 2, v213
	v_mov_b32_e32 v212, 9
	ds_write_b32 v214, v169
	ds_write_b32 v214, v212 offset:4096
	s_mov_b64 exec, -1
	s_branch .Lrk0_c17
; __device__ __forceinline__ void ph_peer_select(const Params& P, int layer, const h16* Q, int nrows, char* smem) {
;     ...
;     for (int i = tid; i < 64 * 50; i += NTHR) {
;       const int tok = i / 50, c = i % 50;
;       const float v = cd[tok * 52 + c];
;       int rank = 0;
;       for (int j = 0; j < 50; ++j) { const float o = cd[tok * 52 + j]; rank += (o > v || (o == v && j < c)) ? 1 : 0; }
;       if (rank < TOPK) { tv[tok * 16 + rank] = v; tp[tok * 16 + rank] = c; }
;     }
.Lrk0_c10:
	v_mov_b32_e32 v212, 0
	v_cmp_ge_f32_e64 s[22:23], v160, v170
	v_cmp_ge_f32_e64 s[24:25], v161, v170
	v_cmp_ge_f32_e64 s[26:27], v162, v170
	v_cmp_ge_f32_e64 s[28:29], v163, v170
	v_addc_co_u32_e64 v212, s[30:31], v212, 0, s[22:23]
	v_addc_co_u32_e64 v212, s[30:31], v212, 0, s[24:25]
	v_addc_co_u32_e64 v212, s[30:31], v212, 0, s[26:27]
	v_addc_co_u32_e64 v212, s[30:31], v212, 0, s[28:29]
	v_cmp_ge_f32_e64 s[22:23], v164, v170
	v_cmp_ge_f32_e64 s[24:25], v165, v170
	v_cmp_ge_f32_e64 s[26:27], v166, v170
	v_cmp_ge_f32_e64 s[28:29], v167, v170
	v_addc_co_u32_e64 v212, s[30:31], v212, 0, s[22:23]
	v_addc_co_u32_e64 v212, s[30:31], v212, 0, s[24:25]
	v_addc_co_u32_e64 v212, s[30:31], v212, 0, s[26:27]
	v_addc_co_u32_e64 v212, s[30:31], v212, 0, s[28:29]
	v_cmp_ge_f32_e64 s[22:23], v168, v170
	v_cmp_ge_f32_e64 s[24:25], v169, v170
	v_cmp_gt_f32_e64 s[26:27], v171, v170
	v_cmp_gt_f32_e64 s[28:29], v172, v170
	v_addc_co_u32_e64 v212, s[30:31], v212, 0, s[22:23]
	v_addc_co_u32_e64 v212, s[30:31], v212, 0, s[24:25]
	v_addc_co_u32_e64 v212, s[30:31], v212, 0, s[26:27]
	v_addc_co_u32_e64 v212, s[30:31], v212, 0, s[28:29]
	v_cmp_gt_f32_e64 s[22:23], v173, v170
	v_cmp_gt_f32_e64 s[24:25], v174, v170
	v_cmp_gt_f32_e64 s[26:27], v175, v170
	v_cmp_gt_f32_e64 s[28:29], v176, v170
	v_addc_co_u32_e64 v212, s[30:31], v212, 0, s[22:23]
	v_addc_co_u32_e64 v212, s[30:31], v212, 0, s[24:25]
	v_addc_co_u32_e64 v212, s[30:31], v212, 0, s[26:27]
	v_addc_co_u32_e64 v212, s[30:31], v212, 0, s[28:29]
	v_cmp_gt_f32_e64 s[22:23], v177, v170
	v_cmp_gt_f32_e64 s[24:25], v178, v170
	v_cmp_gt_f32_e64 s[26:27], v179, v170
	v_cmp_gt_f32_e64 s[28:29], v180, v170
	v_addc_co_u32_e64 v212, s[30:31], v212, 0, s[22:23]
	v_addc_co_u32_e64 v212, s[30:31], v212, 0, s[24:25]
	v_addc_co_u32_e64 v212, s[30:31], v212, 0, s[26:27]
	v_addc_co_u32_e64 v212, s[30:31], v212, 0, s[28:29]
	v_cmp_gt_f32_e64 s[22:23], v181, v170
	v_cmp_gt_f32_e64 s[24:25], v182, v170
	v_cmp_gt_f32_e64 s[26:27], v183, v170
	v_cmp_gt_f32_e64 s[28:29], v184, v170
	v_addc_co_u32_e64 v212, s[30:31], v212, 0, s[22:23]
	v_addc_co_u32_e64 v212, s[30:31], v212, 0, s[24:25]
	v_addc_co_u32_e64 v212, s[30:31], v212, 0, s[26:27]
	v_addc_co_u32_e64 v212, s[30:31], v212, 0, s[28:29]
	v_cmp_gt_f32_e64 s[22:23], v185, v170
	v_cmp_gt_f32_e64 s[24:25], v186, v170
	v_cmp_gt_f32_e64 s[26:27], v187, v170
	v_cmp_gt_f32_e64 s[28:29], v188, v170
	v_addc_co_u32_e64 v212, s[30:31], v212, 0, s[22:23]
	v_addc_co_u32_e64 v212, s[30:31], v212, 0, s[24:25]
	v_addc_co_u32_e64 v212, s[30:31], v212, 0, s[26:27]
	v_addc_co_u32_e64 v212, s[30:31], v212, 0, s[28:29]
	v_cmp_gt_f32_e64 s[22:23], v189, v170
	v_cmp_gt_f32_e64 s[24:25], v190, v170
	v_cmp_gt_f32_e64 s[26:27], v191, v170
	v_cmp_gt_f32_e64 s[28:29], v192, v170
	v_addc_co_u32_e64 v212, s[30:31], v212, 0, s[22:23]
	v_addc_co_u32_e64 v212, s[30:31], v212, 0, s[24:25]
	v_addc_co_u32_e64 v212, s[30:31], v212, 0, s[26:27]
	v_addc_co_u32_e64 v212, s[30:31], v212, 0, s[28:29]
	v_cmp_gt_f32_e64 s[22:23], v193, v170
	v_cmp_gt_f32_e64 s[24:25], v194, v170
	v_cmp_gt_f32_e64 s[26:27], v195, v170
	v_cmp_gt_f32_e64 s[28:29], v196, v170
	v_addc_co_u32_e64 v212, s[30:31], v212, 0, s[22:23]
	v_addc_co_u32_e64 v212, s[30:31], v212, 0, s[24:25]
	v_addc_co_u32_e64 v212, s[30:31], v212, 0, s[26:27]
	v_addc_co_u32_e64 v212, s[30:31], v212, 0, s[28:29]
	v_cmp_gt_f32_e64 s[22:23], v197, v170
	v_cmp_gt_f32_e64 s[24:25], v198, v170
	v_cmp_gt_f32_e64 s[26:27], v199, v170
	v_cmp_gt_f32_e64 s[28:29], v200, v170
	v_addc_co_u32_e64 v212, s[30:31], v212, 0, s[22:23]
	v_addc_co_u32_e64 v212, s[30:31], v212, 0, s[24:25]
	v_addc_co_u32_e64 v212, s[30:31], v212, 0, s[26:27]
	v_addc_co_u32_e64 v212, s[30:31], v212, 0, s[28:29]
	v_cmp_gt_f32_e64 s[22:23], v201, v170
	v_cmp_gt_f32_e64 s[24:25], v202, v170
	v_cmp_gt_f32_e64 s[26:27], v203, v170
	v_cmp_gt_f32_e64 s[28:29], v204, v170
	v_addc_co_u32_e64 v212, s[30:31], v212, 0, s[22:23]
	v_addc_co_u32_e64 v212, s[30:31], v212, 0, s[24:25]
	v_addc_co_u32_e64 v212, s[30:31], v212, 0, s[26:27]
	v_addc_co_u32_e64 v212, s[30:31], v212, 0, s[28:29]
	v_cmp_gt_f32_e64 s[22:23], v205, v170
	v_cmp_gt_f32_e64 s[24:25], v206, v170
	v_cmp_gt_f32_e64 s[26:27], v207, v170
	v_cmp_gt_f32_e64 s[28:29], v208, v170
	v_addc_co_u32_e64 v212, s[30:31], v212, 0, s[22:23]
	v_addc_co_u32_e64 v212, s[30:31], v212, 0, s[24:25]
	v_addc_co_u32_e64 v212, s[30:31], v212, 0, s[26:27]
	v_addc_co_u32_e64 v212, s[30:31], v212, 0, s[28:29]
	v_cmp_gt_f32_e64 s[22:23], v209, v170
	s_nop 0
	s_nop 0
	v_addc_co_u32_e64 v212, s[30:31], v212, 0, s[22:23]
	v_cmp_gt_u32_e32 vcc, 16, v212
	s_and_saveexec_b64 s[40:41], vcc
	v_lshl_add_u32 v214, v212, 2, v213
	v_mov_b32_e32 v212, 10
	ds_write_b32 v214, v170
	ds_write_b32 v214, v212 offset:4096
	s_mov_b64 exec, -1
	s_branch .Lrk0_c18
; __device__ __forceinline__ void ph_peer_select(const Params& P, int layer, const h16* Q, int nrows, char* smem) {
;     ...
;     for (int i = tid; i < 64 * 50; i += NTHR) {
;       const int tok = i / 50, c = i % 50;
;       const float v = cd[tok * 52 + c];
;       int rank = 0;
;       for (int j = 0; j < 50; ++j) { const float o = cd[tok * 52 + j]; rank += (o > v || (o == v && j < c)) ? 1 : 0; }
;       if (rank < TOPK) { tv[tok * 16 + rank] = v; tp[tok * 16 + rank] = c; }
;     }
.Lrk0_c11:
	v_mov_b32_e32 v212, 0
	v_cmp_ge_f32_e64 s[22:23], v160, v171
	v_cmp_ge_f32_e64 s[24:25], v161, v171
	v_cmp_ge_f32_e64 s[26:27], v162, v171
	v_cmp_ge_f32_e64 s[28:29], v163, v171
	v_addc_co_u32_e64 v212, s[30:31], v212, 0, s[22:23]
	v_addc_co_u32_e64 v212, s[30:31], v212, 0, s[24:25]
	v_addc_co_u32_e64 v212, s[30:31], v212, 0, s[26:27]
	v_addc_co_u32_e64 v212, s[30:31], v212, 0, s[28:29]
	v_cmp_ge_f32_e64 s[22:23], v164, v171
	v_cmp_ge_f32_e64 s[24:25], v165, v171
	v_cmp_ge_f32_e64 s[26:27], v166, v171
	v_cmp_ge_f32_e64 s[28:29], v167, v171
	v_addc_co_u32_e64 v212, s[30:31], v212, 0, s[22:23]
	v_addc_co_u32_e64 v212, s[30:31], v212, 0, s[24:25]
	v_addc_co_u32_e64 v212, s[30:31], v212, 0, s[26:27]
	v_addc_co_u32_e64 v212, s[30:31], v212, 0, s[28:29]
	v_cmp_ge_f32_e64 s[22:23], v168, v171
	v_cmp_ge_f32_e64 s[24:25], v169, v171
	v_cmp_ge_f32_e64 s[26:27], v170, v171
	v_cmp_gt_f32_e64 s[28:29], v172, v171
	v_addc_co_u32_e64 v212, s[30:31], v212, 0, s[22:23]
	v_addc_co_u32_e64 v212, s[30:31], v212, 0, s[24:25]
	v_addc_co_u32_e64 v212, s[30:31], v212, 0, s[26:27]
	v_addc_co_u32_e64 v212, s[30:31], v212, 0, s[28:29]
	v_cmp_gt_f32_e64 s[22:23], v173, v171
	v_cmp_gt_f32_e64 s[24:25], v174, v171
	v_cmp_gt_f32_e64 s[26:27], v175, v171
	v_cmp_gt_f32_e64 s[28:29], v176, v171
	v_addc_co_u32_e64 v212, s[30:31], v212, 0, s[22:23]
	v_addc_co_u32_e64 v212, s[30:31], v212, 0, s[24:25]
	v_addc_co_u32_e64 v212, s[30:31], v212, 0, s[26:27]
	v_addc_co_u32_e64 v212, s[30:31], v212, 0, s[28:29]
	v_cmp_gt_f32_e64 s[22:23], v177, v171
	v_cmp_gt_f32_e64 s[24:25], v178, v171
	v_cmp_gt_f32_e64 s[26:27], v179, v171
	v_cmp_gt_f32_e64 s[28:29], v180, v171
	v_addc_co_u32_e64 v212, s[30:31], v212, 0, s[22:23]
	v_addc_co_u32_e64 v212, s[30:31], v212, 0, s[24:25]
	v_addc_co_u32_e64 v212, s[30:31], v212, 0, s[26:27]
	v_addc_co_u32_e64 v212, s[30:31], v212, 0, s[28:29]
	v_cmp_gt_f32_e64 s[22:23], v181, v171
	v_cmp_gt_f32_e64 s[24:25], v182, v171
	v_cmp_gt_f32_e64 s[26:27], v183, v171
	v_cmp_gt_f32_e64 s[28:29], v184, v171
	v_addc_co_u32_e64 v212, s[30:31], v212, 0, s[22:23]
	v_addc_co_u32_e64 v212, s[30:31], v212, 0, s[24:25]
	v_addc_co_u32_e64 v212, s[30:31], v212, 0, s[26:27]
	v_addc_co_u32_e64 v212, s[30:31], v212, 0, s[28:29]
	v_cmp_gt_f32_e64 s[22:23], v185, v171
	v_cmp_gt_f32_e64 s[24:25], v186, v171
	v_cmp_gt_f32_e64 s[26:27], v187, v171
	v_cmp_gt_f32_e64 s[28:29], v188, v171
	v_addc_co_u32_e64 v212, s[30:31], v212, 0, s[22:23]
	v_addc_co_u32_e64 v212, s[30:31], v212, 0, s[24:25]
	v_addc_co_u32_e64 v212, s[30:31], v212, 0, s[26:27]
	v_addc_co_u32_e64 v212, s[30:31], v212, 0, s[28:29]
	v_cmp_gt_f32_e64 s[22:23], v189, v171
	v_cmp_gt_f32_e64 s[24:25], v190, v171
	v_cmp_gt_f32_e64 s[26:27], v191, v171
	v_cmp_gt_f32_e64 s[28:29], v192, v171
	v_addc_co_u32_e64 v212, s[30:31], v212, 0, s[22:23]
	v_addc_co_u32_e64 v212, s[30:31], v212, 0, s[24:25]
	v_addc_co_u32_e64 v212, s[30:31], v212, 0, s[26:27]
	v_addc_co_u32_e64 v212, s[30:31], v212, 0, s[28:29]
	v_cmp_gt_f32_e64 s[22:23], v193, v171
	v_cmp_gt_f32_e64 s[24:25], v194, v171
	v_cmp_gt_f32_e64 s[26:27], v195, v171
	v_cmp_gt_f32_e64 s[28:29], v196, v171
	v_addc_co_u32_e64 v212, s[30:31], v212, 0, s[22:23]
	v_addc_co_u32_e64 v212, s[30:31], v212, 0, s[24:25]
	v_addc_co_u32_e64 v212, s[30:31], v212, 0, s[26:27]
	v_addc_co_u32_e64 v212, s[30:31], v212, 0, s[28:29]
	v_cmp_gt_f32_e64 s[22:23], v197, v171
	v_cmp_gt_f32_e64 s[24:25], v198, v171
	v_cmp_gt_f32_e64 s[26:27], v199, v171
	v_cmp_gt_f32_e64 s[28:29], v200, v171
	v_addc_co_u32_e64 v212, s[30:31], v212, 0, s[22:23]
	v_addc_co_u32_e64 v212, s[30:31], v212, 0, s[24:25]
	v_addc_co_u32_e64 v212, s[30:31], v212, 0, s[26:27]
	v_addc_co_u32_e64 v212, s[30:31], v212, 0, s[28:29]
	v_cmp_gt_f32_e64 s[22:23], v201, v171
	v_cmp_gt_f32_e64 s[24:25], v202, v171
	v_cmp_gt_f32_e64 s[26:27], v203, v171
	v_cmp_gt_f32_e64 s[28:29], v204, v171
	v_addc_co_u32_e64 v212, s[30:31], v212, 0, s[22:23]
	v_addc_co_u32_e64 v212, s[30:31], v212, 0, s[24:25]
	v_addc_co_u32_e64 v212, s[30:31], v212, 0, s[26:27]
	v_addc_co_u32_e64 v212, s[30:31], v212, 0, s[28:29]
	v_cmp_gt_f32_e64 s[22:23], v205, v171
	v_cmp_gt_f32_e64 s[24:25], v206, v171
	v_cmp_gt_f32_e64 s[26:27], v207, v171
	v_cmp_gt_f32_e64 s[28:29], v208, v171
	v_addc_co_u32_e64 v212, s[30:31], v212, 0, s[22:23]
	v_addc_co_u32_e64 v212, s[30:31], v212, 0, s[24:25]
	v_addc_co_u32_e64 v212, s[30:31], v212, 0, s[26:27]
	v_addc_co_u32_e64 v212, s[30:31], v212, 0, s[28:29]
	v_cmp_gt_f32_e64 s[22:23], v209, v171
	s_nop 0
	s_nop 0
	v_addc_co_u32_e64 v212, s[30:31], v212, 0, s[22:23]
	v_cmp_gt_u32_e32 vcc, 16, v212
	s_and_saveexec_b64 s[40:41], vcc
	v_lshl_add_u32 v214, v212, 2, v213
	v_mov_b32_e32 v212, 11
	ds_write_b32 v214, v171
	ds_write_b32 v214, v212 offset:4096
	s_mov_b64 exec, -1
	s_branch .Lrk0_c19
; __device__ __forceinline__ void ph_peer_select(const Params& P, int layer, const h16* Q, int nrows, char* smem) {
;     ...
;     for (int i = tid; i < 64 * 50; i += NTHR) {
;       const int tok = i / 50, c = i % 50;
;       const float v = cd[tok * 52 + c];
;       int rank = 0;
;       for (int j = 0; j < 50; ++j) { const float o = cd[tok * 52 + j]; rank += (o > v || (o == v && j < c)) ? 1 : 0; }
;       if (rank < TOPK) { tv[tok * 16 + rank] = v; tp[tok * 16 + rank] = c; }
;     }
.Lrk0_c12:
	v_mov_b32_e32 v212, 0
	v_cmp_ge_f32_e64 s[22:23], v160, v172
	v_cmp_ge_f32_e64 s[24:25], v161, v172
	v_cmp_ge_f32_e64 s[26:27], v162, v172
	v_cmp_ge_f32_e64 s[28:29], v163, v172
	v_addc_co_u32_e64 v212, s[30:31], v212, 0, s[22:23]
	v_addc_co_u32_e64 v212, s[30:31], v212, 0, s[24:25]
	v_addc_co_u32_e64 v212, s[30:31], v212, 0, s[26:27]
	v_addc_co_u32_e64 v212, s[30:31], v212, 0, s[28:29]
	v_cmp_ge_f32_e64 s[22:23], v164, v172
	v_cmp_ge_f32_e64 s[24:25], v165, v172
	v_cmp_ge_f32_e64 s[26:27], v166, v172
	v_cmp_ge_f32_e64 s[28:29], v167, v172
	v_addc_co_u32_e64 v212, s[30:31], v212, 0, s[22:23]
	v_addc_co_u32_e64 v212, s[30:31], v212, 0, s[24:25]
	v_addc_co_u32_e64 v212, s[30:31], v212, 0, s[26:27]
	v_addc_co_u32_e64 v212, s[30:31], v212, 0, s[28:29]
	v_cmp_ge_f32_e64 s[22:23], v168, v172
	v_cmp_ge_f32_e64 s[24:25], v169, v172
	v_cmp_ge_f32_e64 s[26:27], v170, v172
	v_cmp_ge_f32_e64 s[28:29], v171, v172
	v_addc_co_u32_e64 v212, s[30:31], v212, 0, s[22:23]
	v_addc_co_u32_e64 v212, s[30:31], v212, 0, s[24:25]
	v_addc_co_u32_e64 v212, s[30:31], v212, 0, s[26:27]
	v_addc_co_u32_e64 v212, s[30:31], v212, 0, s[28:29]
	v_cmp_gt_f32_e64 s[22:23], v173, v172
	v_cmp_gt_f32_e64 s[24:25], v174, v172
	v_cmp_gt_f32_e64 s[26:27], v175, v172
	v_cmp_gt_f32_e64 s[28:29], v176, v172
	v_addc_co_u32_e64 v212, s[30:31], v212, 0, s[22:23]
	v_addc_co_u32_e64 v212, s[30:31], v212, 0, s[24:25]
	v_addc_co_u32_e64 v212, s[30:31], v212, 0, s[26:27]
	v_addc_co_u32_e64 v212, s[30:31], v212, 0, s[28:29]
	v_cmp_gt_f32_e64 s[22:23], v177, v172
	v_cmp_gt_f32_e64 s[24:25], v178, v172
	v_cmp_gt_f32_e64 s[26:27], v179, v172
	v_cmp_gt_f32_e64 s[28:29], v180, v172
	v_addc_co_u32_e64 v212, s[30:31], v212, 0, s[22:23]
	v_addc_co_u32_e64 v212, s[30:31], v212, 0, s[24:25]
	v_addc_co_u32_e64 v212, s[30:31], v212, 0, s[26:27]
	v_addc_co_u32_e64 v212, s[30:31], v212, 0, s[28:29]
	v_cmp_gt_f32_e64 s[22:23], v181, v172
	v_cmp_gt_f32_e64 s[24:25], v182, v172
	v_cmp_gt_f32_e64 s[26:27], v183, v172
	v_cmp_gt_f32_e64 s[28:29], v184, v172
	v_addc_co_u32_e64 v212, s[30:31], v212, 0, s[22:23]
	v_addc_co_u32_e64 v212, s[30:31], v212, 0, s[24:25]
	v_addc_co_u32_e64 v212, s[30:31], v212, 0, s[26:27]
	v_addc_co_u32_e64 v212, s[30:31], v212, 0, s[28:29]
	v_cmp_gt_f32_e64 s[22:23], v185, v172
	v_cmp_gt_f32_e64 s[24:25], v186, v172
	v_cmp_gt_f32_e64 s[26:27], v187, v172
	v_cmp_gt_f32_e64 s[28:29], v188, v172
	v_addc_co_u32_e64 v212, s[30:31], v212, 0, s[22:23]
	v_addc_co_u32_e64 v212, s[30:31], v212, 0, s[24:25]
	v_addc_co_u32_e64 v212, s[30:31], v212, 0, s[26:27]
	v_addc_co_u32_e64 v212, s[30:31], v212, 0, s[28:29]
	v_cmp_gt_f32_e64 s[22:23], v189, v172
	v_cmp_gt_f32_e64 s[24:25], v190, v172
	v_cmp_gt_f32_e64 s[26:27], v191, v172
	v_cmp_gt_f32_e64 s[28:29], v192, v172
	v_addc_co_u32_e64 v212, s[30:31], v212, 0, s[22:23]
	v_addc_co_u32_e64 v212, s[30:31], v212, 0, s[24:25]
	v_addc_co_u32_e64 v212, s[30:31], v212, 0, s[26:27]
	v_addc_co_u32_e64 v212, s[30:31], v212, 0, s[28:29]
	v_cmp_gt_f32_e64 s[22:23], v193, v172
	v_cmp_gt_f32_e64 s[24:25], v194, v172
	v_cmp_gt_f32_e64 s[26:27], v195, v172
	v_cmp_gt_f32_e64 s[28:29], v196, v172
	v_addc_co_u32_e64 v212, s[30:31], v212, 0, s[22:23]
	v_addc_co_u32_e64 v212, s[30:31], v212, 0, s[24:25]
	v_addc_co_u32_e64 v212, s[30:31], v212, 0, s[26:27]
	v_addc_co_u32_e64 v212, s[30:31], v212, 0, s[28:29]
	v_cmp_gt_f32_e64 s[22:23], v197, v172
	v_cmp_gt_f32_e64 s[24:25], v198, v172
	v_cmp_gt_f32_e64 s[26:27], v199, v172
	v_cmp_gt_f32_e64 s[28:29], v200, v172
	v_addc_co_u32_e64 v212, s[30:31], v212, 0, s[22:23]
	v_addc_co_u32_e64 v212, s[30:31], v212, 0, s[24:25]
	v_addc_co_u32_e64 v212, s[30:31], v212, 0, s[26:27]
	v_addc_co_u32_e64 v212, s[30:31], v212, 0, s[28:29]
	v_cmp_gt_f32_e64 s[22:23], v201, v172
	v_cmp_gt_f32_e64 s[24:25], v202, v172
	v_cmp_gt_f32_e64 s[26:27], v203, v172
	v_cmp_gt_f32_e64 s[28:29], v204, v172
	v_addc_co_u32_e64 v212, s[30:31], v212, 0, s[22:23]
	v_addc_co_u32_e64 v212, s[30:31], v212, 0, s[24:25]
	v_addc_co_u32_e64 v212, s[30:31], v212, 0, s[26:27]
	v_addc_co_u32_e64 v212, s[30:31], v212, 0, s[28:29]
	v_cmp_gt_f32_e64 s[22:23], v205, v172
	v_cmp_gt_f32_e64 s[24:25], v206, v172
	v_cmp_gt_f32_e64 s[26:27], v207, v172
	v_cmp_gt_f32_e64 s[28:29], v208, v172
	v_addc_co_u32_e64 v212, s[30:31], v212, 0, s[22:23]
	v_addc_co_u32_e64 v212, s[30:31], v212, 0, s[24:25]
	v_addc_co_u32_e64 v212, s[30:31], v212, 0, s[26:27]
	v_addc_co_u32_e64 v212, s[30:31], v212, 0, s[28:29]
	v_cmp_gt_f32_e64 s[22:23], v209, v172
	s_nop 0
	s_nop 0
	v_addc_co_u32_e64 v212, s[30:31], v212, 0, s[22:23]
	v_cmp_gt_u32_e32 vcc, 16, v212
	s_and_saveexec_b64 s[40:41], vcc
	v_lshl_add_u32 v214, v212, 2, v213
	v_mov_b32_e32 v212, 12
	ds_write_b32 v214, v172
	ds_write_b32 v214, v212 offset:4096
	s_mov_b64 exec, -1
	s_branch .Lrk0_c20
; __device__ __forceinline__ void ph_peer_select(const Params& P, int layer, const h16* Q, int nrows, char* smem) {
;     ...
;     for (int i = tid; i < 64 * 50; i += NTHR) {
;       const int tok = i / 50, c = i % 50;
;       const float v = cd[tok * 52 + c];
;       int rank = 0;
;       for (int j = 0; j < 50; ++j) { const float o = cd[tok * 52 + j]; rank += (o > v || (o == v && j < c)) ? 1 : 0; }
;       if (rank < TOPK) { tv[tok * 16 + rank] = v; tp[tok * 16 + rank] = c; }
;     }
.Lrk0_c13:
	v_mov_b32_e32 v212, 0
	v_cmp_ge_f32_e64 s[22:23], v160, v173
	v_cmp_ge_f32_e64 s[24:25], v161, v173
	v_cmp_ge_f32_e64 s[26:27], v162, v173
	v_cmp_ge_f32_e64 s[28:29], v163, v173
	v_addc_co_u32_e64 v212, s[30:31], v212, 0, s[22:23]
	v_addc_co_u32_e64 v212, s[30:31], v212, 0, s[24:25]
	v_addc_co_u32_e64 v212, s[30:31], v212, 0, s[26:27]
	v_addc_co_u32_e64 v212, s[30:31], v212, 0, s[28:29]
	v_cmp_ge_f32_e64 s[22:23], v164, v173
	v_cmp_ge_f32_e64 s[24:25], v165, v173
	v_cmp_ge_f32_e64 s[26:27], v166, v173
	v_cmp_ge_f32_e64 s[28:29], v167, v173
	v_addc_co_u32_e64 v212, s[30:31], v212, 0, s[22:23]
	v_addc_co_u32_e64 v212, s[30:31], v212, 0, s[24:25]
	v_addc_co_u32_e64 v212, s[30:31], v212, 0, s[26:27]
	v_addc_co_u32_e64 v212, s[30:31], v212, 0, s[28:29]
	v_cmp_ge_f32_e64 s[22:23], v168, v173
	v_cmp_ge_f32_e64 s[24:25], v169, v173
	v_cmp_ge_f32_e64 s[26:27], v170, v173
	v_cmp_ge_f32_e64 s[28:29], v171, v173
	v_addc_co_u32_e64 v212, s[30:31], v212, 0, s[22:23]
	v_addc_co_u32_e64 v212, s[30:31], v212, 0, s[24:25]
	v_addc_co_u32_e64 v212, s[30:31], v212, 0, s[26:27]
	v_addc_co_u32_e64 v212, s[30:31], v212, 0, s[28:29]
	v_cmp_ge_f32_e64 s[22:23], v172, v173
	v_cmp_gt_f32_e64 s[24:25], v174, v173
	v_cmp_gt_f32_e64 s[26:27], v175, v173
	v_cmp_gt_f32_e64 s[28:29], v176, v173
	v_addc_co_u32_e64 v212, s[30:31], v212, 0, s[22:23]
	v_addc_co_u32_e64 v212, s[30:31], v212, 0, s[24:25]
	v_addc_co_u32_e64 v212, s[30:31], v212, 0, s[26:27]
	v_addc_co_u32_e64 v212, s[30:31], v212, 0, s[28:29]
	v_cmp_gt_f32_e64 s[22:23], v177, v173
	v_cmp_gt_f32_e64 s[24:25], v178, v173
	v_cmp_gt_f32_e64 s[26:27], v179, v173
	v_cmp_gt_f32_e64 s[28:29], v180, v173
	v_addc_co_u32_e64 v212, s[30:31], v212, 0, s[22:23]
	v_addc_co_u32_e64 v212, s[30:31], v212, 0, s[24:25]
	v_addc_co_u32_e64 v212, s[30:31], v212, 0, s[26:27]
	v_addc_co_u32_e64 v212, s[30:31], v212, 0, s[28:29]
	v_cmp_gt_f32_e64 s[22:23], v181, v173
	v_cmp_gt_f32_e64 s[24:25], v182, v173
	v_cmp_gt_f32_e64 s[26:27], v183, v173
	v_cmp_gt_f32_e64 s[28:29], v184, v173
	v_addc_co_u32_e64 v212, s[30:31], v212, 0, s[22:23]
	v_addc_co_u32_e64 v212, s[30:31], v212, 0, s[24:25]
	v_addc_co_u32_e64 v212, s[30:31], v212, 0, s[26:27]
	v_addc_co_u32_e64 v212, s[30:31], v212, 0, s[28:29]
	v_cmp_gt_f32_e64 s[22:23], v185, v173
	v_cmp_gt_f32_e64 s[24:25], v186, v173
	v_cmp_gt_f32_e64 s[26:27], v187, v173
	v_cmp_gt_f32_e64 s[28:29], v188, v173
	v_addc_co_u32_e64 v212, s[30:31], v212, 0, s[22:23]
	v_addc_co_u32_e64 v212, s[30:31], v212, 0, s[24:25]
	v_addc_co_u32_e64 v212, s[30:31], v212, 0, s[26:27]
	v_addc_co_u32_e64 v212, s[30:31], v212, 0, s[28:29]
	v_cmp_gt_f32_e64 s[22:23], v189, v173
	v_cmp_gt_f32_e64 s[24:25], v190, v173
	v_cmp_gt_f32_e64 s[26:27], v191, v173
	v_cmp_gt_f32_e64 s[28:29], v192, v173
	v_addc_co_u32_e64 v212, s[30:31], v212, 0, s[22:23]
	v_addc_co_u32_e64 v212, s[30:31], v212, 0, s[24:25]
	v_addc_co_u32_e64 v212, s[30:31], v212, 0, s[26:27]
	v_addc_co_u32_e64 v212, s[30:31], v212, 0, s[28:29]
	v_cmp_gt_f32_e64 s[22:23], v193, v173
	v_cmp_gt_f32_e64 s[24:25], v194, v173
	v_cmp_gt_f32_e64 s[26:27], v195, v173
	v_cmp_gt_f32_e64 s[28:29], v196, v173
	v_addc_co_u32_e64 v212, s[30:31], v212, 0, s[22:23]
	v_addc_co_u32_e64 v212, s[30:31], v212, 0, s[24:25]
	v_addc_co_u32_e64 v212, s[30:31], v212, 0, s[26:27]
	v_addc_co_u32_e64 v212, s[30:31], v212, 0, s[28:29]
	v_cmp_gt_f32_e64 s[22:23], v197, v173
	v_cmp_gt_f32_e64 s[24:25], v198, v173
	v_cmp_gt_f32_e64 s[26:27], v199, v173
	v_cmp_gt_f32_e64 s[28:29], v200, v173
	v_addc_co_u32_e64 v212, s[30:31], v212, 0, s[22:23]
	v_addc_co_u32_e64 v212, s[30:31], v212, 0, s[24:25]
	v_addc_co_u32_e64 v212, s[30:31], v212, 0, s[26:27]
	v_addc_co_u32_e64 v212, s[30:31], v212, 0, s[28:29]
	v_cmp_gt_f32_e64 s[22:23], v201, v173
	v_cmp_gt_f32_e64 s[24:25], v202, v173
	v_cmp_gt_f32_e64 s[26:27], v203, v173
	v_cmp_gt_f32_e64 s[28:29], v204, v173
	v_addc_co_u32_e64 v212, s[30:31], v212, 0, s[22:23]
	v_addc_co_u32_e64 v212, s[30:31], v212, 0, s[24:25]
	v_addc_co_u32_e64 v212, s[30:31], v212, 0, s[26:27]
	v_addc_co_u32_e64 v212, s[30:31], v212, 0, s[28:29]
	v_cmp_gt_f32_e64 s[22:23], v205, v173
	v_cmp_gt_f32_e64 s[24:25], v206, v173
	v_cmp_gt_f32_e64 s[26:27], v207, v173
	v_cmp_gt_f32_e64 s[28:29], v208, v173
	v_addc_co_u32_e64 v212, s[30:31], v212, 0, s[22:23]
	v_addc_co_u32_e64 v212, s[30:31], v212, 0, s[24:25]
	v_addc_co_u32_e64 v212, s[30:31], v212, 0, s[26:27]
	v_addc_co_u32_e64 v212, s[30:31], v212, 0, s[28:29]
	v_cmp_gt_f32_e64 s[22:23], v209, v173
	s_nop 0
	s_nop 0
	v_addc_co_u32_e64 v212, s[30:31], v212, 0, s[22:23]
	v_cmp_gt_u32_e32 vcc, 16, v212
	s_and_saveexec_b64 s[40:41], vcc
	v_lshl_add_u32 v214, v212, 2, v213
	v_mov_b32_e32 v212, 13
	ds_write_b32 v214, v173
	ds_write_b32 v214, v212 offset:4096
	s_mov_b64 exec, -1
	s_branch .Lrk0_c21
; __device__ __forceinline__ void ph_peer_select(const Params& P, int layer, const h16* Q, int nrows, char* smem) {
;     ...
;     for (int i = tid; i < 64 * 50; i += NTHR) {
;       const int tok = i / 50, c = i % 50;
;       const float v = cd[tok * 52 + c];
;       int rank = 0;
;       for (int j = 0; j < 50; ++j) { const float o = cd[tok * 52 + j]; rank += (o > v || (o == v && j < c)) ? 1 : 0; }
;       if (rank < TOPK) { tv[tok * 16 + rank] = v; tp[tok * 16 + rank] = c; }
;     }
.Lrk0_c14:
	v_mov_b32_e32 v212, 0
	v_cmp_ge_f32_e64 s[22:23], v160, v174
	v_cmp_ge_f32_e64 s[24:25], v161, v174
	v_cmp_ge_f32_e64 s[26:27], v162, v174
	v_cmp_ge_f32_e64 s[28:29], v163, v174
	v_addc_co_u32_e64 v212, s[30:31], v212, 0, s[22:23]
	v_addc_co_u32_e64 v212, s[30:31], v212, 0, s[24:25]
	v_addc_co_u32_e64 v212, s[30:31], v212, 0, s[26:27]
	v_addc_co_u32_e64 v212, s[30:31], v212, 0, s[28:29]
	v_cmp_ge_f32_e64 s[22:23], v164, v174
	v_cmp_ge_f32_e64 s[24:25], v165, v174
	v_cmp_ge_f32_e64 s[26:27], v166, v174
	v_cmp_ge_f32_e64 s[28:29], v167, v174
	v_addc_co_u32_e64 v212, s[30:31], v212, 0, s[22:23]
	v_addc_co_u32_e64 v212, s[30:31], v212, 0, s[24:25]
	v_addc_co_u32_e64 v212, s[30:31], v212, 0, s[26:27]
	v_addc_co_u32_e64 v212, s[30:31], v212, 0, s[28:29]
	v_cmp_ge_f32_e64 s[22:23], v168, v174
	v_cmp_ge_f32_e64 s[24:25], v169, v174
	v_cmp_ge_f32_e64 s[26:27], v170, v174
	v_cmp_ge_f32_e64 s[28:29], v171, v174
	v_addc_co_u32_e64 v212, s[30:31], v212, 0, s[22:23]
	v_addc_co_u32_e64 v212, s[30:31], v212, 0, s[24:25]
	v_addc_co_u32_e64 v212, s[30:31], v212, 0, s[26:27]
	v_addc_co_u32_e64 v212, s[30:31], v212, 0, s[28:29]
	v_cmp_ge_f32_e64 s[22:23], v172, v174
	v_cmp_ge_f32_e64 s[24:25], v173, v174
	v_cmp_gt_f32_e64 s[26:27], v175, v174
	v_cmp_gt_f32_e64 s[28:29], v176, v174
	v_addc_co_u32_e64 v212, s[30:31], v212, 0, s[22:23]
	v_addc_co_u32_e64 v212, s[30:31], v212, 0, s[24:25]
	v_addc_co_u32_e64 v212, s[30:31], v212, 0, s[26:27]
	v_addc_co_u32_e64 v212, s[30:31], v212, 0, s[28:29]
	v_cmp_gt_f32_e64 s[22:23], v177, v174
	v_cmp_gt_f32_e64 s[24:25], v178, v174
	v_cmp_gt_f32_e64 s[26:27], v179, v174
	v_cmp_gt_f32_e64 s[28:29], v180, v174
	v_addc_co_u32_e64 v212, s[30:31], v212, 0, s[22:23]
	v_addc_co_u32_e64 v212, s[30:31], v212, 0, s[24:25]
	v_addc_co_u32_e64 v212, s[30:31], v212, 0, s[26:27]
	v_addc_co_u32_e64 v212, s[30:31], v212, 0, s[28:29]
	v_cmp_gt_f32_e64 s[22:23], v181, v174
	v_cmp_gt_f32_e64 s[24:25], v182, v174
	v_cmp_gt_f32_e64 s[26:27], v183, v174
	v_cmp_gt_f32_e64 s[28:29], v184, v174
	v_addc_co_u32_e64 v212, s[30:31], v212, 0, s[22:23]
	v_addc_co_u32_e64 v212, s[30:31], v212, 0, s[24:25]
	v_addc_co_u32_e64 v212, s[30:31], v212, 0, s[26:27]
	v_addc_co_u32_e64 v212, s[30:31], v212, 0, s[28:29]
	v_cmp_gt_f32_e64 s[22:23], v185, v174
	v_cmp_gt_f32_e64 s[24:25], v186, v174
	v_cmp_gt_f32_e64 s[26:27], v187, v174
	v_cmp_gt_f32_e64 s[28:29], v188, v174
	v_addc_co_u32_e64 v212, s[30:31], v212, 0, s[22:23]
	v_addc_co_u32_e64 v212, s[30:31], v212, 0, s[24:25]
	v_addc_co_u32_e64 v212, s[30:31], v212, 0, s[26:27]
	v_addc_co_u32_e64 v212, s[30:31], v212, 0, s[28:29]
	v_cmp_gt_f32_e64 s[22:23], v189, v174
	v_cmp_gt_f32_e64 s[24:25], v190, v174
	v_cmp_gt_f32_e64 s[26:27], v191, v174
	v_cmp_gt_f32_e64 s[28:29], v192, v174
	v_addc_co_u32_e64 v212, s[30:31], v212, 0, s[22:23]
	v_addc_co_u32_e64 v212, s[30:31], v212, 0, s[24:25]
	v_addc_co_u32_e64 v212, s[30:31], v212, 0, s[26:27]
	v_addc_co_u32_e64 v212, s[30:31], v212, 0, s[28:29]
	v_cmp_gt_f32_e64 s[22:23], v193, v174
	v_cmp_gt_f32_e64 s[24:25], v194, v174
	v_cmp_gt_f32_e64 s[26:27], v195, v174
	v_cmp_gt_f32_e64 s[28:29], v196, v174
	v_addc_co_u32_e64 v212, s[30:31], v212, 0, s[22:23]
	v_addc_co_u32_e64 v212, s[30:31], v212, 0, s[24:25]
	v_addc_co_u32_e64 v212, s[30:31], v212, 0, s[26:27]
	v_addc_co_u32_e64 v212, s[30:31], v212, 0, s[28:29]
	v_cmp_gt_f32_e64 s[22:23], v197, v174
	v_cmp_gt_f32_e64 s[24:25], v198, v174
	v_cmp_gt_f32_e64 s[26:27], v199, v174
	v_cmp_gt_f32_e64 s[28:29], v200, v174
	v_addc_co_u32_e64 v212, s[30:31], v212, 0, s[22:23]
	v_addc_co_u32_e64 v212, s[30:31], v212, 0, s[24:25]
	v_addc_co_u32_e64 v212, s[30:31], v212, 0, s[26:27]
	v_addc_co_u32_e64 v212, s[30:31], v212, 0, s[28:29]
	v_cmp_gt_f32_e64 s[22:23], v201, v174
	v_cmp_gt_f32_e64 s[24:25], v202, v174
	v_cmp_gt_f32_e64 s[26:27], v203, v174
	v_cmp_gt_f32_e64 s[28:29], v204, v174
	v_addc_co_u32_e64 v212, s[30:31], v212, 0, s[22:23]
	v_addc_co_u32_e64 v212, s[30:31], v212, 0, s[24:25]
	v_addc_co_u32_e64 v212, s[30:31], v212, 0, s[26:27]
	v_addc_co_u32_e64 v212, s[30:31], v212, 0, s[28:29]
	v_cmp_gt_f32_e64 s[22:23], v205, v174
	v_cmp_gt_f32_e64 s[24:25], v206, v174
	v_cmp_gt_f32_e64 s[26:27], v207, v174
	v_cmp_gt_f32_e64 s[28:29], v208, v174
	v_addc_co_u32_e64 v212, s[30:31], v212, 0, s[22:23]
	v_addc_co_u32_e64 v212, s[30:31], v212, 0, s[24:25]
	v_addc_co_u32_e64 v212, s[30:31], v212, 0, s[26:27]
	v_addc_co_u32_e64 v212, s[30:31], v212, 0, s[28:29]
	v_cmp_gt_f32_e64 s[22:23], v209, v174
	s_nop 0
	s_nop 0
	v_addc_co_u32_e64 v212, s[30:31], v212, 0, s[22:23]
	v_cmp_gt_u32_e32 vcc, 16, v212
	s_and_saveexec_b64 s[40:41], vcc
	v_lshl_add_u32 v214, v212, 2, v213
	v_mov_b32_e32 v212, 14
	ds_write_b32 v214, v174
	ds_write_b32 v214, v212 offset:4096
	s_mov_b64 exec, -1
	s_branch .Lrk0_c22
; __device__ __forceinline__ void ph_peer_select(const Params& P, int layer, const h16* Q, int nrows, char* smem) {
;     ...
;     for (int i = tid; i < 64 * 50; i += NTHR) {
;       const int tok = i / 50, c = i % 50;
;       const float v = cd[tok * 52 + c];
;       int rank = 0;
;       for (int j = 0; j < 50; ++j) { const float o = cd[tok * 52 + j]; rank += (o > v || (o == v && j < c)) ? 1 : 0; }
;       if (rank < TOPK) { tv[tok * 16 + rank] = v; tp[tok * 16 + rank] = c; }
;     }
.Lrk0_c15:
	v_mov_b32_e32 v212, 0
	v_cmp_ge_f32_e64 s[22:23], v160, v175
	v_cmp_ge_f32_e64 s[24:25], v161, v175
	v_cmp_ge_f32_e64 s[26:27], v162, v175
	v_cmp_ge_f32_e64 s[28:29], v163, v175
	v_addc_co_u32_e64 v212, s[30:31], v212, 0, s[22:23]
	v_addc_co_u32_e64 v212, s[30:31], v212, 0, s[24:25]
	v_addc_co_u32_e64 v212, s[30:31], v212, 0, s[26:27]
	v_addc_co_u32_e64 v212, s[30:31], v212, 0, s[28:29]
	v_cmp_ge_f32_e64 s[22:23], v164, v175
	v_cmp_ge_f32_e64 s[24:25], v165, v175
	v_cmp_ge_f32_e64 s[26:27], v166, v175
	v_cmp_ge_f32_e64 s[28:29], v167, v175
	v_addc_co_u32_e64 v212, s[30:31], v212, 0, s[22:23]
	v_addc_co_u32_e64 v212, s[30:31], v212, 0, s[24:25]
	v_addc_co_u32_e64 v212, s[30:31], v212, 0, s[26:27]
	v_addc_co_u32_e64 v212, s[30:31], v212, 0, s[28:29]
	v_cmp_ge_f32_e64 s[22:23], v168, v175
	v_cmp_ge_f32_e64 s[24:25], v169, v175
	v_cmp_ge_f32_e64 s[26:27], v170, v175
	v_cmp_ge_f32_e64 s[28:29], v171, v175
	v_addc_co_u32_e64 v212, s[30:31], v212, 0, s[22:23]
	v_addc_co_u32_e64 v212, s[30:31], v212, 0, s[24:25]
	v_addc_co_u32_e64 v212, s[30:31], v212, 0, s[26:27]
	v_addc_co_u32_e64 v212, s[30:31], v212, 0, s[28:29]
	v_cmp_ge_f32_e64 s[22:23], v172, v175
	v_cmp_ge_f32_e64 s[24:25], v173, v175
	v_cmp_ge_f32_e64 s[26:27], v174, v175
	v_cmp_gt_f32_e64 s[28:29], v176, v175
	v_addc_co_u32_e64 v212, s[30:31], v212, 0, s[22:23]
	v_addc_co_u32_e64 v212, s[30:31], v212, 0, s[24:25]
	v_addc_co_u32_e64 v212, s[30:31], v212, 0, s[26:27]
	v_addc_co_u32_e64 v212, s[30:31], v212, 0, s[28:29]
	v_cmp_gt_f32_e64 s[22:23], v177, v175
	v_cmp_gt_f32_e64 s[24:25], v178, v175
	v_cmp_gt_f32_e64 s[26:27], v179, v175
	v_cmp_gt_f32_e64 s[28:29], v180, v175
	v_addc_co_u32_e64 v212, s[30:31], v212, 0, s[22:23]
	v_addc_co_u32_e64 v212, s[30:31], v212, 0, s[24:25]
	v_addc_co_u32_e64 v212, s[30:31], v212, 0, s[26:27]
	v_addc_co_u32_e64 v212, s[30:31], v212, 0, s[28:29]
	v_cmp_gt_f32_e64 s[22:23], v181, v175
	v_cmp_gt_f32_e64 s[24:25], v182, v175
	v_cmp_gt_f32_e64 s[26:27], v183, v175
	v_cmp_gt_f32_e64 s[28:29], v184, v175
	v_addc_co_u32_e64 v212, s[30:31], v212, 0, s[22:23]
	v_addc_co_u32_e64 v212, s[30:31], v212, 0, s[24:25]
	v_addc_co_u32_e64 v212, s[30:31], v212, 0, s[26:27]
	v_addc_co_u32_e64 v212, s[30:31], v212, 0, s[28:29]
	v_cmp_gt_f32_e64 s[22:23], v185, v175
	v_cmp_gt_f32_e64 s[24:25], v186, v175
	v_cmp_gt_f32_e64 s[26:27], v187, v175
	v_cmp_gt_f32_e64 s[28:29], v188, v175
	v_addc_co_u32_e64 v212, s[30:31], v212, 0, s[22:23]
	v_addc_co_u32_e64 v212, s[30:31], v212, 0, s[24:25]
	v_addc_co_u32_e64 v212, s[30:31], v212, 0, s[26:27]
	v_addc_co_u32_e64 v212, s[30:31], v212, 0, s[28:29]
	v_cmp_gt_f32_e64 s[22:23], v189, v175
	v_cmp_gt_f32_e64 s[24:25], v190, v175
	v_cmp_gt_f32_e64 s[26:27], v191, v175
	v_cmp_gt_f32_e64 s[28:29], v192, v175
	v_addc_co_u32_e64 v212, s[30:31], v212, 0, s[22:23]
	v_addc_co_u32_e64 v212, s[30:31], v212, 0, s[24:25]
	v_addc_co_u32_e64 v212, s[30:31], v212, 0, s[26:27]
	v_addc_co_u32_e64 v212, s[30:31], v212, 0, s[28:29]
	v_cmp_gt_f32_e64 s[22:23], v193, v175
	v_cmp_gt_f32_e64 s[24:25], v194, v175
	v_cmp_gt_f32_e64 s[26:27], v195, v175
	v_cmp_gt_f32_e64 s[28:29], v196, v175
	v_addc_co_u32_e64 v212, s[30:31], v212, 0, s[22:23]
	v_addc_co_u32_e64 v212, s[30:31], v212, 0, s[24:25]
	v_addc_co_u32_e64 v212, s[30:31], v212, 0, s[26:27]
	v_addc_co_u32_e64 v212, s[30:31], v212, 0, s[28:29]
	v_cmp_gt_f32_e64 s[22:23], v197, v175
	v_cmp_gt_f32_e64 s[24:25], v198, v175
	v_cmp_gt_f32_e64 s[26:27], v199, v175
	v_cmp_gt_f32_e64 s[28:29], v200, v175
	v_addc_co_u32_e64 v212, s[30:31], v212, 0, s[22:23]
	v_addc_co_u32_e64 v212, s[30:31], v212, 0, s[24:25]
	v_addc_co_u32_e64 v212, s[30:31], v212, 0, s[26:27]
	v_addc_co_u32_e64 v212, s[30:31], v212, 0, s[28:29]
	v_cmp_gt_f32_e64 s[22:23], v201, v175
	v_cmp_gt_f32_e64 s[24:25], v202, v175
	v_cmp_gt_f32_e64 s[26:27], v203, v175
	v_cmp_gt_f32_e64 s[28:29], v204, v175
	v_addc_co_u32_e64 v212, s[30:31], v212, 0, s[22:23]
	v_addc_co_u32_e64 v212, s[30:31], v212, 0, s[24:25]
	v_addc_co_u32_e64 v212, s[30:31], v212, 0, s[26:27]
	v_addc_co_u32_e64 v212, s[30:31], v212, 0, s[28:29]
	v_cmp_gt_f32_e64 s[22:23], v205, v175
	v_cmp_gt_f32_e64 s[24:25], v206, v175
	v_cmp_gt_f32_e64 s[26:27], v207, v175
	v_cmp_gt_f32_e64 s[28:29], v208, v175
	v_addc_co_u32_e64 v212, s[30:31], v212, 0, s[22:23]
	v_addc_co_u32_e64 v212, s[30:31], v212, 0, s[24:25]
	v_addc_co_u32_e64 v212, s[30:31], v212, 0, s[26:27]
	v_addc_co_u32_e64 v212, s[30:31], v212, 0, s[28:29]
	v_cmp_gt_f32_e64 s[22:23], v209, v175
	s_nop 0
	s_nop 0
	v_addc_co_u32_e64 v212, s[30:31], v212, 0, s[22:23]
	v_cmp_gt_u32_e32 vcc, 16, v212
	s_and_saveexec_b64 s[40:41], vcc
	v_lshl_add_u32 v214, v212, 2, v213
	v_mov_b32_e32 v212, 15
	ds_write_b32 v214, v175
	ds_write_b32 v214, v212 offset:4096
	s_mov_b64 exec, -1
	s_branch .Lrk0_c23
; __device__ __forceinline__ void ph_peer_select(const Params& P, int layer, const h16* Q, int nrows, char* smem) {
;     ...
;     for (int i = tid; i < 64 * 50; i += NTHR) {
;       const int tok = i / 50, c = i % 50;
;       const float v = cd[tok * 52 + c];
;       int rank = 0;
;       for (int j = 0; j < 50; ++j) { const float o = cd[tok * 52 + j]; rank += (o > v || (o == v && j < c)) ? 1 : 0; }
;       if (rank < TOPK) { tv[tok * 16 + rank] = v; tp[tok * 16 + rank] = c; }
;     }
.Lrk0_c16:
	v_mov_b32_e32 v212, 0
	v_cmp_ge_f32_e64 s[22:23], v160, v176
	v_cmp_ge_f32_e64 s[24:25], v161, v176
	v_cmp_ge_f32_e64 s[26:27], v162, v176
	v_cmp_ge_f32_e64 s[28:29], v163, v176
	v_addc_co_u32_e64 v212, s[30:31], v212, 0, s[22:23]
	v_addc_co_u32_e64 v212, s[30:31], v212, 0, s[24:25]
	v_addc_co_u32_e64 v212, s[30:31], v212, 0, s[26:27]
	v_addc_co_u32_e64 v212, s[30:31], v212, 0, s[28:29]
	v_cmp_ge_f32_e64 s[22:23], v164, v176
	v_cmp_ge_f32_e64 s[24:25], v165, v176
	v_cmp_ge_f32_e64 s[26:27], v166, v176
	v_cmp_ge_f32_e64 s[28:29], v167, v176
	v_addc_co_u32_e64 v212, s[30:31], v212, 0, s[22:23]
	v_addc_co_u32_e64 v212, s[30:31], v212, 0, s[24:25]
	v_addc_co_u32_e64 v212, s[30:31], v212, 0, s[26:27]
	v_addc_co_u32_e64 v212, s[30:31], v212, 0, s[28:29]
	v_cmp_ge_f32_e64 s[22:23], v168, v176
	v_cmp_ge_f32_e64 s[24:25], v169, v176
	v_cmp_ge_f32_e64 s[26:27], v170, v176
	v_cmp_ge_f32_e64 s[28:29], v171, v176
	v_addc_co_u32_e64 v212, s[30:31], v212, 0, s[22:23]
	v_addc_co_u32_e64 v212, s[30:31], v212, 0, s[24:25]
	v_addc_co_u32_e64 v212, s[30:31], v212, 0, s[26:27]
	v_addc_co_u32_e64 v212, s[30:31], v212, 0, s[28:29]
	v_cmp_ge_f32_e64 s[22:23], v172, v176
	v_cmp_ge_f32_e64 s[24:25], v173, v176
	v_cmp_ge_f32_e64 s[26:27], v174, v176
	v_cmp_ge_f32_e64 s[28:29], v175, v176
	v_addc_co_u32_e64 v212, s[30:31], v212, 0, s[22:23]
	v_addc_co_u32_e64 v212, s[30:31], v212, 0, s[24:25]
	v_addc_co_u32_e64 v212, s[30:31], v212, 0, s[26:27]
	v_addc_co_u32_e64 v212, s[30:31], v212, 0, s[28:29]
	v_cmp_gt_f32_e64 s[22:23], v177, v176
	v_cmp_gt_f32_e64 s[24:25], v178, v176
	v_cmp_gt_f32_e64 s[26:27], v179, v176
	v_cmp_gt_f32_e64 s[28:29], v180, v176
	v_addc_co_u32_e64 v212, s[30:31], v212, 0, s[22:23]
	v_addc_co_u32_e64 v212, s[30:31], v212, 0, s[24:25]
	v_addc_co_u32_e64 v212, s[30:31], v212, 0, s[26:27]
	v_addc_co_u32_e64 v212, s[30:31], v212, 0, s[28:29]
	v_cmp_gt_f32_e64 s[22:23], v181, v176
	v_cmp_gt_f32_e64 s[24:25], v182, v176
	v_cmp_gt_f32_e64 s[26:27], v183, v176
	v_cmp_gt_f32_e64 s[28:29], v184, v176
	v_addc_co_u32_e64 v212, s[30:31], v212, 0, s[22:23]
	v_addc_co_u32_e64 v212, s[30:31], v212, 0, s[24:25]
	v_addc_co_u32_e64 v212, s[30:31], v212, 0, s[26:27]
	v_addc_co_u32_e64 v212, s[30:31], v212, 0, s[28:29]
	v_cmp_gt_f32_e64 s[22:23], v185, v176
	v_cmp_gt_f32_e64 s[24:25], v186, v176
	v_cmp_gt_f32_e64 s[26:27], v187, v176
	v_cmp_gt_f32_e64 s[28:29], v188, v176
	v_addc_co_u32_e64 v212, s[30:31], v212, 0, s[22:23]
	v_addc_co_u32_e64 v212, s[30:31], v212, 0, s[24:25]
	v_addc_co_u32_e64 v212, s[30:31], v212, 0, s[26:27]
	v_addc_co_u32_e64 v212, s[30:31], v212, 0, s[28:29]
	v_cmp_gt_f32_e64 s[22:23], v189, v176
	v_cmp_gt_f32_e64 s[24:25], v190, v176
	v_cmp_gt_f32_e64 s[26:27], v191, v176
	v_cmp_gt_f32_e64 s[28:29], v192, v176
	v_addc_co_u32_e64 v212, s[30:31], v212, 0, s[22:23]
	v_addc_co_u32_e64 v212, s[30:31], v212, 0, s[24:25]
	v_addc_co_u32_e64 v212, s[30:31], v212, 0, s[26:27]
	v_addc_co_u32_e64 v212, s[30:31], v212, 0, s[28:29]
	v_cmp_gt_f32_e64 s[22:23], v193, v176
	v_cmp_gt_f32_e64 s[24:25], v194, v176
	v_cmp_gt_f32_e64 s[26:27], v195, v176
	v_cmp_gt_f32_e64 s[28:29], v196, v176
	v_addc_co_u32_e64 v212, s[30:31], v212, 0, s[22:23]
	v_addc_co_u32_e64 v212, s[30:31], v212, 0, s[24:25]
	v_addc_co_u32_e64 v212, s[30:31], v212, 0, s[26:27]
	v_addc_co_u32_e64 v212, s[30:31], v212, 0, s[28:29]
	v_cmp_gt_f32_e64 s[22:23], v197, v176
	v_cmp_gt_f32_e64 s[24:25], v198, v176
	v_cmp_gt_f32_e64 s[26:27], v199, v176
	v_cmp_gt_f32_e64 s[28:29], v200, v176
	v_addc_co_u32_e64 v212, s[30:31], v212, 0, s[22:23]
	v_addc_co_u32_e64 v212, s[30:31], v212, 0, s[24:25]
	v_addc_co_u32_e64 v212, s[30:31], v212, 0, s[26:27]
	v_addc_co_u32_e64 v212, s[30:31], v212, 0, s[28:29]
	v_cmp_gt_f32_e64 s[22:23], v201, v176
	v_cmp_gt_f32_e64 s[24:25], v202, v176
	v_cmp_gt_f32_e64 s[26:27], v203, v176
	v_cmp_gt_f32_e64 s[28:29], v204, v176
	v_addc_co_u32_e64 v212, s[30:31], v212, 0, s[22:23]
	v_addc_co_u32_e64 v212, s[30:31], v212, 0, s[24:25]
	v_addc_co_u32_e64 v212, s[30:31], v212, 0, s[26:27]
	v_addc_co_u32_e64 v212, s[30:31], v212, 0, s[28:29]
	v_cmp_gt_f32_e64 s[22:23], v205, v176
	v_cmp_gt_f32_e64 s[24:25], v206, v176
	v_cmp_gt_f32_e64 s[26:27], v207, v176
	v_cmp_gt_f32_e64 s[28:29], v208, v176
	v_addc_co_u32_e64 v212, s[30:31], v212, 0, s[22:23]
	v_addc_co_u32_e64 v212, s[30:31], v212, 0, s[24:25]
	v_addc_co_u32_e64 v212, s[30:31], v212, 0, s[26:27]
	v_addc_co_u32_e64 v212, s[30:31], v212, 0, s[28:29]
	v_cmp_gt_f32_e64 s[22:23], v209, v176
	s_nop 0
	s_nop 0
	v_addc_co_u32_e64 v212, s[30:31], v212, 0, s[22:23]
	v_cmp_gt_u32_e32 vcc, 16, v212
	s_and_saveexec_b64 s[40:41], vcc
	v_lshl_add_u32 v214, v212, 2, v213
	v_mov_b32_e32 v212, 16
	ds_write_b32 v214, v176
	ds_write_b32 v214, v212 offset:4096
	s_mov_b64 exec, -1
	s_branch .Lrk0_c24
; __device__ __forceinline__ void ph_peer_select(const Params& P, int layer, const h16* Q, int nrows, char* smem) {
;     ...
;     for (int i = tid; i < 64 * 50; i += NTHR) {
;       const int tok = i / 50, c = i % 50;
;       const float v = cd[tok * 52 + c];
;       int rank = 0;
;       for (int j = 0; j < 50; ++j) { const float o = cd[tok * 52 + j]; rank += (o > v || (o == v && j < c)) ? 1 : 0; }
;       if (rank < TOPK) { tv[tok * 16 + rank] = v; tp[tok * 16 + rank] = c; }
;     }
.Lrk0_c17:
	v_mov_b32_e32 v212, 0
	v_cmp_ge_f32_e64 s[22:23], v160, v177
	v_cmp_ge_f32_e64 s[24:25], v161, v177
	v_cmp_ge_f32_e64 s[26:27], v162, v177
	v_cmp_ge_f32_e64 s[28:29], v163, v177
	v_addc_co_u32_e64 v212, s[30:31], v212, 0, s[22:23]
	v_addc_co_u32_e64 v212, s[30:31], v212, 0, s[24:25]
	v_addc_co_u32_e64 v212, s[30:31], v212, 0, s[26:27]
	v_addc_co_u32_e64 v212, s[30:31], v212, 0, s[28:29]
	v_cmp_ge_f32_e64 s[22:23], v164, v177
	v_cmp_ge_f32_e64 s[24:25], v165, v177
	v_cmp_ge_f32_e64 s[26:27], v166, v177
	v_cmp_ge_f32_e64 s[28:29], v167, v177
	v_addc_co_u32_e64 v212, s[30:31], v212, 0, s[22:23]
	v_addc_co_u32_e64 v212, s[30:31], v212, 0, s[24:25]
	v_addc_co_u32_e64 v212, s[30:31], v212, 0, s[26:27]
	v_addc_co_u32_e64 v212, s[30:31], v212, 0, s[28:29]
	v_cmp_ge_f32_e64 s[22:23], v168, v177
	v_cmp_ge_f32_e64 s[24:25], v169, v177
	v_cmp_ge_f32_e64 s[26:27], v170, v177
	v_cmp_ge_f32_e64 s[28:29], v171, v177
	v_addc_co_u32_e64 v212, s[30:31], v212, 0, s[22:23]
	v_addc_co_u32_e64 v212, s[30:31], v212, 0, s[24:25]
	v_addc_co_u32_e64 v212, s[30:31], v212, 0, s[26:27]
	v_addc_co_u32_e64 v212, s[30:31], v212, 0, s[28:29]
	v_cmp_ge_f32_e64 s[22:23], v172, v177
	v_cmp_ge_f32_e64 s[24:25], v173, v177
	v_cmp_ge_f32_e64 s[26:27], v174, v177
	v_cmp_ge_f32_e64 s[28:29], v175, v177
	v_addc_co_u32_e64 v212, s[30:31], v212, 0, s[22:23]
	v_addc_co_u32_e64 v212, s[30:31], v212, 0, s[24:25]
	v_addc_co_u32_e64 v212, s[30:31], v212, 0, s[26:27]
	v_addc_co_u32_e64 v212, s[30:31], v212, 0, s[28:29]
	v_cmp_ge_f32_e64 s[22:23], v176, v177
	v_cmp_gt_f32_e64 s[24:25], v178, v177
	v_cmp_gt_f32_e64 s[26:27], v179, v177
	v_cmp_gt_f32_e64 s[28:29], v180, v177
	v_addc_co_u32_e64 v212, s[30:31], v212, 0, s[22:23]
	v_addc_co_u32_e64 v212, s[30:31], v212, 0, s[24:25]
	v_addc_co_u32_e64 v212, s[30:31], v212, 0, s[26:27]
	v_addc_co_u32_e64 v212, s[30:31], v212, 0, s[28:29]
	v_cmp_gt_f32_e64 s[22:23], v181, v177
	v_cmp_gt_f32_e64 s[24:25], v182, v177
	v_cmp_gt_f32_e64 s[26:27], v183, v177
	v_cmp_gt_f32_e64 s[28:29], v184, v177
	v_addc_co_u32_e64 v212, s[30:31], v212, 0, s[22:23]
	v_addc_co_u32_e64 v212, s[30:31], v212, 0, s[24:25]
	v_addc_co_u32_e64 v212, s[30:31], v212, 0, s[26:27]
	v_addc_co_u32_e64 v212, s[30:31], v212, 0, s[28:29]
	v_cmp_gt_f32_e64 s[22:23], v185, v177
	v_cmp_gt_f32_e64 s[24:25], v186, v177
	v_cmp_gt_f32_e64 s[26:27], v187, v177
	v_cmp_gt_f32_e64 s[28:29], v188, v177
	v_addc_co_u32_e64 v212, s[30:31], v212, 0, s[22:23]
	v_addc_co_u32_e64 v212, s[30:31], v212, 0, s[24:25]
	v_addc_co_u32_e64 v212, s[30:31], v212, 0, s[26:27]
	v_addc_co_u32_e64 v212, s[30:31], v212, 0, s[28:29]
	v_cmp_gt_f32_e64 s[22:23], v189, v177
	v_cmp_gt_f32_e64 s[24:25], v190, v177
	v_cmp_gt_f32_e64 s[26:27], v191, v177
	v_cmp_gt_f32_e64 s[28:29], v192, v177
	v_addc_co_u32_e64 v212, s[30:31], v212, 0, s[22:23]
	v_addc_co_u32_e64 v212, s[30:31], v212, 0, s[24:25]
	v_addc_co_u32_e64 v212, s[30:31], v212, 0, s[26:27]
	v_addc_co_u32_e64 v212, s[30:31], v212, 0, s[28:29]
	v_cmp_gt_f32_e64 s[22:23], v193, v177
	v_cmp_gt_f32_e64 s[24:25], v194, v177
	v_cmp_gt_f32_e64 s[26:27], v195, v177
	v_cmp_gt_f32_e64 s[28:29], v196, v177
	v_addc_co_u32_e64 v212, s[30:31], v212, 0, s[22:23]
	v_addc_co_u32_e64 v212, s[30:31], v212, 0, s[24:25]
	v_addc_co_u32_e64 v212, s[30:31], v212, 0, s[26:27]
	v_addc_co_u32_e64 v212, s[30:31], v212, 0, s[28:29]
	v_cmp_gt_f32_e64 s[22:23], v197, v177
	v_cmp_gt_f32_e64 s[24:25], v198, v177
	v_cmp_gt_f32_e64 s[26:27], v199, v177
	v_cmp_gt_f32_e64 s[28:29], v200, v177
	v_addc_co_u32_e64 v212, s[30:31], v212, 0, s[22:23]
	v_addc_co_u32_e64 v212, s[30:31], v212, 0, s[24:25]
	v_addc_co_u32_e64 v212, s[30:31], v212, 0, s[26:27]
	v_addc_co_u32_e64 v212, s[30:31], v212, 0, s[28:29]
	v_cmp_gt_f32_e64 s[22:23], v201, v177
	v_cmp_gt_f32_e64 s[24:25], v202, v177
	v_cmp_gt_f32_e64 s[26:27], v203, v177
	v_cmp_gt_f32_e64 s[28:29], v204, v177
	v_addc_co_u32_e64 v212, s[30:31], v212, 0, s[22:23]
	v_addc_co_u32_e64 v212, s[30:31], v212, 0, s[24:25]
	v_addc_co_u32_e64 v212, s[30:31], v212, 0, s[26:27]
	v_addc_co_u32_e64 v212, s[30:31], v212, 0, s[28:29]
	v_cmp_gt_f32_e64 s[22:23], v205, v177
	v_cmp_gt_f32_e64 s[24:25], v206, v177
	v_cmp_gt_f32_e64 s[26:27], v207, v177
	v_cmp_gt_f32_e64 s[28:29], v208, v177
	v_addc_co_u32_e64 v212, s[30:31], v212, 0, s[22:23]
	v_addc_co_u32_e64 v212, s[30:31], v212, 0, s[24:25]
	v_addc_co_u32_e64 v212, s[30:31], v212, 0, s[26:27]
	v_addc_co_u32_e64 v212, s[30:31], v212, 0, s[28:29]
	v_cmp_gt_f32_e64 s[22:23], v209, v177
	s_nop 0
	s_nop 0
	v_addc_co_u32_e64 v212, s[30:31], v212, 0, s[22:23]
	v_cmp_gt_u32_e32 vcc, 16, v212
	s_and_saveexec_b64 s[40:41], vcc
	v_lshl_add_u32 v214, v212, 2, v213
	v_mov_b32_e32 v212, 17
	ds_write_b32 v214, v177
	ds_write_b32 v214, v212 offset:4096
	s_mov_b64 exec, -1
	s_branch .Lrk0_c25
; __device__ __forceinline__ void ph_peer_select(const Params& P, int layer, const h16* Q, int nrows, char* smem) {
;     ...
;     for (int i = tid; i < 64 * 50; i += NTHR) {
;       const int tok = i / 50, c = i % 50;
;       const float v = cd[tok * 52 + c];
;       int rank = 0;
;       for (int j = 0; j < 50; ++j) { const float o = cd[tok * 52 + j]; rank += (o > v || (o == v && j < c)) ? 1 : 0; }
;       if (rank < TOPK) { tv[tok * 16 + rank] = v; tp[tok * 16 + rank] = c; }
;     }
.Lrk0_c18:
	v_mov_b32_e32 v212, 0
	v_cmp_ge_f32_e64 s[22:23], v160, v178
	v_cmp_ge_f32_e64 s[24:25], v161, v178
	v_cmp_ge_f32_e64 s[26:27], v162, v178
	v_cmp_ge_f32_e64 s[28:29], v163, v178
	v_addc_co_u32_e64 v212, s[30:31], v212, 0, s[22:23]
	v_addc_co_u32_e64 v212, s[30:31], v212, 0, s[24:25]
	v_addc_co_u32_e64 v212, s[30:31], v212, 0, s[26:27]
	v_addc_co_u32_e64 v212, s[30:31], v212, 0, s[28:29]
	v_cmp_ge_f32_e64 s[22:23], v164, v178
	v_cmp_ge_f32_e64 s[24:25], v165, v178
	v_cmp_ge_f32_e64 s[26:27], v166, v178
	v_cmp_ge_f32_e64 s[28:29], v167, v178
	v_addc_co_u32_e64 v212, s[30:31], v212, 0, s[22:23]
	v_addc_co_u32_e64 v212, s[30:31], v212, 0, s[24:25]
	v_addc_co_u32_e64 v212, s[30:31], v212, 0, s[26:27]
	v_addc_co_u32_e64 v212, s[30:31], v212, 0, s[28:29]
	v_cmp_ge_f32_e64 s[22:23], v168, v178
	v_cmp_ge_f32_e64 s[24:25], v169, v178
	v_cmp_ge_f32_e64 s[26:27], v170, v178
	v_cmp_ge_f32_e64 s[28:29], v171, v178
	v_addc_co_u32_e64 v212, s[30:31], v212, 0, s[22:23]
	v_addc_co_u32_e64 v212, s[30:31], v212, 0, s[24:25]
	v_addc_co_u32_e64 v212, s[30:31], v212, 0, s[26:27]
	v_addc_co_u32_e64 v212, s[30:31], v212, 0, s[28:29]
	v_cmp_ge_f32_e64 s[22:23], v172, v178
	v_cmp_ge_f32_e64 s[24:25], v173, v178
	v_cmp_ge_f32_e64 s[26:27], v174, v178
	v_cmp_ge_f32_e64 s[28:29], v175, v178
	v_addc_co_u32_e64 v212, s[30:31], v212, 0, s[22:23]
	v_addc_co_u32_e64 v212, s[30:31], v212, 0, s[24:25]
	v_addc_co_u32_e64 v212, s[30:31], v212, 0, s[26:27]
	v_addc_co_u32_e64 v212, s[30:31], v212, 0, s[28:29]
	v_cmp_ge_f32_e64 s[22:23], v176, v178
	v_cmp_ge_f32_e64 s[24:25], v177, v178
	v_cmp_gt_f32_e64 s[26:27], v179, v178
	v_cmp_gt_f32_e64 s[28:29], v180, v178
	v_addc_co_u32_e64 v212, s[30:31], v212, 0, s[22:23]
	v_addc_co_u32_e64 v212, s[30:31], v212, 0, s[24:25]
	v_addc_co_u32_e64 v212, s[30:31], v212, 0, s[26:27]
	v_addc_co_u32_e64 v212, s[30:31], v212, 0, s[28:29]
	v_cmp_gt_f32_e64 s[22:23], v181, v178
	v_cmp_gt_f32_e64 s[24:25], v182, v178
	v_cmp_gt_f32_e64 s[26:27], v183, v178
	v_cmp_gt_f32_e64 s[28:29], v184, v178
	v_addc_co_u32_e64 v212, s[30:31], v212, 0, s[22:23]
	v_addc_co_u32_e64 v212, s[30:31], v212, 0, s[24:25]
	v_addc_co_u32_e64 v212, s[30:31], v212, 0, s[26:27]
	v_addc_co_u32_e64 v212, s[30:31], v212, 0, s[28:29]
	v_cmp_gt_f32_e64 s[22:23], v185, v178
	v_cmp_gt_f32_e64 s[24:25], v186, v178
	v_cmp_gt_f32_e64 s[26:27], v187, v178
	v_cmp_gt_f32_e64 s[28:29], v188, v178
	v_addc_co_u32_e64 v212, s[30:31], v212, 0, s[22:23]
	v_addc_co_u32_e64 v212, s[30:31], v212, 0, s[24:25]
	v_addc_co_u32_e64 v212, s[30:31], v212, 0, s[26:27]
	v_addc_co_u32_e64 v212, s[30:31], v212, 0, s[28:29]
	v_cmp_gt_f32_e64 s[22:23], v189, v178
	v_cmp_gt_f32_e64 s[24:25], v190, v178
	v_cmp_gt_f32_e64 s[26:27], v191, v178
	v_cmp_gt_f32_e64 s[28:29], v192, v178
	v_addc_co_u32_e64 v212, s[30:31], v212, 0, s[22:23]
	v_addc_co_u32_e64 v212, s[30:31], v212, 0, s[24:25]
	v_addc_co_u32_e64 v212, s[30:31], v212, 0, s[26:27]
	v_addc_co_u32_e64 v212, s[30:31], v212, 0, s[28:29]
	v_cmp_gt_f32_e64 s[22:23], v193, v178
	v_cmp_gt_f32_e64 s[24:25], v194, v178
	v_cmp_gt_f32_e64 s[26:27], v195, v178
	v_cmp_gt_f32_e64 s[28:29], v196, v178
	v_addc_co_u32_e64 v212, s[30:31], v212, 0, s[22:23]
	v_addc_co_u32_e64 v212, s[30:31], v212, 0, s[24:25]
	v_addc_co_u32_e64 v212, s[30:31], v212, 0, s[26:27]
	v_addc_co_u32_e64 v212, s[30:31], v212, 0, s[28:29]
	v_cmp_gt_f32_e64 s[22:23], v197, v178
	v_cmp_gt_f32_e64 s[24:25], v198, v178
	v_cmp_gt_f32_e64 s[26:27], v199, v178
	v_cmp_gt_f32_e64 s[28:29], v200, v178
	v_addc_co_u32_e64 v212, s[30:31], v212, 0, s[22:23]
	v_addc_co_u32_e64 v212, s[30:31], v212, 0, s[24:25]
	v_addc_co_u32_e64 v212, s[30:31], v212, 0, s[26:27]
	v_addc_co_u32_e64 v212, s[30:31], v212, 0, s[28:29]
	v_cmp_gt_f32_e64 s[22:23], v201, v178
	v_cmp_gt_f32_e64 s[24:25], v202, v178
	v_cmp_gt_f32_e64 s[26:27], v203, v178
	v_cmp_gt_f32_e64 s[28:29], v204, v178
	v_addc_co_u32_e64 v212, s[30:31], v212, 0, s[22:23]
	v_addc_co_u32_e64 v212, s[30:31], v212, 0, s[24:25]
	v_addc_co_u32_e64 v212, s[30:31], v212, 0, s[26:27]
	v_addc_co_u32_e64 v212, s[30:31], v212, 0, s[28:29]
	v_cmp_gt_f32_e64 s[22:23], v205, v178
	v_cmp_gt_f32_e64 s[24:25], v206, v178
	v_cmp_gt_f32_e64 s[26:27], v207, v178
	v_cmp_gt_f32_e64 s[28:29], v208, v178
	v_addc_co_u32_e64 v212, s[30:31], v212, 0, s[22:23]
	v_addc_co_u32_e64 v212, s[30:31], v212, 0, s[24:25]
	v_addc_co_u32_e64 v212, s[30:31], v212, 0, s[26:27]
	v_addc_co_u32_e64 v212, s[30:31], v212, 0, s[28:29]
	v_cmp_gt_f32_e64 s[22:23], v209, v178
	s_nop 0
	s_nop 0
	v_addc_co_u32_e64 v212, s[30:31], v212, 0, s[22:23]
	v_cmp_gt_u32_e32 vcc, 16, v212
	s_and_saveexec_b64 s[40:41], vcc
	v_lshl_add_u32 v214, v212, 2, v213
	v_mov_b32_e32 v212, 18
	ds_write_b32 v214, v178
	ds_write_b32 v214, v212 offset:4096
	s_mov_b64 exec, -1
	s_branch .Lrk0_c26
; __device__ __forceinline__ void ph_peer_select(const Params& P, int layer, const h16* Q, int nrows, char* smem) {
;     ...
;     for (int i = tid; i < 64 * 50; i += NTHR) {
;       const int tok = i / 50, c = i % 50;
;       const float v = cd[tok * 52 + c];
;       int rank = 0;
;       for (int j = 0; j < 50; ++j) { const float o = cd[tok * 52 + j]; rank += (o > v || (o == v && j < c)) ? 1 : 0; }
;       if (rank < TOPK) { tv[tok * 16 + rank] = v; tp[tok * 16 + rank] = c; }
;     }
.Lrk0_c19:
	v_mov_b32_e32 v212, 0
	v_cmp_ge_f32_e64 s[22:23], v160, v179
	v_cmp_ge_f32_e64 s[24:25], v161, v179
	v_cmp_ge_f32_e64 s[26:27], v162, v179
	v_cmp_ge_f32_e64 s[28:29], v163, v179
	v_addc_co_u32_e64 v212, s[30:31], v212, 0, s[22:23]
	v_addc_co_u32_e64 v212, s[30:31], v212, 0, s[24:25]
	v_addc_co_u32_e64 v212, s[30:31], v212, 0, s[26:27]
	v_addc_co_u32_e64 v212, s[30:31], v212, 0, s[28:29]
	v_cmp_ge_f32_e64 s[22:23], v164, v179
	v_cmp_ge_f32_e64 s[24:25], v165, v179
	v_cmp_ge_f32_e64 s[26:27], v166, v179
	v_cmp_ge_f32_e64 s[28:29], v167, v179
	v_addc_co_u32_e64 v212, s[30:31], v212, 0, s[22:23]
	v_addc_co_u32_e64 v212, s[30:31], v212, 0, s[24:25]
	v_addc_co_u32_e64 v212, s[30:31], v212, 0, s[26:27]
	v_addc_co_u32_e64 v212, s[30:31], v212, 0, s[28:29]
	v_cmp_ge_f32_e64 s[22:23], v168, v179
	v_cmp_ge_f32_e64 s[24:25], v169, v179
	v_cmp_ge_f32_e64 s[26:27], v170, v179
	v_cmp_ge_f32_e64 s[28:29], v171, v179
	v_addc_co_u32_e64 v212, s[30:31], v212, 0, s[22:23]
	v_addc_co_u32_e64 v212, s[30:31], v212, 0, s[24:25]
	v_addc_co_u32_e64 v212, s[30:31], v212, 0, s[26:27]
	v_addc_co_u32_e64 v212, s[30:31], v212, 0, s[28:29]
	v_cmp_ge_f32_e64 s[22:23], v172, v179
	v_cmp_ge_f32_e64 s[24:25], v173, v179
	v_cmp_ge_f32_e64 s[26:27], v174, v179
	v_cmp_ge_f32_e64 s[28:29], v175, v179
	v_addc_co_u32_e64 v212, s[30:31], v212, 0, s[22:23]
	v_addc_co_u32_e64 v212, s[30:31], v212, 0, s[24:25]
	v_addc_co_u32_e64 v212, s[30:31], v212, 0, s[26:27]
	v_addc_co_u32_e64 v212, s[30:31], v212, 0, s[28:29]
	v_cmp_ge_f32_e64 s[22:23], v176, v179
	v_cmp_ge_f32_e64 s[24:25], v177, v179
	v_cmp_ge_f32_e64 s[26:27], v178, v179
	v_cmp_gt_f32_e64 s[28:29], v180, v179
	v_addc_co_u32_e64 v212, s[30:31], v212, 0, s[22:23]
	v_addc_co_u32_e64 v212, s[30:31], v212, 0, s[24:25]
	v_addc_co_u32_e64 v212, s[30:31], v212, 0, s[26:27]
	v_addc_co_u32_e64 v212, s[30:31], v212, 0, s[28:29]
	v_cmp_gt_f32_e64 s[22:23], v181, v179
	v_cmp_gt_f32_e64 s[24:25], v182, v179
	v_cmp_gt_f32_e64 s[26:27], v183, v179
	v_cmp_gt_f32_e64 s[28:29], v184, v179
	v_addc_co_u32_e64 v212, s[30:31], v212, 0, s[22:23]
	v_addc_co_u32_e64 v212, s[30:31], v212, 0, s[24:25]
	v_addc_co_u32_e64 v212, s[30:31], v212, 0, s[26:27]
	v_addc_co_u32_e64 v212, s[30:31], v212, 0, s[28:29]
	v_cmp_gt_f32_e64 s[22:23], v185, v179
	v_cmp_gt_f32_e64 s[24:25], v186, v179
	v_cmp_gt_f32_e64 s[26:27], v187, v179
	v_cmp_gt_f32_e64 s[28:29], v188, v179
	v_addc_co_u32_e64 v212, s[30:31], v212, 0, s[22:23]
	v_addc_co_u32_e64 v212, s[30:31], v212, 0, s[24:25]
	v_addc_co_u32_e64 v212, s[30:31], v212, 0, s[26:27]
	v_addc_co_u32_e64 v212, s[30:31], v212, 0, s[28:29]
	v_cmp_gt_f32_e64 s[22:23], v189, v179
	v_cmp_gt_f32_e64 s[24:25], v190, v179
	v_cmp_gt_f32_e64 s[26:27], v191, v179
	v_cmp_gt_f32_e64 s[28:29], v192, v179
	v_addc_co_u32_e64 v212, s[30:31], v212, 0, s[22:23]
	v_addc_co_u32_e64 v212, s[30:31], v212, 0, s[24:25]
	v_addc_co_u32_e64 v212, s[30:31], v212, 0, s[26:27]
	v_addc_co_u32_e64 v212, s[30:31], v212, 0, s[28:29]
	v_cmp_gt_f32_e64 s[22:23], v193, v179
	v_cmp_gt_f32_e64 s[24:25], v194, v179
	v_cmp_gt_f32_e64 s[26:27], v195, v179
	v_cmp_gt_f32_e64 s[28:29], v196, v179
	v_addc_co_u32_e64 v212, s[30:31], v212, 0, s[22:23]
	v_addc_co_u32_e64 v212, s[30:31], v212, 0, s[24:25]
	v_addc_co_u32_e64 v212, s[30:31], v212, 0, s[26:27]
	v_addc_co_u32_e64 v212, s[30:31], v212, 0, s[28:29]
	v_cmp_gt_f32_e64 s[22:23], v197, v179
	v_cmp_gt_f32_e64 s[24:25], v198, v179
	v_cmp_gt_f32_e64 s[26:27], v199, v179
	v_cmp_gt_f32_e64 s[28:29], v200, v179
	v_addc_co_u32_e64 v212, s[30:31], v212, 0, s[22:23]
	v_addc_co_u32_e64 v212, s[30:31], v212, 0, s[24:25]
	v_addc_co_u32_e64 v212, s[30:31], v212, 0, s[26:27]
	v_addc_co_u32_e64 v212, s[30:31], v212, 0, s[28:29]
	v_cmp_gt_f32_e64 s[22:23], v201, v179
	v_cmp_gt_f32_e64 s[24:25], v202, v179
	v_cmp_gt_f32_e64 s[26:27], v203, v179
	v_cmp_gt_f32_e64 s[28:29], v204, v179
	v_addc_co_u32_e64 v212, s[30:31], v212, 0, s[22:23]
	v_addc_co_u32_e64 v212, s[30:31], v212, 0, s[24:25]
	v_addc_co_u32_e64 v212, s[30:31], v212, 0, s[26:27]
	v_addc_co_u32_e64 v212, s[30:31], v212, 0, s[28:29]
	v_cmp_gt_f32_e64 s[22:23], v205, v179
	v_cmp_gt_f32_e64 s[24:25], v206, v179
	v_cmp_gt_f32_e64 s[26:27], v207, v179
	v_cmp_gt_f32_e64 s[28:29], v208, v179
	v_addc_co_u32_e64 v212, s[30:31], v212, 0, s[22:23]
	v_addc_co_u32_e64 v212, s[30:31], v212, 0, s[24:25]
	v_addc_co_u32_e64 v212, s[30:31], v212, 0, s[26:27]
	v_addc_co_u32_e64 v212, s[30:31], v212, 0, s[28:29]
	v_cmp_gt_f32_e64 s[22:23], v209, v179
	s_nop 0
	s_nop 0
	v_addc_co_u32_e64 v212, s[30:31], v212, 0, s[22:23]
	v_cmp_gt_u32_e32 vcc, 16, v212
	s_and_saveexec_b64 s[40:41], vcc
	v_lshl_add_u32 v214, v212, 2, v213
	v_mov_b32_e32 v212, 19
	ds_write_b32 v214, v179
	ds_write_b32 v214, v212 offset:4096
	s_mov_b64 exec, -1
	s_branch .Lrk0_c27
; __device__ __forceinline__ void ph_peer_select(const Params& P, int layer, const h16* Q, int nrows, char* smem) {
;     ...
;     for (int i = tid; i < 64 * 50; i += NTHR) {
;       const int tok = i / 50, c = i % 50;
;       const float v = cd[tok * 52 + c];
;       int rank = 0;
;       for (int j = 0; j < 50; ++j) { const float o = cd[tok * 52 + j]; rank += (o > v || (o == v && j < c)) ? 1 : 0; }
;       if (rank < TOPK) { tv[tok * 16 + rank] = v; tp[tok * 16 + rank] = c; }
;     }
.Lrk0_c20:
	v_mov_b32_e32 v212, 0
	v_cmp_ge_f32_e64 s[22:23], v160, v180
	v_cmp_ge_f32_e64 s[24:25], v161, v180
	v_cmp_ge_f32_e64 s[26:27], v162, v180
	v_cmp_ge_f32_e64 s[28:29], v163, v180
	v_addc_co_u32_e64 v212, s[30:31], v212, 0, s[22:23]
	v_addc_co_u32_e64 v212, s[30:31], v212, 0, s[24:25]
	v_addc_co_u32_e64 v212, s[30:31], v212, 0, s[26:27]
	v_addc_co_u32_e64 v212, s[30:31], v212, 0, s[28:29]
	v_cmp_ge_f32_e64 s[22:23], v164, v180
	v_cmp_ge_f32_e64 s[24:25], v165, v180
	v_cmp_ge_f32_e64 s[26:27], v166, v180
	v_cmp_ge_f32_e64 s[28:29], v167, v180
	v_addc_co_u32_e64 v212, s[30:31], v212, 0, s[22:23]
	v_addc_co_u32_e64 v212, s[30:31], v212, 0, s[24:25]
	v_addc_co_u32_e64 v212, s[30:31], v212, 0, s[26:27]
	v_addc_co_u32_e64 v212, s[30:31], v212, 0, s[28:29]
	v_cmp_ge_f32_e64 s[22:23], v168, v180
	v_cmp_ge_f32_e64 s[24:25], v169, v180
	v_cmp_ge_f32_e64 s[26:27], v170, v180
	v_cmp_ge_f32_e64 s[28:29], v171, v180
	v_addc_co_u32_e64 v212, s[30:31], v212, 0, s[22:23]
	v_addc_co_u32_e64 v212, s[30:31], v212, 0, s[24:25]
	v_addc_co_u32_e64 v212, s[30:31], v212, 0, s[26:27]
	v_addc_co_u32_e64 v212, s[30:31], v212, 0, s[28:29]
	v_cmp_ge_f32_e64 s[22:23], v172, v180
	v_cmp_ge_f32_e64 s[24:25], v173, v180
	v_cmp_ge_f32_e64 s[26:27], v174, v180
	v_cmp_ge_f32_e64 s[28:29], v175, v180
	v_addc_co_u32_e64 v212, s[30:31], v212, 0, s[22:23]
	v_addc_co_u32_e64 v212, s[30:31], v212, 0, s[24:25]
	v_addc_co_u32_e64 v212, s[30:31], v212, 0, s[26:27]
	v_addc_co_u32_e64 v212, s[30:31], v212, 0, s[28:29]
	v_cmp_ge_f32_e64 s[22:23], v176, v180
	v_cmp_ge_f32_e64 s[24:25], v177, v180
	v_cmp_ge_f32_e64 s[26:27], v178, v180
	v_cmp_ge_f32_e64 s[28:29], v179, v180
	v_addc_co_u32_e64 v212, s[30:31], v212, 0, s[22:23]
	v_addc_co_u32_e64 v212, s[30:31], v212, 0, s[24:25]
	v_addc_co_u32_e64 v212, s[30:31], v212, 0, s[26:27]
	v_addc_co_u32_e64 v212, s[30:31], v212, 0, s[28:29]
	v_cmp_gt_f32_e64 s[22:23], v181, v180
	v_cmp_gt_f32_e64 s[24:25], v182, v180
	v_cmp_gt_f32_e64 s[26:27], v183, v180
	v_cmp_gt_f32_e64 s[28:29], v184, v180
	v_addc_co_u32_e64 v212, s[30:31], v212, 0, s[22:23]
	v_addc_co_u32_e64 v212, s[30:31], v212, 0, s[24:25]
	v_addc_co_u32_e64 v212, s[30:31], v212, 0, s[26:27]
	v_addc_co_u32_e64 v212, s[30:31], v212, 0, s[28:29]
	v_cmp_gt_f32_e64 s[22:23], v185, v180
	v_cmp_gt_f32_e64 s[24:25], v186, v180
	v_cmp_gt_f32_e64 s[26:27], v187, v180
	v_cmp_gt_f32_e64 s[28:29], v188, v180
	v_addc_co_u32_e64 v212, s[30:31], v212, 0, s[22:23]
	v_addc_co_u32_e64 v212, s[30:31], v212, 0, s[24:25]
	v_addc_co_u32_e64 v212, s[30:31], v212, 0, s[26:27]
	v_addc_co_u32_e64 v212, s[30:31], v212, 0, s[28:29]
	v_cmp_gt_f32_e64 s[22:23], v189, v180
	v_cmp_gt_f32_e64 s[24:25], v190, v180
	v_cmp_gt_f32_e64 s[26:27], v191, v180
	v_cmp_gt_f32_e64 s[28:29], v192, v180
	v_addc_co_u32_e64 v212, s[30:31], v212, 0, s[22:23]
	v_addc_co_u32_e64 v212, s[30:31], v212, 0, s[24:25]
	v_addc_co_u32_e64 v212, s[30:31], v212, 0, s[26:27]
	v_addc_co_u32_e64 v212, s[30:31], v212, 0, s[28:29]
	v_cmp_gt_f32_e64 s[22:23], v193, v180
	v_cmp_gt_f32_e64 s[24:25], v194, v180
	v_cmp_gt_f32_e64 s[26:27], v195, v180
	v_cmp_gt_f32_e64 s[28:29], v196, v180
	v_addc_co_u32_e64 v212, s[30:31], v212, 0, s[22:23]
	v_addc_co_u32_e64 v212, s[30:31], v212, 0, s[24:25]
	v_addc_co_u32_e64 v212, s[30:31], v212, 0, s[26:27]
	v_addc_co_u32_e64 v212, s[30:31], v212, 0, s[28:29]
	v_cmp_gt_f32_e64 s[22:23], v197, v180
	v_cmp_gt_f32_e64 s[24:25], v198, v180
	v_cmp_gt_f32_e64 s[26:27], v199, v180
	v_cmp_gt_f32_e64 s[28:29], v200, v180
	v_addc_co_u32_e64 v212, s[30:31], v212, 0, s[22:23]
	v_addc_co_u32_e64 v212, s[30:31], v212, 0, s[24:25]
	v_addc_co_u32_e64 v212, s[30:31], v212, 0, s[26:27]
	v_addc_co_u32_e64 v212, s[30:31], v212, 0, s[28:29]
	v_cmp_gt_f32_e64 s[22:23], v201, v180
	v_cmp_gt_f32_e64 s[24:25], v202, v180
	v_cmp_gt_f32_e64 s[26:27], v203, v180
	v_cmp_gt_f32_e64 s[28:29], v204, v180
	v_addc_co_u32_e64 v212, s[30:31], v212, 0, s[22:23]
	v_addc_co_u32_e64 v212, s[30:31], v212, 0, s[24:25]
	v_addc_co_u32_e64 v212, s[30:31], v212, 0, s[26:27]
	v_addc_co_u32_e64 v212, s[30:31], v212, 0, s[28:29]
	v_cmp_gt_f32_e64 s[22:23], v205, v180
	v_cmp_gt_f32_e64 s[24:25], v206, v180
	v_cmp_gt_f32_e64 s[26:27], v207, v180
	v_cmp_gt_f32_e64 s[28:29], v208, v180
	v_addc_co_u32_e64 v212, s[30:31], v212, 0, s[22:23]
	v_addc_co_u32_e64 v212, s[30:31], v212, 0, s[24:25]
	v_addc_co_u32_e64 v212, s[30:31], v212, 0, s[26:27]
	v_addc_co_u32_e64 v212, s[30:31], v212, 0, s[28:29]
	v_cmp_gt_f32_e64 s[22:23], v209, v180
	s_nop 0
	s_nop 0
	v_addc_co_u32_e64 v212, s[30:31], v212, 0, s[22:23]
	v_cmp_gt_u32_e32 vcc, 16, v212
	s_and_saveexec_b64 s[40:41], vcc
	v_lshl_add_u32 v214, v212, 2, v213
	v_mov_b32_e32 v212, 20
	ds_write_b32 v214, v180
	ds_write_b32 v214, v212 offset:4096
	s_mov_b64 exec, -1
	s_branch .Lrk0_c28
; __device__ __forceinline__ void ph_peer_select(const Params& P, int layer, const h16* Q, int nrows, char* smem) {
;     ...
;     for (int i = tid; i < 64 * 50; i += NTHR) {
;       const int tok = i / 50, c = i % 50;
;       const float v = cd[tok * 52 + c];
;       int rank = 0;
;       for (int j = 0; j < 50; ++j) { const float o = cd[tok * 52 + j]; rank += (o > v || (o == v && j < c)) ? 1 : 0; }
;       if (rank < TOPK) { tv[tok * 16 + rank] = v; tp[tok * 16 + rank] = c; }
;     }
.Lrk0_c21:
	v_mov_b32_e32 v212, 0
	v_cmp_ge_f32_e64 s[22:23], v160, v181
	v_cmp_ge_f32_e64 s[24:25], v161, v181
	v_cmp_ge_f32_e64 s[26:27], v162, v181
	v_cmp_ge_f32_e64 s[28:29], v163, v181
	v_addc_co_u32_e64 v212, s[30:31], v212, 0, s[22:23]
	v_addc_co_u32_e64 v212, s[30:31], v212, 0, s[24:25]
	v_addc_co_u32_e64 v212, s[30:31], v212, 0, s[26:27]
	v_addc_co_u32_e64 v212, s[30:31], v212, 0, s[28:29]
	v_cmp_ge_f32_e64 s[22:23], v164, v181
	v_cmp_ge_f32_e64 s[24:25], v165, v181
	v_cmp_ge_f32_e64 s[26:27], v166, v181
	v_cmp_ge_f32_e64 s[28:29], v167, v181
	v_addc_co_u32_e64 v212, s[30:31], v212, 0, s[22:23]
	v_addc_co_u32_e64 v212, s[30:31], v212, 0, s[24:25]
	v_addc_co_u32_e64 v212, s[30:31], v212, 0, s[26:27]
	v_addc_co_u32_e64 v212, s[30:31], v212, 0, s[28:29]
	v_cmp_ge_f32_e64 s[22:23], v168, v181
	v_cmp_ge_f32_e64 s[24:25], v169, v181
	v_cmp_ge_f32_e64 s[26:27], v170, v181
	v_cmp_ge_f32_e64 s[28:29], v171, v181
	v_addc_co_u32_e64 v212, s[30:31], v212, 0, s[22:23]
	v_addc_co_u32_e64 v212, s[30:31], v212, 0, s[24:25]
	v_addc_co_u32_e64 v212, s[30:31], v212, 0, s[26:27]
	v_addc_co_u32_e64 v212, s[30:31], v212, 0, s[28:29]
	v_cmp_ge_f32_e64 s[22:23], v172, v181
	v_cmp_ge_f32_e64 s[24:25], v173, v181
	v_cmp_ge_f32_e64 s[26:27], v174, v181
	v_cmp_ge_f32_e64 s[28:29], v175, v181
	v_addc_co_u32_e64 v212, s[30:31], v212, 0, s[22:23]
	v_addc_co_u32_e64 v212, s[30:31], v212, 0, s[24:25]
	v_addc_co_u32_e64 v212, s[30:31], v212, 0, s[26:27]
	v_addc_co_u32_e64 v212, s[30:31], v212, 0, s[28:29]
	v_cmp_ge_f32_e64 s[22:23], v176, v181
	v_cmp_ge_f32_e64 s[24:25], v177, v181
	v_cmp_ge_f32_e64 s[26:27], v178, v181
	v_cmp_ge_f32_e64 s[28:29], v179, v181
	v_addc_co_u32_e64 v212, s[30:31], v212, 0, s[22:23]
	v_addc_co_u32_e64 v212, s[30:31], v212, 0, s[24:25]
	v_addc_co_u32_e64 v212, s[30:31], v212, 0, s[26:27]
	v_addc_co_u32_e64 v212, s[30:31], v212, 0, s[28:29]
	v_cmp_ge_f32_e64 s[22:23], v180, v181
	v_cmp_gt_f32_e64 s[24:25], v182, v181
	v_cmp_gt_f32_e64 s[26:27], v183, v181
	v_cmp_gt_f32_e64 s[28:29], v184, v181
	v_addc_co_u32_e64 v212, s[30:31], v212, 0, s[22:23]
	v_addc_co_u32_e64 v212, s[30:31], v212, 0, s[24:25]
	v_addc_co_u32_e64 v212, s[30:31], v212, 0, s[26:27]
	v_addc_co_u32_e64 v212, s[30:31], v212, 0, s[28:29]
	v_cmp_gt_f32_e64 s[22:23], v185, v181
	v_cmp_gt_f32_e64 s[24:25], v186, v181
	v_cmp_gt_f32_e64 s[26:27], v187, v181
	v_cmp_gt_f32_e64 s[28:29], v188, v181
	v_addc_co_u32_e64 v212, s[30:31], v212, 0, s[22:23]
	v_addc_co_u32_e64 v212, s[30:31], v212, 0, s[24:25]
	v_addc_co_u32_e64 v212, s[30:31], v212, 0, s[26:27]
	v_addc_co_u32_e64 v212, s[30:31], v212, 0, s[28:29]
	v_cmp_gt_f32_e64 s[22:23], v189, v181
	v_cmp_gt_f32_e64 s[24:25], v190, v181
	v_cmp_gt_f32_e64 s[26:27], v191, v181
	v_cmp_gt_f32_e64 s[28:29], v192, v181
	v_addc_co_u32_e64 v212, s[30:31], v212, 0, s[22:23]
	v_addc_co_u32_e64 v212, s[30:31], v212, 0, s[24:25]
	v_addc_co_u32_e64 v212, s[30:31], v212, 0, s[26:27]
	v_addc_co_u32_e64 v212, s[30:31], v212, 0, s[28:29]
	v_cmp_gt_f32_e64 s[22:23], v193, v181
	v_cmp_gt_f32_e64 s[24:25], v194, v181
	v_cmp_gt_f32_e64 s[26:27], v195, v181
	v_cmp_gt_f32_e64 s[28:29], v196, v181
	v_addc_co_u32_e64 v212, s[30:31], v212, 0, s[22:23]
	v_addc_co_u32_e64 v212, s[30:31], v212, 0, s[24:25]
	v_addc_co_u32_e64 v212, s[30:31], v212, 0, s[26:27]
	v_addc_co_u32_e64 v212, s[30:31], v212, 0, s[28:29]
	v_cmp_gt_f32_e64 s[22:23], v197, v181
	v_cmp_gt_f32_e64 s[24:25], v198, v181
	v_cmp_gt_f32_e64 s[26:27], v199, v181
	v_cmp_gt_f32_e64 s[28:29], v200, v181
	v_addc_co_u32_e64 v212, s[30:31], v212, 0, s[22:23]
	v_addc_co_u32_e64 v212, s[30:31], v212, 0, s[24:25]
	v_addc_co_u32_e64 v212, s[30:31], v212, 0, s[26:27]
	v_addc_co_u32_e64 v212, s[30:31], v212, 0, s[28:29]
	v_cmp_gt_f32_e64 s[22:23], v201, v181
	v_cmp_gt_f32_e64 s[24:25], v202, v181
	v_cmp_gt_f32_e64 s[26:27], v203, v181
	v_cmp_gt_f32_e64 s[28:29], v204, v181
	v_addc_co_u32_e64 v212, s[30:31], v212, 0, s[22:23]
	v_addc_co_u32_e64 v212, s[30:31], v212, 0, s[24:25]
	v_addc_co_u32_e64 v212, s[30:31], v212, 0, s[26:27]
	v_addc_co_u32_e64 v212, s[30:31], v212, 0, s[28:29]
	v_cmp_gt_f32_e64 s[22:23], v205, v181
	v_cmp_gt_f32_e64 s[24:25], v206, v181
	v_cmp_gt_f32_e64 s[26:27], v207, v181
	v_cmp_gt_f32_e64 s[28:29], v208, v181
	v_addc_co_u32_e64 v212, s[30:31], v212, 0, s[22:23]
	v_addc_co_u32_e64 v212, s[30:31], v212, 0, s[24:25]
	v_addc_co_u32_e64 v212, s[30:31], v212, 0, s[26:27]
	v_addc_co_u32_e64 v212, s[30:31], v212, 0, s[28:29]
	v_cmp_gt_f32_e64 s[22:23], v209, v181
	s_nop 0
	s_nop 0
	v_addc_co_u32_e64 v212, s[30:31], v212, 0, s[22:23]
	v_cmp_gt_u32_e32 vcc, 16, v212
	s_and_saveexec_b64 s[40:41], vcc
	v_lshl_add_u32 v214, v212, 2, v213
	v_mov_b32_e32 v212, 21
	ds_write_b32 v214, v181
	ds_write_b32 v214, v212 offset:4096
	s_mov_b64 exec, -1
	s_branch .Lrk0_c29
; __device__ __forceinline__ void ph_peer_select(const Params& P, int layer, const h16* Q, int nrows, char* smem) {
;     ...
;     for (int i = tid; i < 64 * 50; i += NTHR) {
;       const int tok = i / 50, c = i % 50;
;       const float v = cd[tok * 52 + c];
;       int rank = 0;
;       for (int j = 0; j < 50; ++j) { const float o = cd[tok * 52 + j]; rank += (o > v || (o == v && j < c)) ? 1 : 0; }
;       if (rank < TOPK) { tv[tok * 16 + rank] = v; tp[tok * 16 + rank] = c; }
;     }
.Lrk0_c22:
	v_mov_b32_e32 v212, 0
	v_cmp_ge_f32_e64 s[22:23], v160, v182
	v_cmp_ge_f32_e64 s[24:25], v161, v182
	v_cmp_ge_f32_e64 s[26:27], v162, v182
	v_cmp_ge_f32_e64 s[28:29], v163, v182
	v_addc_co_u32_e64 v212, s[30:31], v212, 0, s[22:23]
	v_addc_co_u32_e64 v212, s[30:31], v212, 0, s[24:25]
	v_addc_co_u32_e64 v212, s[30:31], v212, 0, s[26:27]
	v_addc_co_u32_e64 v212, s[30:31], v212, 0, s[28:29]
	v_cmp_ge_f32_e64 s[22:23], v164, v182
	v_cmp_ge_f32_e64 s[24:25], v165, v182
	v_cmp_ge_f32_e64 s[26:27], v166, v182
	v_cmp_ge_f32_e64 s[28:29], v167, v182
	v_addc_co_u32_e64 v212, s[30:31], v212, 0, s[22:23]
	v_addc_co_u32_e64 v212, s[30:31], v212, 0, s[24:25]
	v_addc_co_u32_e64 v212, s[30:31], v212, 0, s[26:27]
	v_addc_co_u32_e64 v212, s[30:31], v212, 0, s[28:29]
	v_cmp_ge_f32_e64 s[22:23], v168, v182
	v_cmp_ge_f32_e64 s[24:25], v169, v182
	v_cmp_ge_f32_e64 s[26:27], v170, v182
	v_cmp_ge_f32_e64 s[28:29], v171, v182
	v_addc_co_u32_e64 v212, s[30:31], v212, 0, s[22:23]
	v_addc_co_u32_e64 v212, s[30:31], v212, 0, s[24:25]
	v_addc_co_u32_e64 v212, s[30:31], v212, 0, s[26:27]
	v_addc_co_u32_e64 v212, s[30:31], v212, 0, s[28:29]
	v_cmp_ge_f32_e64 s[22:23], v172, v182
	v_cmp_ge_f32_e64 s[24:25], v173, v182
	v_cmp_ge_f32_e64 s[26:27], v174, v182
	v_cmp_ge_f32_e64 s[28:29], v175, v182
	v_addc_co_u32_e64 v212, s[30:31], v212, 0, s[22:23]
	v_addc_co_u32_e64 v212, s[30:31], v212, 0, s[24:25]
	v_addc_co_u32_e64 v212, s[30:31], v212, 0, s[26:27]
	v_addc_co_u32_e64 v212, s[30:31], v212, 0, s[28:29]
	v_cmp_ge_f32_e64 s[22:23], v176, v182
	v_cmp_ge_f32_e64 s[24:25], v177, v182
	v_cmp_ge_f32_e64 s[26:27], v178, v182
	v_cmp_ge_f32_e64 s[28:29], v179, v182
	v_addc_co_u32_e64 v212, s[30:31], v212, 0, s[22:23]
	v_addc_co_u32_e64 v212, s[30:31], v212, 0, s[24:25]
	v_addc_co_u32_e64 v212, s[30:31], v212, 0, s[26:27]
	v_addc_co_u32_e64 v212, s[30:31], v212, 0, s[28:29]
	v_cmp_ge_f32_e64 s[22:23], v180, v182
	v_cmp_ge_f32_e64 s[24:25], v181, v182
	v_cmp_gt_f32_e64 s[26:27], v183, v182
	v_cmp_gt_f32_e64 s[28:29], v184, v182
	v_addc_co_u32_e64 v212, s[30:31], v212, 0, s[22:23]
	v_addc_co_u32_e64 v212, s[30:31], v212, 0, s[24:25]
	v_addc_co_u32_e64 v212, s[30:31], v212, 0, s[26:27]
	v_addc_co_u32_e64 v212, s[30:31], v212, 0, s[28:29]
	v_cmp_gt_f32_e64 s[22:23], v185, v182
	v_cmp_gt_f32_e64 s[24:25], v186, v182
	v_cmp_gt_f32_e64 s[26:27], v187, v182
	v_cmp_gt_f32_e64 s[28:29], v188, v182
	v_addc_co_u32_e64 v212, s[30:31], v212, 0, s[22:23]
	v_addc_co_u32_e64 v212, s[30:31], v212, 0, s[24:25]
	v_addc_co_u32_e64 v212, s[30:31], v212, 0, s[26:27]
	v_addc_co_u32_e64 v212, s[30:31], v212, 0, s[28:29]
	v_cmp_gt_f32_e64 s[22:23], v189, v182
	v_cmp_gt_f32_e64 s[24:25], v190, v182
	v_cmp_gt_f32_e64 s[26:27], v191, v182
	v_cmp_gt_f32_e64 s[28:29], v192, v182
	v_addc_co_u32_e64 v212, s[30:31], v212, 0, s[22:23]
	v_addc_co_u32_e64 v212, s[30:31], v212, 0, s[24:25]
	v_addc_co_u32_e64 v212, s[30:31], v212, 0, s[26:27]
	v_addc_co_u32_e64 v212, s[30:31], v212, 0, s[28:29]
	v_cmp_gt_f32_e64 s[22:23], v193, v182
	v_cmp_gt_f32_e64 s[24:25], v194, v182
	v_cmp_gt_f32_e64 s[26:27], v195, v182
	v_cmp_gt_f32_e64 s[28:29], v196, v182
	v_addc_co_u32_e64 v212, s[30:31], v212, 0, s[22:23]
	v_addc_co_u32_e64 v212, s[30:31], v212, 0, s[24:25]
	v_addc_co_u32_e64 v212, s[30:31], v212, 0, s[26:27]
	v_addc_co_u32_e64 v212, s[30:31], v212, 0, s[28:29]
	v_cmp_gt_f32_e64 s[22:23], v197, v182
	v_cmp_gt_f32_e64 s[24:25], v198, v182
	v_cmp_gt_f32_e64 s[26:27], v199, v182
	v_cmp_gt_f32_e64 s[28:29], v200, v182
	v_addc_co_u32_e64 v212, s[30:31], v212, 0, s[22:23]
	v_addc_co_u32_e64 v212, s[30:31], v212, 0, s[24:25]
	v_addc_co_u32_e64 v212, s[30:31], v212, 0, s[26:27]
	v_addc_co_u32_e64 v212, s[30:31], v212, 0, s[28:29]
	v_cmp_gt_f32_e64 s[22:23], v201, v182
	v_cmp_gt_f32_e64 s[24:25], v202, v182
	v_cmp_gt_f32_e64 s[26:27], v203, v182
	v_cmp_gt_f32_e64 s[28:29], v204, v182
	v_addc_co_u32_e64 v212, s[30:31], v212, 0, s[22:23]
	v_addc_co_u32_e64 v212, s[30:31], v212, 0, s[24:25]
	v_addc_co_u32_e64 v212, s[30:31], v212, 0, s[26:27]
	v_addc_co_u32_e64 v212, s[30:31], v212, 0, s[28:29]
	v_cmp_gt_f32_e64 s[22:23], v205, v182
	v_cmp_gt_f32_e64 s[24:25], v206, v182
	v_cmp_gt_f32_e64 s[26:27], v207, v182
	v_cmp_gt_f32_e64 s[28:29], v208, v182
	v_addc_co_u32_e64 v212, s[30:31], v212, 0, s[22:23]
	v_addc_co_u32_e64 v212, s[30:31], v212, 0, s[24:25]
	v_addc_co_u32_e64 v212, s[30:31], v212, 0, s[26:27]
	v_addc_co_u32_e64 v212, s[30:31], v212, 0, s[28:29]
	v_cmp_gt_f32_e64 s[22:23], v209, v182
	s_nop 0
	s_nop 0
	v_addc_co_u32_e64 v212, s[30:31], v212, 0, s[22:23]
	v_cmp_gt_u32_e32 vcc, 16, v212
	s_and_saveexec_b64 s[40:41], vcc
	v_lshl_add_u32 v214, v212, 2, v213
	v_mov_b32_e32 v212, 22
	ds_write_b32 v214, v182
	ds_write_b32 v214, v212 offset:4096
	s_mov_b64 exec, -1
	s_branch .Lrk0_c30
; __device__ __forceinline__ void ph_peer_select(const Params& P, int layer, const h16* Q, int nrows, char* smem) {
;     ...
;     for (int i = tid; i < 64 * 50; i += NTHR) {
;       const int tok = i / 50, c = i % 50;
;       const float v = cd[tok * 52 + c];
;       int rank = 0;
;       for (int j = 0; j < 50; ++j) { const float o = cd[tok * 52 + j]; rank += (o > v || (o == v && j < c)) ? 1 : 0; }
;       if (rank < TOPK) { tv[tok * 16 + rank] = v; tp[tok * 16 + rank] = c; }
;     }
.Lrk0_c23:
	v_mov_b32_e32 v212, 0
	v_cmp_ge_f32_e64 s[22:23], v160, v183
	v_cmp_ge_f32_e64 s[24:25], v161, v183
	v_cmp_ge_f32_e64 s[26:27], v162, v183
	v_cmp_ge_f32_e64 s[28:29], v163, v183
	v_addc_co_u32_e64 v212, s[30:31], v212, 0, s[22:23]
	v_addc_co_u32_e64 v212, s[30:31], v212, 0, s[24:25]
	v_addc_co_u32_e64 v212, s[30:31], v212, 0, s[26:27]
	v_addc_co_u32_e64 v212, s[30:31], v212, 0, s[28:29]
	v_cmp_ge_f32_e64 s[22:23], v164, v183
	v_cmp_ge_f32_e64 s[24:25], v165, v183
	v_cmp_ge_f32_e64 s[26:27], v166, v183
	v_cmp_ge_f32_e64 s[28:29], v167, v183
	v_addc_co_u32_e64 v212, s[30:31], v212, 0, s[22:23]
	v_addc_co_u32_e64 v212, s[30:31], v212, 0, s[24:25]
	v_addc_co_u32_e64 v212, s[30:31], v212, 0, s[26:27]
	v_addc_co_u32_e64 v212, s[30:31], v212, 0, s[28:29]
	v_cmp_ge_f32_e64 s[22:23], v168, v183
	v_cmp_ge_f32_e64 s[24:25], v169, v183
	v_cmp_ge_f32_e64 s[26:27], v170, v183
	v_cmp_ge_f32_e64 s[28:29], v171, v183
	v_addc_co_u32_e64 v212, s[30:31], v212, 0, s[22:23]
	v_addc_co_u32_e64 v212, s[30:31], v212, 0, s[24:25]
	v_addc_co_u32_e64 v212, s[30:31], v212, 0, s[26:27]
	v_addc_co_u32_e64 v212, s[30:31], v212, 0, s[28:29]
	v_cmp_ge_f32_e64 s[22:23], v172, v183
	v_cmp_ge_f32_e64 s[24:25], v173, v183
	v_cmp_ge_f32_e64 s[26:27], v174, v183
	v_cmp_ge_f32_e64 s[28:29], v175, v183
	v_addc_co_u32_e64 v212, s[30:31], v212, 0, s[22:23]
	v_addc_co_u32_e64 v212, s[30:31], v212, 0, s[24:25]
	v_addc_co_u32_e64 v212, s[30:31], v212, 0, s[26:27]
	v_addc_co_u32_e64 v212, s[30:31], v212, 0, s[28:29]
	v_cmp_ge_f32_e64 s[22:23], v176, v183
	v_cmp_ge_f32_e64 s[24:25], v177, v183
	v_cmp_ge_f32_e64 s[26:27], v178, v183
	v_cmp_ge_f32_e64 s[28:29], v179, v183
	v_addc_co_u32_e64 v212, s[30:31], v212, 0, s[22:23]
	v_addc_co_u32_e64 v212, s[30:31], v212, 0, s[24:25]
	v_addc_co_u32_e64 v212, s[30:31], v212, 0, s[26:27]
	v_addc_co_u32_e64 v212, s[30:31], v212, 0, s[28:29]
	v_cmp_ge_f32_e64 s[22:23], v180, v183
	v_cmp_ge_f32_e64 s[24:25], v181, v183
	v_cmp_ge_f32_e64 s[26:27], v182, v183
	v_cmp_gt_f32_e64 s[28:29], v184, v183
	v_addc_co_u32_e64 v212, s[30:31], v212, 0, s[22:23]
	v_addc_co_u32_e64 v212, s[30:31], v212, 0, s[24:25]
	v_addc_co_u32_e64 v212, s[30:31], v212, 0, s[26:27]
	v_addc_co_u32_e64 v212, s[30:31], v212, 0, s[28:29]
	v_cmp_gt_f32_e64 s[22:23], v185, v183
	v_cmp_gt_f32_e64 s[24:25], v186, v183
	v_cmp_gt_f32_e64 s[26:27], v187, v183
	v_cmp_gt_f32_e64 s[28:29], v188, v183
	v_addc_co_u32_e64 v212, s[30:31], v212, 0, s[22:23]
	v_addc_co_u32_e64 v212, s[30:31], v212, 0, s[24:25]
	v_addc_co_u32_e64 v212, s[30:31], v212, 0, s[26:27]
	v_addc_co_u32_e64 v212, s[30:31], v212, 0, s[28:29]
	v_cmp_gt_f32_e64 s[22:23], v189, v183
	v_cmp_gt_f32_e64 s[24:25], v190, v183
	v_cmp_gt_f32_e64 s[26:27], v191, v183
	v_cmp_gt_f32_e64 s[28:29], v192, v183
	v_addc_co_u32_e64 v212, s[30:31], v212, 0, s[22:23]
	v_addc_co_u32_e64 v212, s[30:31], v212, 0, s[24:25]
	v_addc_co_u32_e64 v212, s[30:31], v212, 0, s[26:27]
	v_addc_co_u32_e64 v212, s[30:31], v212, 0, s[28:29]
	v_cmp_gt_f32_e64 s[22:23], v193, v183
	v_cmp_gt_f32_e64 s[24:25], v194, v183
	v_cmp_gt_f32_e64 s[26:27], v195, v183
	v_cmp_gt_f32_e64 s[28:29], v196, v183
	v_addc_co_u32_e64 v212, s[30:31], v212, 0, s[22:23]
	v_addc_co_u32_e64 v212, s[30:31], v212, 0, s[24:25]
	v_addc_co_u32_e64 v212, s[30:31], v212, 0, s[26:27]
	v_addc_co_u32_e64 v212, s[30:31], v212, 0, s[28:29]
	v_cmp_gt_f32_e64 s[22:23], v197, v183
	v_cmp_gt_f32_e64 s[24:25], v198, v183
	v_cmp_gt_f32_e64 s[26:27], v199, v183
	v_cmp_gt_f32_e64 s[28:29], v200, v183
	v_addc_co_u32_e64 v212, s[30:31], v212, 0, s[22:23]
	v_addc_co_u32_e64 v212, s[30:31], v212, 0, s[24:25]
	v_addc_co_u32_e64 v212, s[30:31], v212, 0, s[26:27]
	v_addc_co_u32_e64 v212, s[30:31], v212, 0, s[28:29]
	v_cmp_gt_f32_e64 s[22:23], v201, v183
	v_cmp_gt_f32_e64 s[24:25], v202, v183
	v_cmp_gt_f32_e64 s[26:27], v203, v183
	v_cmp_gt_f32_e64 s[28:29], v204, v183
	v_addc_co_u32_e64 v212, s[30:31], v212, 0, s[22:23]
	v_addc_co_u32_e64 v212, s[30:31], v212, 0, s[24:25]
	v_addc_co_u32_e64 v212, s[30:31], v212, 0, s[26:27]
	v_addc_co_u32_e64 v212, s[30:31], v212, 0, s[28:29]
	v_cmp_gt_f32_e64 s[22:23], v205, v183
	v_cmp_gt_f32_e64 s[24:25], v206, v183
	v_cmp_gt_f32_e64 s[26:27], v207, v183
	v_cmp_gt_f32_e64 s[28:29], v208, v183
	v_addc_co_u32_e64 v212, s[30:31], v212, 0, s[22:23]
	v_addc_co_u32_e64 v212, s[30:31], v212, 0, s[24:25]
	v_addc_co_u32_e64 v212, s[30:31], v212, 0, s[26:27]
	v_addc_co_u32_e64 v212, s[30:31], v212, 0, s[28:29]
	v_cmp_gt_f32_e64 s[22:23], v209, v183
	s_nop 0
	s_nop 0
	v_addc_co_u32_e64 v212, s[30:31], v212, 0, s[22:23]
	v_cmp_gt_u32_e32 vcc, 16, v212
	s_and_saveexec_b64 s[40:41], vcc
	v_lshl_add_u32 v214, v212, 2, v213
	v_mov_b32_e32 v212, 23
	ds_write_b32 v214, v183
	ds_write_b32 v214, v212 offset:4096
	s_mov_b64 exec, -1
	s_branch .Lrk0_c31
; __device__ __forceinline__ void ph_peer_select(const Params& P, int layer, const h16* Q, int nrows, char* smem) {
;     ...
;     for (int i = tid; i < 64 * 50; i += NTHR) {
;       const int tok = i / 50, c = i % 50;
;       const float v = cd[tok * 52 + c];
;       int rank = 0;
;       for (int j = 0; j < 50; ++j) { const float o = cd[tok * 52 + j]; rank += (o > v || (o == v && j < c)) ? 1 : 0; }
;       if (rank < TOPK) { tv[tok * 16 + rank] = v; tp[tok * 16 + rank] = c; }
;     }
.Lrk0_c24:
	v_mov_b32_e32 v212, 0
	v_cmp_ge_f32_e64 s[22:23], v160, v184
	v_cmp_ge_f32_e64 s[24:25], v161, v184
	v_cmp_ge_f32_e64 s[26:27], v162, v184
	v_cmp_ge_f32_e64 s[28:29], v163, v184
	v_addc_co_u32_e64 v212, s[30:31], v212, 0, s[22:23]
	v_addc_co_u32_e64 v212, s[30:31], v212, 0, s[24:25]
	v_addc_co_u32_e64 v212, s[30:31], v212, 0, s[26:27]
	v_addc_co_u32_e64 v212, s[30:31], v212, 0, s[28:29]
	v_cmp_ge_f32_e64 s[22:23], v164, v184
	v_cmp_ge_f32_e64 s[24:25], v165, v184
	v_cmp_ge_f32_e64 s[26:27], v166, v184
	v_cmp_ge_f32_e64 s[28:29], v167, v184
	v_addc_co_u32_e64 v212, s[30:31], v212, 0, s[22:23]
	v_addc_co_u32_e64 v212, s[30:31], v212, 0, s[24:25]
	v_addc_co_u32_e64 v212, s[30:31], v212, 0, s[26:27]
	v_addc_co_u32_e64 v212, s[30:31], v212, 0, s[28:29]
	v_cmp_ge_f32_e64 s[22:23], v168, v184
	v_cmp_ge_f32_e64 s[24:25], v169, v184
	v_cmp_ge_f32_e64 s[26:27], v170, v184
	v_cmp_ge_f32_e64 s[28:29], v171, v184
	v_addc_co_u32_e64 v212, s[30:31], v212, 0, s[22:23]
	v_addc_co_u32_e64 v212, s[30:31], v212, 0, s[24:25]
	v_addc_co_u32_e64 v212, s[30:31], v212, 0, s[26:27]
	v_addc_co_u32_e64 v212, s[30:31], v212, 0, s[28:29]
	v_cmp_ge_f32_e64 s[22:23], v172, v184
	v_cmp_ge_f32_e64 s[24:25], v173, v184
	v_cmp_ge_f32_e64 s[26:27], v174, v184
	v_cmp_ge_f32_e64 s[28:29], v175, v184
	v_addc_co_u32_e64 v212, s[30:31], v212, 0, s[22:23]
	v_addc_co_u32_e64 v212, s[30:31], v212, 0, s[24:25]
	v_addc_co_u32_e64 v212, s[30:31], v212, 0, s[26:27]
	v_addc_co_u32_e64 v212, s[30:31], v212, 0, s[28:29]
	v_cmp_ge_f32_e64 s[22:23], v176, v184
	v_cmp_ge_f32_e64 s[24:25], v177, v184
	v_cmp_ge_f32_e64 s[26:27], v178, v184
	v_cmp_ge_f32_e64 s[28:29], v179, v184
	v_addc_co_u32_e64 v212, s[30:31], v212, 0, s[22:23]
	v_addc_co_u32_e64 v212, s[30:31], v212, 0, s[24:25]
	v_addc_co_u32_e64 v212, s[30:31], v212, 0, s[26:27]
	v_addc_co_u32_e64 v212, s[30:31], v212, 0, s[28:29]
	v_cmp_ge_f32_e64 s[22:23], v180, v184
	v_cmp_ge_f32_e64 s[24:25], v181, v184
	v_cmp_ge_f32_e64 s[26:27], v182, v184
	v_cmp_ge_f32_e64 s[28:29], v183, v184
	v_addc_co_u32_e64 v212, s[30:31], v212, 0, s[22:23]
	v_addc_co_u32_e64 v212, s[30:31], v212, 0, s[24:25]
	v_addc_co_u32_e64 v212, s[30:31], v212, 0, s[26:27]
	v_addc_co_u32_e64 v212, s[30:31], v212, 0, s[28:29]
	v_cmp_gt_f32_e64 s[22:23], v185, v184
	v_cmp_gt_f32_e64 s[24:25], v186, v184
	v_cmp_gt_f32_e64 s[26:27], v187, v184
	v_cmp_gt_f32_e64 s[28:29], v188, v184
	v_addc_co_u32_e64 v212, s[30:31], v212, 0, s[22:23]
	v_addc_co_u32_e64 v212, s[30:31], v212, 0, s[24:25]
	v_addc_co_u32_e64 v212, s[30:31], v212, 0, s[26:27]
	v_addc_co_u32_e64 v212, s[30:31], v212, 0, s[28:29]
	v_cmp_gt_f32_e64 s[22:23], v189, v184
	v_cmp_gt_f32_e64 s[24:25], v190, v184
	v_cmp_gt_f32_e64 s[26:27], v191, v184
	v_cmp_gt_f32_e64 s[28:29], v192, v184
	v_addc_co_u32_e64 v212, s[30:31], v212, 0, s[22:23]
	v_addc_co_u32_e64 v212, s[30:31], v212, 0, s[24:25]
	v_addc_co_u32_e64 v212, s[30:31], v212, 0, s[26:27]
	v_addc_co_u32_e64 v212, s[30:31], v212, 0, s[28:29]
	v_cmp_gt_f32_e64 s[22:23], v193, v184
	v_cmp_gt_f32_e64 s[24:25], v194, v184
	v_cmp_gt_f32_e64 s[26:27], v195, v184
	v_cmp_gt_f32_e64 s[28:29], v196, v184
	v_addc_co_u32_e64 v212, s[30:31], v212, 0, s[22:23]
	v_addc_co_u32_e64 v212, s[30:31], v212, 0, s[24:25]
	v_addc_co_u32_e64 v212, s[30:31], v212, 0, s[26:27]
	v_addc_co_u32_e64 v212, s[30:31], v212, 0, s[28:29]
	v_cmp_gt_f32_e64 s[22:23], v197, v184
	v_cmp_gt_f32_e64 s[24:25], v198, v184
	v_cmp_gt_f32_e64 s[26:27], v199, v184
	v_cmp_gt_f32_e64 s[28:29], v200, v184
	v_addc_co_u32_e64 v212, s[30:31], v212, 0, s[22:23]
	v_addc_co_u32_e64 v212, s[30:31], v212, 0, s[24:25]
	v_addc_co_u32_e64 v212, s[30:31], v212, 0, s[26:27]
	v_addc_co_u32_e64 v212, s[30:31], v212, 0, s[28:29]
	v_cmp_gt_f32_e64 s[22:23], v201, v184
	v_cmp_gt_f32_e64 s[24:25], v202, v184
	v_cmp_gt_f32_e64 s[26:27], v203, v184
	v_cmp_gt_f32_e64 s[28:29], v204, v184
	v_addc_co_u32_e64 v212, s[30:31], v212, 0, s[22:23]
	v_addc_co_u32_e64 v212, s[30:31], v212, 0, s[24:25]
	v_addc_co_u32_e64 v212, s[30:31], v212, 0, s[26:27]
	v_addc_co_u32_e64 v212, s[30:31], v212, 0, s[28:29]
	v_cmp_gt_f32_e64 s[22:23], v205, v184
	v_cmp_gt_f32_e64 s[24:25], v206, v184
	v_cmp_gt_f32_e64 s[26:27], v207, v184
	v_cmp_gt_f32_e64 s[28:29], v208, v184
	v_addc_co_u32_e64 v212, s[30:31], v212, 0, s[22:23]
	v_addc_co_u32_e64 v212, s[30:31], v212, 0, s[24:25]
	v_addc_co_u32_e64 v212, s[30:31], v212, 0, s[26:27]
	v_addc_co_u32_e64 v212, s[30:31], v212, 0, s[28:29]
	v_cmp_gt_f32_e64 s[22:23], v209, v184
	s_nop 0
	s_nop 0
	v_addc_co_u32_e64 v212, s[30:31], v212, 0, s[22:23]
	v_cmp_gt_u32_e32 vcc, 16, v212
	s_and_saveexec_b64 s[40:41], vcc
	v_lshl_add_u32 v214, v212, 2, v213
	v_mov_b32_e32 v212, 24
	ds_write_b32 v214, v184
	ds_write_b32 v214, v212 offset:4096
	s_mov_b64 exec, -1
	s_branch .Lrk0_c32
; __device__ __forceinline__ void ph_peer_select(const Params& P, int layer, const h16* Q, int nrows, char* smem) {
;     ...
;     for (int i = tid; i < 64 * 50; i += NTHR) {
;       const int tok = i / 50, c = i % 50;
;       const float v = cd[tok * 52 + c];
;       int rank = 0;
;       for (int j = 0; j < 50; ++j) { const float o = cd[tok * 52 + j]; rank += (o > v || (o == v && j < c)) ? 1 : 0; }
;       if (rank < TOPK) { tv[tok * 16 + rank] = v; tp[tok * 16 + rank] = c; }
;     }
.Lrk0_c25:
	v_mov_b32_e32 v212, 0
	v_cmp_ge_f32_e64 s[22:23], v160, v185
	v_cmp_ge_f32_e64 s[24:25], v161, v185
	v_cmp_ge_f32_e64 s[26:27], v162, v185
	v_cmp_ge_f32_e64 s[28:29], v163, v185
	v_addc_co_u32_e64 v212, s[30:31], v212, 0, s[22:23]
	v_addc_co_u32_e64 v212, s[30:31], v212, 0, s[24:25]
	v_addc_co_u32_e64 v212, s[30:31], v212, 0, s[26:27]
	v_addc_co_u32_e64 v212, s[30:31], v212, 0, s[28:29]
	v_cmp_ge_f32_e64 s[22:23], v164, v185
	v_cmp_ge_f32_e64 s[24:25], v165, v185
	v_cmp_ge_f32_e64 s[26:27], v166, v185
	v_cmp_ge_f32_e64 s[28:29], v167, v185
	v_addc_co_u32_e64 v212, s[30:31], v212, 0, s[22:23]
	v_addc_co_u32_e64 v212, s[30:31], v212, 0, s[24:25]
	v_addc_co_u32_e64 v212, s[30:31], v212, 0, s[26:27]
	v_addc_co_u32_e64 v212, s[30:31], v212, 0, s[28:29]
	v_cmp_ge_f32_e64 s[22:23], v168, v185
	v_cmp_ge_f32_e64 s[24:25], v169, v185
	v_cmp_ge_f32_e64 s[26:27], v170, v185
	v_cmp_ge_f32_e64 s[28:29], v171, v185
	v_addc_co_u32_e64 v212, s[30:31], v212, 0, s[22:23]
	v_addc_co_u32_e64 v212, s[30:31], v212, 0, s[24:25]
	v_addc_co_u32_e64 v212, s[30:31], v212, 0, s[26:27]
	v_addc_co_u32_e64 v212, s[30:31], v212, 0, s[28:29]
	v_cmp_ge_f32_e64 s[22:23], v172, v185
	v_cmp_ge_f32_e64 s[24:25], v173, v185
	v_cmp_ge_f32_e64 s[26:27], v174, v185
	v_cmp_ge_f32_e64 s[28:29], v175, v185
	v_addc_co_u32_e64 v212, s[30:31], v212, 0, s[22:23]
	v_addc_co_u32_e64 v212, s[30:31], v212, 0, s[24:25]
	v_addc_co_u32_e64 v212, s[30:31], v212, 0, s[26:27]
	v_addc_co_u32_e64 v212, s[30:31], v212, 0, s[28:29]
	v_cmp_ge_f32_e64 s[22:23], v176, v185
	v_cmp_ge_f32_e64 s[24:25], v177, v185
	v_cmp_ge_f32_e64 s[26:27], v178, v185
	v_cmp_ge_f32_e64 s[28:29], v179, v185
	v_addc_co_u32_e64 v212, s[30:31], v212, 0, s[22:23]
	v_addc_co_u32_e64 v212, s[30:31], v212, 0, s[24:25]
	v_addc_co_u32_e64 v212, s[30:31], v212, 0, s[26:27]
	v_addc_co_u32_e64 v212, s[30:31], v212, 0, s[28:29]
	v_cmp_ge_f32_e64 s[22:23], v180, v185
	v_cmp_ge_f32_e64 s[24:25], v181, v185
	v_cmp_ge_f32_e64 s[26:27], v182, v185
	v_cmp_ge_f32_e64 s[28:29], v183, v185
	v_addc_co_u32_e64 v212, s[30:31], v212, 0, s[22:23]
	v_addc_co_u32_e64 v212, s[30:31], v212, 0, s[24:25]
	v_addc_co_u32_e64 v212, s[30:31], v212, 0, s[26:27]
	v_addc_co_u32_e64 v212, s[30:31], v212, 0, s[28:29]
	v_cmp_ge_f32_e64 s[22:23], v184, v185
	v_cmp_gt_f32_e64 s[24:25], v186, v185
	v_cmp_gt_f32_e64 s[26:27], v187, v185
	v_cmp_gt_f32_e64 s[28:29], v188, v185
	v_addc_co_u32_e64 v212, s[30:31], v212, 0, s[22:23]
	v_addc_co_u32_e64 v212, s[30:31], v212, 0, s[24:25]
	v_addc_co_u32_e64 v212, s[30:31], v212, 0, s[26:27]
	v_addc_co_u32_e64 v212, s[30:31], v212, 0, s[28:29]
	v_cmp_gt_f32_e64 s[22:23], v189, v185
	v_cmp_gt_f32_e64 s[24:25], v190, v185
	v_cmp_gt_f32_e64 s[26:27], v191, v185
	v_cmp_gt_f32_e64 s[28:29], v192, v185
	v_addc_co_u32_e64 v212, s[30:31], v212, 0, s[22:23]
	v_addc_co_u32_e64 v212, s[30:31], v212, 0, s[24:25]
	v_addc_co_u32_e64 v212, s[30:31], v212, 0, s[26:27]
	v_addc_co_u32_e64 v212, s[30:31], v212, 0, s[28:29]
	v_cmp_gt_f32_e64 s[22:23], v193, v185
	v_cmp_gt_f32_e64 s[24:25], v194, v185
	v_cmp_gt_f32_e64 s[26:27], v195, v185
	v_cmp_gt_f32_e64 s[28:29], v196, v185
	v_addc_co_u32_e64 v212, s[30:31], v212, 0, s[22:23]
	v_addc_co_u32_e64 v212, s[30:31], v212, 0, s[24:25]
	v_addc_co_u32_e64 v212, s[30:31], v212, 0, s[26:27]
	v_addc_co_u32_e64 v212, s[30:31], v212, 0, s[28:29]
	v_cmp_gt_f32_e64 s[22:23], v197, v185
	v_cmp_gt_f32_e64 s[24:25], v198, v185
	v_cmp_gt_f32_e64 s[26:27], v199, v185
	v_cmp_gt_f32_e64 s[28:29], v200, v185
	v_addc_co_u32_e64 v212, s[30:31], v212, 0, s[22:23]
	v_addc_co_u32_e64 v212, s[30:31], v212, 0, s[24:25]
	v_addc_co_u32_e64 v212, s[30:31], v212, 0, s[26:27]
	v_addc_co_u32_e64 v212, s[30:31], v212, 0, s[28:29]
	v_cmp_gt_f32_e64 s[22:23], v201, v185
	v_cmp_gt_f32_e64 s[24:25], v202, v185
	v_cmp_gt_f32_e64 s[26:27], v203, v185
	v_cmp_gt_f32_e64 s[28:29], v204, v185
	v_addc_co_u32_e64 v212, s[30:31], v212, 0, s[22:23]
	v_addc_co_u32_e64 v212, s[30:31], v212, 0, s[24:25]
	v_addc_co_u32_e64 v212, s[30:31], v212, 0, s[26:27]
	v_addc_co_u32_e64 v212, s[30:31], v212, 0, s[28:29]
	v_cmp_gt_f32_e64 s[22:23], v205, v185
	v_cmp_gt_f32_e64 s[24:25], v206, v185
	v_cmp_gt_f32_e64 s[26:27], v207, v185
	v_cmp_gt_f32_e64 s[28:29], v208, v185
	v_addc_co_u32_e64 v212, s[30:31], v212, 0, s[22:23]
	v_addc_co_u32_e64 v212, s[30:31], v212, 0, s[24:25]
	v_addc_co_u32_e64 v212, s[30:31], v212, 0, s[26:27]
	v_addc_co_u32_e64 v212, s[30:31], v212, 0, s[28:29]
	v_cmp_gt_f32_e64 s[22:23], v209, v185
	s_nop 0
	s_nop 0
	v_addc_co_u32_e64 v212, s[30:31], v212, 0, s[22:23]
	v_cmp_gt_u32_e32 vcc, 16, v212
	s_and_saveexec_b64 s[40:41], vcc
	v_lshl_add_u32 v214, v212, 2, v213
	v_mov_b32_e32 v212, 25
	ds_write_b32 v214, v185
	ds_write_b32 v214, v212 offset:4096
	s_mov_b64 exec, -1
	s_branch .Lrk0_c33
; __device__ __forceinline__ void ph_peer_select(const Params& P, int layer, const h16* Q, int nrows, char* smem) {
;     ...
;     for (int i = tid; i < 64 * 50; i += NTHR) {
;       const int tok = i / 50, c = i % 50;
;       const float v = cd[tok * 52 + c];
;       int rank = 0;
;       for (int j = 0; j < 50; ++j) { const float o = cd[tok * 52 + j]; rank += (o > v || (o == v && j < c)) ? 1 : 0; }
;       if (rank < TOPK) { tv[tok * 16 + rank] = v; tp[tok * 16 + rank] = c; }
;     }
.Lrk0_c26:
	v_mov_b32_e32 v212, 0
	v_cmp_ge_f32_e64 s[22:23], v160, v186
	v_cmp_ge_f32_e64 s[24:25], v161, v186
	v_cmp_ge_f32_e64 s[26:27], v162, v186
	v_cmp_ge_f32_e64 s[28:29], v163, v186
	v_addc_co_u32_e64 v212, s[30:31], v212, 0, s[22:23]
	v_addc_co_u32_e64 v212, s[30:31], v212, 0, s[24:25]
	v_addc_co_u32_e64 v212, s[30:31], v212, 0, s[26:27]
	v_addc_co_u32_e64 v212, s[30:31], v212, 0, s[28:29]
	v_cmp_ge_f32_e64 s[22:23], v164, v186
	v_cmp_ge_f32_e64 s[24:25], v165, v186
	v_cmp_ge_f32_e64 s[26:27], v166, v186
	v_cmp_ge_f32_e64 s[28:29], v167, v186
	v_addc_co_u32_e64 v212, s[30:31], v212, 0, s[22:23]
	v_addc_co_u32_e64 v212, s[30:31], v212, 0, s[24:25]
	v_addc_co_u32_e64 v212, s[30:31], v212, 0, s[26:27]
	v_addc_co_u32_e64 v212, s[30:31], v212, 0, s[28:29]
	v_cmp_ge_f32_e64 s[22:23], v168, v186
	v_cmp_ge_f32_e64 s[24:25], v169, v186
	v_cmp_ge_f32_e64 s[26:27], v170, v186
	v_cmp_ge_f32_e64 s[28:29], v171, v186
	v_addc_co_u32_e64 v212, s[30:31], v212, 0, s[22:23]
	v_addc_co_u32_e64 v212, s[30:31], v212, 0, s[24:25]
	v_addc_co_u32_e64 v212, s[30:31], v212, 0, s[26:27]
	v_addc_co_u32_e64 v212, s[30:31], v212, 0, s[28:29]
	v_cmp_ge_f32_e64 s[22:23], v172, v186
	v_cmp_ge_f32_e64 s[24:25], v173, v186
	v_cmp_ge_f32_e64 s[26:27], v174, v186
	v_cmp_ge_f32_e64 s[28:29], v175, v186
	v_addc_co_u32_e64 v212, s[30:31], v212, 0, s[22:23]
	v_addc_co_u32_e64 v212, s[30:31], v212, 0, s[24:25]
	v_addc_co_u32_e64 v212, s[30:31], v212, 0, s[26:27]
	v_addc_co_u32_e64 v212, s[30:31], v212, 0, s[28:29]
	v_cmp_ge_f32_e64 s[22:23], v176, v186
	v_cmp_ge_f32_e64 s[24:25], v177, v186
	v_cmp_ge_f32_e64 s[26:27], v178, v186
	v_cmp_ge_f32_e64 s[28:29], v179, v186
	v_addc_co_u32_e64 v212, s[30:31], v212, 0, s[22:23]
	v_addc_co_u32_e64 v212, s[30:31], v212, 0, s[24:25]
	v_addc_co_u32_e64 v212, s[30:31], v212, 0, s[26:27]
	v_addc_co_u32_e64 v212, s[30:31], v212, 0, s[28:29]
	v_cmp_ge_f32_e64 s[22:23], v180, v186
	v_cmp_ge_f32_e64 s[24:25], v181, v186
	v_cmp_ge_f32_e64 s[26:27], v182, v186
	v_cmp_ge_f32_e64 s[28:29], v183, v186
	v_addc_co_u32_e64 v212, s[30:31], v212, 0, s[22:23]
	v_addc_co_u32_e64 v212, s[30:31], v212, 0, s[24:25]
	v_addc_co_u32_e64 v212, s[30:31], v212, 0, s[26:27]
	v_addc_co_u32_e64 v212, s[30:31], v212, 0, s[28:29]
	v_cmp_ge_f32_e64 s[22:23], v184, v186
	v_cmp_ge_f32_e64 s[24:25], v185, v186
	v_cmp_gt_f32_e64 s[26:27], v187, v186
	v_cmp_gt_f32_e64 s[28:29], v188, v186
	v_addc_co_u32_e64 v212, s[30:31], v212, 0, s[22:23]
	v_addc_co_u32_e64 v212, s[30:31], v212, 0, s[24:25]
	v_addc_co_u32_e64 v212, s[30:31], v212, 0, s[26:27]
	v_addc_co_u32_e64 v212, s[30:31], v212, 0, s[28:29]
	v_cmp_gt_f32_e64 s[22:23], v189, v186
	v_cmp_gt_f32_e64 s[24:25], v190, v186
	v_cmp_gt_f32_e64 s[26:27], v191, v186
	v_cmp_gt_f32_e64 s[28:29], v192, v186
	v_addc_co_u32_e64 v212, s[30:31], v212, 0, s[22:23]
	v_addc_co_u32_e64 v212, s[30:31], v212, 0, s[24:25]
	v_addc_co_u32_e64 v212, s[30:31], v212, 0, s[26:27]
	v_addc_co_u32_e64 v212, s[30:31], v212, 0, s[28:29]
	v_cmp_gt_f32_e64 s[22:23], v193, v186
	v_cmp_gt_f32_e64 s[24:25], v194, v186
	v_cmp_gt_f32_e64 s[26:27], v195, v186
	v_cmp_gt_f32_e64 s[28:29], v196, v186
	v_addc_co_u32_e64 v212, s[30:31], v212, 0, s[22:23]
	v_addc_co_u32_e64 v212, s[30:31], v212, 0, s[24:25]
	v_addc_co_u32_e64 v212, s[30:31], v212, 0, s[26:27]
	v_addc_co_u32_e64 v212, s[30:31], v212, 0, s[28:29]
	v_cmp_gt_f32_e64 s[22:23], v197, v186
	v_cmp_gt_f32_e64 s[24:25], v198, v186
	v_cmp_gt_f32_e64 s[26:27], v199, v186
	v_cmp_gt_f32_e64 s[28:29], v200, v186
	v_addc_co_u32_e64 v212, s[30:31], v212, 0, s[22:23]
	v_addc_co_u32_e64 v212, s[30:31], v212, 0, s[24:25]
	v_addc_co_u32_e64 v212, s[30:31], v212, 0, s[26:27]
	v_addc_co_u32_e64 v212, s[30:31], v212, 0, s[28:29]
	v_cmp_gt_f32_e64 s[22:23], v201, v186
	v_cmp_gt_f32_e64 s[24:25], v202, v186
	v_cmp_gt_f32_e64 s[26:27], v203, v186
	v_cmp_gt_f32_e64 s[28:29], v204, v186
	v_addc_co_u32_e64 v212, s[30:31], v212, 0, s[22:23]
	v_addc_co_u32_e64 v212, s[30:31], v212, 0, s[24:25]
	v_addc_co_u32_e64 v212, s[30:31], v212, 0, s[26:27]
	v_addc_co_u32_e64 v212, s[30:31], v212, 0, s[28:29]
	v_cmp_gt_f32_e64 s[22:23], v205, v186
	v_cmp_gt_f32_e64 s[24:25], v206, v186
	v_cmp_gt_f32_e64 s[26:27], v207, v186
	v_cmp_gt_f32_e64 s[28:29], v208, v186
	v_addc_co_u32_e64 v212, s[30:31], v212, 0, s[22:23]
	v_addc_co_u32_e64 v212, s[30:31], v212, 0, s[24:25]
	v_addc_co_u32_e64 v212, s[30:31], v212, 0, s[26:27]
	v_addc_co_u32_e64 v212, s[30:31], v212, 0, s[28:29]
	v_cmp_gt_f32_e64 s[22:23], v209, v186
	s_nop 0
	s_nop 0
	v_addc_co_u32_e64 v212, s[30:31], v212, 0, s[22:23]
	v_cmp_gt_u32_e32 vcc, 16, v212
	s_and_saveexec_b64 s[40:41], vcc
	v_lshl_add_u32 v214, v212, 2, v213
	v_mov_b32_e32 v212, 26
	ds_write_b32 v214, v186
	ds_write_b32 v214, v212 offset:4096
	s_mov_b64 exec, -1
	s_branch .Lrk0_c34
; __device__ __forceinline__ void ph_peer_select(const Params& P, int layer, const h16* Q, int nrows, char* smem) {
;     ...
;     for (int i = tid; i < 64 * 50; i += NTHR) {
;       const int tok = i / 50, c = i % 50;
;       const float v = cd[tok * 52 + c];
;       int rank = 0;
;       for (int j = 0; j < 50; ++j) { const float o = cd[tok * 52 + j]; rank += (o > v || (o == v && j < c)) ? 1 : 0; }
;       if (rank < TOPK) { tv[tok * 16 + rank] = v; tp[tok * 16 + rank] = c; }
;     }
.Lrk0_c27:
	v_mov_b32_e32 v212, 0
	v_cmp_ge_f32_e64 s[22:23], v160, v187
	v_cmp_ge_f32_e64 s[24:25], v161, v187
	v_cmp_ge_f32_e64 s[26:27], v162, v187
	v_cmp_ge_f32_e64 s[28:29], v163, v187
	v_addc_co_u32_e64 v212, s[30:31], v212, 0, s[22:23]
	v_addc_co_u32_e64 v212, s[30:31], v212, 0, s[24:25]
	v_addc_co_u32_e64 v212, s[30:31], v212, 0, s[26:27]
	v_addc_co_u32_e64 v212, s[30:31], v212, 0, s[28:29]
	v_cmp_ge_f32_e64 s[22:23], v164, v187
	v_cmp_ge_f32_e64 s[24:25], v165, v187
	v_cmp_ge_f32_e64 s[26:27], v166, v187
	v_cmp_ge_f32_e64 s[28:29], v167, v187
	v_addc_co_u32_e64 v212, s[30:31], v212, 0, s[22:23]
	v_addc_co_u32_e64 v212, s[30:31], v212, 0, s[24:25]
	v_addc_co_u32_e64 v212, s[30:31], v212, 0, s[26:27]
	v_addc_co_u32_e64 v212, s[30:31], v212, 0, s[28:29]
	v_cmp_ge_f32_e64 s[22:23], v168, v187
	v_cmp_ge_f32_e64 s[24:25], v169, v187
	v_cmp_ge_f32_e64 s[26:27], v170, v187
	v_cmp_ge_f32_e64 s[28:29], v171, v187
	v_addc_co_u32_e64 v212, s[30:31], v212, 0, s[22:23]
	v_addc_co_u32_e64 v212, s[30:31], v212, 0, s[24:25]
	v_addc_co_u32_e64 v212, s[30:31], v212, 0, s[26:27]
	v_addc_co_u32_e64 v212, s[30:31], v212, 0, s[28:29]
	v_cmp_ge_f32_e64 s[22:23], v172, v187
	v_cmp_ge_f32_e64 s[24:25], v173, v187
	v_cmp_ge_f32_e64 s[26:27], v174, v187
	v_cmp_ge_f32_e64 s[28:29], v175, v187
	v_addc_co_u32_e64 v212, s[30:31], v212, 0, s[22:23]
	v_addc_co_u32_e64 v212, s[30:31], v212, 0, s[24:25]
	v_addc_co_u32_e64 v212, s[30:31], v212, 0, s[26:27]
	v_addc_co_u32_e64 v212, s[30:31], v212, 0, s[28:29]
	v_cmp_ge_f32_e64 s[22:23], v176, v187
	v_cmp_ge_f32_e64 s[24:25], v177, v187
	v_cmp_ge_f32_e64 s[26:27], v178, v187
	v_cmp_ge_f32_e64 s[28:29], v179, v187
	v_addc_co_u32_e64 v212, s[30:31], v212, 0, s[22:23]
	v_addc_co_u32_e64 v212, s[30:31], v212, 0, s[24:25]
	v_addc_co_u32_e64 v212, s[30:31], v212, 0, s[26:27]
	v_addc_co_u32_e64 v212, s[30:31], v212, 0, s[28:29]
	v_cmp_ge_f32_e64 s[22:23], v180, v187
	v_cmp_ge_f32_e64 s[24:25], v181, v187
	v_cmp_ge_f32_e64 s[26:27], v182, v187
	v_cmp_ge_f32_e64 s[28:29], v183, v187
	v_addc_co_u32_e64 v212, s[30:31], v212, 0, s[22:23]
	v_addc_co_u32_e64 v212, s[30:31], v212, 0, s[24:25]
	v_addc_co_u32_e64 v212, s[30:31], v212, 0, s[26:27]
	v_addc_co_u32_e64 v212, s[30:31], v212, 0, s[28:29]
	v_cmp_ge_f32_e64 s[22:23], v184, v187
	v_cmp_ge_f32_e64 s[24:25], v185, v187
	v_cmp_ge_f32_e64 s[26:27], v186, v187
	v_cmp_gt_f32_e64 s[28:29], v188, v187
	v_addc_co_u32_e64 v212, s[30:31], v212, 0, s[22:23]
	v_addc_co_u32_e64 v212, s[30:31], v212, 0, s[24:25]
	v_addc_co_u32_e64 v212, s[30:31], v212, 0, s[26:27]
	v_addc_co_u32_e64 v212, s[30:31], v212, 0, s[28:29]
	v_cmp_gt_f32_e64 s[22:23], v189, v187
	v_cmp_gt_f32_e64 s[24:25], v190, v187
	v_cmp_gt_f32_e64 s[26:27], v191, v187
	v_cmp_gt_f32_e64 s[28:29], v192, v187
	v_addc_co_u32_e64 v212, s[30:31], v212, 0, s[22:23]
	v_addc_co_u32_e64 v212, s[30:31], v212, 0, s[24:25]
	v_addc_co_u32_e64 v212, s[30:31], v212, 0, s[26:27]
	v_addc_co_u32_e64 v212, s[30:31], v212, 0, s[28:29]
	v_cmp_gt_f32_e64 s[22:23], v193, v187
	v_cmp_gt_f32_e64 s[24:25], v194, v187
	v_cmp_gt_f32_e64 s[26:27], v195, v187
	v_cmp_gt_f32_e64 s[28:29], v196, v187
	v_addc_co_u32_e64 v212, s[30:31], v212, 0, s[22:23]
	v_addc_co_u32_e64 v212, s[30:31], v212, 0, s[24:25]
	v_addc_co_u32_e64 v212, s[30:31], v212, 0, s[26:27]
	v_addc_co_u32_e64 v212, s[30:31], v212, 0, s[28:29]
	v_cmp_gt_f32_e64 s[22:23], v197, v187
	v_cmp_gt_f32_e64 s[24:25], v198, v187
	v_cmp_gt_f32_e64 s[26:27], v199, v187
	v_cmp_gt_f32_e64 s[28:29], v200, v187
	v_addc_co_u32_e64 v212, s[30:31], v212, 0, s[22:23]
	v_addc_co_u32_e64 v212, s[30:31], v212, 0, s[24:25]
	v_addc_co_u32_e64 v212, s[30:31], v212, 0, s[26:27]
	v_addc_co_u32_e64 v212, s[30:31], v212, 0, s[28:29]
	v_cmp_gt_f32_e64 s[22:23], v201, v187
	v_cmp_gt_f32_e64 s[24:25], v202, v187
	v_cmp_gt_f32_e64 s[26:27], v203, v187
	v_cmp_gt_f32_e64 s[28:29], v204, v187
	v_addc_co_u32_e64 v212, s[30:31], v212, 0, s[22:23]
	v_addc_co_u32_e64 v212, s[30:31], v212, 0, s[24:25]
	v_addc_co_u32_e64 v212, s[30:31], v212, 0, s[26:27]
	v_addc_co_u32_e64 v212, s[30:31], v212, 0, s[28:29]
	v_cmp_gt_f32_e64 s[22:23], v205, v187
	v_cmp_gt_f32_e64 s[24:25], v206, v187
	v_cmp_gt_f32_e64 s[26:27], v207, v187
	v_cmp_gt_f32_e64 s[28:29], v208, v187
	v_addc_co_u32_e64 v212, s[30:31], v212, 0, s[22:23]
	v_addc_co_u32_e64 v212, s[30:31], v212, 0, s[24:25]
	v_addc_co_u32_e64 v212, s[30:31], v212, 0, s[26:27]
	v_addc_co_u32_e64 v212, s[30:31], v212, 0, s[28:29]
	v_cmp_gt_f32_e64 s[22:23], v209, v187
	s_nop 0
	s_nop 0
	v_addc_co_u32_e64 v212, s[30:31], v212, 0, s[22:23]
	v_cmp_gt_u32_e32 vcc, 16, v212
	s_and_saveexec_b64 s[40:41], vcc
	v_lshl_add_u32 v214, v212, 2, v213
	v_mov_b32_e32 v212, 27
	ds_write_b32 v214, v187
	ds_write_b32 v214, v212 offset:4096
	s_mov_b64 exec, -1
	s_branch .Lrk0_c35
; __device__ __forceinline__ void ph_peer_select(const Params& P, int layer, const h16* Q, int nrows, char* smem) {
;     ...
;     for (int i = tid; i < 64 * 50; i += NTHR) {
;       const int tok = i / 50, c = i % 50;
;       const float v = cd[tok * 52 + c];
;       int rank = 0;
;       for (int j = 0; j < 50; ++j) { const float o = cd[tok * 52 + j]; rank += (o > v || (o == v && j < c)) ? 1 : 0; }
;       if (rank < TOPK) { tv[tok * 16 + rank] = v; tp[tok * 16 + rank] = c; }
;     }
.Lrk0_c28:
	v_mov_b32_e32 v212, 0
	v_cmp_ge_f32_e64 s[22:23], v160, v188
	v_cmp_ge_f32_e64 s[24:25], v161, v188
	v_cmp_ge_f32_e64 s[26:27], v162, v188
	v_cmp_ge_f32_e64 s[28:29], v163, v188
	v_addc_co_u32_e64 v212, s[30:31], v212, 0, s[22:23]
	v_addc_co_u32_e64 v212, s[30:31], v212, 0, s[24:25]
	v_addc_co_u32_e64 v212, s[30:31], v212, 0, s[26:27]
	v_addc_co_u32_e64 v212, s[30:31], v212, 0, s[28:29]
	v_cmp_ge_f32_e64 s[22:23], v164, v188
	v_cmp_ge_f32_e64 s[24:25], v165, v188
	v_cmp_ge_f32_e64 s[26:27], v166, v188
	v_cmp_ge_f32_e64 s[28:29], v167, v188
	v_addc_co_u32_e64 v212, s[30:31], v212, 0, s[22:23]
	v_addc_co_u32_e64 v212, s[30:31], v212, 0, s[24:25]
	v_addc_co_u32_e64 v212, s[30:31], v212, 0, s[26:27]
	v_addc_co_u32_e64 v212, s[30:31], v212, 0, s[28:29]
	v_cmp_ge_f32_e64 s[22:23], v168, v188
	v_cmp_ge_f32_e64 s[24:25], v169, v188
	v_cmp_ge_f32_e64 s[26:27], v170, v188
	v_cmp_ge_f32_e64 s[28:29], v171, v188
	v_addc_co_u32_e64 v212, s[30:31], v212, 0, s[22:23]
	v_addc_co_u32_e64 v212, s[30:31], v212, 0, s[24:25]
	v_addc_co_u32_e64 v212, s[30:31], v212, 0, s[26:27]
	v_addc_co_u32_e64 v212, s[30:31], v212, 0, s[28:29]
	v_cmp_ge_f32_e64 s[22:23], v172, v188
	v_cmp_ge_f32_e64 s[24:25], v173, v188
	v_cmp_ge_f32_e64 s[26:27], v174, v188
	v_cmp_ge_f32_e64 s[28:29], v175, v188
	v_addc_co_u32_e64 v212, s[30:31], v212, 0, s[22:23]
	v_addc_co_u32_e64 v212, s[30:31], v212, 0, s[24:25]
	v_addc_co_u32_e64 v212, s[30:31], v212, 0, s[26:27]
	v_addc_co_u32_e64 v212, s[30:31], v212, 0, s[28:29]
	v_cmp_ge_f32_e64 s[22:23], v176, v188
	v_cmp_ge_f32_e64 s[24:25], v177, v188
	v_cmp_ge_f32_e64 s[26:27], v178, v188
	v_cmp_ge_f32_e64 s[28:29], v179, v188
	v_addc_co_u32_e64 v212, s[30:31], v212, 0, s[22:23]
	v_addc_co_u32_e64 v212, s[30:31], v212, 0, s[24:25]
	v_addc_co_u32_e64 v212, s[30:31], v212, 0, s[26:27]
	v_addc_co_u32_e64 v212, s[30:31], v212, 0, s[28:29]
	v_cmp_ge_f32_e64 s[22:23], v180, v188
	v_cmp_ge_f32_e64 s[24:25], v181, v188
	v_cmp_ge_f32_e64 s[26:27], v182, v188
	v_cmp_ge_f32_e64 s[28:29], v183, v188
	v_addc_co_u32_e64 v212, s[30:31], v212, 0, s[22:23]
	v_addc_co_u32_e64 v212, s[30:31], v212, 0, s[24:25]
	v_addc_co_u32_e64 v212, s[30:31], v212, 0, s[26:27]
	v_addc_co_u32_e64 v212, s[30:31], v212, 0, s[28:29]
	v_cmp_ge_f32_e64 s[22:23], v184, v188
	v_cmp_ge_f32_e64 s[24:25], v185, v188
	v_cmp_ge_f32_e64 s[26:27], v186, v188
	v_cmp_ge_f32_e64 s[28:29], v187, v188
	v_addc_co_u32_e64 v212, s[30:31], v212, 0, s[22:23]
	v_addc_co_u32_e64 v212, s[30:31], v212, 0, s[24:25]
	v_addc_co_u32_e64 v212, s[30:31], v212, 0, s[26:27]
	v_addc_co_u32_e64 v212, s[30:31], v212, 0, s[28:29]
	v_cmp_gt_f32_e64 s[22:23], v189, v188
	v_cmp_gt_f32_e64 s[24:25], v190, v188
	v_cmp_gt_f32_e64 s[26:27], v191, v188
	v_cmp_gt_f32_e64 s[28:29], v192, v188
	v_addc_co_u32_e64 v212, s[30:31], v212, 0, s[22:23]
	v_addc_co_u32_e64 v212, s[30:31], v212, 0, s[24:25]
	v_addc_co_u32_e64 v212, s[30:31], v212, 0, s[26:27]
	v_addc_co_u32_e64 v212, s[30:31], v212, 0, s[28:29]
	v_cmp_gt_f32_e64 s[22:23], v193, v188
	v_cmp_gt_f32_e64 s[24:25], v194, v188
	v_cmp_gt_f32_e64 s[26:27], v195, v188
	v_cmp_gt_f32_e64 s[28:29], v196, v188
	v_addc_co_u32_e64 v212, s[30:31], v212, 0, s[22:23]
	v_addc_co_u32_e64 v212, s[30:31], v212, 0, s[24:25]
	v_addc_co_u32_e64 v212, s[30:31], v212, 0, s[26:27]
	v_addc_co_u32_e64 v212, s[30:31], v212, 0, s[28:29]
	v_cmp_gt_f32_e64 s[22:23], v197, v188
	v_cmp_gt_f32_e64 s[24:25], v198, v188
	v_cmp_gt_f32_e64 s[26:27], v199, v188
	v_cmp_gt_f32_e64 s[28:29], v200, v188
	v_addc_co_u32_e64 v212, s[30:31], v212, 0, s[22:23]
	v_addc_co_u32_e64 v212, s[30:31], v212, 0, s[24:25]
	v_addc_co_u32_e64 v212, s[30:31], v212, 0, s[26:27]
	v_addc_co_u32_e64 v212, s[30:31], v212, 0, s[28:29]
	v_cmp_gt_f32_e64 s[22:23], v201, v188
	v_cmp_gt_f32_e64 s[24:25], v202, v188
	v_cmp_gt_f32_e64 s[26:27], v203, v188
	v_cmp_gt_f32_e64 s[28:29], v204, v188
	v_addc_co_u32_e64 v212, s[30:31], v212, 0, s[22:23]
	v_addc_co_u32_e64 v212, s[30:31], v212, 0, s[24:25]
	v_addc_co_u32_e64 v212, s[30:31], v212, 0, s[26:27]
	v_addc_co_u32_e64 v212, s[30:31], v212, 0, s[28:29]
	v_cmp_gt_f32_e64 s[22:23], v205, v188
	v_cmp_gt_f32_e64 s[24:25], v206, v188
	v_cmp_gt_f32_e64 s[26:27], v207, v188
	v_cmp_gt_f32_e64 s[28:29], v208, v188
	v_addc_co_u32_e64 v212, s[30:31], v212, 0, s[22:23]
	v_addc_co_u32_e64 v212, s[30:31], v212, 0, s[24:25]
	v_addc_co_u32_e64 v212, s[30:31], v212, 0, s[26:27]
	v_addc_co_u32_e64 v212, s[30:31], v212, 0, s[28:29]
	v_cmp_gt_f32_e64 s[22:23], v209, v188
	s_nop 0
	s_nop 0
	v_addc_co_u32_e64 v212, s[30:31], v212, 0, s[22:23]
	v_cmp_gt_u32_e32 vcc, 16, v212
	s_and_saveexec_b64 s[40:41], vcc
	v_lshl_add_u32 v214, v212, 2, v213
	v_mov_b32_e32 v212, 28
	ds_write_b32 v214, v188
	ds_write_b32 v214, v212 offset:4096
	s_mov_b64 exec, -1
	s_branch .Lrk0_c36
; __device__ __forceinline__ void ph_peer_select(const Params& P, int layer, const h16* Q, int nrows, char* smem) {
;     ...
;     for (int i = tid; i < 64 * 50; i += NTHR) {
;       const int tok = i / 50, c = i % 50;
;       const float v = cd[tok * 52 + c];
;       int rank = 0;
;       for (int j = 0; j < 50; ++j) { const float o = cd[tok * 52 + j]; rank += (o > v || (o == v && j < c)) ? 1 : 0; }
;       if (rank < TOPK) { tv[tok * 16 + rank] = v; tp[tok * 16 + rank] = c; }
;     }
.Lrk0_c29:
	v_mov_b32_e32 v212, 0
	v_cmp_ge_f32_e64 s[22:23], v160, v189
	v_cmp_ge_f32_e64 s[24:25], v161, v189
	v_cmp_ge_f32_e64 s[26:27], v162, v189
	v_cmp_ge_f32_e64 s[28:29], v163, v189
	v_addc_co_u32_e64 v212, s[30:31], v212, 0, s[22:23]
	v_addc_co_u32_e64 v212, s[30:31], v212, 0, s[24:25]
	v_addc_co_u32_e64 v212, s[30:31], v212, 0, s[26:27]
	v_addc_co_u32_e64 v212, s[30:31], v212, 0, s[28:29]
	v_cmp_ge_f32_e64 s[22:23], v164, v189
	v_cmp_ge_f32_e64 s[24:25], v165, v189
	v_cmp_ge_f32_e64 s[26:27], v166, v189
	v_cmp_ge_f32_e64 s[28:29], v167, v189
	v_addc_co_u32_e64 v212, s[30:31], v212, 0, s[22:23]
	v_addc_co_u32_e64 v212, s[30:31], v212, 0, s[24:25]
	v_addc_co_u32_e64 v212, s[30:31], v212, 0, s[26:27]
	v_addc_co_u32_e64 v212, s[30:31], v212, 0, s[28:29]
	v_cmp_ge_f32_e64 s[22:23], v168, v189
	v_cmp_ge_f32_e64 s[24:25], v169, v189
	v_cmp_ge_f32_e64 s[26:27], v170, v189
	v_cmp_ge_f32_e64 s[28:29], v171, v189
	v_addc_co_u32_e64 v212, s[30:31], v212, 0, s[22:23]
	v_addc_co_u32_e64 v212, s[30:31], v212, 0, s[24:25]
	v_addc_co_u32_e64 v212, s[30:31], v212, 0, s[26:27]
	v_addc_co_u32_e64 v212, s[30:31], v212, 0, s[28:29]
	v_cmp_ge_f32_e64 s[22:23], v172, v189
	v_cmp_ge_f32_e64 s[24:25], v173, v189
	v_cmp_ge_f32_e64 s[26:27], v174, v189
	v_cmp_ge_f32_e64 s[28:29], v175, v189
	v_addc_co_u32_e64 v212, s[30:31], v212, 0, s[22:23]
	v_addc_co_u32_e64 v212, s[30:31], v212, 0, s[24:25]
	v_addc_co_u32_e64 v212, s[30:31], v212, 0, s[26:27]
	v_addc_co_u32_e64 v212, s[30:31], v212, 0, s[28:29]
	v_cmp_ge_f32_e64 s[22:23], v176, v189
	v_cmp_ge_f32_e64 s[24:25], v177, v189
	v_cmp_ge_f32_e64 s[26:27], v178, v189
	v_cmp_ge_f32_e64 s[28:29], v179, v189
	v_addc_co_u32_e64 v212, s[30:31], v212, 0, s[22:23]
	v_addc_co_u32_e64 v212, s[30:31], v212, 0, s[24:25]
	v_addc_co_u32_e64 v212, s[30:31], v212, 0, s[26:27]
	v_addc_co_u32_e64 v212, s[30:31], v212, 0, s[28:29]
	v_cmp_ge_f32_e64 s[22:23], v180, v189
	v_cmp_ge_f32_e64 s[24:25], v181, v189
	v_cmp_ge_f32_e64 s[26:27], v182, v189
	v_cmp_ge_f32_e64 s[28:29], v183, v189
	v_addc_co_u32_e64 v212, s[30:31], v212, 0, s[22:23]
	v_addc_co_u32_e64 v212, s[30:31], v212, 0, s[24:25]
	v_addc_co_u32_e64 v212, s[30:31], v212, 0, s[26:27]
	v_addc_co_u32_e64 v212, s[30:31], v212, 0, s[28:29]
	v_cmp_ge_f32_e64 s[22:23], v184, v189
	v_cmp_ge_f32_e64 s[24:25], v185, v189
	v_cmp_ge_f32_e64 s[26:27], v186, v189
	v_cmp_ge_f32_e64 s[28:29], v187, v189
	v_addc_co_u32_e64 v212, s[30:31], v212, 0, s[22:23]
	v_addc_co_u32_e64 v212, s[30:31], v212, 0, s[24:25]
	v_addc_co_u32_e64 v212, s[30:31], v212, 0, s[26:27]
	v_addc_co_u32_e64 v212, s[30:31], v212, 0, s[28:29]
	v_cmp_ge_f32_e64 s[22:23], v188, v189
	v_cmp_gt_f32_e64 s[24:25], v190, v189
	v_cmp_gt_f32_e64 s[26:27], v191, v189
	v_cmp_gt_f32_e64 s[28:29], v192, v189
	v_addc_co_u32_e64 v212, s[30:31], v212, 0, s[22:23]
	v_addc_co_u32_e64 v212, s[30:31], v212, 0, s[24:25]
	v_addc_co_u32_e64 v212, s[30:31], v212, 0, s[26:27]
	v_addc_co_u32_e64 v212, s[30:31], v212, 0, s[28:29]
	v_cmp_gt_f32_e64 s[22:23], v193, v189
	v_cmp_gt_f32_e64 s[24:25], v194, v189
	v_cmp_gt_f32_e64 s[26:27], v195, v189
	v_cmp_gt_f32_e64 s[28:29], v196, v189
	v_addc_co_u32_e64 v212, s[30:31], v212, 0, s[22:23]
	v_addc_co_u32_e64 v212, s[30:31], v212, 0, s[24:25]
	v_addc_co_u32_e64 v212, s[30:31], v212, 0, s[26:27]
	v_addc_co_u32_e64 v212, s[30:31], v212, 0, s[28:29]
	v_cmp_gt_f32_e64 s[22:23], v197, v189
	v_cmp_gt_f32_e64 s[24:25], v198, v189
	v_cmp_gt_f32_e64 s[26:27], v199, v189
	v_cmp_gt_f32_e64 s[28:29], v200, v189
	v_addc_co_u32_e64 v212, s[30:31], v212, 0, s[22:23]
	v_addc_co_u32_e64 v212, s[30:31], v212, 0, s[24:25]
	v_addc_co_u32_e64 v212, s[30:31], v212, 0, s[26:27]
	v_addc_co_u32_e64 v212, s[30:31], v212, 0, s[28:29]
	v_cmp_gt_f32_e64 s[22:23], v201, v189
	v_cmp_gt_f32_e64 s[24:25], v202, v189
	v_cmp_gt_f32_e64 s[26:27], v203, v189
	v_cmp_gt_f32_e64 s[28:29], v204, v189
	v_addc_co_u32_e64 v212, s[30:31], v212, 0, s[22:23]
	v_addc_co_u32_e64 v212, s[30:31], v212, 0, s[24:25]
	v_addc_co_u32_e64 v212, s[30:31], v212, 0, s[26:27]
	v_addc_co_u32_e64 v212, s[30:31], v212, 0, s[28:29]
	v_cmp_gt_f32_e64 s[22:23], v205, v189
	v_cmp_gt_f32_e64 s[24:25], v206, v189
	v_cmp_gt_f32_e64 s[26:27], v207, v189
	v_cmp_gt_f32_e64 s[28:29], v208, v189
	v_addc_co_u32_e64 v212, s[30:31], v212, 0, s[22:23]
	v_addc_co_u32_e64 v212, s[30:31], v212, 0, s[24:25]
	v_addc_co_u32_e64 v212, s[30:31], v212, 0, s[26:27]
	v_addc_co_u32_e64 v212, s[30:31], v212, 0, s[28:29]
	v_cmp_gt_f32_e64 s[22:23], v209, v189
	s_nop 0
	s_nop 0
	v_addc_co_u32_e64 v212, s[30:31], v212, 0, s[22:23]
	v_cmp_gt_u32_e32 vcc, 16, v212
	s_and_saveexec_b64 s[40:41], vcc
	v_lshl_add_u32 v214, v212, 2, v213
	v_mov_b32_e32 v212, 29
	ds_write_b32 v214, v189
	ds_write_b32 v214, v212 offset:4096
	s_mov_b64 exec, -1
	s_branch .Lrk0_c37
; __device__ __forceinline__ void ph_peer_select(const Params& P, int layer, const h16* Q, int nrows, char* smem) {
;     ...
;     for (int i = tid; i < 64 * 50; i += NTHR) {
;       const int tok = i / 50, c = i % 50;
;       const float v = cd[tok * 52 + c];
;       int rank = 0;
;       for (int j = 0; j < 50; ++j) { const float o = cd[tok * 52 + j]; rank += (o > v || (o == v && j < c)) ? 1 : 0; }
;       if (rank < TOPK) { tv[tok * 16 + rank] = v; tp[tok * 16 + rank] = c; }
;     }
.Lrk0_c30:
	v_mov_b32_e32 v212, 0
	v_cmp_ge_f32_e64 s[22:23], v160, v190
	v_cmp_ge_f32_e64 s[24:25], v161, v190
	v_cmp_ge_f32_e64 s[26:27], v162, v190
	v_cmp_ge_f32_e64 s[28:29], v163, v190
	v_addc_co_u32_e64 v212, s[30:31], v212, 0, s[22:23]
	v_addc_co_u32_e64 v212, s[30:31], v212, 0, s[24:25]
	v_addc_co_u32_e64 v212, s[30:31], v212, 0, s[26:27]
	v_addc_co_u32_e64 v212, s[30:31], v212, 0, s[28:29]
	v_cmp_ge_f32_e64 s[22:23], v164, v190
	v_cmp_ge_f32_e64 s[24:25], v165, v190
	v_cmp_ge_f32_e64 s[26:27], v166, v190
	v_cmp_ge_f32_e64 s[28:29], v167, v190
	v_addc_co_u32_e64 v212, s[30:31], v212, 0, s[22:23]
	v_addc_co_u32_e64 v212, s[30:31], v212, 0, s[24:25]
	v_addc_co_u32_e64 v212, s[30:31], v212, 0, s[26:27]
	v_addc_co_u32_e64 v212, s[30:31], v212, 0, s[28:29]
	v_cmp_ge_f32_e64 s[22:23], v168, v190
	v_cmp_ge_f32_e64 s[24:25], v169, v190
	v_cmp_ge_f32_e64 s[26:27], v170, v190
	v_cmp_ge_f32_e64 s[28:29], v171, v190
	v_addc_co_u32_e64 v212, s[30:31], v212, 0, s[22:23]
	v_addc_co_u32_e64 v212, s[30:31], v212, 0, s[24:25]
	v_addc_co_u32_e64 v212, s[30:31], v212, 0, s[26:27]
	v_addc_co_u32_e64 v212, s[30:31], v212, 0, s[28:29]
	v_cmp_ge_f32_e64 s[22:23], v172, v190
	v_cmp_ge_f32_e64 s[24:25], v173, v190
	v_cmp_ge_f32_e64 s[26:27], v174, v190
	v_cmp_ge_f32_e64 s[28:29], v175, v190
	v_addc_co_u32_e64 v212, s[30:31], v212, 0, s[22:23]
	v_addc_co_u32_e64 v212, s[30:31], v212, 0, s[24:25]
	v_addc_co_u32_e64 v212, s[30:31], v212, 0, s[26:27]
	v_addc_co_u32_e64 v212, s[30:31], v212, 0, s[28:29]
	v_cmp_ge_f32_e64 s[22:23], v176, v190
	v_cmp_ge_f32_e64 s[24:25], v177, v190
	v_cmp_ge_f32_e64 s[26:27], v178, v190
	v_cmp_ge_f32_e64 s[28:29], v179, v190
	v_addc_co_u32_e64 v212, s[30:31], v212, 0, s[22:23]
	v_addc_co_u32_e64 v212, s[30:31], v212, 0, s[24:25]
	v_addc_co_u32_e64 v212, s[30:31], v212, 0, s[26:27]
	v_addc_co_u32_e64 v212, s[30:31], v212, 0, s[28:29]
	v_cmp_ge_f32_e64 s[22:23], v180, v190
	v_cmp_ge_f32_e64 s[24:25], v181, v190
	v_cmp_ge_f32_e64 s[26:27], v182, v190
	v_cmp_ge_f32_e64 s[28:29], v183, v190
	v_addc_co_u32_e64 v212, s[30:31], v212, 0, s[22:23]
	v_addc_co_u32_e64 v212, s[30:31], v212, 0, s[24:25]
	v_addc_co_u32_e64 v212, s[30:31], v212, 0, s[26:27]
	v_addc_co_u32_e64 v212, s[30:31], v212, 0, s[28:29]
	v_cmp_ge_f32_e64 s[22:23], v184, v190
	v_cmp_ge_f32_e64 s[24:25], v185, v190
	v_cmp_ge_f32_e64 s[26:27], v186, v190
	v_cmp_ge_f32_e64 s[28:29], v187, v190
	v_addc_co_u32_e64 v212, s[30:31], v212, 0, s[22:23]
	v_addc_co_u32_e64 v212, s[30:31], v212, 0, s[24:25]
	v_addc_co_u32_e64 v212, s[30:31], v212, 0, s[26:27]
	v_addc_co_u32_e64 v212, s[30:31], v212, 0, s[28:29]
	v_cmp_ge_f32_e64 s[22:23], v188, v190
	v_cmp_ge_f32_e64 s[24:25], v189, v190
	v_cmp_gt_f32_e64 s[26:27], v191, v190
	v_cmp_gt_f32_e64 s[28:29], v192, v190
	v_addc_co_u32_e64 v212, s[30:31], v212, 0, s[22:23]
	v_addc_co_u32_e64 v212, s[30:31], v212, 0, s[24:25]
	v_addc_co_u32_e64 v212, s[30:31], v212, 0, s[26:27]
	v_addc_co_u32_e64 v212, s[30:31], v212, 0, s[28:29]
	v_cmp_gt_f32_e64 s[22:23], v193, v190
	v_cmp_gt_f32_e64 s[24:25], v194, v190
	v_cmp_gt_f32_e64 s[26:27], v195, v190
	v_cmp_gt_f32_e64 s[28:29], v196, v190
	v_addc_co_u32_e64 v212, s[30:31], v212, 0, s[22:23]
	v_addc_co_u32_e64 v212, s[30:31], v212, 0, s[24:25]
	v_addc_co_u32_e64 v212, s[30:31], v212, 0, s[26:27]
	v_addc_co_u32_e64 v212, s[30:31], v212, 0, s[28:29]
	v_cmp_gt_f32_e64 s[22:23], v197, v190
	v_cmp_gt_f32_e64 s[24:25], v198, v190
	v_cmp_gt_f32_e64 s[26:27], v199, v190
	v_cmp_gt_f32_e64 s[28:29], v200, v190
	v_addc_co_u32_e64 v212, s[30:31], v212, 0, s[22:23]
	v_addc_co_u32_e64 v212, s[30:31], v212, 0, s[24:25]
	v_addc_co_u32_e64 v212, s[30:31], v212, 0, s[26:27]
	v_addc_co_u32_e64 v212, s[30:31], v212, 0, s[28:29]
	v_cmp_gt_f32_e64 s[22:23], v201, v190
	v_cmp_gt_f32_e64 s[24:25], v202, v190
	v_cmp_gt_f32_e64 s[26:27], v203, v190
	v_cmp_gt_f32_e64 s[28:29], v204, v190
	v_addc_co_u32_e64 v212, s[30:31], v212, 0, s[22:23]
	v_addc_co_u32_e64 v212, s[30:31], v212, 0, s[24:25]
	v_addc_co_u32_e64 v212, s[30:31], v212, 0, s[26:27]
	v_addc_co_u32_e64 v212, s[30:31], v212, 0, s[28:29]
	v_cmp_gt_f32_e64 s[22:23], v205, v190
	v_cmp_gt_f32_e64 s[24:25], v206, v190
	v_cmp_gt_f32_e64 s[26:27], v207, v190
	v_cmp_gt_f32_e64 s[28:29], v208, v190
	v_addc_co_u32_e64 v212, s[30:31], v212, 0, s[22:23]
	v_addc_co_u32_e64 v212, s[30:31], v212, 0, s[24:25]
	v_addc_co_u32_e64 v212, s[30:31], v212, 0, s[26:27]
	v_addc_co_u32_e64 v212, s[30:31], v212, 0, s[28:29]
	v_cmp_gt_f32_e64 s[22:23], v209, v190
	s_nop 0
	s_nop 0
	v_addc_co_u32_e64 v212, s[30:31], v212, 0, s[22:23]
	v_cmp_gt_u32_e32 vcc, 16, v212
	s_and_saveexec_b64 s[40:41], vcc
	v_lshl_add_u32 v214, v212, 2, v213
	v_mov_b32_e32 v212, 30
	ds_write_b32 v214, v190
	ds_write_b32 v214, v212 offset:4096
	s_mov_b64 exec, -1
	s_branch .Lrk0_c38
; __device__ __forceinline__ void ph_peer_select(const Params& P, int layer, const h16* Q, int nrows, char* smem) {
;     ...
;     for (int i = tid; i < 64 * 50; i += NTHR) {
;       const int tok = i / 50, c = i % 50;
;       const float v = cd[tok * 52 + c];
;       int rank = 0;
;       for (int j = 0; j < 50; ++j) { const float o = cd[tok * 52 + j]; rank += (o > v || (o == v && j < c)) ? 1 : 0; }
;       if (rank < TOPK) { tv[tok * 16 + rank] = v; tp[tok * 16 + rank] = c; }
;     }
.Lrk0_c31:
	v_mov_b32_e32 v212, 0
	v_cmp_ge_f32_e64 s[22:23], v160, v191
	v_cmp_ge_f32_e64 s[24:25], v161, v191
	v_cmp_ge_f32_e64 s[26:27], v162, v191
	v_cmp_ge_f32_e64 s[28:29], v163, v191
	v_addc_co_u32_e64 v212, s[30:31], v212, 0, s[22:23]
	v_addc_co_u32_e64 v212, s[30:31], v212, 0, s[24:25]
	v_addc_co_u32_e64 v212, s[30:31], v212, 0, s[26:27]
	v_addc_co_u32_e64 v212, s[30:31], v212, 0, s[28:29]
	v_cmp_ge_f32_e64 s[22:23], v164, v191
	v_cmp_ge_f32_e64 s[24:25], v165, v191
	v_cmp_ge_f32_e64 s[26:27], v166, v191
	v_cmp_ge_f32_e64 s[28:29], v167, v191
	v_addc_co_u32_e64 v212, s[30:31], v212, 0, s[22:23]
	v_addc_co_u32_e64 v212, s[30:31], v212, 0, s[24:25]
	v_addc_co_u32_e64 v212, s[30:31], v212, 0, s[26:27]
	v_addc_co_u32_e64 v212, s[30:31], v212, 0, s[28:29]
	v_cmp_ge_f32_e64 s[22:23], v168, v191
	v_cmp_ge_f32_e64 s[24:25], v169, v191
	v_cmp_ge_f32_e64 s[26:27], v170, v191
	v_cmp_ge_f32_e64 s[28:29], v171, v191
	v_addc_co_u32_e64 v212, s[30:31], v212, 0, s[22:23]
	v_addc_co_u32_e64 v212, s[30:31], v212, 0, s[24:25]
	v_addc_co_u32_e64 v212, s[30:31], v212, 0, s[26:27]
	v_addc_co_u32_e64 v212, s[30:31], v212, 0, s[28:29]
	v_cmp_ge_f32_e64 s[22:23], v172, v191
	v_cmp_ge_f32_e64 s[24:25], v173, v191
	v_cmp_ge_f32_e64 s[26:27], v174, v191
	v_cmp_ge_f32_e64 s[28:29], v175, v191
	v_addc_co_u32_e64 v212, s[30:31], v212, 0, s[22:23]
	v_addc_co_u32_e64 v212, s[30:31], v212, 0, s[24:25]
	v_addc_co_u32_e64 v212, s[30:31], v212, 0, s[26:27]
	v_addc_co_u32_e64 v212, s[30:31], v212, 0, s[28:29]
	v_cmp_ge_f32_e64 s[22:23], v176, v191
	v_cmp_ge_f32_e64 s[24:25], v177, v191
	v_cmp_ge_f32_e64 s[26:27], v178, v191
	v_cmp_ge_f32_e64 s[28:29], v179, v191
	v_addc_co_u32_e64 v212, s[30:31], v212, 0, s[22:23]
	v_addc_co_u32_e64 v212, s[30:31], v212, 0, s[24:25]
	v_addc_co_u32_e64 v212, s[30:31], v212, 0, s[26:27]
	v_addc_co_u32_e64 v212, s[30:31], v212, 0, s[28:29]
	v_cmp_ge_f32_e64 s[22:23], v180, v191
	v_cmp_ge_f32_e64 s[24:25], v181, v191
	v_cmp_ge_f32_e64 s[26:27], v182, v191
	v_cmp_ge_f32_e64 s[28:29], v183, v191
	v_addc_co_u32_e64 v212, s[30:31], v212, 0, s[22:23]
	v_addc_co_u32_e64 v212, s[30:31], v212, 0, s[24:25]
	v_addc_co_u32_e64 v212, s[30:31], v212, 0, s[26:27]
	v_addc_co_u32_e64 v212, s[30:31], v212, 0, s[28:29]
	v_cmp_ge_f32_e64 s[22:23], v184, v191
	v_cmp_ge_f32_e64 s[24:25], v185, v191
	v_cmp_ge_f32_e64 s[26:27], v186, v191
	v_cmp_ge_f32_e64 s[28:29], v187, v191
	v_addc_co_u32_e64 v212, s[30:31], v212, 0, s[22:23]
	v_addc_co_u32_e64 v212, s[30:31], v212, 0, s[24:25]
	v_addc_co_u32_e64 v212, s[30:31], v212, 0, s[26:27]
	v_addc_co_u32_e64 v212, s[30:31], v212, 0, s[28:29]
	v_cmp_ge_f32_e64 s[22:23], v188, v191
	v_cmp_ge_f32_e64 s[24:25], v189, v191
	v_cmp_ge_f32_e64 s[26:27], v190, v191
	v_cmp_gt_f32_e64 s[28:29], v192, v191
	v_addc_co_u32_e64 v212, s[30:31], v212, 0, s[22:23]
	v_addc_co_u32_e64 v212, s[30:31], v212, 0, s[24:25]
	v_addc_co_u32_e64 v212, s[30:31], v212, 0, s[26:27]
	v_addc_co_u32_e64 v212, s[30:31], v212, 0, s[28:29]
	v_cmp_gt_f32_e64 s[22:23], v193, v191
	v_cmp_gt_f32_e64 s[24:25], v194, v191
	v_cmp_gt_f32_e64 s[26:27], v195, v191
	v_cmp_gt_f32_e64 s[28:29], v196, v191
	v_addc_co_u32_e64 v212, s[30:31], v212, 0, s[22:23]
	v_addc_co_u32_e64 v212, s[30:31], v212, 0, s[24:25]
	v_addc_co_u32_e64 v212, s[30:31], v212, 0, s[26:27]
	v_addc_co_u32_e64 v212, s[30:31], v212, 0, s[28:29]
	v_cmp_gt_f32_e64 s[22:23], v197, v191
	v_cmp_gt_f32_e64 s[24:25], v198, v191
	v_cmp_gt_f32_e64 s[26:27], v199, v191
	v_cmp_gt_f32_e64 s[28:29], v200, v191
	v_addc_co_u32_e64 v212, s[30:31], v212, 0, s[22:23]
	v_addc_co_u32_e64 v212, s[30:31], v212, 0, s[24:25]
	v_addc_co_u32_e64 v212, s[30:31], v212, 0, s[26:27]
	v_addc_co_u32_e64 v212, s[30:31], v212, 0, s[28:29]
	v_cmp_gt_f32_e64 s[22:23], v201, v191
	v_cmp_gt_f32_e64 s[24:25], v202, v191
	v_cmp_gt_f32_e64 s[26:27], v203, v191
	v_cmp_gt_f32_e64 s[28:29], v204, v191
	v_addc_co_u32_e64 v212, s[30:31], v212, 0, s[22:23]
	v_addc_co_u32_e64 v212, s[30:31], v212, 0, s[24:25]
	v_addc_co_u32_e64 v212, s[30:31], v212, 0, s[26:27]
	v_addc_co_u32_e64 v212, s[30:31], v212, 0, s[28:29]
	v_cmp_gt_f32_e64 s[22:23], v205, v191
	v_cmp_gt_f32_e64 s[24:25], v206, v191
	v_cmp_gt_f32_e64 s[26:27], v207, v191
	v_cmp_gt_f32_e64 s[28:29], v208, v191
	v_addc_co_u32_e64 v212, s[30:31], v212, 0, s[22:23]
	v_addc_co_u32_e64 v212, s[30:31], v212, 0, s[24:25]
	v_addc_co_u32_e64 v212, s[30:31], v212, 0, s[26:27]
	v_addc_co_u32_e64 v212, s[30:31], v212, 0, s[28:29]
	v_cmp_gt_f32_e64 s[22:23], v209, v191
	s_nop 0
	s_nop 0
	v_addc_co_u32_e64 v212, s[30:31], v212, 0, s[22:23]
	v_cmp_gt_u32_e32 vcc, 16, v212
	s_and_saveexec_b64 s[40:41], vcc
	v_lshl_add_u32 v214, v212, 2, v213
	v_mov_b32_e32 v212, 31
	ds_write_b32 v214, v191
	ds_write_b32 v214, v212 offset:4096
	s_mov_b64 exec, -1
	s_branch .Lrk0_c39
; __device__ __forceinline__ void ph_peer_select(const Params& P, int layer, const h16* Q, int nrows, char* smem) {
;     ...
;     for (int i = tid; i < 64 * 50; i += NTHR) {
;       const int tok = i / 50, c = i % 50;
;       const float v = cd[tok * 52 + c];
;       int rank = 0;
;       for (int j = 0; j < 50; ++j) { const float o = cd[tok * 52 + j]; rank += (o > v || (o == v && j < c)) ? 1 : 0; }
;       if (rank < TOPK) { tv[tok * 16 + rank] = v; tp[tok * 16 + rank] = c; }
;     }
.Lrk0_c32:
	v_mov_b32_e32 v212, 0
	v_cmp_ge_f32_e64 s[22:23], v160, v192
	v_cmp_ge_f32_e64 s[24:25], v161, v192
	v_cmp_ge_f32_e64 s[26:27], v162, v192
	v_cmp_ge_f32_e64 s[28:29], v163, v192
	v_addc_co_u32_e64 v212, s[30:31], v212, 0, s[22:23]
	v_addc_co_u32_e64 v212, s[30:31], v212, 0, s[24:25]
	v_addc_co_u32_e64 v212, s[30:31], v212, 0, s[26:27]
	v_addc_co_u32_e64 v212, s[30:31], v212, 0, s[28:29]
	v_cmp_ge_f32_e64 s[22:23], v164, v192
	v_cmp_ge_f32_e64 s[24:25], v165, v192
	v_cmp_ge_f32_e64 s[26:27], v166, v192
	v_cmp_ge_f32_e64 s[28:29], v167, v192
	v_addc_co_u32_e64 v212, s[30:31], v212, 0, s[22:23]
	v_addc_co_u32_e64 v212, s[30:31], v212, 0, s[24:25]
	v_addc_co_u32_e64 v212, s[30:31], v212, 0, s[26:27]
	v_addc_co_u32_e64 v212, s[30:31], v212, 0, s[28:29]
	v_cmp_ge_f32_e64 s[22:23], v168, v192
	v_cmp_ge_f32_e64 s[24:25], v169, v192
	v_cmp_ge_f32_e64 s[26:27], v170, v192
	v_cmp_ge_f32_e64 s[28:29], v171, v192
	v_addc_co_u32_e64 v212, s[30:31], v212, 0, s[22:23]
	v_addc_co_u32_e64 v212, s[30:31], v212, 0, s[24:25]
	v_addc_co_u32_e64 v212, s[30:31], v212, 0, s[26:27]
	v_addc_co_u32_e64 v212, s[30:31], v212, 0, s[28:29]
	v_cmp_ge_f32_e64 s[22:23], v172, v192
	v_cmp_ge_f32_e64 s[24:25], v173, v192
	v_cmp_ge_f32_e64 s[26:27], v174, v192
	v_cmp_ge_f32_e64 s[28:29], v175, v192
	v_addc_co_u32_e64 v212, s[30:31], v212, 0, s[22:23]
	v_addc_co_u32_e64 v212, s[30:31], v212, 0, s[24:25]
	v_addc_co_u32_e64 v212, s[30:31], v212, 0, s[26:27]
	v_addc_co_u32_e64 v212, s[30:31], v212, 0, s[28:29]
	v_cmp_ge_f32_e64 s[22:23], v176, v192
	v_cmp_ge_f32_e64 s[24:25], v177, v192
	v_cmp_ge_f32_e64 s[26:27], v178, v192
	v_cmp_ge_f32_e64 s[28:29], v179, v192
	v_addc_co_u32_e64 v212, s[30:31], v212, 0, s[22:23]
	v_addc_co_u32_e64 v212, s[30:31], v212, 0, s[24:25]
	v_addc_co_u32_e64 v212, s[30:31], v212, 0, s[26:27]
	v_addc_co_u32_e64 v212, s[30:31], v212, 0, s[28:29]
	v_cmp_ge_f32_e64 s[22:23], v180, v192
	v_cmp_ge_f32_e64 s[24:25], v181, v192
	v_cmp_ge_f32_e64 s[26:27], v182, v192
	v_cmp_ge_f32_e64 s[28:29], v183, v192
	v_addc_co_u32_e64 v212, s[30:31], v212, 0, s[22:23]
	v_addc_co_u32_e64 v212, s[30:31], v212, 0, s[24:25]
	v_addc_co_u32_e64 v212, s[30:31], v212, 0, s[26:27]
	v_addc_co_u32_e64 v212, s[30:31], v212, 0, s[28:29]
	v_cmp_ge_f32_e64 s[22:23], v184, v192
	v_cmp_ge_f32_e64 s[24:25], v185, v192
	v_cmp_ge_f32_e64 s[26:27], v186, v192
	v_cmp_ge_f32_e64 s[28:29], v187, v192
	v_addc_co_u32_e64 v212, s[30:31], v212, 0, s[22:23]
	v_addc_co_u32_e64 v212, s[30:31], v212, 0, s[24:25]
	v_addc_co_u32_e64 v212, s[30:31], v212, 0, s[26:27]
	v_addc_co_u32_e64 v212, s[30:31], v212, 0, s[28:29]
	v_cmp_ge_f32_e64 s[22:23], v188, v192
	v_cmp_ge_f32_e64 s[24:25], v189, v192
	v_cmp_ge_f32_e64 s[26:27], v190, v192
	v_cmp_ge_f32_e64 s[28:29], v191, v192
	v_addc_co_u32_e64 v212, s[30:31], v212, 0, s[22:23]
	v_addc_co_u32_e64 v212, s[30:31], v212, 0, s[24:25]
	v_addc_co_u32_e64 v212, s[30:31], v212, 0, s[26:27]
	v_addc_co_u32_e64 v212, s[30:31], v212, 0, s[28:29]
	v_cmp_gt_f32_e64 s[22:23], v193, v192
	v_cmp_gt_f32_e64 s[24:25], v194, v192
	v_cmp_gt_f32_e64 s[26:27], v195, v192
	v_cmp_gt_f32_e64 s[28:29], v196, v192
	v_addc_co_u32_e64 v212, s[30:31], v212, 0, s[22:23]
	v_addc_co_u32_e64 v212, s[30:31], v212, 0, s[24:25]
	v_addc_co_u32_e64 v212, s[30:31], v212, 0, s[26:27]
	v_addc_co_u32_e64 v212, s[30:31], v212, 0, s[28:29]
	v_cmp_gt_f32_e64 s[22:23], v197, v192
	v_cmp_gt_f32_e64 s[24:25], v198, v192
	v_cmp_gt_f32_e64 s[26:27], v199, v192
	v_cmp_gt_f32_e64 s[28:29], v200, v192
	v_addc_co_u32_e64 v212, s[30:31], v212, 0, s[22:23]
	v_addc_co_u32_e64 v212, s[30:31], v212, 0, s[24:25]
	v_addc_co_u32_e64 v212, s[30:31], v212, 0, s[26:27]
	v_addc_co_u32_e64 v212, s[30:31], v212, 0, s[28:29]
	v_cmp_gt_f32_e64 s[22:23], v201, v192
	v_cmp_gt_f32_e64 s[24:25], v202, v192
	v_cmp_gt_f32_e64 s[26:27], v203, v192
	v_cmp_gt_f32_e64 s[28:29], v204, v192
	v_addc_co_u32_e64 v212, s[30:31], v212, 0, s[22:23]
	v_addc_co_u32_e64 v212, s[30:31], v212, 0, s[24:25]
	v_addc_co_u32_e64 v212, s[30:31], v212, 0, s[26:27]
	v_addc_co_u32_e64 v212, s[30:31], v212, 0, s[28:29]
	v_cmp_gt_f32_e64 s[22:23], v205, v192
	v_cmp_gt_f32_e64 s[24:25], v206, v192
	v_cmp_gt_f32_e64 s[26:27], v207, v192
	v_cmp_gt_f32_e64 s[28:29], v208, v192
	v_addc_co_u32_e64 v212, s[30:31], v212, 0, s[22:23]
	v_addc_co_u32_e64 v212, s[30:31], v212, 0, s[24:25]
	v_addc_co_u32_e64 v212, s[30:31], v212, 0, s[26:27]
	v_addc_co_u32_e64 v212, s[30:31], v212, 0, s[28:29]
	v_cmp_gt_f32_e64 s[22:23], v209, v192
	s_nop 0
	s_nop 0
	v_addc_co_u32_e64 v212, s[30:31], v212, 0, s[22:23]
	v_cmp_gt_u32_e32 vcc, 16, v212
	s_and_saveexec_b64 s[40:41], vcc
	v_lshl_add_u32 v214, v212, 2, v213
	v_mov_b32_e32 v212, 32
	ds_write_b32 v214, v192
	ds_write_b32 v214, v212 offset:4096
	s_mov_b64 exec, -1
	s_branch .Lrk0_c40
; __device__ __forceinline__ void ph_peer_select(const Params& P, int layer, const h16* Q, int nrows, char* smem) {
;     ...
;     for (int i = tid; i < 64 * 50; i += NTHR) {
;       const int tok = i / 50, c = i % 50;
;       const float v = cd[tok * 52 + c];
;       int rank = 0;
;       for (int j = 0; j < 50; ++j) { const float o = cd[tok * 52 + j]; rank += (o > v || (o == v && j < c)) ? 1 : 0; }
;       if (rank < TOPK) { tv[tok * 16 + rank] = v; tp[tok * 16 + rank] = c; }
;     }
.Lrk0_c33:
	v_mov_b32_e32 v212, 0
	v_cmp_ge_f32_e64 s[22:23], v160, v193
	v_cmp_ge_f32_e64 s[24:25], v161, v193
	v_cmp_ge_f32_e64 s[26:27], v162, v193
	v_cmp_ge_f32_e64 s[28:29], v163, v193
	v_addc_co_u32_e64 v212, s[30:31], v212, 0, s[22:23]
	v_addc_co_u32_e64 v212, s[30:31], v212, 0, s[24:25]
	v_addc_co_u32_e64 v212, s[30:31], v212, 0, s[26:27]
	v_addc_co_u32_e64 v212, s[30:31], v212, 0, s[28:29]
	v_cmp_ge_f32_e64 s[22:23], v164, v193
	v_cmp_ge_f32_e64 s[24:25], v165, v193
	v_cmp_ge_f32_e64 s[26:27], v166, v193
	v_cmp_ge_f32_e64 s[28:29], v167, v193
	v_addc_co_u32_e64 v212, s[30:31], v212, 0, s[22:23]
	v_addc_co_u32_e64 v212, s[30:31], v212, 0, s[24:25]
	v_addc_co_u32_e64 v212, s[30:31], v212, 0, s[26:27]
	v_addc_co_u32_e64 v212, s[30:31], v212, 0, s[28:29]
	v_cmp_ge_f32_e64 s[22:23], v168, v193
	v_cmp_ge_f32_e64 s[24:25], v169, v193
	v_cmp_ge_f32_e64 s[26:27], v170, v193
	v_cmp_ge_f32_e64 s[28:29], v171, v193
	v_addc_co_u32_e64 v212, s[30:31], v212, 0, s[22:23]
	v_addc_co_u32_e64 v212, s[30:31], v212, 0, s[24:25]
	v_addc_co_u32_e64 v212, s[30:31], v212, 0, s[26:27]
	v_addc_co_u32_e64 v212, s[30:31], v212, 0, s[28:29]
	v_cmp_ge_f32_e64 s[22:23], v172, v193
	v_cmp_ge_f32_e64 s[24:25], v173, v193
	v_cmp_ge_f32_e64 s[26:27], v174, v193
	v_cmp_ge_f32_e64 s[28:29], v175, v193
	v_addc_co_u32_e64 v212, s[30:31], v212, 0, s[22:23]
	v_addc_co_u32_e64 v212, s[30:31], v212, 0, s[24:25]
	v_addc_co_u32_e64 v212, s[30:31], v212, 0, s[26:27]
	v_addc_co_u32_e64 v212, s[30:31], v212, 0, s[28:29]
	v_cmp_ge_f32_e64 s[22:23], v176, v193
	v_cmp_ge_f32_e64 s[24:25], v177, v193
	v_cmp_ge_f32_e64 s[26:27], v178, v193
	v_cmp_ge_f32_e64 s[28:29], v179, v193
	v_addc_co_u32_e64 v212, s[30:31], v212, 0, s[22:23]
	v_addc_co_u32_e64 v212, s[30:31], v212, 0, s[24:25]
	v_addc_co_u32_e64 v212, s[30:31], v212, 0, s[26:27]
	v_addc_co_u32_e64 v212, s[30:31], v212, 0, s[28:29]
	v_cmp_ge_f32_e64 s[22:23], v180, v193
	v_cmp_ge_f32_e64 s[24:25], v181, v193
	v_cmp_ge_f32_e64 s[26:27], v182, v193
	v_cmp_ge_f32_e64 s[28:29], v183, v193
	v_addc_co_u32_e64 v212, s[30:31], v212, 0, s[22:23]
	v_addc_co_u32_e64 v212, s[30:31], v212, 0, s[24:25]
	v_addc_co_u32_e64 v212, s[30:31], v212, 0, s[26:27]
	v_addc_co_u32_e64 v212, s[30:31], v212, 0, s[28:29]
	v_cmp_ge_f32_e64 s[22:23], v184, v193
	v_cmp_ge_f32_e64 s[24:25], v185, v193
	v_cmp_ge_f32_e64 s[26:27], v186, v193
	v_cmp_ge_f32_e64 s[28:29], v187, v193
	v_addc_co_u32_e64 v212, s[30:31], v212, 0, s[22:23]
	v_addc_co_u32_e64 v212, s[30:31], v212, 0, s[24:25]
	v_addc_co_u32_e64 v212, s[30:31], v212, 0, s[26:27]
	v_addc_co_u32_e64 v212, s[30:31], v212, 0, s[28:29]
	v_cmp_ge_f32_e64 s[22:23], v188, v193
	v_cmp_ge_f32_e64 s[24:25], v189, v193
	v_cmp_ge_f32_e64 s[26:27], v190, v193
	v_cmp_ge_f32_e64 s[28:29], v191, v193
	v_addc_co_u32_e64 v212, s[30:31], v212, 0, s[22:23]
	v_addc_co_u32_e64 v212, s[30:31], v212, 0, s[24:25]
	v_addc_co_u32_e64 v212, s[30:31], v212, 0, s[26:27]
	v_addc_co_u32_e64 v212, s[30:31], v212, 0, s[28:29]
	v_cmp_ge_f32_e64 s[22:23], v192, v193
	v_cmp_gt_f32_e64 s[24:25], v194, v193
	v_cmp_gt_f32_e64 s[26:27], v195, v193
	v_cmp_gt_f32_e64 s[28:29], v196, v193
	v_addc_co_u32_e64 v212, s[30:31], v212, 0, s[22:23]
	v_addc_co_u32_e64 v212, s[30:31], v212, 0, s[24:25]
	v_addc_co_u32_e64 v212, s[30:31], v212, 0, s[26:27]
	v_addc_co_u32_e64 v212, s[30:31], v212, 0, s[28:29]
	v_cmp_gt_f32_e64 s[22:23], v197, v193
	v_cmp_gt_f32_e64 s[24:25], v198, v193
	v_cmp_gt_f32_e64 s[26:27], v199, v193
	v_cmp_gt_f32_e64 s[28:29], v200, v193
	v_addc_co_u32_e64 v212, s[30:31], v212, 0, s[22:23]
	v_addc_co_u32_e64 v212, s[30:31], v212, 0, s[24:25]
	v_addc_co_u32_e64 v212, s[30:31], v212, 0, s[26:27]
	v_addc_co_u32_e64 v212, s[30:31], v212, 0, s[28:29]
	v_cmp_gt_f32_e64 s[22:23], v201, v193
	v_cmp_gt_f32_e64 s[24:25], v202, v193
	v_cmp_gt_f32_e64 s[26:27], v203, v193
	v_cmp_gt_f32_e64 s[28:29], v204, v193
	v_addc_co_u32_e64 v212, s[30:31], v212, 0, s[22:23]
	v_addc_co_u32_e64 v212, s[30:31], v212, 0, s[24:25]
	v_addc_co_u32_e64 v212, s[30:31], v212, 0, s[26:27]
	v_addc_co_u32_e64 v212, s[30:31], v212, 0, s[28:29]
	v_cmp_gt_f32_e64 s[22:23], v205, v193
	v_cmp_gt_f32_e64 s[24:25], v206, v193
	v_cmp_gt_f32_e64 s[26:27], v207, v193
	v_cmp_gt_f32_e64 s[28:29], v208, v193
	v_addc_co_u32_e64 v212, s[30:31], v212, 0, s[22:23]
	v_addc_co_u32_e64 v212, s[30:31], v212, 0, s[24:25]
	v_addc_co_u32_e64 v212, s[30:31], v212, 0, s[26:27]
	v_addc_co_u32_e64 v212, s[30:31], v212, 0, s[28:29]
	v_cmp_gt_f32_e64 s[22:23], v209, v193
	s_nop 0
	s_nop 0
	v_addc_co_u32_e64 v212, s[30:31], v212, 0, s[22:23]
	v_cmp_gt_u32_e32 vcc, 16, v212
	s_and_saveexec_b64 s[40:41], vcc
	v_lshl_add_u32 v214, v212, 2, v213
	v_mov_b32_e32 v212, 33
	ds_write_b32 v214, v193
	ds_write_b32 v214, v212 offset:4096
	s_mov_b64 exec, -1
	s_branch .Lrk0_c41
; __device__ __forceinline__ void ph_peer_select(const Params& P, int layer, const h16* Q, int nrows, char* smem) {
;     ...
;     for (int i = tid; i < 64 * 50; i += NTHR) {
;       const int tok = i / 50, c = i % 50;
;       const float v = cd[tok * 52 + c];
;       int rank = 0;
;       for (int j = 0; j < 50; ++j) { const float o = cd[tok * 52 + j]; rank += (o > v || (o == v && j < c)) ? 1 : 0; }
;       if (rank < TOPK) { tv[tok * 16 + rank] = v; tp[tok * 16 + rank] = c; }
;     }
.Lrk0_c34:
	v_mov_b32_e32 v212, 0
	v_cmp_ge_f32_e64 s[22:23], v160, v194
	v_cmp_ge_f32_e64 s[24:25], v161, v194
	v_cmp_ge_f32_e64 s[26:27], v162, v194
	v_cmp_ge_f32_e64 s[28:29], v163, v194
	v_addc_co_u32_e64 v212, s[30:31], v212, 0, s[22:23]
	v_addc_co_u32_e64 v212, s[30:31], v212, 0, s[24:25]
	v_addc_co_u32_e64 v212, s[30:31], v212, 0, s[26:27]
	v_addc_co_u32_e64 v212, s[30:31], v212, 0, s[28:29]
	v_cmp_ge_f32_e64 s[22:23], v164, v194
	v_cmp_ge_f32_e64 s[24:25], v165, v194
	v_cmp_ge_f32_e64 s[26:27], v166, v194
	v_cmp_ge_f32_e64 s[28:29], v167, v194
	v_addc_co_u32_e64 v212, s[30:31], v212, 0, s[22:23]
	v_addc_co_u32_e64 v212, s[30:31], v212, 0, s[24:25]
	v_addc_co_u32_e64 v212, s[30:31], v212, 0, s[26:27]
	v_addc_co_u32_e64 v212, s[30:31], v212, 0, s[28:29]
	v_cmp_ge_f32_e64 s[22:23], v168, v194
	v_cmp_ge_f32_e64 s[24:25], v169, v194
	v_cmp_ge_f32_e64 s[26:27], v170, v194
	v_cmp_ge_f32_e64 s[28:29], v171, v194
	v_addc_co_u32_e64 v212, s[30:31], v212, 0, s[22:23]
	v_addc_co_u32_e64 v212, s[30:31], v212, 0, s[24:25]
	v_addc_co_u32_e64 v212, s[30:31], v212, 0, s[26:27]
	v_addc_co_u32_e64 v212, s[30:31], v212, 0, s[28:29]
	v_cmp_ge_f32_e64 s[22:23], v172, v194
	v_cmp_ge_f32_e64 s[24:25], v173, v194
	v_cmp_ge_f32_e64 s[26:27], v174, v194
	v_cmp_ge_f32_e64 s[28:29], v175, v194
	v_addc_co_u32_e64 v212, s[30:31], v212, 0, s[22:23]
	v_addc_co_u32_e64 v212, s[30:31], v212, 0, s[24:25]
	v_addc_co_u32_e64 v212, s[30:31], v212, 0, s[26:27]
	v_addc_co_u32_e64 v212, s[30:31], v212, 0, s[28:29]
	v_cmp_ge_f32_e64 s[22:23], v176, v194
	v_cmp_ge_f32_e64 s[24:25], v177, v194
	v_cmp_ge_f32_e64 s[26:27], v178, v194
	v_cmp_ge_f32_e64 s[28:29], v179, v194
	v_addc_co_u32_e64 v212, s[30:31], v212, 0, s[22:23]
	v_addc_co_u32_e64 v212, s[30:31], v212, 0, s[24:25]
	v_addc_co_u32_e64 v212, s[30:31], v212, 0, s[26:27]
	v_addc_co_u32_e64 v212, s[30:31], v212, 0, s[28:29]
	v_cmp_ge_f32_e64 s[22:23], v180, v194
	v_cmp_ge_f32_e64 s[24:25], v181, v194
	v_cmp_ge_f32_e64 s[26:27], v182, v194
	v_cmp_ge_f32_e64 s[28:29], v183, v194
	v_addc_co_u32_e64 v212, s[30:31], v212, 0, s[22:23]
	v_addc_co_u32_e64 v212, s[30:31], v212, 0, s[24:25]
	v_addc_co_u32_e64 v212, s[30:31], v212, 0, s[26:27]
	v_addc_co_u32_e64 v212, s[30:31], v212, 0, s[28:29]
	v_cmp_ge_f32_e64 s[22:23], v184, v194
	v_cmp_ge_f32_e64 s[24:25], v185, v194
	v_cmp_ge_f32_e64 s[26:27], v186, v194
	v_cmp_ge_f32_e64 s[28:29], v187, v194
	v_addc_co_u32_e64 v212, s[30:31], v212, 0, s[22:23]
	v_addc_co_u32_e64 v212, s[30:31], v212, 0, s[24:25]
	v_addc_co_u32_e64 v212, s[30:31], v212, 0, s[26:27]
	v_addc_co_u32_e64 v212, s[30:31], v212, 0, s[28:29]
	v_cmp_ge_f32_e64 s[22:23], v188, v194
	v_cmp_ge_f32_e64 s[24:25], v189, v194
	v_cmp_ge_f32_e64 s[26:27], v190, v194
	v_cmp_ge_f32_e64 s[28:29], v191, v194
	v_addc_co_u32_e64 v212, s[30:31], v212, 0, s[22:23]
	v_addc_co_u32_e64 v212, s[30:31], v212, 0, s[24:25]
	v_addc_co_u32_e64 v212, s[30:31], v212, 0, s[26:27]
	v_addc_co_u32_e64 v212, s[30:31], v212, 0, s[28:29]
	v_cmp_ge_f32_e64 s[22:23], v192, v194
	v_cmp_ge_f32_e64 s[24:25], v193, v194
	v_cmp_gt_f32_e64 s[26:27], v195, v194
	v_cmp_gt_f32_e64 s[28:29], v196, v194
	v_addc_co_u32_e64 v212, s[30:31], v212, 0, s[22:23]
	v_addc_co_u32_e64 v212, s[30:31], v212, 0, s[24:25]
	v_addc_co_u32_e64 v212, s[30:31], v212, 0, s[26:27]
	v_addc_co_u32_e64 v212, s[30:31], v212, 0, s[28:29]
	v_cmp_gt_f32_e64 s[22:23], v197, v194
	v_cmp_gt_f32_e64 s[24:25], v198, v194
	v_cmp_gt_f32_e64 s[26:27], v199, v194
	v_cmp_gt_f32_e64 s[28:29], v200, v194
	v_addc_co_u32_e64 v212, s[30:31], v212, 0, s[22:23]
	v_addc_co_u32_e64 v212, s[30:31], v212, 0, s[24:25]
	v_addc_co_u32_e64 v212, s[30:31], v212, 0, s[26:27]
	v_addc_co_u32_e64 v212, s[30:31], v212, 0, s[28:29]
	v_cmp_gt_f32_e64 s[22:23], v201, v194
	v_cmp_gt_f32_e64 s[24:25], v202, v194
	v_cmp_gt_f32_e64 s[26:27], v203, v194
	v_cmp_gt_f32_e64 s[28:29], v204, v194
	v_addc_co_u32_e64 v212, s[30:31], v212, 0, s[22:23]
	v_addc_co_u32_e64 v212, s[30:31], v212, 0, s[24:25]
	v_addc_co_u32_e64 v212, s[30:31], v212, 0, s[26:27]
	v_addc_co_u32_e64 v212, s[30:31], v212, 0, s[28:29]
	v_cmp_gt_f32_e64 s[22:23], v205, v194
	v_cmp_gt_f32_e64 s[24:25], v206, v194
	v_cmp_gt_f32_e64 s[26:27], v207, v194
	v_cmp_gt_f32_e64 s[28:29], v208, v194
	v_addc_co_u32_e64 v212, s[30:31], v212, 0, s[22:23]
	v_addc_co_u32_e64 v212, s[30:31], v212, 0, s[24:25]
	v_addc_co_u32_e64 v212, s[30:31], v212, 0, s[26:27]
	v_addc_co_u32_e64 v212, s[30:31], v212, 0, s[28:29]
	v_cmp_gt_f32_e64 s[22:23], v209, v194
	s_nop 0
	s_nop 0
	v_addc_co_u32_e64 v212, s[30:31], v212, 0, s[22:23]
	v_cmp_gt_u32_e32 vcc, 16, v212
	s_and_saveexec_b64 s[40:41], vcc
	v_lshl_add_u32 v214, v212, 2, v213
	v_mov_b32_e32 v212, 34
	ds_write_b32 v214, v194
	ds_write_b32 v214, v212 offset:4096
	s_mov_b64 exec, -1
	s_branch .Lrk0_c42
; __device__ __forceinline__ void ph_peer_select(const Params& P, int layer, const h16* Q, int nrows, char* smem) {
;     ...
;     for (int i = tid; i < 64 * 50; i += NTHR) {
;       const int tok = i / 50, c = i % 50;
;       const float v = cd[tok * 52 + c];
;       int rank = 0;
;       for (int j = 0; j < 50; ++j) { const float o = cd[tok * 52 + j]; rank += (o > v || (o == v && j < c)) ? 1 : 0; }
;       if (rank < TOPK) { tv[tok * 16 + rank] = v; tp[tok * 16 + rank] = c; }
;     }
.Lrk0_c35:
	v_mov_b32_e32 v212, 0
	v_cmp_ge_f32_e64 s[22:23], v160, v195
	v_cmp_ge_f32_e64 s[24:25], v161, v195
	v_cmp_ge_f32_e64 s[26:27], v162, v195
	v_cmp_ge_f32_e64 s[28:29], v163, v195
	v_addc_co_u32_e64 v212, s[30:31], v212, 0, s[22:23]
	v_addc_co_u32_e64 v212, s[30:31], v212, 0, s[24:25]
	v_addc_co_u32_e64 v212, s[30:31], v212, 0, s[26:27]
	v_addc_co_u32_e64 v212, s[30:31], v212, 0, s[28:29]
	v_cmp_ge_f32_e64 s[22:23], v164, v195
	v_cmp_ge_f32_e64 s[24:25], v165, v195
	v_cmp_ge_f32_e64 s[26:27], v166, v195
	v_cmp_ge_f32_e64 s[28:29], v167, v195
	v_addc_co_u32_e64 v212, s[30:31], v212, 0, s[22:23]
	v_addc_co_u32_e64 v212, s[30:31], v212, 0, s[24:25]
	v_addc_co_u32_e64 v212, s[30:31], v212, 0, s[26:27]
	v_addc_co_u32_e64 v212, s[30:31], v212, 0, s[28:29]
	v_cmp_ge_f32_e64 s[22:23], v168, v195
	v_cmp_ge_f32_e64 s[24:25], v169, v195
	v_cmp_ge_f32_e64 s[26:27], v170, v195
	v_cmp_ge_f32_e64 s[28:29], v171, v195
	v_addc_co_u32_e64 v212, s[30:31], v212, 0, s[22:23]
	v_addc_co_u32_e64 v212, s[30:31], v212, 0, s[24:25]
	v_addc_co_u32_e64 v212, s[30:31], v212, 0, s[26:27]
	v_addc_co_u32_e64 v212, s[30:31], v212, 0, s[28:29]
	v_cmp_ge_f32_e64 s[22:23], v172, v195
	v_cmp_ge_f32_e64 s[24:25], v173, v195
	v_cmp_ge_f32_e64 s[26:27], v174, v195
	v_cmp_ge_f32_e64 s[28:29], v175, v195
	v_addc_co_u32_e64 v212, s[30:31], v212, 0, s[22:23]
	v_addc_co_u32_e64 v212, s[30:31], v212, 0, s[24:25]
	v_addc_co_u32_e64 v212, s[30:31], v212, 0, s[26:27]
	v_addc_co_u32_e64 v212, s[30:31], v212, 0, s[28:29]
	v_cmp_ge_f32_e64 s[22:23], v176, v195
	v_cmp_ge_f32_e64 s[24:25], v177, v195
	v_cmp_ge_f32_e64 s[26:27], v178, v195
	v_cmp_ge_f32_e64 s[28:29], v179, v195
	v_addc_co_u32_e64 v212, s[30:31], v212, 0, s[22:23]
	v_addc_co_u32_e64 v212, s[30:31], v212, 0, s[24:25]
	v_addc_co_u32_e64 v212, s[30:31], v212, 0, s[26:27]
	v_addc_co_u32_e64 v212, s[30:31], v212, 0, s[28:29]
	v_cmp_ge_f32_e64 s[22:23], v180, v195
	v_cmp_ge_f32_e64 s[24:25], v181, v195
	v_cmp_ge_f32_e64 s[26:27], v182, v195
	v_cmp_ge_f32_e64 s[28:29], v183, v195
	v_addc_co_u32_e64 v212, s[30:31], v212, 0, s[22:23]
	v_addc_co_u32_e64 v212, s[30:31], v212, 0, s[24:25]
	v_addc_co_u32_e64 v212, s[30:31], v212, 0, s[26:27]
	v_addc_co_u32_e64 v212, s[30:31], v212, 0, s[28:29]
	v_cmp_ge_f32_e64 s[22:23], v184, v195
	v_cmp_ge_f32_e64 s[24:25], v185, v195
	v_cmp_ge_f32_e64 s[26:27], v186, v195
	v_cmp_ge_f32_e64 s[28:29], v187, v195
	v_addc_co_u32_e64 v212, s[30:31], v212, 0, s[22:23]
	v_addc_co_u32_e64 v212, s[30:31], v212, 0, s[24:25]
	v_addc_co_u32_e64 v212, s[30:31], v212, 0, s[26:27]
	v_addc_co_u32_e64 v212, s[30:31], v212, 0, s[28:29]
	v_cmp_ge_f32_e64 s[22:23], v188, v195
	v_cmp_ge_f32_e64 s[24:25], v189, v195
	v_cmp_ge_f32_e64 s[26:27], v190, v195
	v_cmp_ge_f32_e64 s[28:29], v191, v195
	v_addc_co_u32_e64 v212, s[30:31], v212, 0, s[22:23]
	v_addc_co_u32_e64 v212, s[30:31], v212, 0, s[24:25]
	v_addc_co_u32_e64 v212, s[30:31], v212, 0, s[26:27]
	v_addc_co_u32_e64 v212, s[30:31], v212, 0, s[28:29]
	v_cmp_ge_f32_e64 s[22:23], v192, v195
	v_cmp_ge_f32_e64 s[24:25], v193, v195
	v_cmp_ge_f32_e64 s[26:27], v194, v195
	v_cmp_gt_f32_e64 s[28:29], v196, v195
	v_addc_co_u32_e64 v212, s[30:31], v212, 0, s[22:23]
	v_addc_co_u32_e64 v212, s[30:31], v212, 0, s[24:25]
	v_addc_co_u32_e64 v212, s[30:31], v212, 0, s[26:27]
	v_addc_co_u32_e64 v212, s[30:31], v212, 0, s[28:29]
	v_cmp_gt_f32_e64 s[22:23], v197, v195
	v_cmp_gt_f32_e64 s[24:25], v198, v195
	v_cmp_gt_f32_e64 s[26:27], v199, v195
	v_cmp_gt_f32_e64 s[28:29], v200, v195
	v_addc_co_u32_e64 v212, s[30:31], v212, 0, s[22:23]
	v_addc_co_u32_e64 v212, s[30:31], v212, 0, s[24:25]
	v_addc_co_u32_e64 v212, s[30:31], v212, 0, s[26:27]
	v_addc_co_u32_e64 v212, s[30:31], v212, 0, s[28:29]
	v_cmp_gt_f32_e64 s[22:23], v201, v195
	v_cmp_gt_f32_e64 s[24:25], v202, v195
	v_cmp_gt_f32_e64 s[26:27], v203, v195
	v_cmp_gt_f32_e64 s[28:29], v204, v195
	v_addc_co_u32_e64 v212, s[30:31], v212, 0, s[22:23]
	v_addc_co_u32_e64 v212, s[30:31], v212, 0, s[24:25]
	v_addc_co_u32_e64 v212, s[30:31], v212, 0, s[26:27]
	v_addc_co_u32_e64 v212, s[30:31], v212, 0, s[28:29]
	v_cmp_gt_f32_e64 s[22:23], v205, v195
	v_cmp_gt_f32_e64 s[24:25], v206, v195
	v_cmp_gt_f32_e64 s[26:27], v207, v195
	v_cmp_gt_f32_e64 s[28:29], v208, v195
	v_addc_co_u32_e64 v212, s[30:31], v212, 0, s[22:23]
	v_addc_co_u32_e64 v212, s[30:31], v212, 0, s[24:25]
	v_addc_co_u32_e64 v212, s[30:31], v212, 0, s[26:27]
	v_addc_co_u32_e64 v212, s[30:31], v212, 0, s[28:29]
	v_cmp_gt_f32_e64 s[22:23], v209, v195
	s_nop 0
	s_nop 0
	v_addc_co_u32_e64 v212, s[30:31], v212, 0, s[22:23]
	v_cmp_gt_u32_e32 vcc, 16, v212
	s_and_saveexec_b64 s[40:41], vcc
	v_lshl_add_u32 v214, v212, 2, v213
	v_mov_b32_e32 v212, 35
	ds_write_b32 v214, v195
	ds_write_b32 v214, v212 offset:4096
	s_mov_b64 exec, -1
	s_branch .Lrk0_c43
; __device__ __forceinline__ void ph_peer_select(const Params& P, int layer, const h16* Q, int nrows, char* smem) {
;     ...
;     for (int i = tid; i < 64 * 50; i += NTHR) {
;       const int tok = i / 50, c = i % 50;
;       const float v = cd[tok * 52 + c];
;       int rank = 0;
;       for (int j = 0; j < 50; ++j) { const float o = cd[tok * 52 + j]; rank += (o > v || (o == v && j < c)) ? 1 : 0; }
;       if (rank < TOPK) { tv[tok * 16 + rank] = v; tp[tok * 16 + rank] = c; }
;     }
.Lrk0_c36:
	v_mov_b32_e32 v212, 0
	v_cmp_ge_f32_e64 s[22:23], v160, v196
	v_cmp_ge_f32_e64 s[24:25], v161, v196
	v_cmp_ge_f32_e64 s[26:27], v162, v196
	v_cmp_ge_f32_e64 s[28:29], v163, v196
	v_addc_co_u32_e64 v212, s[30:31], v212, 0, s[22:23]
	v_addc_co_u32_e64 v212, s[30:31], v212, 0, s[24:25]
	v_addc_co_u32_e64 v212, s[30:31], v212, 0, s[26:27]
	v_addc_co_u32_e64 v212, s[30:31], v212, 0, s[28:29]
	v_cmp_ge_f32_e64 s[22:23], v164, v196
	v_cmp_ge_f32_e64 s[24:25], v165, v196
	v_cmp_ge_f32_e64 s[26:27], v166, v196
	v_cmp_ge_f32_e64 s[28:29], v167, v196
	v_addc_co_u32_e64 v212, s[30:31], v212, 0, s[22:23]
	v_addc_co_u32_e64 v212, s[30:31], v212, 0, s[24:25]
	v_addc_co_u32_e64 v212, s[30:31], v212, 0, s[26:27]
	v_addc_co_u32_e64 v212, s[30:31], v212, 0, s[28:29]
	v_cmp_ge_f32_e64 s[22:23], v168, v196
	v_cmp_ge_f32_e64 s[24:25], v169, v196
	v_cmp_ge_f32_e64 s[26:27], v170, v196
	v_cmp_ge_f32_e64 s[28:29], v171, v196
	v_addc_co_u32_e64 v212, s[30:31], v212, 0, s[22:23]
	v_addc_co_u32_e64 v212, s[30:31], v212, 0, s[24:25]
	v_addc_co_u32_e64 v212, s[30:31], v212, 0, s[26:27]
	v_addc_co_u32_e64 v212, s[30:31], v212, 0, s[28:29]
	v_cmp_ge_f32_e64 s[22:23], v172, v196
	v_cmp_ge_f32_e64 s[24:25], v173, v196
	v_cmp_ge_f32_e64 s[26:27], v174, v196
	v_cmp_ge_f32_e64 s[28:29], v175, v196
	v_addc_co_u32_e64 v212, s[30:31], v212, 0, s[22:23]
	v_addc_co_u32_e64 v212, s[30:31], v212, 0, s[24:25]
	v_addc_co_u32_e64 v212, s[30:31], v212, 0, s[26:27]
	v_addc_co_u32_e64 v212, s[30:31], v212, 0, s[28:29]
	v_cmp_ge_f32_e64 s[22:23], v176, v196
	v_cmp_ge_f32_e64 s[24:25], v177, v196
	v_cmp_ge_f32_e64 s[26:27], v178, v196
	v_cmp_ge_f32_e64 s[28:29], v179, v196
	v_addc_co_u32_e64 v212, s[30:31], v212, 0, s[22:23]
	v_addc_co_u32_e64 v212, s[30:31], v212, 0, s[24:25]
	v_addc_co_u32_e64 v212, s[30:31], v212, 0, s[26:27]
	v_addc_co_u32_e64 v212, s[30:31], v212, 0, s[28:29]
	v_cmp_ge_f32_e64 s[22:23], v180, v196
	v_cmp_ge_f32_e64 s[24:25], v181, v196
	v_cmp_ge_f32_e64 s[26:27], v182, v196
	v_cmp_ge_f32_e64 s[28:29], v183, v196
	v_addc_co_u32_e64 v212, s[30:31], v212, 0, s[22:23]
	v_addc_co_u32_e64 v212, s[30:31], v212, 0, s[24:25]
	v_addc_co_u32_e64 v212, s[30:31], v212, 0, s[26:27]
	v_addc_co_u32_e64 v212, s[30:31], v212, 0, s[28:29]
	v_cmp_ge_f32_e64 s[22:23], v184, v196
	v_cmp_ge_f32_e64 s[24:25], v185, v196
	v_cmp_ge_f32_e64 s[26:27], v186, v196
	v_cmp_ge_f32_e64 s[28:29], v187, v196
	v_addc_co_u32_e64 v212, s[30:31], v212, 0, s[22:23]
	v_addc_co_u32_e64 v212, s[30:31], v212, 0, s[24:25]
	v_addc_co_u32_e64 v212, s[30:31], v212, 0, s[26:27]
	v_addc_co_u32_e64 v212, s[30:31], v212, 0, s[28:29]
	v_cmp_ge_f32_e64 s[22:23], v188, v196
	v_cmp_ge_f32_e64 s[24:25], v189, v196
	v_cmp_ge_f32_e64 s[26:27], v190, v196
	v_cmp_ge_f32_e64 s[28:29], v191, v196
	v_addc_co_u32_e64 v212, s[30:31], v212, 0, s[22:23]
	v_addc_co_u32_e64 v212, s[30:31], v212, 0, s[24:25]
	v_addc_co_u32_e64 v212, s[30:31], v212, 0, s[26:27]
	v_addc_co_u32_e64 v212, s[30:31], v212, 0, s[28:29]
	v_cmp_ge_f32_e64 s[22:23], v192, v196
	v_cmp_ge_f32_e64 s[24:25], v193, v196
	v_cmp_ge_f32_e64 s[26:27], v194, v196
	v_cmp_ge_f32_e64 s[28:29], v195, v196
	v_addc_co_u32_e64 v212, s[30:31], v212, 0, s[22:23]
	v_addc_co_u32_e64 v212, s[30:31], v212, 0, s[24:25]
	v_addc_co_u32_e64 v212, s[30:31], v212, 0, s[26:27]
	v_addc_co_u32_e64 v212, s[30:31], v212, 0, s[28:29]
	v_cmp_gt_f32_e64 s[22:23], v197, v196
	v_cmp_gt_f32_e64 s[24:25], v198, v196
	v_cmp_gt_f32_e64 s[26:27], v199, v196
	v_cmp_gt_f32_e64 s[28:29], v200, v196
	v_addc_co_u32_e64 v212, s[30:31], v212, 0, s[22:23]
	v_addc_co_u32_e64 v212, s[30:31], v212, 0, s[24:25]
	v_addc_co_u32_e64 v212, s[30:31], v212, 0, s[26:27]
	v_addc_co_u32_e64 v212, s[30:31], v212, 0, s[28:29]
	v_cmp_gt_f32_e64 s[22:23], v201, v196
	v_cmp_gt_f32_e64 s[24:25], v202, v196
	v_cmp_gt_f32_e64 s[26:27], v203, v196
	v_cmp_gt_f32_e64 s[28:29], v204, v196
	v_addc_co_u32_e64 v212, s[30:31], v212, 0, s[22:23]
	v_addc_co_u32_e64 v212, s[30:31], v212, 0, s[24:25]
	v_addc_co_u32_e64 v212, s[30:31], v212, 0, s[26:27]
	v_addc_co_u32_e64 v212, s[30:31], v212, 0, s[28:29]
	v_cmp_gt_f32_e64 s[22:23], v205, v196
	v_cmp_gt_f32_e64 s[24:25], v206, v196
	v_cmp_gt_f32_e64 s[26:27], v207, v196
	v_cmp_gt_f32_e64 s[28:29], v208, v196
	v_addc_co_u32_e64 v212, s[30:31], v212, 0, s[22:23]
	v_addc_co_u32_e64 v212, s[30:31], v212, 0, s[24:25]
	v_addc_co_u32_e64 v212, s[30:31], v212, 0, s[26:27]
	v_addc_co_u32_e64 v212, s[30:31], v212, 0, s[28:29]
	v_cmp_gt_f32_e64 s[22:23], v209, v196
	s_nop 0
	s_nop 0
	v_addc_co_u32_e64 v212, s[30:31], v212, 0, s[22:23]
	v_cmp_gt_u32_e32 vcc, 16, v212
	s_and_saveexec_b64 s[40:41], vcc
	v_lshl_add_u32 v214, v212, 2, v213
	v_mov_b32_e32 v212, 36
	ds_write_b32 v214, v196
	ds_write_b32 v214, v212 offset:4096
	s_mov_b64 exec, -1
	s_branch .Lrk0_c44
; __device__ __forceinline__ void ph_peer_select(const Params& P, int layer, const h16* Q, int nrows, char* smem) {
;     ...
;     for (int i = tid; i < 64 * 50; i += NTHR) {
;       const int tok = i / 50, c = i % 50;
;       const float v = cd[tok * 52 + c];
;       int rank = 0;
;       for (int j = 0; j < 50; ++j) { const float o = cd[tok * 52 + j]; rank += (o > v || (o == v && j < c)) ? 1 : 0; }
;       if (rank < TOPK) { tv[tok * 16 + rank] = v; tp[tok * 16 + rank] = c; }
;     }
.Lrk0_c37:
	v_mov_b32_e32 v212, 0
	v_cmp_ge_f32_e64 s[22:23], v160, v197
	v_cmp_ge_f32_e64 s[24:25], v161, v197
	v_cmp_ge_f32_e64 s[26:27], v162, v197
	v_cmp_ge_f32_e64 s[28:29], v163, v197
	v_addc_co_u32_e64 v212, s[30:31], v212, 0, s[22:23]
	v_addc_co_u32_e64 v212, s[30:31], v212, 0, s[24:25]
	v_addc_co_u32_e64 v212, s[30:31], v212, 0, s[26:27]
	v_addc_co_u32_e64 v212, s[30:31], v212, 0, s[28:29]
	v_cmp_ge_f32_e64 s[22:23], v164, v197
	v_cmp_ge_f32_e64 s[24:25], v165, v197
	v_cmp_ge_f32_e64 s[26:27], v166, v197
	v_cmp_ge_f32_e64 s[28:29], v167, v197
	v_addc_co_u32_e64 v212, s[30:31], v212, 0, s[22:23]
	v_addc_co_u32_e64 v212, s[30:31], v212, 0, s[24:25]
	v_addc_co_u32_e64 v212, s[30:31], v212, 0, s[26:27]
	v_addc_co_u32_e64 v212, s[30:31], v212, 0, s[28:29]
	v_cmp_ge_f32_e64 s[22:23], v168, v197
	v_cmp_ge_f32_e64 s[24:25], v169, v197
	v_cmp_ge_f32_e64 s[26:27], v170, v197
	v_cmp_ge_f32_e64 s[28:29], v171, v197
	v_addc_co_u32_e64 v212, s[30:31], v212, 0, s[22:23]
	v_addc_co_u32_e64 v212, s[30:31], v212, 0, s[24:25]
	v_addc_co_u32_e64 v212, s[30:31], v212, 0, s[26:27]
	v_addc_co_u32_e64 v212, s[30:31], v212, 0, s[28:29]
	v_cmp_ge_f32_e64 s[22:23], v172, v197
	v_cmp_ge_f32_e64 s[24:25], v173, v197
	v_cmp_ge_f32_e64 s[26:27], v174, v197
	v_cmp_ge_f32_e64 s[28:29], v175, v197
	v_addc_co_u32_e64 v212, s[30:31], v212, 0, s[22:23]
	v_addc_co_u32_e64 v212, s[30:31], v212, 0, s[24:25]
	v_addc_co_u32_e64 v212, s[30:31], v212, 0, s[26:27]
	v_addc_co_u32_e64 v212, s[30:31], v212, 0, s[28:29]
	v_cmp_ge_f32_e64 s[22:23], v176, v197
	v_cmp_ge_f32_e64 s[24:25], v177, v197
	v_cmp_ge_f32_e64 s[26:27], v178, v197
	v_cmp_ge_f32_e64 s[28:29], v179, v197
	v_addc_co_u32_e64 v212, s[30:31], v212, 0, s[22:23]
	v_addc_co_u32_e64 v212, s[30:31], v212, 0, s[24:25]
	v_addc_co_u32_e64 v212, s[30:31], v212, 0, s[26:27]
	v_addc_co_u32_e64 v212, s[30:31], v212, 0, s[28:29]
	v_cmp_ge_f32_e64 s[22:23], v180, v197
	v_cmp_ge_f32_e64 s[24:25], v181, v197
	v_cmp_ge_f32_e64 s[26:27], v182, v197
	v_cmp_ge_f32_e64 s[28:29], v183, v197
	v_addc_co_u32_e64 v212, s[30:31], v212, 0, s[22:23]
	v_addc_co_u32_e64 v212, s[30:31], v212, 0, s[24:25]
	v_addc_co_u32_e64 v212, s[30:31], v212, 0, s[26:27]
	v_addc_co_u32_e64 v212, s[30:31], v212, 0, s[28:29]
	v_cmp_ge_f32_e64 s[22:23], v184, v197
	v_cmp_ge_f32_e64 s[24:25], v185, v197
	v_cmp_ge_f32_e64 s[26:27], v186, v197
	v_cmp_ge_f32_e64 s[28:29], v187, v197
	v_addc_co_u32_e64 v212, s[30:31], v212, 0, s[22:23]
	v_addc_co_u32_e64 v212, s[30:31], v212, 0, s[24:25]
	v_addc_co_u32_e64 v212, s[30:31], v212, 0, s[26:27]
	v_addc_co_u32_e64 v212, s[30:31], v212, 0, s[28:29]
	v_cmp_ge_f32_e64 s[22:23], v188, v197
	v_cmp_ge_f32_e64 s[24:25], v189, v197
	v_cmp_ge_f32_e64 s[26:27], v190, v197
	v_cmp_ge_f32_e64 s[28:29], v191, v197
	v_addc_co_u32_e64 v212, s[30:31], v212, 0, s[22:23]
	v_addc_co_u32_e64 v212, s[30:31], v212, 0, s[24:25]
	v_addc_co_u32_e64 v212, s[30:31], v212, 0, s[26:27]
	v_addc_co_u32_e64 v212, s[30:31], v212, 0, s[28:29]
	v_cmp_ge_f32_e64 s[22:23], v192, v197
	v_cmp_ge_f32_e64 s[24:25], v193, v197
	v_cmp_ge_f32_e64 s[26:27], v194, v197
	v_cmp_ge_f32_e64 s[28:29], v195, v197
	v_addc_co_u32_e64 v212, s[30:31], v212, 0, s[22:23]
	v_addc_co_u32_e64 v212, s[30:31], v212, 0, s[24:25]
	v_addc_co_u32_e64 v212, s[30:31], v212, 0, s[26:27]
	v_addc_co_u32_e64 v212, s[30:31], v212, 0, s[28:29]
	v_cmp_ge_f32_e64 s[22:23], v196, v197
	v_cmp_gt_f32_e64 s[24:25], v198, v197
	v_cmp_gt_f32_e64 s[26:27], v199, v197
	v_cmp_gt_f32_e64 s[28:29], v200, v197
	v_addc_co_u32_e64 v212, s[30:31], v212, 0, s[22:23]
	v_addc_co_u32_e64 v212, s[30:31], v212, 0, s[24:25]
	v_addc_co_u32_e64 v212, s[30:31], v212, 0, s[26:27]
	v_addc_co_u32_e64 v212, s[30:31], v212, 0, s[28:29]
	v_cmp_gt_f32_e64 s[22:23], v201, v197
	v_cmp_gt_f32_e64 s[24:25], v202, v197
	v_cmp_gt_f32_e64 s[26:27], v203, v197
	v_cmp_gt_f32_e64 s[28:29], v204, v197
	v_addc_co_u32_e64 v212, s[30:31], v212, 0, s[22:23]
	v_addc_co_u32_e64 v212, s[30:31], v212, 0, s[24:25]
	v_addc_co_u32_e64 v212, s[30:31], v212, 0, s[26:27]
	v_addc_co_u32_e64 v212, s[30:31], v212, 0, s[28:29]
	v_cmp_gt_f32_e64 s[22:23], v205, v197
	v_cmp_gt_f32_e64 s[24:25], v206, v197
	v_cmp_gt_f32_e64 s[26:27], v207, v197
	v_cmp_gt_f32_e64 s[28:29], v208, v197
	v_addc_co_u32_e64 v212, s[30:31], v212, 0, s[22:23]
	v_addc_co_u32_e64 v212, s[30:31], v212, 0, s[24:25]
	v_addc_co_u32_e64 v212, s[30:31], v212, 0, s[26:27]
	v_addc_co_u32_e64 v212, s[30:31], v212, 0, s[28:29]
	v_cmp_gt_f32_e64 s[22:23], v209, v197
	s_nop 0
	s_nop 0
	v_addc_co_u32_e64 v212, s[30:31], v212, 0, s[22:23]
	v_cmp_gt_u32_e32 vcc, 16, v212
	s_and_saveexec_b64 s[40:41], vcc
	v_lshl_add_u32 v214, v212, 2, v213
	v_mov_b32_e32 v212, 37
	ds_write_b32 v214, v197
	ds_write_b32 v214, v212 offset:4096
	s_mov_b64 exec, -1
	s_branch .Lrk0_c45
; __device__ __forceinline__ void ph_peer_select(const Params& P, int layer, const h16* Q, int nrows, char* smem) {
;     ...
;     for (int i = tid; i < 64 * 50; i += NTHR) {
;       const int tok = i / 50, c = i % 50;
;       const float v = cd[tok * 52 + c];
;       int rank = 0;
;       for (int j = 0; j < 50; ++j) { const float o = cd[tok * 52 + j]; rank += (o > v || (o == v && j < c)) ? 1 : 0; }
;       if (rank < TOPK) { tv[tok * 16 + rank] = v; tp[tok * 16 + rank] = c; }
;     }
.Lrk0_c38:
	v_mov_b32_e32 v212, 0
	v_cmp_ge_f32_e64 s[22:23], v160, v198
	v_cmp_ge_f32_e64 s[24:25], v161, v198
	v_cmp_ge_f32_e64 s[26:27], v162, v198
	v_cmp_ge_f32_e64 s[28:29], v163, v198
	v_addc_co_u32_e64 v212, s[30:31], v212, 0, s[22:23]
	v_addc_co_u32_e64 v212, s[30:31], v212, 0, s[24:25]
	v_addc_co_u32_e64 v212, s[30:31], v212, 0, s[26:27]
	v_addc_co_u32_e64 v212, s[30:31], v212, 0, s[28:29]
	v_cmp_ge_f32_e64 s[22:23], v164, v198
	v_cmp_ge_f32_e64 s[24:25], v165, v198
	v_cmp_ge_f32_e64 s[26:27], v166, v198
	v_cmp_ge_f32_e64 s[28:29], v167, v198
	v_addc_co_u32_e64 v212, s[30:31], v212, 0, s[22:23]
	v_addc_co_u32_e64 v212, s[30:31], v212, 0, s[24:25]
	v_addc_co_u32_e64 v212, s[30:31], v212, 0, s[26:27]
	v_addc_co_u32_e64 v212, s[30:31], v212, 0, s[28:29]
	v_cmp_ge_f32_e64 s[22:23], v168, v198
	v_cmp_ge_f32_e64 s[24:25], v169, v198
	v_cmp_ge_f32_e64 s[26:27], v170, v198
	v_cmp_ge_f32_e64 s[28:29], v171, v198
	v_addc_co_u32_e64 v212, s[30:31], v212, 0, s[22:23]
	v_addc_co_u32_e64 v212, s[30:31], v212, 0, s[24:25]
	v_addc_co_u32_e64 v212, s[30:31], v212, 0, s[26:27]
	v_addc_co_u32_e64 v212, s[30:31], v212, 0, s[28:29]
	v_cmp_ge_f32_e64 s[22:23], v172, v198
	v_cmp_ge_f32_e64 s[24:25], v173, v198
	v_cmp_ge_f32_e64 s[26:27], v174, v198
	v_cmp_ge_f32_e64 s[28:29], v175, v198
	v_addc_co_u32_e64 v212, s[30:31], v212, 0, s[22:23]
	v_addc_co_u32_e64 v212, s[30:31], v212, 0, s[24:25]
	v_addc_co_u32_e64 v212, s[30:31], v212, 0, s[26:27]
	v_addc_co_u32_e64 v212, s[30:31], v212, 0, s[28:29]
	v_cmp_ge_f32_e64 s[22:23], v176, v198
	v_cmp_ge_f32_e64 s[24:25], v177, v198
	v_cmp_ge_f32_e64 s[26:27], v178, v198
	v_cmp_ge_f32_e64 s[28:29], v179, v198
	v_addc_co_u32_e64 v212, s[30:31], v212, 0, s[22:23]
	v_addc_co_u32_e64 v212, s[30:31], v212, 0, s[24:25]
	v_addc_co_u32_e64 v212, s[30:31], v212, 0, s[26:27]
	v_addc_co_u32_e64 v212, s[30:31], v212, 0, s[28:29]
	v_cmp_ge_f32_e64 s[22:23], v180, v198
	v_cmp_ge_f32_e64 s[24:25], v181, v198
	v_cmp_ge_f32_e64 s[26:27], v182, v198
	v_cmp_ge_f32_e64 s[28:29], v183, v198
	v_addc_co_u32_e64 v212, s[30:31], v212, 0, s[22:23]
	v_addc_co_u32_e64 v212, s[30:31], v212, 0, s[24:25]
	v_addc_co_u32_e64 v212, s[30:31], v212, 0, s[26:27]
	v_addc_co_u32_e64 v212, s[30:31], v212, 0, s[28:29]
	v_cmp_ge_f32_e64 s[22:23], v184, v198
	v_cmp_ge_f32_e64 s[24:25], v185, v198
	v_cmp_ge_f32_e64 s[26:27], v186, v198
	v_cmp_ge_f32_e64 s[28:29], v187, v198
	v_addc_co_u32_e64 v212, s[30:31], v212, 0, s[22:23]
	v_addc_co_u32_e64 v212, s[30:31], v212, 0, s[24:25]
	v_addc_co_u32_e64 v212, s[30:31], v212, 0, s[26:27]
	v_addc_co_u32_e64 v212, s[30:31], v212, 0, s[28:29]
	v_cmp_ge_f32_e64 s[22:23], v188, v198
	v_cmp_ge_f32_e64 s[24:25], v189, v198
	v_cmp_ge_f32_e64 s[26:27], v190, v198
	v_cmp_ge_f32_e64 s[28:29], v191, v198
	v_addc_co_u32_e64 v212, s[30:31], v212, 0, s[22:23]
	v_addc_co_u32_e64 v212, s[30:31], v212, 0, s[24:25]
	v_addc_co_u32_e64 v212, s[30:31], v212, 0, s[26:27]
	v_addc_co_u32_e64 v212, s[30:31], v212, 0, s[28:29]
	v_cmp_ge_f32_e64 s[22:23], v192, v198
	v_cmp_ge_f32_e64 s[24:25], v193, v198
	v_cmp_ge_f32_e64 s[26:27], v194, v198
	v_cmp_ge_f32_e64 s[28:29], v195, v198
	v_addc_co_u32_e64 v212, s[30:31], v212, 0, s[22:23]
	v_addc_co_u32_e64 v212, s[30:31], v212, 0, s[24:25]
	v_addc_co_u32_e64 v212, s[30:31], v212, 0, s[26:27]
	v_addc_co_u32_e64 v212, s[30:31], v212, 0, s[28:29]
	v_cmp_ge_f32_e64 s[22:23], v196, v198
	v_cmp_ge_f32_e64 s[24:25], v197, v198
	v_cmp_gt_f32_e64 s[26:27], v199, v198
	v_cmp_gt_f32_e64 s[28:29], v200, v198
	v_addc_co_u32_e64 v212, s[30:31], v212, 0, s[22:23]
	v_addc_co_u32_e64 v212, s[30:31], v212, 0, s[24:25]
	v_addc_co_u32_e64 v212, s[30:31], v212, 0, s[26:27]
	v_addc_co_u32_e64 v212, s[30:31], v212, 0, s[28:29]
	v_cmp_gt_f32_e64 s[22:23], v201, v198
	v_cmp_gt_f32_e64 s[24:25], v202, v198
	v_cmp_gt_f32_e64 s[26:27], v203, v198
	v_cmp_gt_f32_e64 s[28:29], v204, v198
	v_addc_co_u32_e64 v212, s[30:31], v212, 0, s[22:23]
	v_addc_co_u32_e64 v212, s[30:31], v212, 0, s[24:25]
	v_addc_co_u32_e64 v212, s[30:31], v212, 0, s[26:27]
	v_addc_co_u32_e64 v212, s[30:31], v212, 0, s[28:29]
	v_cmp_gt_f32_e64 s[22:23], v205, v198
	v_cmp_gt_f32_e64 s[24:25], v206, v198
	v_cmp_gt_f32_e64 s[26:27], v207, v198
	v_cmp_gt_f32_e64 s[28:29], v208, v198
	v_addc_co_u32_e64 v212, s[30:31], v212, 0, s[22:23]
	v_addc_co_u32_e64 v212, s[30:31], v212, 0, s[24:25]
	v_addc_co_u32_e64 v212, s[30:31], v212, 0, s[26:27]
	v_addc_co_u32_e64 v212, s[30:31], v212, 0, s[28:29]
	v_cmp_gt_f32_e64 s[22:23], v209, v198
	s_nop 0
	s_nop 0
	v_addc_co_u32_e64 v212, s[30:31], v212, 0, s[22:23]
	v_cmp_gt_u32_e32 vcc, 16, v212
	s_and_saveexec_b64 s[40:41], vcc
	v_lshl_add_u32 v214, v212, 2, v213
	v_mov_b32_e32 v212, 38
	ds_write_b32 v214, v198
	ds_write_b32 v214, v212 offset:4096
	s_mov_b64 exec, -1
	s_branch .Lrk0_c46
; __device__ __forceinline__ void ph_peer_select(const Params& P, int layer, const h16* Q, int nrows, char* smem) {
;     ...
;     for (int i = tid; i < 64 * 50; i += NTHR) {
;       const int tok = i / 50, c = i % 50;
;       const float v = cd[tok * 52 + c];
;       int rank = 0;
;       for (int j = 0; j < 50; ++j) { const float o = cd[tok * 52 + j]; rank += (o > v || (o == v && j < c)) ? 1 : 0; }
;       if (rank < TOPK) { tv[tok * 16 + rank] = v; tp[tok * 16 + rank] = c; }
;     }
.Lrk0_c39:
	v_mov_b32_e32 v212, 0
	v_cmp_ge_f32_e64 s[22:23], v160, v199
	v_cmp_ge_f32_e64 s[24:25], v161, v199
	v_cmp_ge_f32_e64 s[26:27], v162, v199
	v_cmp_ge_f32_e64 s[28:29], v163, v199
	v_addc_co_u32_e64 v212, s[30:31], v212, 0, s[22:23]
	v_addc_co_u32_e64 v212, s[30:31], v212, 0, s[24:25]
	v_addc_co_u32_e64 v212, s[30:31], v212, 0, s[26:27]
	v_addc_co_u32_e64 v212, s[30:31], v212, 0, s[28:29]
	v_cmp_ge_f32_e64 s[22:23], v164, v199
	v_cmp_ge_f32_e64 s[24:25], v165, v199
	v_cmp_ge_f32_e64 s[26:27], v166, v199
	v_cmp_ge_f32_e64 s[28:29], v167, v199
	v_addc_co_u32_e64 v212, s[30:31], v212, 0, s[22:23]
	v_addc_co_u32_e64 v212, s[30:31], v212, 0, s[24:25]
	v_addc_co_u32_e64 v212, s[30:31], v212, 0, s[26:27]
	v_addc_co_u32_e64 v212, s[30:31], v212, 0, s[28:29]
	v_cmp_ge_f32_e64 s[22:23], v168, v199
	v_cmp_ge_f32_e64 s[24:25], v169, v199
	v_cmp_ge_f32_e64 s[26:27], v170, v199
	v_cmp_ge_f32_e64 s[28:29], v171, v199
	v_addc_co_u32_e64 v212, s[30:31], v212, 0, s[22:23]
	v_addc_co_u32_e64 v212, s[30:31], v212, 0, s[24:25]
	v_addc_co_u32_e64 v212, s[30:31], v212, 0, s[26:27]
	v_addc_co_u32_e64 v212, s[30:31], v212, 0, s[28:29]
	v_cmp_ge_f32_e64 s[22:23], v172, v199
	v_cmp_ge_f32_e64 s[24:25], v173, v199
	v_cmp_ge_f32_e64 s[26:27], v174, v199
	v_cmp_ge_f32_e64 s[28:29], v175, v199
	v_addc_co_u32_e64 v212, s[30:31], v212, 0, s[22:23]
	v_addc_co_u32_e64 v212, s[30:31], v212, 0, s[24:25]
	v_addc_co_u32_e64 v212, s[30:31], v212, 0, s[26:27]
	v_addc_co_u32_e64 v212, s[30:31], v212, 0, s[28:29]
	v_cmp_ge_f32_e64 s[22:23], v176, v199
	v_cmp_ge_f32_e64 s[24:25], v177, v199
	v_cmp_ge_f32_e64 s[26:27], v178, v199
	v_cmp_ge_f32_e64 s[28:29], v179, v199
	v_addc_co_u32_e64 v212, s[30:31], v212, 0, s[22:23]
	v_addc_co_u32_e64 v212, s[30:31], v212, 0, s[24:25]
	v_addc_co_u32_e64 v212, s[30:31], v212, 0, s[26:27]
	v_addc_co_u32_e64 v212, s[30:31], v212, 0, s[28:29]
	v_cmp_ge_f32_e64 s[22:23], v180, v199
	v_cmp_ge_f32_e64 s[24:25], v181, v199
	v_cmp_ge_f32_e64 s[26:27], v182, v199
	v_cmp_ge_f32_e64 s[28:29], v183, v199
	v_addc_co_u32_e64 v212, s[30:31], v212, 0, s[22:23]
	v_addc_co_u32_e64 v212, s[30:31], v212, 0, s[24:25]
	v_addc_co_u32_e64 v212, s[30:31], v212, 0, s[26:27]
	v_addc_co_u32_e64 v212, s[30:31], v212, 0, s[28:29]
	v_cmp_ge_f32_e64 s[22:23], v184, v199
	v_cmp_ge_f32_e64 s[24:25], v185, v199
	v_cmp_ge_f32_e64 s[26:27], v186, v199
	v_cmp_ge_f32_e64 s[28:29], v187, v199
	v_addc_co_u32_e64 v212, s[30:31], v212, 0, s[22:23]
	v_addc_co_u32_e64 v212, s[30:31], v212, 0, s[24:25]
	v_addc_co_u32_e64 v212, s[30:31], v212, 0, s[26:27]
	v_addc_co_u32_e64 v212, s[30:31], v212, 0, s[28:29]
	v_cmp_ge_f32_e64 s[22:23], v188, v199
	v_cmp_ge_f32_e64 s[24:25], v189, v199
	v_cmp_ge_f32_e64 s[26:27], v190, v199
	v_cmp_ge_f32_e64 s[28:29], v191, v199
	v_addc_co_u32_e64 v212, s[30:31], v212, 0, s[22:23]
	v_addc_co_u32_e64 v212, s[30:31], v212, 0, s[24:25]
	v_addc_co_u32_e64 v212, s[30:31], v212, 0, s[26:27]
	v_addc_co_u32_e64 v212, s[30:31], v212, 0, s[28:29]
	v_cmp_ge_f32_e64 s[22:23], v192, v199
	v_cmp_ge_f32_e64 s[24:25], v193, v199
	v_cmp_ge_f32_e64 s[26:27], v194, v199
	v_cmp_ge_f32_e64 s[28:29], v195, v199
	v_addc_co_u32_e64 v212, s[30:31], v212, 0, s[22:23]
	v_addc_co_u32_e64 v212, s[30:31], v212, 0, s[24:25]
	v_addc_co_u32_e64 v212, s[30:31], v212, 0, s[26:27]
	v_addc_co_u32_e64 v212, s[30:31], v212, 0, s[28:29]
	v_cmp_ge_f32_e64 s[22:23], v196, v199
	v_cmp_ge_f32_e64 s[24:25], v197, v199
	v_cmp_ge_f32_e64 s[26:27], v198, v199
	v_cmp_gt_f32_e64 s[28:29], v200, v199
	v_addc_co_u32_e64 v212, s[30:31], v212, 0, s[22:23]
	v_addc_co_u32_e64 v212, s[30:31], v212, 0, s[24:25]
	v_addc_co_u32_e64 v212, s[30:31], v212, 0, s[26:27]
	v_addc_co_u32_e64 v212, s[30:31], v212, 0, s[28:29]
	v_cmp_gt_f32_e64 s[22:23], v201, v199
	v_cmp_gt_f32_e64 s[24:25], v202, v199
	v_cmp_gt_f32_e64 s[26:27], v203, v199
	v_cmp_gt_f32_e64 s[28:29], v204, v199
	v_addc_co_u32_e64 v212, s[30:31], v212, 0, s[22:23]
	v_addc_co_u32_e64 v212, s[30:31], v212, 0, s[24:25]
	v_addc_co_u32_e64 v212, s[30:31], v212, 0, s[26:27]
	v_addc_co_u32_e64 v212, s[30:31], v212, 0, s[28:29]
	v_cmp_gt_f32_e64 s[22:23], v205, v199
	v_cmp_gt_f32_e64 s[24:25], v206, v199
	v_cmp_gt_f32_e64 s[26:27], v207, v199
	v_cmp_gt_f32_e64 s[28:29], v208, v199
	v_addc_co_u32_e64 v212, s[30:31], v212, 0, s[22:23]
	v_addc_co_u32_e64 v212, s[30:31], v212, 0, s[24:25]
	v_addc_co_u32_e64 v212, s[30:31], v212, 0, s[26:27]
	v_addc_co_u32_e64 v212, s[30:31], v212, 0, s[28:29]
	v_cmp_gt_f32_e64 s[22:23], v209, v199
	s_nop 0
	s_nop 0
	v_addc_co_u32_e64 v212, s[30:31], v212, 0, s[22:23]
	v_cmp_gt_u32_e32 vcc, 16, v212
	s_and_saveexec_b64 s[40:41], vcc
	v_lshl_add_u32 v214, v212, 2, v213
	v_mov_b32_e32 v212, 39
	ds_write_b32 v214, v199
	ds_write_b32 v214, v212 offset:4096
	s_mov_b64 exec, -1
	s_branch .Lrk0_c47
; __device__ __forceinline__ void ph_peer_select(const Params& P, int layer, const h16* Q, int nrows, char* smem) {
;     ...
;     for (int i = tid; i < 64 * 50; i += NTHR) {
;       const int tok = i / 50, c = i % 50;
;       const float v = cd[tok * 52 + c];
;       int rank = 0;
;       for (int j = 0; j < 50; ++j) { const float o = cd[tok * 52 + j]; rank += (o > v || (o == v && j < c)) ? 1 : 0; }
;       if (rank < TOPK) { tv[tok * 16 + rank] = v; tp[tok * 16 + rank] = c; }
;     }
.Lrk0_c40:
	v_mov_b32_e32 v212, 0
	v_cmp_ge_f32_e64 s[22:23], v160, v200
	v_cmp_ge_f32_e64 s[24:25], v161, v200
	v_cmp_ge_f32_e64 s[26:27], v162, v200
	v_cmp_ge_f32_e64 s[28:29], v163, v200
	v_addc_co_u32_e64 v212, s[30:31], v212, 0, s[22:23]
	v_addc_co_u32_e64 v212, s[30:31], v212, 0, s[24:25]
	v_addc_co_u32_e64 v212, s[30:31], v212, 0, s[26:27]
	v_addc_co_u32_e64 v212, s[30:31], v212, 0, s[28:29]
	v_cmp_ge_f32_e64 s[22:23], v164, v200
	v_cmp_ge_f32_e64 s[24:25], v165, v200
	v_cmp_ge_f32_e64 s[26:27], v166, v200
	v_cmp_ge_f32_e64 s[28:29], v167, v200
	v_addc_co_u32_e64 v212, s[30:31], v212, 0, s[22:23]
	v_addc_co_u32_e64 v212, s[30:31], v212, 0, s[24:25]
	v_addc_co_u32_e64 v212, s[30:31], v212, 0, s[26:27]
	v_addc_co_u32_e64 v212, s[30:31], v212, 0, s[28:29]
	v_cmp_ge_f32_e64 s[22:23], v168, v200
	v_cmp_ge_f32_e64 s[24:25], v169, v200
	v_cmp_ge_f32_e64 s[26:27], v170, v200
	v_cmp_ge_f32_e64 s[28:29], v171, v200
	v_addc_co_u32_e64 v212, s[30:31], v212, 0, s[22:23]
	v_addc_co_u32_e64 v212, s[30:31], v212, 0, s[24:25]
	v_addc_co_u32_e64 v212, s[30:31], v212, 0, s[26:27]
	v_addc_co_u32_e64 v212, s[30:31], v212, 0, s[28:29]
	v_cmp_ge_f32_e64 s[22:23], v172, v200
	v_cmp_ge_f32_e64 s[24:25], v173, v200
	v_cmp_ge_f32_e64 s[26:27], v174, v200
	v_cmp_ge_f32_e64 s[28:29], v175, v200
	v_addc_co_u32_e64 v212, s[30:31], v212, 0, s[22:23]
	v_addc_co_u32_e64 v212, s[30:31], v212, 0, s[24:25]
	v_addc_co_u32_e64 v212, s[30:31], v212, 0, s[26:27]
	v_addc_co_u32_e64 v212, s[30:31], v212, 0, s[28:29]
	v_cmp_ge_f32_e64 s[22:23], v176, v200
	v_cmp_ge_f32_e64 s[24:25], v177, v200
	v_cmp_ge_f32_e64 s[26:27], v178, v200
	v_cmp_ge_f32_e64 s[28:29], v179, v200
	v_addc_co_u32_e64 v212, s[30:31], v212, 0, s[22:23]
	v_addc_co_u32_e64 v212, s[30:31], v212, 0, s[24:25]
	v_addc_co_u32_e64 v212, s[30:31], v212, 0, s[26:27]
	v_addc_co_u32_e64 v212, s[30:31], v212, 0, s[28:29]
	v_cmp_ge_f32_e64 s[22:23], v180, v200
	v_cmp_ge_f32_e64 s[24:25], v181, v200
	v_cmp_ge_f32_e64 s[26:27], v182, v200
	v_cmp_ge_f32_e64 s[28:29], v183, v200
	v_addc_co_u32_e64 v212, s[30:31], v212, 0, s[22:23]
	v_addc_co_u32_e64 v212, s[30:31], v212, 0, s[24:25]
	v_addc_co_u32_e64 v212, s[30:31], v212, 0, s[26:27]
	v_addc_co_u32_e64 v212, s[30:31], v212, 0, s[28:29]
	v_cmp_ge_f32_e64 s[22:23], v184, v200
	v_cmp_ge_f32_e64 s[24:25], v185, v200
	v_cmp_ge_f32_e64 s[26:27], v186, v200
	v_cmp_ge_f32_e64 s[28:29], v187, v200
	v_addc_co_u32_e64 v212, s[30:31], v212, 0, s[22:23]
	v_addc_co_u32_e64 v212, s[30:31], v212, 0, s[24:25]
	v_addc_co_u32_e64 v212, s[30:31], v212, 0, s[26:27]
	v_addc_co_u32_e64 v212, s[30:31], v212, 0, s[28:29]
	v_cmp_ge_f32_e64 s[22:23], v188, v200
	v_cmp_ge_f32_e64 s[24:25], v189, v200
	v_cmp_ge_f32_e64 s[26:27], v190, v200
	v_cmp_ge_f32_e64 s[28:29], v191, v200
	v_addc_co_u32_e64 v212, s[30:31], v212, 0, s[22:23]
	v_addc_co_u32_e64 v212, s[30:31], v212, 0, s[24:25]
	v_addc_co_u32_e64 v212, s[30:31], v212, 0, s[26:27]
	v_addc_co_u32_e64 v212, s[30:31], v212, 0, s[28:29]
	v_cmp_ge_f32_e64 s[22:23], v192, v200
	v_cmp_ge_f32_e64 s[24:25], v193, v200
	v_cmp_ge_f32_e64 s[26:27], v194, v200
	v_cmp_ge_f32_e64 s[28:29], v195, v200
	v_addc_co_u32_e64 v212, s[30:31], v212, 0, s[22:23]
	v_addc_co_u32_e64 v212, s[30:31], v212, 0, s[24:25]
	v_addc_co_u32_e64 v212, s[30:31], v212, 0, s[26:27]
	v_addc_co_u32_e64 v212, s[30:31], v212, 0, s[28:29]
	v_cmp_ge_f32_e64 s[22:23], v196, v200
	v_cmp_ge_f32_e64 s[24:25], v197, v200
	v_cmp_ge_f32_e64 s[26:27], v198, v200
	v_cmp_ge_f32_e64 s[28:29], v199, v200
	v_addc_co_u32_e64 v212, s[30:31], v212, 0, s[22:23]
	v_addc_co_u32_e64 v212, s[30:31], v212, 0, s[24:25]
	v_addc_co_u32_e64 v212, s[30:31], v212, 0, s[26:27]
	v_addc_co_u32_e64 v212, s[30:31], v212, 0, s[28:29]
	v_cmp_gt_f32_e64 s[22:23], v201, v200
	v_cmp_gt_f32_e64 s[24:25], v202, v200
	v_cmp_gt_f32_e64 s[26:27], v203, v200
	v_cmp_gt_f32_e64 s[28:29], v204, v200
	v_addc_co_u32_e64 v212, s[30:31], v212, 0, s[22:23]
	v_addc_co_u32_e64 v212, s[30:31], v212, 0, s[24:25]
	v_addc_co_u32_e64 v212, s[30:31], v212, 0, s[26:27]
	v_addc_co_u32_e64 v212, s[30:31], v212, 0, s[28:29]
	v_cmp_gt_f32_e64 s[22:23], v205, v200
	v_cmp_gt_f32_e64 s[24:25], v206, v200
	v_cmp_gt_f32_e64 s[26:27], v207, v200
	v_cmp_gt_f32_e64 s[28:29], v208, v200
	v_addc_co_u32_e64 v212, s[30:31], v212, 0, s[22:23]
	v_addc_co_u32_e64 v212, s[30:31], v212, 0, s[24:25]
	v_addc_co_u32_e64 v212, s[30:31], v212, 0, s[26:27]
	v_addc_co_u32_e64 v212, s[30:31], v212, 0, s[28:29]
	v_cmp_gt_f32_e64 s[22:23], v209, v200
	s_nop 0
	s_nop 0
	v_addc_co_u32_e64 v212, s[30:31], v212, 0, s[22:23]
	v_cmp_gt_u32_e32 vcc, 16, v212
	s_and_saveexec_b64 s[40:41], vcc
	v_lshl_add_u32 v214, v212, 2, v213
	v_mov_b32_e32 v212, 40
	ds_write_b32 v214, v200
	ds_write_b32 v214, v212 offset:4096
	s_mov_b64 exec, -1
	s_branch .Lrk0_c48
; __device__ __forceinline__ void ph_peer_select(const Params& P, int layer, const h16* Q, int nrows, char* smem) {
;     ...
;     for (int i = tid; i < 64 * 50; i += NTHR) {
;       const int tok = i / 50, c = i % 50;
;       const float v = cd[tok * 52 + c];
;       int rank = 0;
;       for (int j = 0; j < 50; ++j) { const float o = cd[tok * 52 + j]; rank += (o > v || (o == v && j < c)) ? 1 : 0; }
;       if (rank < TOPK) { tv[tok * 16 + rank] = v; tp[tok * 16 + rank] = c; }
;     }
.Lrk0_c41:
	v_mov_b32_e32 v212, 0
	v_cmp_ge_f32_e64 s[22:23], v160, v201
	v_cmp_ge_f32_e64 s[24:25], v161, v201
	v_cmp_ge_f32_e64 s[26:27], v162, v201
	v_cmp_ge_f32_e64 s[28:29], v163, v201
	v_addc_co_u32_e64 v212, s[30:31], v212, 0, s[22:23]
	v_addc_co_u32_e64 v212, s[30:31], v212, 0, s[24:25]
	v_addc_co_u32_e64 v212, s[30:31], v212, 0, s[26:27]
	v_addc_co_u32_e64 v212, s[30:31], v212, 0, s[28:29]
	v_cmp_ge_f32_e64 s[22:23], v164, v201
	v_cmp_ge_f32_e64 s[24:25], v165, v201
	v_cmp_ge_f32_e64 s[26:27], v166, v201
	v_cmp_ge_f32_e64 s[28:29], v167, v201
	v_addc_co_u32_e64 v212, s[30:31], v212, 0, s[22:23]
	v_addc_co_u32_e64 v212, s[30:31], v212, 0, s[24:25]
	v_addc_co_u32_e64 v212, s[30:31], v212, 0, s[26:27]
	v_addc_co_u32_e64 v212, s[30:31], v212, 0, s[28:29]
	v_cmp_ge_f32_e64 s[22:23], v168, v201
	v_cmp_ge_f32_e64 s[24:25], v169, v201
	v_cmp_ge_f32_e64 s[26:27], v170, v201
	v_cmp_ge_f32_e64 s[28:29], v171, v201
	v_addc_co_u32_e64 v212, s[30:31], v212, 0, s[22:23]
	v_addc_co_u32_e64 v212, s[30:31], v212, 0, s[24:25]
	v_addc_co_u32_e64 v212, s[30:31], v212, 0, s[26:27]
	v_addc_co_u32_e64 v212, s[30:31], v212, 0, s[28:29]
	v_cmp_ge_f32_e64 s[22:23], v172, v201
	v_cmp_ge_f32_e64 s[24:25], v173, v201
	v_cmp_ge_f32_e64 s[26:27], v174, v201
	v_cmp_ge_f32_e64 s[28:29], v175, v201
	v_addc_co_u32_e64 v212, s[30:31], v212, 0, s[22:23]
	v_addc_co_u32_e64 v212, s[30:31], v212, 0, s[24:25]
	v_addc_co_u32_e64 v212, s[30:31], v212, 0, s[26:27]
	v_addc_co_u32_e64 v212, s[30:31], v212, 0, s[28:29]
	v_cmp_ge_f32_e64 s[22:23], v176, v201
	v_cmp_ge_f32_e64 s[24:25], v177, v201
	v_cmp_ge_f32_e64 s[26:27], v178, v201
	v_cmp_ge_f32_e64 s[28:29], v179, v201
	v_addc_co_u32_e64 v212, s[30:31], v212, 0, s[22:23]
	v_addc_co_u32_e64 v212, s[30:31], v212, 0, s[24:25]
	v_addc_co_u32_e64 v212, s[30:31], v212, 0, s[26:27]
	v_addc_co_u32_e64 v212, s[30:31], v212, 0, s[28:29]
	v_cmp_ge_f32_e64 s[22:23], v180, v201
	v_cmp_ge_f32_e64 s[24:25], v181, v201
	v_cmp_ge_f32_e64 s[26:27], v182, v201
	v_cmp_ge_f32_e64 s[28:29], v183, v201
	v_addc_co_u32_e64 v212, s[30:31], v212, 0, s[22:23]
	v_addc_co_u32_e64 v212, s[30:31], v212, 0, s[24:25]
	v_addc_co_u32_e64 v212, s[30:31], v212, 0, s[26:27]
	v_addc_co_u32_e64 v212, s[30:31], v212, 0, s[28:29]
	v_cmp_ge_f32_e64 s[22:23], v184, v201
	v_cmp_ge_f32_e64 s[24:25], v185, v201
	v_cmp_ge_f32_e64 s[26:27], v186, v201
	v_cmp_ge_f32_e64 s[28:29], v187, v201
	v_addc_co_u32_e64 v212, s[30:31], v212, 0, s[22:23]
	v_addc_co_u32_e64 v212, s[30:31], v212, 0, s[24:25]
	v_addc_co_u32_e64 v212, s[30:31], v212, 0, s[26:27]
	v_addc_co_u32_e64 v212, s[30:31], v212, 0, s[28:29]
	v_cmp_ge_f32_e64 s[22:23], v188, v201
	v_cmp_ge_f32_e64 s[24:25], v189, v201
	v_cmp_ge_f32_e64 s[26:27], v190, v201
	v_cmp_ge_f32_e64 s[28:29], v191, v201
	v_addc_co_u32_e64 v212, s[30:31], v212, 0, s[22:23]
	v_addc_co_u32_e64 v212, s[30:31], v212, 0, s[24:25]
	v_addc_co_u32_e64 v212, s[30:31], v212, 0, s[26:27]
	v_addc_co_u32_e64 v212, s[30:31], v212, 0, s[28:29]
	v_cmp_ge_f32_e64 s[22:23], v192, v201
	v_cmp_ge_f32_e64 s[24:25], v193, v201
	v_cmp_ge_f32_e64 s[26:27], v194, v201
	v_cmp_ge_f32_e64 s[28:29], v195, v201
	v_addc_co_u32_e64 v212, s[30:31], v212, 0, s[22:23]
	v_addc_co_u32_e64 v212, s[30:31], v212, 0, s[24:25]
	v_addc_co_u32_e64 v212, s[30:31], v212, 0, s[26:27]
	v_addc_co_u32_e64 v212, s[30:31], v212, 0, s[28:29]
	v_cmp_ge_f32_e64 s[22:23], v196, v201
	v_cmp_ge_f32_e64 s[24:25], v197, v201
	v_cmp_ge_f32_e64 s[26:27], v198, v201
	v_cmp_ge_f32_e64 s[28:29], v199, v201
	v_addc_co_u32_e64 v212, s[30:31], v212, 0, s[22:23]
	v_addc_co_u32_e64 v212, s[30:31], v212, 0, s[24:25]
	v_addc_co_u32_e64 v212, s[30:31], v212, 0, s[26:27]
	v_addc_co_u32_e64 v212, s[30:31], v212, 0, s[28:29]
	v_cmp_ge_f32_e64 s[22:23], v200, v201
	v_cmp_gt_f32_e64 s[24:25], v202, v201
	v_cmp_gt_f32_e64 s[26:27], v203, v201
	v_cmp_gt_f32_e64 s[28:29], v204, v201
	v_addc_co_u32_e64 v212, s[30:31], v212, 0, s[22:23]
	v_addc_co_u32_e64 v212, s[30:31], v212, 0, s[24:25]
	v_addc_co_u32_e64 v212, s[30:31], v212, 0, s[26:27]
	v_addc_co_u32_e64 v212, s[30:31], v212, 0, s[28:29]
	v_cmp_gt_f32_e64 s[22:23], v205, v201
	v_cmp_gt_f32_e64 s[24:25], v206, v201
	v_cmp_gt_f32_e64 s[26:27], v207, v201
	v_cmp_gt_f32_e64 s[28:29], v208, v201
	v_addc_co_u32_e64 v212, s[30:31], v212, 0, s[22:23]
	v_addc_co_u32_e64 v212, s[30:31], v212, 0, s[24:25]
	v_addc_co_u32_e64 v212, s[30:31], v212, 0, s[26:27]
	v_addc_co_u32_e64 v212, s[30:31], v212, 0, s[28:29]
	v_cmp_gt_f32_e64 s[22:23], v209, v201
	s_nop 0
	s_nop 0
	v_addc_co_u32_e64 v212, s[30:31], v212, 0, s[22:23]
	v_cmp_gt_u32_e32 vcc, 16, v212
	s_and_saveexec_b64 s[40:41], vcc
	v_lshl_add_u32 v214, v212, 2, v213
	v_mov_b32_e32 v212, 41
	ds_write_b32 v214, v201
	ds_write_b32 v214, v212 offset:4096
	s_mov_b64 exec, -1
	s_branch .Lrk0_c49
; __device__ __forceinline__ void ph_peer_select(const Params& P, int layer, const h16* Q, int nrows, char* smem) {
;     ...
;     for (int i = tid; i < 64 * 50; i += NTHR) {
;       const int tok = i / 50, c = i % 50;
;       const float v = cd[tok * 52 + c];
;       int rank = 0;
;       for (int j = 0; j < 50; ++j) { const float o = cd[tok * 52 + j]; rank += (o > v || (o == v && j < c)) ? 1 : 0; }
;       if (rank < TOPK) { tv[tok * 16 + rank] = v; tp[tok * 16 + rank] = c; }
;     }
.Lrk0_c42:
	v_mov_b32_e32 v212, 0
	v_cmp_ge_f32_e64 s[22:23], v160, v202
	v_cmp_ge_f32_e64 s[24:25], v161, v202
	v_cmp_ge_f32_e64 s[26:27], v162, v202
	v_cmp_ge_f32_e64 s[28:29], v163, v202
	v_addc_co_u32_e64 v212, s[30:31], v212, 0, s[22:23]
	v_addc_co_u32_e64 v212, s[30:31], v212, 0, s[24:25]
	v_addc_co_u32_e64 v212, s[30:31], v212, 0, s[26:27]
	v_addc_co_u32_e64 v212, s[30:31], v212, 0, s[28:29]
	v_cmp_ge_f32_e64 s[22:23], v164, v202
	v_cmp_ge_f32_e64 s[24:25], v165, v202
	v_cmp_ge_f32_e64 s[26:27], v166, v202
	v_cmp_ge_f32_e64 s[28:29], v167, v202
	v_addc_co_u32_e64 v212, s[30:31], v212, 0, s[22:23]
	v_addc_co_u32_e64 v212, s[30:31], v212, 0, s[24:25]
	v_addc_co_u32_e64 v212, s[30:31], v212, 0, s[26:27]
	v_addc_co_u32_e64 v212, s[30:31], v212, 0, s[28:29]
	v_cmp_ge_f32_e64 s[22:23], v168, v202
	v_cmp_ge_f32_e64 s[24:25], v169, v202
	v_cmp_ge_f32_e64 s[26:27], v170, v202
	v_cmp_ge_f32_e64 s[28:29], v171, v202
	v_addc_co_u32_e64 v212, s[30:31], v212, 0, s[22:23]
	v_addc_co_u32_e64 v212, s[30:31], v212, 0, s[24:25]
	v_addc_co_u32_e64 v212, s[30:31], v212, 0, s[26:27]
	v_addc_co_u32_e64 v212, s[30:31], v212, 0, s[28:29]
	v_cmp_ge_f32_e64 s[22:23], v172, v202
	v_cmp_ge_f32_e64 s[24:25], v173, v202
	v_cmp_ge_f32_e64 s[26:27], v174, v202
	v_cmp_ge_f32_e64 s[28:29], v175, v202
	v_addc_co_u32_e64 v212, s[30:31], v212, 0, s[22:23]
	v_addc_co_u32_e64 v212, s[30:31], v212, 0, s[24:25]
	v_addc_co_u32_e64 v212, s[30:31], v212, 0, s[26:27]
	v_addc_co_u32_e64 v212, s[30:31], v212, 0, s[28:29]
	v_cmp_ge_f32_e64 s[22:23], v176, v202
	v_cmp_ge_f32_e64 s[24:25], v177, v202
	v_cmp_ge_f32_e64 s[26:27], v178, v202
	v_cmp_ge_f32_e64 s[28:29], v179, v202
	v_addc_co_u32_e64 v212, s[30:31], v212, 0, s[22:23]
	v_addc_co_u32_e64 v212, s[30:31], v212, 0, s[24:25]
	v_addc_co_u32_e64 v212, s[30:31], v212, 0, s[26:27]
	v_addc_co_u32_e64 v212, s[30:31], v212, 0, s[28:29]
	v_cmp_ge_f32_e64 s[22:23], v180, v202
	v_cmp_ge_f32_e64 s[24:25], v181, v202
	v_cmp_ge_f32_e64 s[26:27], v182, v202
	v_cmp_ge_f32_e64 s[28:29], v183, v202
	v_addc_co_u32_e64 v212, s[30:31], v212, 0, s[22:23]
	v_addc_co_u32_e64 v212, s[30:31], v212, 0, s[24:25]
	v_addc_co_u32_e64 v212, s[30:31], v212, 0, s[26:27]
	v_addc_co_u32_e64 v212, s[30:31], v212, 0, s[28:29]
	v_cmp_ge_f32_e64 s[22:23], v184, v202
	v_cmp_ge_f32_e64 s[24:25], v185, v202
	v_cmp_ge_f32_e64 s[26:27], v186, v202
	v_cmp_ge_f32_e64 s[28:29], v187, v202
	v_addc_co_u32_e64 v212, s[30:31], v212, 0, s[22:23]
	v_addc_co_u32_e64 v212, s[30:31], v212, 0, s[24:25]
	v_addc_co_u32_e64 v212, s[30:31], v212, 0, s[26:27]
	v_addc_co_u32_e64 v212, s[30:31], v212, 0, s[28:29]
	v_cmp_ge_f32_e64 s[22:23], v188, v202
	v_cmp_ge_f32_e64 s[24:25], v189, v202
	v_cmp_ge_f32_e64 s[26:27], v190, v202
	v_cmp_ge_f32_e64 s[28:29], v191, v202
	v_addc_co_u32_e64 v212, s[30:31], v212, 0, s[22:23]
	v_addc_co_u32_e64 v212, s[30:31], v212, 0, s[24:25]
	v_addc_co_u32_e64 v212, s[30:31], v212, 0, s[26:27]
	v_addc_co_u32_e64 v212, s[30:31], v212, 0, s[28:29]
	v_cmp_ge_f32_e64 s[22:23], v192, v202
	v_cmp_ge_f32_e64 s[24:25], v193, v202
	v_cmp_ge_f32_e64 s[26:27], v194, v202
	v_cmp_ge_f32_e64 s[28:29], v195, v202
	v_addc_co_u32_e64 v212, s[30:31], v212, 0, s[22:23]
	v_addc_co_u32_e64 v212, s[30:31], v212, 0, s[24:25]
	v_addc_co_u32_e64 v212, s[30:31], v212, 0, s[26:27]
	v_addc_co_u32_e64 v212, s[30:31], v212, 0, s[28:29]
	v_cmp_ge_f32_e64 s[22:23], v196, v202
	v_cmp_ge_f32_e64 s[24:25], v197, v202
	v_cmp_ge_f32_e64 s[26:27], v198, v202
	v_cmp_ge_f32_e64 s[28:29], v199, v202
	v_addc_co_u32_e64 v212, s[30:31], v212, 0, s[22:23]
	v_addc_co_u32_e64 v212, s[30:31], v212, 0, s[24:25]
	v_addc_co_u32_e64 v212, s[30:31], v212, 0, s[26:27]
	v_addc_co_u32_e64 v212, s[30:31], v212, 0, s[28:29]
	v_cmp_ge_f32_e64 s[22:23], v200, v202
	v_cmp_ge_f32_e64 s[24:25], v201, v202
	v_cmp_gt_f32_e64 s[26:27], v203, v202
	v_cmp_gt_f32_e64 s[28:29], v204, v202
	v_addc_co_u32_e64 v212, s[30:31], v212, 0, s[22:23]
	v_addc_co_u32_e64 v212, s[30:31], v212, 0, s[24:25]
	v_addc_co_u32_e64 v212, s[30:31], v212, 0, s[26:27]
	v_addc_co_u32_e64 v212, s[30:31], v212, 0, s[28:29]
	v_cmp_gt_f32_e64 s[22:23], v205, v202
	v_cmp_gt_f32_e64 s[24:25], v206, v202
	v_cmp_gt_f32_e64 s[26:27], v207, v202
	v_cmp_gt_f32_e64 s[28:29], v208, v202
	v_addc_co_u32_e64 v212, s[30:31], v212, 0, s[22:23]
	v_addc_co_u32_e64 v212, s[30:31], v212, 0, s[24:25]
	v_addc_co_u32_e64 v212, s[30:31], v212, 0, s[26:27]
	v_addc_co_u32_e64 v212, s[30:31], v212, 0, s[28:29]
	v_cmp_gt_f32_e64 s[22:23], v209, v202
	s_nop 0
	s_nop 0
	v_addc_co_u32_e64 v212, s[30:31], v212, 0, s[22:23]
	v_cmp_gt_u32_e32 vcc, 16, v212
	s_and_saveexec_b64 s[40:41], vcc
	v_lshl_add_u32 v214, v212, 2, v213
	v_mov_b32_e32 v212, 42
	ds_write_b32 v214, v202
	ds_write_b32 v214, v212 offset:4096
	s_mov_b64 exec, -1
	s_branch .Lrk0_end
; __device__ __forceinline__ void ph_peer_select(const Params& P, int layer, const h16* Q, int nrows, char* smem) {
;     ...
;     for (int i = tid; i < 64 * 50; i += NTHR) {
;       const int tok = i / 50, c = i % 50;
;       const float v = cd[tok * 52 + c];
;       int rank = 0;
;       for (int j = 0; j < 50; ++j) { const float o = cd[tok * 52 + j]; rank += (o > v || (o == v && j < c)) ? 1 : 0; }
;       if (rank < TOPK) { tv[tok * 16 + rank] = v; tp[tok * 16 + rank] = c; }
;     }
.Lrk0_c43:
	v_mov_b32_e32 v212, 0
	v_cmp_ge_f32_e64 s[22:23], v160, v203
	v_cmp_ge_f32_e64 s[24:25], v161, v203
	v_cmp_ge_f32_e64 s[26:27], v162, v203
	v_cmp_ge_f32_e64 s[28:29], v163, v203
	v_addc_co_u32_e64 v212, s[30:31], v212, 0, s[22:23]
	v_addc_co_u32_e64 v212, s[30:31], v212, 0, s[24:25]
	v_addc_co_u32_e64 v212, s[30:31], v212, 0, s[26:27]
	v_addc_co_u32_e64 v212, s[30:31], v212, 0, s[28:29]
	v_cmp_ge_f32_e64 s[22:23], v164, v203
	v_cmp_ge_f32_e64 s[24:25], v165, v203
	v_cmp_ge_f32_e64 s[26:27], v166, v203
	v_cmp_ge_f32_e64 s[28:29], v167, v203
	v_addc_co_u32_e64 v212, s[30:31], v212, 0, s[22:23]
	v_addc_co_u32_e64 v212, s[30:31], v212, 0, s[24:25]
	v_addc_co_u32_e64 v212, s[30:31], v212, 0, s[26:27]
	v_addc_co_u32_e64 v212, s[30:31], v212, 0, s[28:29]
	v_cmp_ge_f32_e64 s[22:23], v168, v203
	v_cmp_ge_f32_e64 s[24:25], v169, v203
	v_cmp_ge_f32_e64 s[26:27], v170, v203
	v_cmp_ge_f32_e64 s[28:29], v171, v203
	v_addc_co_u32_e64 v212, s[30:31], v212, 0, s[22:23]
	v_addc_co_u32_e64 v212, s[30:31], v212, 0, s[24:25]
	v_addc_co_u32_e64 v212, s[30:31], v212, 0, s[26:27]
	v_addc_co_u32_e64 v212, s[30:31], v212, 0, s[28:29]
	v_cmp_ge_f32_e64 s[22:23], v172, v203
	v_cmp_ge_f32_e64 s[24:25], v173, v203
	v_cmp_ge_f32_e64 s[26:27], v174, v203
	v_cmp_ge_f32_e64 s[28:29], v175, v203
	v_addc_co_u32_e64 v212, s[30:31], v212, 0, s[22:23]
	v_addc_co_u32_e64 v212, s[30:31], v212, 0, s[24:25]
	v_addc_co_u32_e64 v212, s[30:31], v212, 0, s[26:27]
	v_addc_co_u32_e64 v212, s[30:31], v212, 0, s[28:29]
	v_cmp_ge_f32_e64 s[22:23], v176, v203
	v_cmp_ge_f32_e64 s[24:25], v177, v203
	v_cmp_ge_f32_e64 s[26:27], v178, v203
	v_cmp_ge_f32_e64 s[28:29], v179, v203
	v_addc_co_u32_e64 v212, s[30:31], v212, 0, s[22:23]
	v_addc_co_u32_e64 v212, s[30:31], v212, 0, s[24:25]
	v_addc_co_u32_e64 v212, s[30:31], v212, 0, s[26:27]
	v_addc_co_u32_e64 v212, s[30:31], v212, 0, s[28:29]
	v_cmp_ge_f32_e64 s[22:23], v180, v203
	v_cmp_ge_f32_e64 s[24:25], v181, v203
	v_cmp_ge_f32_e64 s[26:27], v182, v203
	v_cmp_ge_f32_e64 s[28:29], v183, v203
	v_addc_co_u32_e64 v212, s[30:31], v212, 0, s[22:23]
	v_addc_co_u32_e64 v212, s[30:31], v212, 0, s[24:25]
	v_addc_co_u32_e64 v212, s[30:31], v212, 0, s[26:27]
	v_addc_co_u32_e64 v212, s[30:31], v212, 0, s[28:29]
	v_cmp_ge_f32_e64 s[22:23], v184, v203
	v_cmp_ge_f32_e64 s[24:25], v185, v203
	v_cmp_ge_f32_e64 s[26:27], v186, v203
	v_cmp_ge_f32_e64 s[28:29], v187, v203
	v_addc_co_u32_e64 v212, s[30:31], v212, 0, s[22:23]
	v_addc_co_u32_e64 v212, s[30:31], v212, 0, s[24:25]
	v_addc_co_u32_e64 v212, s[30:31], v212, 0, s[26:27]
	v_addc_co_u32_e64 v212, s[30:31], v212, 0, s[28:29]
	v_cmp_ge_f32_e64 s[22:23], v188, v203
	v_cmp_ge_f32_e64 s[24:25], v189, v203
	v_cmp_ge_f32_e64 s[26:27], v190, v203
	v_cmp_ge_f32_e64 s[28:29], v191, v203
	v_addc_co_u32_e64 v212, s[30:31], v212, 0, s[22:23]
	v_addc_co_u32_e64 v212, s[30:31], v212, 0, s[24:25]
	v_addc_co_u32_e64 v212, s[30:31], v212, 0, s[26:27]
	v_addc_co_u32_e64 v212, s[30:31], v212, 0, s[28:29]
	v_cmp_ge_f32_e64 s[22:23], v192, v203
	v_cmp_ge_f32_e64 s[24:25], v193, v203
	v_cmp_ge_f32_e64 s[26:27], v194, v203
	v_cmp_ge_f32_e64 s[28:29], v195, v203
	v_addc_co_u32_e64 v212, s[30:31], v212, 0, s[22:23]
	v_addc_co_u32_e64 v212, s[30:31], v212, 0, s[24:25]
	v_addc_co_u32_e64 v212, s[30:31], v212, 0, s[26:27]
	v_addc_co_u32_e64 v212, s[30:31], v212, 0, s[28:29]
	v_cmp_ge_f32_e64 s[22:23], v196, v203
	v_cmp_ge_f32_e64 s[24:25], v197, v203
	v_cmp_ge_f32_e64 s[26:27], v198, v203
	v_cmp_ge_f32_e64 s[28:29], v199, v203
	v_addc_co_u32_e64 v212, s[30:31], v212, 0, s[22:23]
	v_addc_co_u32_e64 v212, s[30:31], v212, 0, s[24:25]
	v_addc_co_u32_e64 v212, s[30:31], v212, 0, s[26:27]
	v_addc_co_u32_e64 v212, s[30:31], v212, 0, s[28:29]
	v_cmp_ge_f32_e64 s[22:23], v200, v203
	v_cmp_ge_f32_e64 s[24:25], v201, v203
	v_cmp_ge_f32_e64 s[26:27], v202, v203
	v_cmp_gt_f32_e64 s[28:29], v204, v203
	v_addc_co_u32_e64 v212, s[30:31], v212, 0, s[22:23]
	v_addc_co_u32_e64 v212, s[30:31], v212, 0, s[24:25]
	v_addc_co_u32_e64 v212, s[30:31], v212, 0, s[26:27]
	v_addc_co_u32_e64 v212, s[30:31], v212, 0, s[28:29]
	v_cmp_gt_f32_e64 s[22:23], v205, v203
	v_cmp_gt_f32_e64 s[24:25], v206, v203
	v_cmp_gt_f32_e64 s[26:27], v207, v203
	v_cmp_gt_f32_e64 s[28:29], v208, v203
	v_addc_co_u32_e64 v212, s[30:31], v212, 0, s[22:23]
	v_addc_co_u32_e64 v212, s[30:31], v212, 0, s[24:25]
	v_addc_co_u32_e64 v212, s[30:31], v212, 0, s[26:27]
	v_addc_co_u32_e64 v212, s[30:31], v212, 0, s[28:29]
	v_cmp_gt_f32_e64 s[22:23], v209, v203
	s_nop 0
	s_nop 0
	v_addc_co_u32_e64 v212, s[30:31], v212, 0, s[22:23]
	v_cmp_gt_u32_e32 vcc, 16, v212
	s_and_saveexec_b64 s[40:41], vcc
	v_lshl_add_u32 v214, v212, 2, v213
	v_mov_b32_e32 v212, 43
	ds_write_b32 v214, v203
	ds_write_b32 v214, v212 offset:4096
	s_mov_b64 exec, -1
	s_branch .Lrk0_end
; __device__ __forceinline__ void ph_peer_select(const Params& P, int layer, const h16* Q, int nrows, char* smem) {
;     ...
;     for (int i = tid; i < 64 * 50; i += NTHR) {
;       const int tok = i / 50, c = i % 50;
;       const float v = cd[tok * 52 + c];
;       int rank = 0;
;       for (int j = 0; j < 50; ++j) { const float o = cd[tok * 52 + j]; rank += (o > v || (o == v && j < c)) ? 1 : 0; }
;       if (rank < TOPK) { tv[tok * 16 + rank] = v; tp[tok * 16 + rank] = c; }
;     }
.Lrk0_c44:
	v_mov_b32_e32 v212, 0
	v_cmp_ge_f32_e64 s[22:23], v160, v204
	v_cmp_ge_f32_e64 s[24:25], v161, v204
	v_cmp_ge_f32_e64 s[26:27], v162, v204
	v_cmp_ge_f32_e64 s[28:29], v163, v204
	v_addc_co_u32_e64 v212, s[30:31], v212, 0, s[22:23]
	v_addc_co_u32_e64 v212, s[30:31], v212, 0, s[24:25]
	v_addc_co_u32_e64 v212, s[30:31], v212, 0, s[26:27]
	v_addc_co_u32_e64 v212, s[30:31], v212, 0, s[28:29]
	v_cmp_ge_f32_e64 s[22:23], v164, v204
	v_cmp_ge_f32_e64 s[24:25], v165, v204
	v_cmp_ge_f32_e64 s[26:27], v166, v204
	v_cmp_ge_f32_e64 s[28:29], v167, v204
	v_addc_co_u32_e64 v212, s[30:31], v212, 0, s[22:23]
	v_addc_co_u32_e64 v212, s[30:31], v212, 0, s[24:25]
	v_addc_co_u32_e64 v212, s[30:31], v212, 0, s[26:27]
	v_addc_co_u32_e64 v212, s[30:31], v212, 0, s[28:29]
	v_cmp_ge_f32_e64 s[22:23], v168, v204
	v_cmp_ge_f32_e64 s[24:25], v169, v204
	v_cmp_ge_f32_e64 s[26:27], v170, v204
	v_cmp_ge_f32_e64 s[28:29], v171, v204
	v_addc_co_u32_e64 v212, s[30:31], v212, 0, s[22:23]
	v_addc_co_u32_e64 v212, s[30:31], v212, 0, s[24:25]
	v_addc_co_u32_e64 v212, s[30:31], v212, 0, s[26:27]
	v_addc_co_u32_e64 v212, s[30:31], v212, 0, s[28:29]
	v_cmp_ge_f32_e64 s[22:23], v172, v204
	v_cmp_ge_f32_e64 s[24:25], v173, v204
	v_cmp_ge_f32_e64 s[26:27], v174, v204
	v_cmp_ge_f32_e64 s[28:29], v175, v204
	v_addc_co_u32_e64 v212, s[30:31], v212, 0, s[22:23]
	v_addc_co_u32_e64 v212, s[30:31], v212, 0, s[24:25]
	v_addc_co_u32_e64 v212, s[30:31], v212, 0, s[26:27]
	v_addc_co_u32_e64 v212, s[30:31], v212, 0, s[28:29]
	v_cmp_ge_f32_e64 s[22:23], v176, v204
	v_cmp_ge_f32_e64 s[24:25], v177, v204
	v_cmp_ge_f32_e64 s[26:27], v178, v204
	v_cmp_ge_f32_e64 s[28:29], v179, v204
	v_addc_co_u32_e64 v212, s[30:31], v212, 0, s[22:23]
	v_addc_co_u32_e64 v212, s[30:31], v212, 0, s[24:25]
	v_addc_co_u32_e64 v212, s[30:31], v212, 0, s[26:27]
	v_addc_co_u32_e64 v212, s[30:31], v212, 0, s[28:29]
	v_cmp_ge_f32_e64 s[22:23], v180, v204
	v_cmp_ge_f32_e64 s[24:25], v181, v204
	v_cmp_ge_f32_e64 s[26:27], v182, v204
	v_cmp_ge_f32_e64 s[28:29], v183, v204
	v_addc_co_u32_e64 v212, s[30:31], v212, 0, s[22:23]
	v_addc_co_u32_e64 v212, s[30:31], v212, 0, s[24:25]
	v_addc_co_u32_e64 v212, s[30:31], v212, 0, s[26:27]
	v_addc_co_u32_e64 v212, s[30:31], v212, 0, s[28:29]
	v_cmp_ge_f32_e64 s[22:23], v184, v204
	v_cmp_ge_f32_e64 s[24:25], v185, v204
	v_cmp_ge_f32_e64 s[26:27], v186, v204
	v_cmp_ge_f32_e64 s[28:29], v187, v204
	v_addc_co_u32_e64 v212, s[30:31], v212, 0, s[22:23]
	v_addc_co_u32_e64 v212, s[30:31], v212, 0, s[24:25]
	v_addc_co_u32_e64 v212, s[30:31], v212, 0, s[26:27]
	v_addc_co_u32_e64 v212, s[30:31], v212, 0, s[28:29]
	v_cmp_ge_f32_e64 s[22:23], v188, v204
	v_cmp_ge_f32_e64 s[24:25], v189, v204
	v_cmp_ge_f32_e64 s[26:27], v190, v204
	v_cmp_ge_f32_e64 s[28:29], v191, v204
	v_addc_co_u32_e64 v212, s[30:31], v212, 0, s[22:23]
	v_addc_co_u32_e64 v212, s[30:31], v212, 0, s[24:25]
	v_addc_co_u32_e64 v212, s[30:31], v212, 0, s[26:27]
	v_addc_co_u32_e64 v212, s[30:31], v212, 0, s[28:29]
	v_cmp_ge_f32_e64 s[22:23], v192, v204
	v_cmp_ge_f32_e64 s[24:25], v193, v204
	v_cmp_ge_f32_e64 s[26:27], v194, v204
	v_cmp_ge_f32_e64 s[28:29], v195, v204
	v_addc_co_u32_e64 v212, s[30:31], v212, 0, s[22:23]
	v_addc_co_u32_e64 v212, s[30:31], v212, 0, s[24:25]
	v_addc_co_u32_e64 v212, s[30:31], v212, 0, s[26:27]
	v_addc_co_u32_e64 v212, s[30:31], v212, 0, s[28:29]
	v_cmp_ge_f32_e64 s[22:23], v196, v204
	v_cmp_ge_f32_e64 s[24:25], v197, v204
	v_cmp_ge_f32_e64 s[26:27], v198, v204
	v_cmp_ge_f32_e64 s[28:29], v199, v204
	v_addc_co_u32_e64 v212, s[30:31], v212, 0, s[22:23]
	v_addc_co_u32_e64 v212, s[30:31], v212, 0, s[24:25]
	v_addc_co_u32_e64 v212, s[30:31], v212, 0, s[26:27]
	v_addc_co_u32_e64 v212, s[30:31], v212, 0, s[28:29]
	v_cmp_ge_f32_e64 s[22:23], v200, v204
	v_cmp_ge_f32_e64 s[24:25], v201, v204
	v_cmp_ge_f32_e64 s[26:27], v202, v204
	v_cmp_ge_f32_e64 s[28:29], v203, v204
	v_addc_co_u32_e64 v212, s[30:31], v212, 0, s[22:23]
	v_addc_co_u32_e64 v212, s[30:31], v212, 0, s[24:25]
	v_addc_co_u32_e64 v212, s[30:31], v212, 0, s[26:27]
	v_addc_co_u32_e64 v212, s[30:31], v212, 0, s[28:29]
	v_cmp_gt_f32_e64 s[22:23], v205, v204
	v_cmp_gt_f32_e64 s[24:25], v206, v204
	v_cmp_gt_f32_e64 s[26:27], v207, v204
	v_cmp_gt_f32_e64 s[28:29], v208, v204
	v_addc_co_u32_e64 v212, s[30:31], v212, 0, s[22:23]
	v_addc_co_u32_e64 v212, s[30:31], v212, 0, s[24:25]
	v_addc_co_u32_e64 v212, s[30:31], v212, 0, s[26:27]
	v_addc_co_u32_e64 v212, s[30:31], v212, 0, s[28:29]
	v_cmp_gt_f32_e64 s[22:23], v209, v204
	s_nop 0
	s_nop 0
	v_addc_co_u32_e64 v212, s[30:31], v212, 0, s[22:23]
	v_cmp_gt_u32_e32 vcc, 16, v212
	s_and_saveexec_b64 s[40:41], vcc
	v_lshl_add_u32 v214, v212, 2, v213
	v_mov_b32_e32 v212, 44
	ds_write_b32 v214, v204
	ds_write_b32 v214, v212 offset:4096
	s_mov_b64 exec, -1
	s_branch .Lrk0_end
; __device__ __forceinline__ void ph_peer_select(const Params& P, int layer, const h16* Q, int nrows, char* smem) {
;     ...
;     for (int i = tid; i < 64 * 50; i += NTHR) {
;       const int tok = i / 50, c = i % 50;
;       const float v = cd[tok * 52 + c];
;       int rank = 0;
;       for (int j = 0; j < 50; ++j) { const float o = cd[tok * 52 + j]; rank += (o > v || (o == v && j < c)) ? 1 : 0; }
;       if (rank < TOPK) { tv[tok * 16 + rank] = v; tp[tok * 16 + rank] = c; }
;     }
.Lrk0_c45:
	v_mov_b32_e32 v212, 0
	v_cmp_ge_f32_e64 s[22:23], v160, v205
	v_cmp_ge_f32_e64 s[24:25], v161, v205
	v_cmp_ge_f32_e64 s[26:27], v162, v205
	v_cmp_ge_f32_e64 s[28:29], v163, v205
	v_addc_co_u32_e64 v212, s[30:31], v212, 0, s[22:23]
	v_addc_co_u32_e64 v212, s[30:31], v212, 0, s[24:25]
	v_addc_co_u32_e64 v212, s[30:31], v212, 0, s[26:27]
	v_addc_co_u32_e64 v212, s[30:31], v212, 0, s[28:29]
	v_cmp_ge_f32_e64 s[22:23], v164, v205
	v_cmp_ge_f32_e64 s[24:25], v165, v205
	v_cmp_ge_f32_e64 s[26:27], v166, v205
	v_cmp_ge_f32_e64 s[28:29], v167, v205
	v_addc_co_u32_e64 v212, s[30:31], v212, 0, s[22:23]
	v_addc_co_u32_e64 v212, s[30:31], v212, 0, s[24:25]
	v_addc_co_u32_e64 v212, s[30:31], v212, 0, s[26:27]
	v_addc_co_u32_e64 v212, s[30:31], v212, 0, s[28:29]
	v_cmp_ge_f32_e64 s[22:23], v168, v205
	v_cmp_ge_f32_e64 s[24:25], v169, v205
	v_cmp_ge_f32_e64 s[26:27], v170, v205
	v_cmp_ge_f32_e64 s[28:29], v171, v205
	v_addc_co_u32_e64 v212, s[30:31], v212, 0, s[22:23]
	v_addc_co_u32_e64 v212, s[30:31], v212, 0, s[24:25]
	v_addc_co_u32_e64 v212, s[30:31], v212, 0, s[26:27]
	v_addc_co_u32_e64 v212, s[30:31], v212, 0, s[28:29]
	v_cmp_ge_f32_e64 s[22:23], v172, v205
	v_cmp_ge_f32_e64 s[24:25], v173, v205
	v_cmp_ge_f32_e64 s[26:27], v174, v205
	v_cmp_ge_f32_e64 s[28:29], v175, v205
	v_addc_co_u32_e64 v212, s[30:31], v212, 0, s[22:23]
	v_addc_co_u32_e64 v212, s[30:31], v212, 0, s[24:25]
	v_addc_co_u32_e64 v212, s[30:31], v212, 0, s[26:27]
	v_addc_co_u32_e64 v212, s[30:31], v212, 0, s[28:29]
	v_cmp_ge_f32_e64 s[22:23], v176, v205
	v_cmp_ge_f32_e64 s[24:25], v177, v205
	v_cmp_ge_f32_e64 s[26:27], v178, v205
	v_cmp_ge_f32_e64 s[28:29], v179, v205
	v_addc_co_u32_e64 v212, s[30:31], v212, 0, s[22:23]
	v_addc_co_u32_e64 v212, s[30:31], v212, 0, s[24:25]
	v_addc_co_u32_e64 v212, s[30:31], v212, 0, s[26:27]
	v_addc_co_u32_e64 v212, s[30:31], v212, 0, s[28:29]
	v_cmp_ge_f32_e64 s[22:23], v180, v205
	v_cmp_ge_f32_e64 s[24:25], v181, v205
	v_cmp_ge_f32_e64 s[26:27], v182, v205
	v_cmp_ge_f32_e64 s[28:29], v183, v205
	v_addc_co_u32_e64 v212, s[30:31], v212, 0, s[22:23]
	v_addc_co_u32_e64 v212, s[30:31], v212, 0, s[24:25]
	v_addc_co_u32_e64 v212, s[30:31], v212, 0, s[26:27]
	v_addc_co_u32_e64 v212, s[30:31], v212, 0, s[28:29]
	v_cmp_ge_f32_e64 s[22:23], v184, v205
	v_cmp_ge_f32_e64 s[24:25], v185, v205
	v_cmp_ge_f32_e64 s[26:27], v186, v205
	v_cmp_ge_f32_e64 s[28:29], v187, v205
	v_addc_co_u32_e64 v212, s[30:31], v212, 0, s[22:23]
	v_addc_co_u32_e64 v212, s[30:31], v212, 0, s[24:25]
	v_addc_co_u32_e64 v212, s[30:31], v212, 0, s[26:27]
	v_addc_co_u32_e64 v212, s[30:31], v212, 0, s[28:29]
	v_cmp_ge_f32_e64 s[22:23], v188, v205
	v_cmp_ge_f32_e64 s[24:25], v189, v205
	v_cmp_ge_f32_e64 s[26:27], v190, v205
	v_cmp_ge_f32_e64 s[28:29], v191, v205
	v_addc_co_u32_e64 v212, s[30:31], v212, 0, s[22:23]
	v_addc_co_u32_e64 v212, s[30:31], v212, 0, s[24:25]
	v_addc_co_u32_e64 v212, s[30:31], v212, 0, s[26:27]
	v_addc_co_u32_e64 v212, s[30:31], v212, 0, s[28:29]
	v_cmp_ge_f32_e64 s[22:23], v192, v205
	v_cmp_ge_f32_e64 s[24:25], v193, v205
	v_cmp_ge_f32_e64 s[26:27], v194, v205
	v_cmp_ge_f32_e64 s[28:29], v195, v205
	v_addc_co_u32_e64 v212, s[30:31], v212, 0, s[22:23]
	v_addc_co_u32_e64 v212, s[30:31], v212, 0, s[24:25]
	v_addc_co_u32_e64 v212, s[30:31], v212, 0, s[26:27]
	v_addc_co_u32_e64 v212, s[30:31], v212, 0, s[28:29]
	v_cmp_ge_f32_e64 s[22:23], v196, v205
	v_cmp_ge_f32_e64 s[24:25], v197, v205
	v_cmp_ge_f32_e64 s[26:27], v198, v205
	v_cmp_ge_f32_e64 s[28:29], v199, v205
	v_addc_co_u32_e64 v212, s[30:31], v212, 0, s[22:23]
	v_addc_co_u32_e64 v212, s[30:31], v212, 0, s[24:25]
	v_addc_co_u32_e64 v212, s[30:31], v212, 0, s[26:27]
	v_addc_co_u32_e64 v212, s[30:31], v212, 0, s[28:29]
	v_cmp_ge_f32_e64 s[22:23], v200, v205
	v_cmp_ge_f32_e64 s[24:25], v201, v205
	v_cmp_ge_f32_e64 s[26:27], v202, v205
	v_cmp_ge_f32_e64 s[28:29], v203, v205
	v_addc_co_u32_e64 v212, s[30:31], v212, 0, s[22:23]
	v_addc_co_u32_e64 v212, s[30:31], v212, 0, s[24:25]
	v_addc_co_u32_e64 v212, s[30:31], v212, 0, s[26:27]
	v_addc_co_u32_e64 v212, s[30:31], v212, 0, s[28:29]
	v_cmp_ge_f32_e64 s[22:23], v204, v205
	v_cmp_gt_f32_e64 s[24:25], v206, v205
	v_cmp_gt_f32_e64 s[26:27], v207, v205
	v_cmp_gt_f32_e64 s[28:29], v208, v205
	v_addc_co_u32_e64 v212, s[30:31], v212, 0, s[22:23]
	v_addc_co_u32_e64 v212, s[30:31], v212, 0, s[24:25]
	v_addc_co_u32_e64 v212, s[30:31], v212, 0, s[26:27]
	v_addc_co_u32_e64 v212, s[30:31], v212, 0, s[28:29]
	v_cmp_gt_f32_e64 s[22:23], v209, v205
	s_nop 0
	s_nop 0
	v_addc_co_u32_e64 v212, s[30:31], v212, 0, s[22:23]
	v_cmp_gt_u32_e32 vcc, 16, v212
	s_and_saveexec_b64 s[40:41], vcc
	v_lshl_add_u32 v214, v212, 2, v213
	v_mov_b32_e32 v212, 45
	ds_write_b32 v214, v205
	ds_write_b32 v214, v212 offset:4096
	s_mov_b64 exec, -1
	s_branch .Lrk0_end
; __device__ __forceinline__ void ph_peer_select(const Params& P, int layer, const h16* Q, int nrows, char* smem) {
;     ...
;     for (int i = tid; i < 64 * 50; i += NTHR) {
;       const int tok = i / 50, c = i % 50;
;       const float v = cd[tok * 52 + c];
;       int rank = 0;
;       for (int j = 0; j < 50; ++j) { const float o = cd[tok * 52 + j]; rank += (o > v || (o == v && j < c)) ? 1 : 0; }
;       if (rank < TOPK) { tv[tok * 16 + rank] = v; tp[tok * 16 + rank] = c; }
;     }
.Lrk0_c46:
	v_mov_b32_e32 v212, 0
	v_cmp_ge_f32_e64 s[22:23], v160, v206
	v_cmp_ge_f32_e64 s[24:25], v161, v206
	v_cmp_ge_f32_e64 s[26:27], v162, v206
	v_cmp_ge_f32_e64 s[28:29], v163, v206
	v_addc_co_u32_e64 v212, s[30:31], v212, 0, s[22:23]
	v_addc_co_u32_e64 v212, s[30:31], v212, 0, s[24:25]
	v_addc_co_u32_e64 v212, s[30:31], v212, 0, s[26:27]
	v_addc_co_u32_e64 v212, s[30:31], v212, 0, s[28:29]
	v_cmp_ge_f32_e64 s[22:23], v164, v206
	v_cmp_ge_f32_e64 s[24:25], v165, v206
	v_cmp_ge_f32_e64 s[26:27], v166, v206
	v_cmp_ge_f32_e64 s[28:29], v167, v206
	v_addc_co_u32_e64 v212, s[30:31], v212, 0, s[22:23]
	v_addc_co_u32_e64 v212, s[30:31], v212, 0, s[24:25]
	v_addc_co_u32_e64 v212, s[30:31], v212, 0, s[26:27]
	v_addc_co_u32_e64 v212, s[30:31], v212, 0, s[28:29]
	v_cmp_ge_f32_e64 s[22:23], v168, v206
	v_cmp_ge_f32_e64 s[24:25], v169, v206
	v_cmp_ge_f32_e64 s[26:27], v170, v206
	v_cmp_ge_f32_e64 s[28:29], v171, v206
	v_addc_co_u32_e64 v212, s[30:31], v212, 0, s[22:23]
	v_addc_co_u32_e64 v212, s[30:31], v212, 0, s[24:25]
	v_addc_co_u32_e64 v212, s[30:31], v212, 0, s[26:27]
	v_addc_co_u32_e64 v212, s[30:31], v212, 0, s[28:29]
	v_cmp_ge_f32_e64 s[22:23], v172, v206
	v_cmp_ge_f32_e64 s[24:25], v173, v206
	v_cmp_ge_f32_e64 s[26:27], v174, v206
	v_cmp_ge_f32_e64 s[28:29], v175, v206
	v_addc_co_u32_e64 v212, s[30:31], v212, 0, s[22:23]
	v_addc_co_u32_e64 v212, s[30:31], v212, 0, s[24:25]
	v_addc_co_u32_e64 v212, s[30:31], v212, 0, s[26:27]
	v_addc_co_u32_e64 v212, s[30:31], v212, 0, s[28:29]
	v_cmp_ge_f32_e64 s[22:23], v176, v206
	v_cmp_ge_f32_e64 s[24:25], v177, v206
	v_cmp_ge_f32_e64 s[26:27], v178, v206
	v_cmp_ge_f32_e64 s[28:29], v179, v206
	v_addc_co_u32_e64 v212, s[30:31], v212, 0, s[22:23]
	v_addc_co_u32_e64 v212, s[30:31], v212, 0, s[24:25]
	v_addc_co_u32_e64 v212, s[30:31], v212, 0, s[26:27]
	v_addc_co_u32_e64 v212, s[30:31], v212, 0, s[28:29]
	v_cmp_ge_f32_e64 s[22:23], v180, v206
	v_cmp_ge_f32_e64 s[24:25], v181, v206
	v_cmp_ge_f32_e64 s[26:27], v182, v206
	v_cmp_ge_f32_e64 s[28:29], v183, v206
	v_addc_co_u32_e64 v212, s[30:31], v212, 0, s[22:23]
	v_addc_co_u32_e64 v212, s[30:31], v212, 0, s[24:25]
	v_addc_co_u32_e64 v212, s[30:31], v212, 0, s[26:27]
	v_addc_co_u32_e64 v212, s[30:31], v212, 0, s[28:29]
	v_cmp_ge_f32_e64 s[22:23], v184, v206
	v_cmp_ge_f32_e64 s[24:25], v185, v206
	v_cmp_ge_f32_e64 s[26:27], v186, v206
	v_cmp_ge_f32_e64 s[28:29], v187, v206
	v_addc_co_u32_e64 v212, s[30:31], v212, 0, s[22:23]
	v_addc_co_u32_e64 v212, s[30:31], v212, 0, s[24:25]
	v_addc_co_u32_e64 v212, s[30:31], v212, 0, s[26:27]
	v_addc_co_u32_e64 v212, s[30:31], v212, 0, s[28:29]
	v_cmp_ge_f32_e64 s[22:23], v188, v206
	v_cmp_ge_f32_e64 s[24:25], v189, v206
	v_cmp_ge_f32_e64 s[26:27], v190, v206
	v_cmp_ge_f32_e64 s[28:29], v191, v206
	v_addc_co_u32_e64 v212, s[30:31], v212, 0, s[22:23]
	v_addc_co_u32_e64 v212, s[30:31], v212, 0, s[24:25]
	v_addc_co_u32_e64 v212, s[30:31], v212, 0, s[26:27]
	v_addc_co_u32_e64 v212, s[30:31], v212, 0, s[28:29]
	v_cmp_ge_f32_e64 s[22:23], v192, v206
	v_cmp_ge_f32_e64 s[24:25], v193, v206
	v_cmp_ge_f32_e64 s[26:27], v194, v206
	v_cmp_ge_f32_e64 s[28:29], v195, v206
	v_addc_co_u32_e64 v212, s[30:31], v212, 0, s[22:23]
	v_addc_co_u32_e64 v212, s[30:31], v212, 0, s[24:25]
	v_addc_co_u32_e64 v212, s[30:31], v212, 0, s[26:27]
	v_addc_co_u32_e64 v212, s[30:31], v212, 0, s[28:29]
	v_cmp_ge_f32_e64 s[22:23], v196, v206
	v_cmp_ge_f32_e64 s[24:25], v197, v206
	v_cmp_ge_f32_e64 s[26:27], v198, v206
	v_cmp_ge_f32_e64 s[28:29], v199, v206
	v_addc_co_u32_e64 v212, s[30:31], v212, 0, s[22:23]
	v_addc_co_u32_e64 v212, s[30:31], v212, 0, s[24:25]
	v_addc_co_u32_e64 v212, s[30:31], v212, 0, s[26:27]
	v_addc_co_u32_e64 v212, s[30:31], v212, 0, s[28:29]
	v_cmp_ge_f32_e64 s[22:23], v200, v206
	v_cmp_ge_f32_e64 s[24:25], v201, v206
	v_cmp_ge_f32_e64 s[26:27], v202, v206
	v_cmp_ge_f32_e64 s[28:29], v203, v206
	v_addc_co_u32_e64 v212, s[30:31], v212, 0, s[22:23]
	v_addc_co_u32_e64 v212, s[30:31], v212, 0, s[24:25]
	v_addc_co_u32_e64 v212, s[30:31], v212, 0, s[26:27]
	v_addc_co_u32_e64 v212, s[30:31], v212, 0, s[28:29]
	v_cmp_ge_f32_e64 s[22:23], v204, v206
	v_cmp_ge_f32_e64 s[24:25], v205, v206
	v_cmp_gt_f32_e64 s[26:27], v207, v206
	v_cmp_gt_f32_e64 s[28:29], v208, v206
	v_addc_co_u32_e64 v212, s[30:31], v212, 0, s[22:23]
	v_addc_co_u32_e64 v212, s[30:31], v212, 0, s[24:25]
	v_addc_co_u32_e64 v212, s[30:31], v212, 0, s[26:27]
	v_addc_co_u32_e64 v212, s[30:31], v212, 0, s[28:29]
	v_cmp_gt_f32_e64 s[22:23], v209, v206
	s_nop 0
	s_nop 0
	v_addc_co_u32_e64 v212, s[30:31], v212, 0, s[22:23]
	v_cmp_gt_u32_e32 vcc, 16, v212
	s_and_saveexec_b64 s[40:41], vcc
	v_lshl_add_u32 v214, v212, 2, v213
	v_mov_b32_e32 v212, 46
	ds_write_b32 v214, v206
	ds_write_b32 v214, v212 offset:4096
	s_mov_b64 exec, -1
	s_branch .Lrk0_end
; __device__ __forceinline__ void ph_peer_select(const Params& P, int layer, const h16* Q, int nrows, char* smem) {
;     ...
;     for (int i = tid; i < 64 * 50; i += NTHR) {
;       const int tok = i / 50, c = i % 50;
;       const float v = cd[tok * 52 + c];
;       int rank = 0;
;       for (int j = 0; j < 50; ++j) { const float o = cd[tok * 52 + j]; rank += (o > v || (o == v && j < c)) ? 1 : 0; }
;       if (rank < TOPK) { tv[tok * 16 + rank] = v; tp[tok * 16 + rank] = c; }
;     }
.Lrk0_c47:
	v_mov_b32_e32 v212, 0
	v_cmp_ge_f32_e64 s[22:23], v160, v207
	v_cmp_ge_f32_e64 s[24:25], v161, v207
	v_cmp_ge_f32_e64 s[26:27], v162, v207
	v_cmp_ge_f32_e64 s[28:29], v163, v207
	v_addc_co_u32_e64 v212, s[30:31], v212, 0, s[22:23]
	v_addc_co_u32_e64 v212, s[30:31], v212, 0, s[24:25]
	v_addc_co_u32_e64 v212, s[30:31], v212, 0, s[26:27]
	v_addc_co_u32_e64 v212, s[30:31], v212, 0, s[28:29]
	v_cmp_ge_f32_e64 s[22:23], v164, v207
	v_cmp_ge_f32_e64 s[24:25], v165, v207
	v_cmp_ge_f32_e64 s[26:27], v166, v207
	v_cmp_ge_f32_e64 s[28:29], v167, v207
	v_addc_co_u32_e64 v212, s[30:31], v212, 0, s[22:23]
	v_addc_co_u32_e64 v212, s[30:31], v212, 0, s[24:25]
	v_addc_co_u32_e64 v212, s[30:31], v212, 0, s[26:27]
	v_addc_co_u32_e64 v212, s[30:31], v212, 0, s[28:29]
	v_cmp_ge_f32_e64 s[22:23], v168, v207
	v_cmp_ge_f32_e64 s[24:25], v169, v207
	v_cmp_ge_f32_e64 s[26:27], v170, v207
	v_cmp_ge_f32_e64 s[28:29], v171, v207
	v_addc_co_u32_e64 v212, s[30:31], v212, 0, s[22:23]
	v_addc_co_u32_e64 v212, s[30:31], v212, 0, s[24:25]
	v_addc_co_u32_e64 v212, s[30:31], v212, 0, s[26:27]
	v_addc_co_u32_e64 v212, s[30:31], v212, 0, s[28:29]
	v_cmp_ge_f32_e64 s[22:23], v172, v207
	v_cmp_ge_f32_e64 s[24:25], v173, v207
	v_cmp_ge_f32_e64 s[26:27], v174, v207
	v_cmp_ge_f32_e64 s[28:29], v175, v207
	v_addc_co_u32_e64 v212, s[30:31], v212, 0, s[22:23]
	v_addc_co_u32_e64 v212, s[30:31], v212, 0, s[24:25]
	v_addc_co_u32_e64 v212, s[30:31], v212, 0, s[26:27]
	v_addc_co_u32_e64 v212, s[30:31], v212, 0, s[28:29]
	v_cmp_ge_f32_e64 s[22:23], v176, v207
	v_cmp_ge_f32_e64 s[24:25], v177, v207
	v_cmp_ge_f32_e64 s[26:27], v178, v207
	v_cmp_ge_f32_e64 s[28:29], v179, v207
	v_addc_co_u32_e64 v212, s[30:31], v212, 0, s[22:23]
	v_addc_co_u32_e64 v212, s[30:31], v212, 0, s[24:25]
	v_addc_co_u32_e64 v212, s[30:31], v212, 0, s[26:27]
	v_addc_co_u32_e64 v212, s[30:31], v212, 0, s[28:29]
	v_cmp_ge_f32_e64 s[22:23], v180, v207
	v_cmp_ge_f32_e64 s[24:25], v181, v207
	v_cmp_ge_f32_e64 s[26:27], v182, v207
	v_cmp_ge_f32_e64 s[28:29], v183, v207
	v_addc_co_u32_e64 v212, s[30:31], v212, 0, s[22:23]
	v_addc_co_u32_e64 v212, s[30:31], v212, 0, s[24:25]
	v_addc_co_u32_e64 v212, s[30:31], v212, 0, s[26:27]
	v_addc_co_u32_e64 v212, s[30:31], v212, 0, s[28:29]
	v_cmp_ge_f32_e64 s[22:23], v184, v207
	v_cmp_ge_f32_e64 s[24:25], v185, v207
	v_cmp_ge_f32_e64 s[26:27], v186, v207
	v_cmp_ge_f32_e64 s[28:29], v187, v207
	v_addc_co_u32_e64 v212, s[30:31], v212, 0, s[22:23]
	v_addc_co_u32_e64 v212, s[30:31], v212, 0, s[24:25]
	v_addc_co_u32_e64 v212, s[30:31], v212, 0, s[26:27]
	v_addc_co_u32_e64 v212, s[30:31], v212, 0, s[28:29]
	v_cmp_ge_f32_e64 s[22:23], v188, v207
	v_cmp_ge_f32_e64 s[24:25], v189, v207
	v_cmp_ge_f32_e64 s[26:27], v190, v207
	v_cmp_ge_f32_e64 s[28:29], v191, v207
	v_addc_co_u32_e64 v212, s[30:31], v212, 0, s[22:23]
	v_addc_co_u32_e64 v212, s[30:31], v212, 0, s[24:25]
	v_addc_co_u32_e64 v212, s[30:31], v212, 0, s[26:27]
	v_addc_co_u32_e64 v212, s[30:31], v212, 0, s[28:29]
	v_cmp_ge_f32_e64 s[22:23], v192, v207
	v_cmp_ge_f32_e64 s[24:25], v193, v207
	v_cmp_ge_f32_e64 s[26:27], v194, v207
	v_cmp_ge_f32_e64 s[28:29], v195, v207
	v_addc_co_u32_e64 v212, s[30:31], v212, 0, s[22:23]
	v_addc_co_u32_e64 v212, s[30:31], v212, 0, s[24:25]
	v_addc_co_u32_e64 v212, s[30:31], v212, 0, s[26:27]
	v_addc_co_u32_e64 v212, s[30:31], v212, 0, s[28:29]
	v_cmp_ge_f32_e64 s[22:23], v196, v207
	v_cmp_ge_f32_e64 s[24:25], v197, v207
	v_cmp_ge_f32_e64 s[26:27], v198, v207
	v_cmp_ge_f32_e64 s[28:29], v199, v207
	v_addc_co_u32_e64 v212, s[30:31], v212, 0, s[22:23]
	v_addc_co_u32_e64 v212, s[30:31], v212, 0, s[24:25]
	v_addc_co_u32_e64 v212, s[30:31], v212, 0, s[26:27]
	v_addc_co_u32_e64 v212, s[30:31], v212, 0, s[28:29]
	v_cmp_ge_f32_e64 s[22:23], v200, v207
	v_cmp_ge_f32_e64 s[24:25], v201, v207
	v_cmp_ge_f32_e64 s[26:27], v202, v207
	v_cmp_ge_f32_e64 s[28:29], v203, v207
	v_addc_co_u32_e64 v212, s[30:31], v212, 0, s[22:23]
	v_addc_co_u32_e64 v212, s[30:31], v212, 0, s[24:25]
	v_addc_co_u32_e64 v212, s[30:31], v212, 0, s[26:27]
	v_addc_co_u32_e64 v212, s[30:31], v212, 0, s[28:29]
	v_cmp_ge_f32_e64 s[22:23], v204, v207
	v_cmp_ge_f32_e64 s[24:25], v205, v207
	v_cmp_ge_f32_e64 s[26:27], v206, v207
	v_cmp_gt_f32_e64 s[28:29], v208, v207
	v_addc_co_u32_e64 v212, s[30:31], v212, 0, s[22:23]
	v_addc_co_u32_e64 v212, s[30:31], v212, 0, s[24:25]
	v_addc_co_u32_e64 v212, s[30:31], v212, 0, s[26:27]
	v_addc_co_u32_e64 v212, s[30:31], v212, 0, s[28:29]
	v_cmp_gt_f32_e64 s[22:23], v209, v207
	s_nop 0
	s_nop 0
	v_addc_co_u32_e64 v212, s[30:31], v212, 0, s[22:23]
	v_cmp_gt_u32_e32 vcc, 16, v212
	s_and_saveexec_b64 s[40:41], vcc
	v_lshl_add_u32 v214, v212, 2, v213
	v_mov_b32_e32 v212, 47
	ds_write_b32 v214, v207
	ds_write_b32 v214, v212 offset:4096
	s_mov_b64 exec, -1
	s_branch .Lrk0_end
; __device__ __forceinline__ void ph_peer_select(const Params& P, int layer, const h16* Q, int nrows, char* smem) {
;     ...
;     for (int i = tid; i < 64 * 50; i += NTHR) {
;       const int tok = i / 50, c = i % 50;
;       const float v = cd[tok * 52 + c];
;       int rank = 0;
;       for (int j = 0; j < 50; ++j) { const float o = cd[tok * 52 + j]; rank += (o > v || (o == v && j < c)) ? 1 : 0; }
;       if (rank < TOPK) { tv[tok * 16 + rank] = v; tp[tok * 16 + rank] = c; }
;     }
.Lrk0_c48:
	v_mov_b32_e32 v212, 0
	v_cmp_ge_f32_e64 s[22:23], v160, v208
	v_cmp_ge_f32_e64 s[24:25], v161, v208
	v_cmp_ge_f32_e64 s[26:27], v162, v208
	v_cmp_ge_f32_e64 s[28:29], v163, v208
	v_addc_co_u32_e64 v212, s[30:31], v212, 0, s[22:23]
	v_addc_co_u32_e64 v212, s[30:31], v212, 0, s[24:25]
	v_addc_co_u32_e64 v212, s[30:31], v212, 0, s[26:27]
	v_addc_co_u32_e64 v212, s[30:31], v212, 0, s[28:29]
	v_cmp_ge_f32_e64 s[22:23], v164, v208
	v_cmp_ge_f32_e64 s[24:25], v165, v208
	v_cmp_ge_f32_e64 s[26:27], v166, v208
	v_cmp_ge_f32_e64 s[28:29], v167, v208
	v_addc_co_u32_e64 v212, s[30:31], v212, 0, s[22:23]
	v_addc_co_u32_e64 v212, s[30:31], v212, 0, s[24:25]
	v_addc_co_u32_e64 v212, s[30:31], v212, 0, s[26:27]
	v_addc_co_u32_e64 v212, s[30:31], v212, 0, s[28:29]
	v_cmp_ge_f32_e64 s[22:23], v168, v208
	v_cmp_ge_f32_e64 s[24:25], v169, v208
	v_cmp_ge_f32_e64 s[26:27], v170, v208
	v_cmp_ge_f32_e64 s[28:29], v171, v208
	v_addc_co_u32_e64 v212, s[30:31], v212, 0, s[22:23]
	v_addc_co_u32_e64 v212, s[30:31], v212, 0, s[24:25]
	v_addc_co_u32_e64 v212, s[30:31], v212, 0, s[26:27]
	v_addc_co_u32_e64 v212, s[30:31], v212, 0, s[28:29]
	v_cmp_ge_f32_e64 s[22:23], v172, v208
	v_cmp_ge_f32_e64 s[24:25], v173, v208
	v_cmp_ge_f32_e64 s[26:27], v174, v208
	v_cmp_ge_f32_e64 s[28:29], v175, v208
	v_addc_co_u32_e64 v212, s[30:31], v212, 0, s[22:23]
	v_addc_co_u32_e64 v212, s[30:31], v212, 0, s[24:25]
	v_addc_co_u32_e64 v212, s[30:31], v212, 0, s[26:27]
	v_addc_co_u32_e64 v212, s[30:31], v212, 0, s[28:29]
	v_cmp_ge_f32_e64 s[22:23], v176, v208
	v_cmp_ge_f32_e64 s[24:25], v177, v208
	v_cmp_ge_f32_e64 s[26:27], v178, v208
	v_cmp_ge_f32_e64 s[28:29], v179, v208
	v_addc_co_u32_e64 v212, s[30:31], v212, 0, s[22:23]
	v_addc_co_u32_e64 v212, s[30:31], v212, 0, s[24:25]
	v_addc_co_u32_e64 v212, s[30:31], v212, 0, s[26:27]
	v_addc_co_u32_e64 v212, s[30:31], v212, 0, s[28:29]
	v_cmp_ge_f32_e64 s[22:23], v180, v208
	v_cmp_ge_f32_e64 s[24:25], v181, v208
	v_cmp_ge_f32_e64 s[26:27], v182, v208
	v_cmp_ge_f32_e64 s[28:29], v183, v208
	v_addc_co_u32_e64 v212, s[30:31], v212, 0, s[22:23]
	v_addc_co_u32_e64 v212, s[30:31], v212, 0, s[24:25]
	v_addc_co_u32_e64 v212, s[30:31], v212, 0, s[26:27]
	v_addc_co_u32_e64 v212, s[30:31], v212, 0, s[28:29]
	v_cmp_ge_f32_e64 s[22:23], v184, v208
	v_cmp_ge_f32_e64 s[24:25], v185, v208
	v_cmp_ge_f32_e64 s[26:27], v186, v208
	v_cmp_ge_f32_e64 s[28:29], v187, v208
	v_addc_co_u32_e64 v212, s[30:31], v212, 0, s[22:23]
	v_addc_co_u32_e64 v212, s[30:31], v212, 0, s[24:25]
	v_addc_co_u32_e64 v212, s[30:31], v212, 0, s[26:27]
	v_addc_co_u32_e64 v212, s[30:31], v212, 0, s[28:29]
	v_cmp_ge_f32_e64 s[22:23], v188, v208
	v_cmp_ge_f32_e64 s[24:25], v189, v208
	v_cmp_ge_f32_e64 s[26:27], v190, v208
	v_cmp_ge_f32_e64 s[28:29], v191, v208
	v_addc_co_u32_e64 v212, s[30:31], v212, 0, s[22:23]
	v_addc_co_u32_e64 v212, s[30:31], v212, 0, s[24:25]
	v_addc_co_u32_e64 v212, s[30:31], v212, 0, s[26:27]
	v_addc_co_u32_e64 v212, s[30:31], v212, 0, s[28:29]
	v_cmp_ge_f32_e64 s[22:23], v192, v208
	v_cmp_ge_f32_e64 s[24:25], v193, v208
	v_cmp_ge_f32_e64 s[26:27], v194, v208
	v_cmp_ge_f32_e64 s[28:29], v195, v208
	v_addc_co_u32_e64 v212, s[30:31], v212, 0, s[22:23]
	v_addc_co_u32_e64 v212, s[30:31], v212, 0, s[24:25]
	v_addc_co_u32_e64 v212, s[30:31], v212, 0, s[26:27]
	v_addc_co_u32_e64 v212, s[30:31], v212, 0, s[28:29]
	v_cmp_ge_f32_e64 s[22:23], v196, v208
	v_cmp_ge_f32_e64 s[24:25], v197, v208
	v_cmp_ge_f32_e64 s[26:27], v198, v208
	v_cmp_ge_f32_e64 s[28:29], v199, v208
	v_addc_co_u32_e64 v212, s[30:31], v212, 0, s[22:23]
	v_addc_co_u32_e64 v212, s[30:31], v212, 0, s[24:25]
	v_addc_co_u32_e64 v212, s[30:31], v212, 0, s[26:27]
	v_addc_co_u32_e64 v212, s[30:31], v212, 0, s[28:29]
	v_cmp_ge_f32_e64 s[22:23], v200, v208
	v_cmp_ge_f32_e64 s[24:25], v201, v208
	v_cmp_ge_f32_e64 s[26:27], v202, v208
	v_cmp_ge_f32_e64 s[28:29], v203, v208
	v_addc_co_u32_e64 v212, s[30:31], v212, 0, s[22:23]
	v_addc_co_u32_e64 v212, s[30:31], v212, 0, s[24:25]
	v_addc_co_u32_e64 v212, s[30:31], v212, 0, s[26:27]
	v_addc_co_u32_e64 v212, s[30:31], v212, 0, s[28:29]
	v_cmp_ge_f32_e64 s[22:23], v204, v208
	v_cmp_ge_f32_e64 s[24:25], v205, v208
	v_cmp_ge_f32_e64 s[26:27], v206, v208
	v_cmp_ge_f32_e64 s[28:29], v207, v208
	v_addc_co_u32_e64 v212, s[30:31], v212, 0, s[22:23]
	v_addc_co_u32_e64 v212, s[30:31], v212, 0, s[24:25]
	v_addc_co_u32_e64 v212, s[30:31], v212, 0, s[26:27]
	v_addc_co_u32_e64 v212, s[30:31], v212, 0, s[28:29]
	v_cmp_gt_f32_e64 s[22:23], v209, v208
	s_nop 0
	s_nop 0
	v_addc_co_u32_e64 v212, s[30:31], v212, 0, s[22:23]
	v_cmp_gt_u32_e32 vcc, 16, v212
	s_and_saveexec_b64 s[40:41], vcc
	v_lshl_add_u32 v214, v212, 2, v213
	v_mov_b32_e32 v212, 48
	ds_write_b32 v214, v208
	ds_write_b32 v214, v212 offset:4096
	s_mov_b64 exec, -1
	s_branch .Lrk0_end
; __device__ __forceinline__ void ph_peer_select(const Params& P, int layer, const h16* Q, int nrows, char* smem) {
;     ...
;     for (int i = tid; i < 64 * 50; i += NTHR) {
;       const int tok = i / 50, c = i % 50;
;       const float v = cd[tok * 52 + c];
;       int rank = 0;
;       for (int j = 0; j < 50; ++j) { const float o = cd[tok * 52 + j]; rank += (o > v || (o == v && j < c)) ? 1 : 0; }
;       if (rank < TOPK) { tv[tok * 16 + rank] = v; tp[tok * 16 + rank] = c; }
;     }
;     __syncthreads();
;     for (int i = tid; i < 64 * 16; i += NTHR) {
;       const int tok = i / 16, k = i % 16;
.Lrk0_c49:
	v_mov_b32_e32 v212, 0
	v_cmp_ge_f32_e64 s[22:23], v160, v209
	v_cmp_ge_f32_e64 s[24:25], v161, v209
	v_cmp_ge_f32_e64 s[26:27], v162, v209
	v_cmp_ge_f32_e64 s[28:29], v163, v209
	v_addc_co_u32_e64 v212, s[30:31], v212, 0, s[22:23]
	v_addc_co_u32_e64 v212, s[30:31], v212, 0, s[24:25]
	v_addc_co_u32_e64 v212, s[30:31], v212, 0, s[26:27]
	v_addc_co_u32_e64 v212, s[30:31], v212, 0, s[28:29]
	v_cmp_ge_f32_e64 s[22:23], v164, v209
	v_cmp_ge_f32_e64 s[24:25], v165, v209
	v_cmp_ge_f32_e64 s[26:27], v166, v209
	v_cmp_ge_f32_e64 s[28:29], v167, v209
	v_addc_co_u32_e64 v212, s[30:31], v212, 0, s[22:23]
	v_addc_co_u32_e64 v212, s[30:31], v212, 0, s[24:25]
	v_addc_co_u32_e64 v212, s[30:31], v212, 0, s[26:27]
	v_addc_co_u32_e64 v212, s[30:31], v212, 0, s[28:29]
	v_cmp_ge_f32_e64 s[22:23], v168, v209
	v_cmp_ge_f32_e64 s[24:25], v169, v209
	v_cmp_ge_f32_e64 s[26:27], v170, v209
	v_cmp_ge_f32_e64 s[28:29], v171, v209
	v_addc_co_u32_e64 v212, s[30:31], v212, 0, s[22:23]
	v_addc_co_u32_e64 v212, s[30:31], v212, 0, s[24:25]
	v_addc_co_u32_e64 v212, s[30:31], v212, 0, s[26:27]
	v_addc_co_u32_e64 v212, s[30:31], v212, 0, s[28:29]
	v_cmp_ge_f32_e64 s[22:23], v172, v209
	v_cmp_ge_f32_e64 s[24:25], v173, v209
	v_cmp_ge_f32_e64 s[26:27], v174, v209
	v_cmp_ge_f32_e64 s[28:29], v175, v209
	v_addc_co_u32_e64 v212, s[30:31], v212, 0, s[22:23]
	v_addc_co_u32_e64 v212, s[30:31], v212, 0, s[24:25]
	v_addc_co_u32_e64 v212, s[30:31], v212, 0, s[26:27]
	v_addc_co_u32_e64 v212, s[30:31], v212, 0, s[28:29]
	v_cmp_ge_f32_e64 s[22:23], v176, v209
	v_cmp_ge_f32_e64 s[24:25], v177, v209
	v_cmp_ge_f32_e64 s[26:27], v178, v209
	v_cmp_ge_f32_e64 s[28:29], v179, v209
	v_addc_co_u32_e64 v212, s[30:31], v212, 0, s[22:23]
	v_addc_co_u32_e64 v212, s[30:31], v212, 0, s[24:25]
	v_addc_co_u32_e64 v212, s[30:31], v212, 0, s[26:27]
	v_addc_co_u32_e64 v212, s[30:31], v212, 0, s[28:29]
	v_cmp_ge_f32_e64 s[22:23], v180, v209
	v_cmp_ge_f32_e64 s[24:25], v181, v209
	v_cmp_ge_f32_e64 s[26:27], v182, v209
	v_cmp_ge_f32_e64 s[28:29], v183, v209
	v_addc_co_u32_e64 v212, s[30:31], v212, 0, s[22:23]
	v_addc_co_u32_e64 v212, s[30:31], v212, 0, s[24:25]
	v_addc_co_u32_e64 v212, s[30:31], v212, 0, s[26:27]
	v_addc_co_u32_e64 v212, s[30:31], v212, 0, s[28:29]
	v_cmp_ge_f32_e64 s[22:23], v184, v209
	v_cmp_ge_f32_e64 s[24:25], v185, v209
	v_cmp_ge_f32_e64 s[26:27], v186, v209
	v_cmp_ge_f32_e64 s[28:29], v187, v209
	v_addc_co_u32_e64 v212, s[30:31], v212, 0, s[22:23]
	v_addc_co_u32_e64 v212, s[30:31], v212, 0, s[24:25]
	v_addc_co_u32_e64 v212, s[30:31], v212, 0, s[26:27]
	v_addc_co_u32_e64 v212, s[30:31], v212, 0, s[28:29]
	v_cmp_ge_f32_e64 s[22:23], v188, v209
	v_cmp_ge_f32_e64 s[24:25], v189, v209
	v_cmp_ge_f32_e64 s[26:27], v190, v209
	v_cmp_ge_f32_e64 s[28:29], v191, v209
	v_addc_co_u32_e64 v212, s[30:31], v212, 0, s[22:23]
	v_addc_co_u32_e64 v212, s[30:31], v212, 0, s[24:25]
	v_addc_co_u32_e64 v212, s[30:31], v212, 0, s[26:27]
	v_addc_co_u32_e64 v212, s[30:31], v212, 0, s[28:29]
	v_cmp_ge_f32_e64 s[22:23], v192, v209
	v_cmp_ge_f32_e64 s[24:25], v193, v209
	v_cmp_ge_f32_e64 s[26:27], v194, v209
	v_cmp_ge_f32_e64 s[28:29], v195, v209
	v_addc_co_u32_e64 v212, s[30:31], v212, 0, s[22:23]
	v_addc_co_u32_e64 v212, s[30:31], v212, 0, s[24:25]
	v_addc_co_u32_e64 v212, s[30:31], v212, 0, s[26:27]
	v_addc_co_u32_e64 v212, s[30:31], v212, 0, s[28:29]
	v_cmp_ge_f32_e64 s[22:23], v196, v209
	v_cmp_ge_f32_e64 s[24:25], v197, v209
	v_cmp_ge_f32_e64 s[26:27], v198, v209
	v_cmp_ge_f32_e64 s[28:29], v199, v209
	v_addc_co_u32_e64 v212, s[30:31], v212, 0, s[22:23]
	v_addc_co_u32_e64 v212, s[30:31], v212, 0, s[24:25]
	v_addc_co_u32_e64 v212, s[30:31], v212, 0, s[26:27]
	v_addc_co_u32_e64 v212, s[30:31], v212, 0, s[28:29]
	v_cmp_ge_f32_e64 s[22:23], v200, v209
	v_cmp_ge_f32_e64 s[24:25], v201, v209
	v_cmp_ge_f32_e64 s[26:27], v202, v209
	v_cmp_ge_f32_e64 s[28:29], v203, v209
	v_addc_co_u32_e64 v212, s[30:31], v212, 0, s[22:23]
	v_addc_co_u32_e64 v212, s[30:31], v212, 0, s[24:25]
	v_addc_co_u32_e64 v212, s[30:31], v212, 0, s[26:27]
	v_addc_co_u32_e64 v212, s[30:31], v212, 0, s[28:29]
	v_cmp_ge_f32_e64 s[22:23], v204, v209
	v_cmp_ge_f32_e64 s[24:25], v205, v209
	v_cmp_ge_f32_e64 s[26:27], v206, v209
	v_cmp_ge_f32_e64 s[28:29], v207, v209
	v_addc_co_u32_e64 v212, s[30:31], v212, 0, s[22:23]
	v_addc_co_u32_e64 v212, s[30:31], v212, 0, s[24:25]
	v_addc_co_u32_e64 v212, s[30:31], v212, 0, s[26:27]
	v_addc_co_u32_e64 v212, s[30:31], v212, 0, s[28:29]
	v_cmp_ge_f32_e64 s[22:23], v208, v209
	s_nop 0
	s_nop 0
	v_addc_co_u32_e64 v212, s[30:31], v212, 0, s[22:23]
	v_cmp_gt_u32_e32 vcc, 16, v212
	s_and_saveexec_b64 s[40:41], vcc
	v_lshl_add_u32 v214, v212, 2, v213
	v_mov_b32_e32 v212, 49
	ds_write_b32 v214, v209
	ds_write_b32 v214, v212 offset:4096
	s_mov_b64 exec, -1
	s_branch .Lrk0_end
.Lrk0_end:
.LBB0_1898:
	s_or_b64 exec, exec, s[38:39]
	s_waitcnt lgkmcnt(0)
	s_barrier
	s_and_saveexec_b64 s[22:23], s[16:17]
	s_cbranch_execz .LBB0_1871
	s_lshl_b32 s4, s56, 4
	s_mov_b64 s[24:25], 0
	v_mov_b32_e32 v6, v86
	v_mov_b32_e32 v8, v1

; __device__ __forceinline__ void ph_peer_select(const Params& P, int layer, const h16* Q, int nrows, char* smem) {
;     ...
;     __syncthreads();
;     for (int i = tid; i < 64 * 16; i += NTHR) {
;       const int tok = i / 16, k = i % 16;
.Lrk1_end:
.LBB0_3612:
	s_or_b64 exec, exec, s[38:39]
	s_waitcnt lgkmcnt(0)
	s_barrier
	s_and_saveexec_b64 s[22:23], s[16:17]
	s_cbranch_execz .LBB0_3585
	s_lshl_b32 s4, s54, 4
	s_mov_b64 s[24:25], 0
	v_mov_b32_e32 v6, v86
	v_mov_b32_e32 v8, v1
